# stack6 + row-stat atomics deferred and issued in batches of 4 per half unit (2 instead of 8 covered waits)
# speedup vs baseline: 1.0102x; 1.0012x over previous
; DEVI unsigned pk2(float lo, float hi) { unsigned r; asm("v_cvt_pk_bf16_f32 %0, %1, %2" : "=v"(r) : "v"(lo), "v"(hi)); return r; }
;     DEVI void operator()(const f32x4 (&acc)[2][2][4][2], const pg8::Unit& u, int wr, int wc, int fr, int fq) const {
;     ...
;                         *(f32x4*)(zdst + (size_t)row * DM + col) = zz;
;                         sum += zz[0] + zz[1] + zz[2] + zz[3]; sq += zz[0] * zz[0] + zz[1] * zz[1] + zz[2] * zz[2] + zz[3] * zz[3];
;                         z[n] = zz;
;                     }
;                     u32x4 o; o.x = pk2(z[0][0], z[0][1]); o.y = pk2(z[0][2], z[0][3]); o.z = pk2(z[1][0], z[1][1]); o.w = pk2(z[1][2], z[1][3]);
;                     if (zb) *(u32x4*)(zb + (size_t)row * DM + colb + bj * 128) = o;
;                 }
;                 sum += __shfl_xor(sum, 16); sq += __shfl_xor(sq, 16);
;                 sum += __shfl_xor(sum, 32); sq += __shfl_xor(sq, 32);
;                 if (fq == 0) { atomicAdd(stout + 2 * (size_t)row, sum); atomicAdd(stout + 2 * (size_t)row + 1, sq); }
.LBB0_515:
	v_add_f32_e32 v154, v124, v125
	v_mul_f32_e32 v125, v125, v125
	v_fmac_f32_e32 v125, v124, v124
	v_add_f32_e32 v124, v120, v121
	v_mul_f32_e32 v121, v121, v121
	v_fmac_f32_e32 v121, v120, v120
	v_add_f32_e32 v124, v122, v124
	v_fmac_f32_e32 v121, v122, v122
	v_mul_f32_e32 v122, v117, v117
	v_fmac_f32_e32 v125, v126, v126
	v_fmac_f32_e32 v122, v116, v116
	v_add_f32_e32 v154, v126, v154
	v_fmac_f32_e32 v125, v127, v127
	v_fmac_f32_e32 v121, v123, v123
	v_fmac_f32_e32 v122, v118, v118
	v_add_f32_e32 v154, v127, v154
	v_add_f32_e32 v120, v125, v121
	v_add_f32_e32 v121, v116, v117
	v_fmac_f32_e32 v122, v119, v119
	v_add_f32_e32 v154, 0, v154
	v_add_f32_e32 v124, v123, v124
	v_add_f32_e32 v121, v118, v121
	v_add_f32_e32 v120, v120, v122
	v_add_f32_e32 v122, v112, v113
	v_add_f32_e32 v124, v154, v124
	v_add_f32_e32 v121, v119, v121
	v_add_f32_e32 v122, v114, v122
	v_add_f32_e32 v121, v124, v121
	v_add_f32_e32 v122, v115, v122
	v_add_f32_e32 v121, v121, v122
	v_mul_f32_e32 v122, v113, v113
	v_fmac_f32_e32 v122, v112, v112
	v_fmac_f32_e32 v122, v114, v114
	v_fmac_f32_e32 v122, v115, v115
	v_and_b32_e32 v123, 64, v162
	v_add_f32_e32 v122, v120, v122
	v_xor_b32_e32 v120, 16, v162
	v_add_u32_e32 v123, 64, v123
	v_cmp_lt_i32_e32 vcc, v120, v123
	v_cvt_pk_bf16_f32 v124, v116, v117
	global_store_dwordx4 v[150:151], v[112:115], off offset:528
	v_cvt_pk_bf16_f32 v127, v114, v115
	s_nop 0
	v_cndmask_b32_e32 v120, v162, v120, vcc
	v_lshlrev_b32_e32 v120, 2, v120
	ds_bpermute_b32 v125, v120, v121
	ds_bpermute_b32 v126, v120, v122
	s_waitcnt lgkmcnt(0)
	v_add_f32_e32 v116, v121, v125
	v_xor_b32_e32 v121, 32, v162
	v_cmp_lt_i32_e32 vcc, v121, v123
	v_add_f32_e32 v117, v122, v126
	v_cvt_pk_bf16_f32 v125, v118, v119
	v_cvt_pk_bf16_f32 v126, v112, v113
	flat_store_dwordx4 v[152:153], v[124:127] offset:256
	v_cndmask_b32_e32 v121, v162, v121, vcc
	v_lshlrev_b32_e32 v121, 2, v121
	ds_bpermute_b32 v122, v121, v116
	ds_bpermute_b32 v123, v121, v117
	s_mov_b32 s100, -1
	s_mov_b32 s101, 0
	s_mov_b32 s98, 0xffff0000
	s_mov_b32 s99, 0
	s_and_saveexec_b64 s[28:29], s[100:101]
	s_cbranch_execz .LBB0_517
	s_waitcnt lgkmcnt(0)
	v_add_f32_e32 v115, v116, v122
	v_lshl_add_u64 v[112:113], v[148:149], 3, s[6:7]
	v_add_f32_e32 v114, v117, v123
	v_cndmask_b32_e64 v115, v115, v114, s[98:99]
	v_cndmask_b32_e64 v114, 0, 4, s[98:99]
	v_or_b32_e32 v112, v112, v114
	v_mov_b32_e32 v250, v112
	v_mov_b32_e32 v251, v113
	v_mov_b32_e32 v252, v115

; DEVI unsigned pk2(float lo, float hi) { unsigned r; asm("v_cvt_pk_bf16_f32 %0, %1, %2" : "=v"(r) : "v"(lo), "v"(hi)); return r; }
;     DEVI void operator()(const f32x4 (&acc)[2][2][4][2], const pg8::Unit& u, int wr, int wc, int fr, int fq) const {
;     ...
;                         *(f32x4*)(zdst + (size_t)row * DM + col) = zz;
;                         sum += zz[0] + zz[1] + zz[2] + zz[3]; sq += zz[0] * zz[0] + zz[1] * zz[1] + zz[2] * zz[2] + zz[3] * zz[3];
;                         z[n] = zz;
;                     }
;                     u32x4 o; o.x = pk2(z[0][0], z[0][1]); o.y = pk2(z[0][2], z[0][3]); o.z = pk2(z[1][0], z[1][1]); o.w = pk2(z[1][2], z[1][3]);
;                     if (zb) *(u32x4*)(zb + (size_t)row * DM + colb + bj * 128) = o;
;                 }
;                 sum += __shfl_xor(sum, 16); sq += __shfl_xor(sq, 16);
;                 sum += __shfl_xor(sum, 32); sq += __shfl_xor(sq, 32);
;                 if (fq == 0) { atomicAdd(stout + 2 * (size_t)row, sum); atomicAdd(stout + 2 * (size_t)row + 1, sq); }
.LBB0_525:
	v_add_f32_e32 v118, v108, v109
	v_mul_f32_e32 v109, v109, v109
	v_fmac_f32_e32 v109, v108, v108
	v_add_f32_e32 v108, v104, v105
	v_mul_f32_e32 v105, v105, v105
	v_fmac_f32_e32 v105, v104, v104
	v_add_f32_e32 v108, v106, v108
	v_fmac_f32_e32 v105, v106, v106
	v_mul_f32_e32 v106, v101, v101
	v_fmac_f32_e32 v109, v110, v110
	v_fmac_f32_e32 v106, v100, v100
	v_add_f32_e32 v118, v110, v118
	v_fmac_f32_e32 v109, v111, v111
	v_fmac_f32_e32 v105, v107, v107
	v_fmac_f32_e32 v106, v102, v102
	v_add_f32_e32 v118, v111, v118
	v_add_f32_e32 v104, v109, v105
	v_add_f32_e32 v105, v100, v101
	v_fmac_f32_e32 v106, v103, v103
	v_add_f32_e32 v118, 0, v118
	v_add_f32_e32 v108, v107, v108
	v_add_f32_e32 v105, v102, v105
	v_add_f32_e32 v104, v104, v106
	v_add_f32_e32 v106, v96, v97
	v_add_f32_e32 v108, v118, v108
	v_add_f32_e32 v105, v103, v105
	v_add_f32_e32 v106, v98, v106
	v_add_f32_e32 v105, v108, v105
	v_add_f32_e32 v106, v99, v106
	v_add_f32_e32 v105, v105, v106
	v_mul_f32_e32 v106, v97, v97
	v_fmac_f32_e32 v106, v96, v96
	v_fmac_f32_e32 v106, v98, v98
	v_fmac_f32_e32 v106, v99, v99
	v_add_f32_e32 v104, v104, v106
	ds_bpermute_b32 v107, v120, v105
	ds_bpermute_b32 v108, v120, v104
	v_cvt_pk_bf16_f32 v106, v100, v101
	global_store_dwordx4 v[114:115], v[96:99], off offset:528
	v_cvt_pk_bf16_f32 v109, v98, v99
	s_waitcnt lgkmcnt(0)
	v_add_f32_e32 v100, v105, v107
	v_add_f32_e32 v101, v104, v108
	ds_bpermute_b32 v104, v121, v100
	ds_bpermute_b32 v105, v121, v101
	v_cvt_pk_bf16_f32 v107, v102, v103
	v_cvt_pk_bf16_f32 v108, v96, v97
	flat_store_dwordx4 v[116:117], v[106:109] offset:256
	s_mov_b32 s100, -1
	s_mov_b32 s101, 0
	s_mov_b32 s98, 0xffff0000
	s_mov_b32 s99, 0
	s_and_saveexec_b64 s[28:29], s[100:101]
	s_cbranch_execz .LBB0_527
	s_waitcnt lgkmcnt(0)
	v_add_f32_e32 v99, v100, v104
	v_lshl_add_u64 v[96:97], v[112:113], 3, s[6:7]
	v_add_f32_e32 v98, v101, v105
	v_cndmask_b32_e64 v99, v99, v98, s[98:99]
	v_cndmask_b32_e64 v98, 0, 4, s[98:99]
	v_or_b32_e32 v96, v96, v98
	v_mov_b32_e32 v253, v99

; DEVI unsigned pk2(float lo, float hi) { unsigned r; asm("v_cvt_pk_bf16_f32 %0, %1, %2" : "=v"(r) : "v"(lo), "v"(hi)); return r; }
;     DEVI void operator()(const f32x4 (&acc)[2][2][4][2], const pg8::Unit& u, int wr, int wc, int fr, int fq) const {
;     ...
;                         *(f32x4*)(zdst + (size_t)row * DM + col) = zz;
;                         sum += zz[0] + zz[1] + zz[2] + zz[3]; sq += zz[0] * zz[0] + zz[1] * zz[1] + zz[2] * zz[2] + zz[3] * zz[3];
;                         z[n] = zz;
;                     }
;                     u32x4 o; o.x = pk2(z[0][0], z[0][1]); o.y = pk2(z[0][2], z[0][3]); o.z = pk2(z[1][0], z[1][1]); o.w = pk2(z[1][2], z[1][3]);
;                     if (zb) *(u32x4*)(zb + (size_t)row * DM + colb + bj * 128) = o;
;                 }
;                 sum += __shfl_xor(sum, 16); sq += __shfl_xor(sq, 16);
;                 sum += __shfl_xor(sum, 32); sq += __shfl_xor(sq, 32);
;                 if (fq == 0) { atomicAdd(stout + 2 * (size_t)row, sum); atomicAdd(stout + 2 * (size_t)row + 1, sq); }
.LBB0_535:
	v_add_f32_e32 v102, v92, v93
	v_mul_f32_e32 v93, v93, v93
	v_fmac_f32_e32 v93, v92, v92
	v_add_f32_e32 v92, v88, v89
	v_mul_f32_e32 v89, v89, v89
	v_fmac_f32_e32 v89, v88, v88
	v_add_f32_e32 v92, v90, v92
	v_fmac_f32_e32 v89, v90, v90
	v_mul_f32_e32 v90, v85, v85
	v_fmac_f32_e32 v93, v94, v94
	v_fmac_f32_e32 v90, v84, v84
	v_add_f32_e32 v102, v94, v102
	v_fmac_f32_e32 v93, v95, v95
	v_fmac_f32_e32 v89, v91, v91
	v_fmac_f32_e32 v90, v86, v86
	v_add_f32_e32 v102, v95, v102
	v_add_f32_e32 v88, v93, v89
	v_add_f32_e32 v89, v84, v85
	v_fmac_f32_e32 v90, v87, v87
	v_add_f32_e32 v102, 0, v102
	v_add_f32_e32 v92, v91, v92
	v_add_f32_e32 v89, v86, v89
	v_add_f32_e32 v88, v88, v90
	v_add_f32_e32 v90, v80, v81
	v_add_f32_e32 v92, v102, v92
	v_add_f32_e32 v89, v87, v89
	v_add_f32_e32 v90, v82, v90
	v_add_f32_e32 v89, v92, v89
	v_add_f32_e32 v90, v83, v90
	v_add_f32_e32 v89, v89, v90
	v_mul_f32_e32 v90, v81, v81
	v_fmac_f32_e32 v90, v80, v80
	v_fmac_f32_e32 v90, v82, v82
	v_fmac_f32_e32 v90, v83, v83
	v_add_f32_e32 v88, v88, v90
	ds_bpermute_b32 v91, v120, v89
	ds_bpermute_b32 v92, v120, v88
	v_cvt_pk_bf16_f32 v90, v84, v85
	global_store_dwordx4 v[98:99], v[80:83], off offset:528
	v_cvt_pk_bf16_f32 v93, v82, v83
	s_waitcnt lgkmcnt(0)
	v_add_f32_e32 v84, v89, v91
	v_add_f32_e32 v85, v88, v92
	ds_bpermute_b32 v88, v121, v84
	ds_bpermute_b32 v89, v121, v85
	v_cvt_pk_bf16_f32 v91, v86, v87
	v_cvt_pk_bf16_f32 v92, v80, v81
	flat_store_dwordx4 v[100:101], v[90:93] offset:256
	s_mov_b32 s100, -1
	s_mov_b32 s101, 0
	s_mov_b32 s98, 0xffff0000
	s_mov_b32 s99, 0
	s_and_saveexec_b64 s[28:29], s[100:101]
	s_cbranch_execz .LBB0_537
	s_waitcnt lgkmcnt(0)
	v_add_f32_e32 v83, v84, v88
	v_lshl_add_u64 v[80:81], v[96:97], 3, s[6:7]
	v_add_f32_e32 v82, v85, v89
	v_cndmask_b32_e64 v83, v83, v82, s[98:99]
	v_cndmask_b32_e64 v82, 0, 4, s[98:99]
	v_or_b32_e32 v80, v80, v82
	v_mov_b32_e32 v254, v83

; DEVI unsigned pk2(float lo, float hi) { unsigned r; asm("v_cvt_pk_bf16_f32 %0, %1, %2" : "=v"(r) : "v"(lo), "v"(hi)); return r; }
;     DEVI void operator()(const f32x4 (&acc)[2][2][4][2], const pg8::Unit& u, int wr, int wc, int fr, int fq) const {
;     ...
;                         *(f32x4*)(zdst + (size_t)row * DM + col) = zz;
;                         sum += zz[0] + zz[1] + zz[2] + zz[3]; sq += zz[0] * zz[0] + zz[1] * zz[1] + zz[2] * zz[2] + zz[3] * zz[3];
;                         z[n] = zz;
;                     }
;                     u32x4 o; o.x = pk2(z[0][0], z[0][1]); o.y = pk2(z[0][2], z[0][3]); o.z = pk2(z[1][0], z[1][1]); o.w = pk2(z[1][2], z[1][3]);
;                     if (zb) *(u32x4*)(zb + (size_t)row * DM + colb + bj * 128) = o;
;                 }
;                 sum += __shfl_xor(sum, 16); sq += __shfl_xor(sq, 16);
;                 sum += __shfl_xor(sum, 32); sq += __shfl_xor(sq, 32);
;                 if (fq == 0) { atomicAdd(stout + 2 * (size_t)row, sum); atomicAdd(stout + 2 * (size_t)row + 1, sq); }
.LBB0_545:
	v_add_f32_e32 v86, v76, v77
	v_mul_f32_e32 v77, v77, v77
	v_fmac_f32_e32 v77, v76, v76
	v_add_f32_e32 v76, v72, v73
	v_mul_f32_e32 v73, v73, v73
	v_fmac_f32_e32 v73, v72, v72
	v_add_f32_e32 v76, v74, v76
	v_fmac_f32_e32 v73, v74, v74
	v_mul_f32_e32 v74, v69, v69
	v_fmac_f32_e32 v77, v78, v78
	v_fmac_f32_e32 v74, v68, v68
	v_add_f32_e32 v86, v78, v86
	v_fmac_f32_e32 v77, v79, v79
	v_fmac_f32_e32 v73, v75, v75
	v_fmac_f32_e32 v74, v70, v70
	v_add_f32_e32 v86, v79, v86
	v_add_f32_e32 v72, v77, v73
	v_add_f32_e32 v73, v68, v69
	v_fmac_f32_e32 v74, v71, v71
	v_add_f32_e32 v86, 0, v86
	v_add_f32_e32 v76, v75, v76
	v_add_f32_e32 v73, v70, v73
	v_add_f32_e32 v72, v72, v74
	v_add_f32_e32 v74, v64, v65
	v_add_f32_e32 v76, v86, v76
	v_add_f32_e32 v73, v71, v73
	v_add_f32_e32 v74, v66, v74
	v_add_f32_e32 v73, v76, v73
	v_add_f32_e32 v74, v67, v74
	v_add_f32_e32 v73, v73, v74
	v_mul_f32_e32 v74, v65, v65
	v_fmac_f32_e32 v74, v64, v64
	v_fmac_f32_e32 v74, v66, v66
	v_fmac_f32_e32 v74, v67, v67
	v_add_f32_e32 v72, v72, v74
	ds_bpermute_b32 v75, v120, v73
	ds_bpermute_b32 v76, v120, v72
	v_cvt_pk_bf16_f32 v74, v68, v69
	global_store_dwordx4 v[82:83], v[64:67], off offset:528
	v_cvt_pk_bf16_f32 v77, v66, v67
	s_waitcnt lgkmcnt(0)
	v_add_f32_e32 v68, v73, v75
	v_add_f32_e32 v69, v72, v76
	ds_bpermute_b32 v72, v121, v68
	ds_bpermute_b32 v73, v121, v69
	v_cvt_pk_bf16_f32 v75, v70, v71
	v_cvt_pk_bf16_f32 v76, v64, v65
	flat_store_dwordx4 v[84:85], v[74:77] offset:256
	s_mov_b32 s100, -1
	s_mov_b32 s101, 0
	s_mov_b32 s98, 0xffff0000
	s_mov_b32 s99, 0
	s_and_saveexec_b64 s[28:29], s[100:101]
	s_cbranch_execz .LBB0_547
	s_waitcnt lgkmcnt(0)
	v_add_f32_e32 v67, v68, v72
	v_lshl_add_u64 v[64:65], v[80:81], 3, s[6:7]
	v_add_f32_e32 v66, v69, v73
	v_cndmask_b32_e64 v67, v67, v66, s[98:99]
	v_cndmask_b32_e64 v66, 0, 4, s[98:99]
	v_or_b32_e32 v64, v64, v66
	v_mov_b32_e32 v255, v67
	flat_atomic_add_f32 v[250:251], v252
	flat_atomic_add_f32 v[250:251], v253 offset:128
	flat_atomic_add_f32 v[250:251], v254 offset:256
	flat_atomic_add_f32 v[250:251], v255 offset:384

; DEVI unsigned pk2(float lo, float hi) { unsigned r; asm("v_cvt_pk_bf16_f32 %0, %1, %2" : "=v"(r) : "v"(lo), "v"(hi)); return r; }
;     DEVI void operator()(const f32x4 (&acc)[2][2][4][2], const pg8::Unit& u, int wr, int wc, int fr, int fq) const {
;     ...
;                         *(f32x4*)(zdst + (size_t)row * DM + col) = zz;
;                         sum += zz[0] + zz[1] + zz[2] + zz[3]; sq += zz[0] * zz[0] + zz[1] * zz[1] + zz[2] * zz[2] + zz[3] * zz[3];
;                         z[n] = zz;
;                     }
;                     u32x4 o; o.x = pk2(z[0][0], z[0][1]); o.y = pk2(z[0][2], z[0][3]); o.z = pk2(z[1][0], z[1][1]); o.w = pk2(z[1][2], z[1][3]);
;                     if (zb) *(u32x4*)(zb + (size_t)row * DM + colb + bj * 128) = o;
;                 }
;                 sum += __shfl_xor(sum, 16); sq += __shfl_xor(sq, 16);
;                 sum += __shfl_xor(sum, 32); sq += __shfl_xor(sq, 32);
;                 if (fq == 0) { atomicAdd(stout + 2 * (size_t)row, sum); atomicAdd(stout + 2 * (size_t)row + 1, sq); }
.LBB0_555:
	v_add_f32_e32 v70, v60, v61
	v_mul_f32_e32 v61, v61, v61
	v_fmac_f32_e32 v61, v60, v60
	v_add_f32_e32 v60, v56, v57
	v_mul_f32_e32 v57, v57, v57
	v_fmac_f32_e32 v57, v56, v56
	v_add_f32_e32 v60, v58, v60
	v_fmac_f32_e32 v57, v58, v58
	v_mul_f32_e32 v58, v53, v53
	v_fmac_f32_e32 v61, v62, v62
	v_fmac_f32_e32 v58, v52, v52
	v_add_f32_e32 v70, v62, v70
	v_fmac_f32_e32 v61, v63, v63
	v_fmac_f32_e32 v57, v59, v59
	v_fmac_f32_e32 v58, v54, v54
	v_add_f32_e32 v70, v63, v70
	v_add_f32_e32 v56, v61, v57
	v_add_f32_e32 v57, v52, v53
	v_fmac_f32_e32 v58, v55, v55
	v_add_f32_e32 v70, 0, v70
	v_add_f32_e32 v60, v59, v60
	v_add_f32_e32 v57, v54, v57
	v_add_f32_e32 v56, v56, v58
	v_add_f32_e32 v58, v48, v49
	v_add_f32_e32 v60, v70, v60
	v_add_f32_e32 v57, v55, v57
	v_add_f32_e32 v58, v50, v58
	v_add_f32_e32 v57, v60, v57
	v_add_f32_e32 v58, v51, v58
	v_add_f32_e32 v57, v57, v58
	v_mul_f32_e32 v58, v49, v49
	v_fmac_f32_e32 v58, v48, v48
	v_fmac_f32_e32 v58, v50, v50
	v_fmac_f32_e32 v58, v51, v51
	v_add_f32_e32 v56, v56, v58
	ds_bpermute_b32 v59, v120, v57
	ds_bpermute_b32 v60, v120, v56
	v_cvt_pk_bf16_f32 v58, v52, v53
	global_store_dwordx4 v[66:67], v[48:51], off offset:528
	v_cvt_pk_bf16_f32 v61, v50, v51
	s_waitcnt lgkmcnt(0)
	v_add_f32_e32 v52, v57, v59
	v_add_f32_e32 v53, v56, v60
	ds_bpermute_b32 v56, v121, v52
	ds_bpermute_b32 v57, v121, v53
	v_cvt_pk_bf16_f32 v59, v54, v55
	v_cvt_pk_bf16_f32 v60, v48, v49
	flat_store_dwordx4 v[68:69], v[58:61] offset:256
	s_mov_b32 s100, -1
	s_mov_b32 s101, 0
	s_mov_b32 s98, 0xffff0000
	s_mov_b32 s99, 0
	s_and_saveexec_b64 s[28:29], s[100:101]
	s_cbranch_execz .LBB0_557
	s_waitcnt lgkmcnt(0)
	v_add_f32_e32 v51, v52, v56
	v_lshl_add_u64 v[48:49], v[64:65], 3, s[6:7]
	v_add_f32_e32 v50, v53, v57
	v_cndmask_b32_e64 v51, v51, v50, s[98:99]
	v_cndmask_b32_e64 v50, 0, 4, s[98:99]
	v_or_b32_e32 v48, v48, v50
	v_mov_b32_e32 v250, v48
	v_mov_b32_e32 v251, v49
	v_mov_b32_e32 v252, v51

; DEVI unsigned pk2(float lo, float hi) { unsigned r; asm("v_cvt_pk_bf16_f32 %0, %1, %2" : "=v"(r) : "v"(lo), "v"(hi)); return r; }
;     DEVI void operator()(const f32x4 (&acc)[2][2][4][2], const pg8::Unit& u, int wr, int wc, int fr, int fq) const {
;     ...
;                         *(f32x4*)(zdst + (size_t)row * DM + col) = zz;
;                         sum += zz[0] + zz[1] + zz[2] + zz[3]; sq += zz[0] * zz[0] + zz[1] * zz[1] + zz[2] * zz[2] + zz[3] * zz[3];
;                         z[n] = zz;
;                     }
;                     u32x4 o; o.x = pk2(z[0][0], z[0][1]); o.y = pk2(z[0][2], z[0][3]); o.z = pk2(z[1][0], z[1][1]); o.w = pk2(z[1][2], z[1][3]);
;                     if (zb) *(u32x4*)(zb + (size_t)row * DM + colb + bj * 128) = o;
;                 }
;                 sum += __shfl_xor(sum, 16); sq += __shfl_xor(sq, 16);
;                 sum += __shfl_xor(sum, 32); sq += __shfl_xor(sq, 32);
;                 if (fq == 0) { atomicAdd(stout + 2 * (size_t)row, sum); atomicAdd(stout + 2 * (size_t)row + 1, sq); }
.LBB0_565:
	v_add_f32_e32 v54, v44, v45
	v_mul_f32_e32 v45, v45, v45
	v_fmac_f32_e32 v45, v44, v44
	v_add_f32_e32 v44, v40, v41
	v_mul_f32_e32 v41, v41, v41
	v_fmac_f32_e32 v41, v40, v40
	v_add_f32_e32 v44, v42, v44
	v_fmac_f32_e32 v41, v42, v42
	v_mul_f32_e32 v42, v37, v37
	v_fmac_f32_e32 v45, v46, v46
	v_fmac_f32_e32 v42, v36, v36
	v_add_f32_e32 v54, v46, v54
	v_fmac_f32_e32 v45, v47, v47
	v_fmac_f32_e32 v41, v43, v43
	v_fmac_f32_e32 v42, v38, v38
	v_add_f32_e32 v54, v47, v54
	v_add_f32_e32 v40, v45, v41
	v_add_f32_e32 v41, v36, v37
	v_fmac_f32_e32 v42, v39, v39
	v_add_f32_e32 v54, 0, v54
	v_add_f32_e32 v44, v43, v44
	v_add_f32_e32 v41, v38, v41
	v_add_f32_e32 v40, v40, v42
	v_add_f32_e32 v42, v32, v33
	v_add_f32_e32 v44, v54, v44
	v_add_f32_e32 v41, v39, v41
	v_add_f32_e32 v42, v34, v42
	v_add_f32_e32 v41, v44, v41
	v_add_f32_e32 v42, v35, v42
	v_add_f32_e32 v41, v41, v42
	v_mul_f32_e32 v42, v33, v33
	v_fmac_f32_e32 v42, v32, v32
	v_fmac_f32_e32 v42, v34, v34
	v_fmac_f32_e32 v42, v35, v35
	v_add_f32_e32 v40, v40, v42
	ds_bpermute_b32 v43, v120, v41
	ds_bpermute_b32 v44, v120, v40
	v_cvt_pk_bf16_f32 v42, v36, v37
	global_store_dwordx4 v[50:51], v[32:35], off offset:528
	v_cvt_pk_bf16_f32 v45, v34, v35
	s_waitcnt lgkmcnt(0)
	v_add_f32_e32 v36, v41, v43
	v_add_f32_e32 v37, v40, v44
	ds_bpermute_b32 v40, v121, v36
	ds_bpermute_b32 v41, v121, v37
	v_cvt_pk_bf16_f32 v43, v38, v39
	v_cvt_pk_bf16_f32 v44, v32, v33
	flat_store_dwordx4 v[52:53], v[42:45] offset:256
	s_mov_b32 s100, -1
	s_mov_b32 s101, 0
	s_mov_b32 s98, 0xffff0000
	s_mov_b32 s99, 0
	s_and_saveexec_b64 s[28:29], s[100:101]
	s_cbranch_execz .LBB0_567
	s_waitcnt lgkmcnt(0)
	v_add_f32_e32 v35, v36, v40
	v_lshl_add_u64 v[32:33], v[48:49], 3, s[6:7]
	v_add_f32_e32 v34, v37, v41
	v_cndmask_b32_e64 v35, v35, v34, s[98:99]
	v_cndmask_b32_e64 v34, 0, 4, s[98:99]
	v_or_b32_e32 v32, v32, v34
	v_mov_b32_e32 v253, v35

; DEVI unsigned pk2(float lo, float hi) { unsigned r; asm("v_cvt_pk_bf16_f32 %0, %1, %2" : "=v"(r) : "v"(lo), "v"(hi)); return r; }
;     DEVI void operator()(const f32x4 (&acc)[2][2][4][2], const pg8::Unit& u, int wr, int wc, int fr, int fq) const {
;     ...
;                         *(f32x4*)(zdst + (size_t)row * DM + col) = zz;
;                         sum += zz[0] + zz[1] + zz[2] + zz[3]; sq += zz[0] * zz[0] + zz[1] * zz[1] + zz[2] * zz[2] + zz[3] * zz[3];
;                         z[n] = zz;
;                     }
;                     u32x4 o; o.x = pk2(z[0][0], z[0][1]); o.y = pk2(z[0][2], z[0][3]); o.z = pk2(z[1][0], z[1][1]); o.w = pk2(z[1][2], z[1][3]);
;                     if (zb) *(u32x4*)(zb + (size_t)row * DM + colb + bj * 128) = o;
;                 }
;                 sum += __shfl_xor(sum, 16); sq += __shfl_xor(sq, 16);
;                 sum += __shfl_xor(sum, 32); sq += __shfl_xor(sq, 32);
;                 if (fq == 0) { atomicAdd(stout + 2 * (size_t)row, sum); atomicAdd(stout + 2 * (size_t)row + 1, sq); }
.LBB0_575:
	v_add_f32_e32 v38, v28, v29
	v_mul_f32_e32 v29, v29, v29
	v_fmac_f32_e32 v29, v28, v28
	v_add_f32_e32 v28, v24, v25
	v_mul_f32_e32 v25, v25, v25
	v_fmac_f32_e32 v25, v24, v24
	v_add_f32_e32 v28, v26, v28
	v_fmac_f32_e32 v25, v26, v26
	v_mul_f32_e32 v26, v21, v21
	v_fmac_f32_e32 v29, v30, v30
	v_fmac_f32_e32 v26, v20, v20
	v_add_f32_e32 v38, v30, v38
	v_fmac_f32_e32 v29, v31, v31
	v_fmac_f32_e32 v25, v27, v27
	v_fmac_f32_e32 v26, v22, v22
	v_add_f32_e32 v38, v31, v38
	v_add_f32_e32 v24, v29, v25
	v_add_f32_e32 v25, v20, v21
	v_fmac_f32_e32 v26, v23, v23
	v_add_f32_e32 v38, 0, v38
	v_add_f32_e32 v28, v27, v28
	v_add_f32_e32 v25, v22, v25
	v_add_f32_e32 v24, v24, v26
	v_add_f32_e32 v26, v16, v17
	v_add_f32_e32 v28, v38, v28
	v_add_f32_e32 v25, v23, v25
	v_add_f32_e32 v26, v18, v26
	v_add_f32_e32 v25, v28, v25
	v_add_f32_e32 v26, v19, v26
	v_add_f32_e32 v25, v25, v26
	v_mul_f32_e32 v26, v17, v17
	v_fmac_f32_e32 v26, v16, v16
	v_fmac_f32_e32 v26, v18, v18
	v_fmac_f32_e32 v26, v19, v19
	v_add_f32_e32 v24, v24, v26
	ds_bpermute_b32 v27, v120, v25
	ds_bpermute_b32 v28, v120, v24
	v_cvt_pk_bf16_f32 v26, v20, v21
	global_store_dwordx4 v[34:35], v[16:19], off offset:528
	v_cvt_pk_bf16_f32 v29, v18, v19
	s_waitcnt lgkmcnt(0)
	v_add_f32_e32 v20, v25, v27
	v_add_f32_e32 v21, v24, v28
	ds_bpermute_b32 v24, v121, v20
	ds_bpermute_b32 v25, v121, v21
	v_cvt_pk_bf16_f32 v27, v22, v23
	v_cvt_pk_bf16_f32 v28, v16, v17
	flat_store_dwordx4 v[36:37], v[26:29] offset:256
	s_mov_b32 s100, -1
	s_mov_b32 s101, 0
	s_mov_b32 s98, 0xffff0000
	s_mov_b32 s99, 0
	s_and_saveexec_b64 s[28:29], s[100:101]
	s_cbranch_execz .LBB0_577
	s_waitcnt lgkmcnt(0)
	v_add_f32_e32 v19, v20, v24
	v_lshl_add_u64 v[16:17], v[32:33], 3, s[6:7]
	v_add_f32_e32 v18, v21, v25
	v_cndmask_b32_e64 v19, v19, v18, s[98:99]
	v_cndmask_b32_e64 v18, 0, 4, s[98:99]
	v_or_b32_e32 v16, v16, v18
	v_mov_b32_e32 v254, v19

; DEVI unsigned pk2(float lo, float hi) { unsigned r; asm("v_cvt_pk_bf16_f32 %0, %1, %2" : "=v"(r) : "v"(lo), "v"(hi)); return r; }
;     DEVI void operator()(const f32x4 (&acc)[2][2][4][2], const pg8::Unit& u, int wr, int wc, int fr, int fq) const {
;     ...
;                         *(f32x4*)(zdst + (size_t)row * DM + col) = zz;
;                         sum += zz[0] + zz[1] + zz[2] + zz[3]; sq += zz[0] * zz[0] + zz[1] * zz[1] + zz[2] * zz[2] + zz[3] * zz[3];
;                         z[n] = zz;
;                     }
;                     u32x4 o; o.x = pk2(z[0][0], z[0][1]); o.y = pk2(z[0][2], z[0][3]); o.z = pk2(z[1][0], z[1][1]); o.w = pk2(z[1][2], z[1][3]);
;                     if (zb) *(u32x4*)(zb + (size_t)row * DM + colb + bj * 128) = o;
;                 }
;                 sum += __shfl_xor(sum, 16); sq += __shfl_xor(sq, 16);
;                 sum += __shfl_xor(sum, 32); sq += __shfl_xor(sq, 32);
;                 if (fq == 0) { atomicAdd(stout + 2 * (size_t)row, sum); atomicAdd(stout + 2 * (size_t)row + 1, sq); }
.LBB0_585:
	v_add_f32_e32 v22, v12, v13
	v_mul_f32_e32 v13, v13, v13
	v_fmac_f32_e32 v13, v12, v12
	v_add_f32_e32 v12, v8, v9
	v_mul_f32_e32 v9, v9, v9
	v_fmac_f32_e32 v9, v8, v8
	v_add_f32_e32 v12, v10, v12
	v_fmac_f32_e32 v9, v10, v10
	v_mul_f32_e32 v10, v5, v5
	v_fmac_f32_e32 v13, v14, v14
	v_fmac_f32_e32 v10, v4, v4
	v_add_f32_e32 v22, v14, v22
	v_fmac_f32_e32 v13, v15, v15
	v_fmac_f32_e32 v9, v11, v11
	v_fmac_f32_e32 v10, v6, v6
	v_add_f32_e32 v22, v15, v22
	v_add_f32_e32 v8, v13, v9
	v_add_f32_e32 v9, v4, v5
	v_fmac_f32_e32 v10, v7, v7
	v_add_f32_e32 v22, 0, v22
	v_add_f32_e32 v12, v11, v12
	v_add_f32_e32 v9, v6, v9
	v_add_f32_e32 v8, v8, v10
	v_add_f32_e32 v10, v0, v1
	v_add_f32_e32 v12, v22, v12
	v_add_f32_e32 v9, v7, v9
	v_add_f32_e32 v10, v2, v10
	v_add_f32_e32 v9, v12, v9
	v_add_f32_e32 v10, v3, v10
	v_add_f32_e32 v9, v9, v10
	v_mul_f32_e32 v10, v1, v1
	v_fmac_f32_e32 v10, v0, v0
	v_fmac_f32_e32 v10, v2, v2
	v_fmac_f32_e32 v10, v3, v3
	v_add_f32_e32 v8, v8, v10
	ds_bpermute_b32 v11, v120, v9
	ds_bpermute_b32 v12, v120, v8
	v_cvt_pk_bf16_f32 v10, v4, v5
	global_store_dwordx4 v[18:19], v[0:3], off offset:528
	v_cvt_pk_bf16_f32 v13, v2, v3
	s_waitcnt lgkmcnt(0)
	v_add_f32_e32 v4, v9, v11
	v_add_f32_e32 v5, v8, v12
	ds_bpermute_b32 v8, v121, v4
	ds_bpermute_b32 v9, v121, v5
	v_cvt_pk_bf16_f32 v11, v6, v7
	v_cvt_pk_bf16_f32 v12, v0, v1
	flat_store_dwordx4 v[20:21], v[10:13] offset:256
	s_mov_b32 s100, -1
	s_mov_b32 s101, 0
	s_mov_b32 s98, 0xffff0000
	s_mov_b32 s99, 0
	s_and_saveexec_b64 s[0:1], s[100:101]
	s_cbranch_execz .LBB0_587
	s_waitcnt lgkmcnt(0)
	v_add_f32_e32 v3, v4, v8
	v_lshl_add_u64 v[0:1], v[16:17], 3, s[6:7]
	v_add_f32_e32 v2, v5, v9
	v_cndmask_b32_e64 v3, v3, v2, s[98:99]
	v_cndmask_b32_e64 v2, 0, 4, s[98:99]
	v_or_b32_e32 v0, v0, v2
	v_mov_b32_e32 v255, v3
	flat_atomic_add_f32 v[250:251], v252
	flat_atomic_add_f32 v[250:251], v253 offset:128
	flat_atomic_add_f32 v[250:251], v254 offset:256
	flat_atomic_add_f32 v[250:251], v255 offset:384

; DEVI unsigned pk2(float lo, float hi) { unsigned r; asm("v_cvt_pk_bf16_f32 %0, %1, %2" : "=v"(r) : "v"(lo), "v"(hi)); return r; }
;     DEVI void operator()(const f32x4 (&acc)[2][2][4][2], const pg8::Unit& u, int wr, int wc, int fr, int fq) const {
;     ...
;                         f32x4 zz = ALPHA * xv + acc[ai][bj][m][n];
;                         if (bias) zz += *(const f32x4*)(bias + col);
;                         *(f32x4*)(zdst + (size_t)row * DM + col) = zz;
;                         sum += zz[0] + zz[1] + zz[2] + zz[3]; sq += zz[0] * zz[0] + zz[1] * zz[1] + zz[2] * zz[2] + zz[3] * zz[3];
;                         z[n] = zz;
;                     }
;                     u32x4 o; o.x = pk2(z[0][0], z[0][1]); o.y = pk2(z[0][2], z[0][3]); o.z = pk2(z[1][0], z[1][1]); o.w = pk2(z[1][2], z[1][3]);
;                     if (zb) *(u32x4*)(zb + (size_t)row * DM + colb + bj * 128) = o;
;                 }
;                 sum += __shfl_xor(sum, 16); sq += __shfl_xor(sq, 16);
;                 sum += __shfl_xor(sum, 32); sq += __shfl_xor(sq, 32);
;                 if (fq == 0) { atomicAdd(stout + 2 * (size_t)row, sum); atomicAdd(stout + 2 * (size_t)row + 1, sq); }
.LBB0_807:
	v_add_f32_e32 v132, v124, v125
	v_mul_f32_e32 v125, v125, v125
	v_fmac_f32_e32 v125, v124, v124
	v_add_f32_e32 v124, v120, v121
	v_mul_f32_e32 v121, v121, v121
	v_fmac_f32_e32 v121, v120, v120
	v_fmac_f32_e32 v125, v126, v126
	v_fmac_f32_e32 v121, v122, v122
	v_add_f32_e32 v132, v126, v132
	v_fmac_f32_e32 v125, v127, v127
	v_fmac_f32_e32 v121, v123, v123
	v_add_f32_e32 v132, v127, v132
	v_add_f32_e32 v124, v122, v124
	v_add_f32_e32 v120, v125, v121
	v_add_f32_e32 v121, v116, v117
	v_add_f32_e32 v132, 0, v132
	v_add_f32_e32 v124, v123, v124
	v_add_f32_e32 v121, v118, v121
	v_add_f32_e32 v124, v132, v124
	v_add_f32_e32 v121, v119, v121
	v_add_f32_e32 v124, v124, v121
	v_mul_f32_e32 v121, v117, v117
	v_fmac_f32_e32 v121, v116, v116
	v_fmac_f32_e32 v121, v118, v118
	v_fmac_f32_e32 v121, v119, v119
	v_add_f32_e32 v125, v120, v121
	v_pk_fma_f32 v[122:123], v[130:131], s[26:27], v[114:115] op_sel_hi:[1,0,1]
	v_pk_fma_f32 v[120:121], v[128:129], s[26:27], v[112:113] op_sel_hi:[1,0,1]
	v_and_b32_e32 v115, 64, v174
	v_add_f32_e32 v112, v120, v121
	v_xor_b32_e32 v114, 16, v174
	v_add_u32_e32 v115, 64, v115
	v_add_f32_e32 v112, v122, v112
	v_cmp_lt_i32_e32 vcc, v114, v115
	v_add_f32_e32 v112, v123, v112
	v_mul_f32_e32 v113, v121, v121
	v_cndmask_b32_e32 v114, v174, v114, vcc
	v_add_f32_e32 v112, v124, v112
	v_fmac_f32_e32 v113, v120, v120
	v_lshlrev_b32_e32 v130, 2, v114
	v_fmac_f32_e32 v113, v122, v122
	ds_bpermute_b32 v114, v130, v112
	v_fmac_f32_e32 v113, v123, v123
	v_add_f32_e32 v113, v125, v113
	ds_bpermute_b32 v124, v130, v113
	global_store_dwordx4 v[160:161], v[120:123], off offset:528
	s_waitcnt lgkmcnt(0)
	v_add_f32_e32 v112, v112, v114
	v_xor_b32_e32 v114, 32, v174
	v_cmp_lt_i32_e32 vcc, v114, v115
	v_add_f32_e32 v113, v113, v124
	v_cvt_pk_bf16_f32 v116, v116, v117
	v_cvt_pk_bf16_f32 v117, v118, v119
	v_cvt_pk_bf16_f32 v118, v120, v121
	v_cvt_pk_bf16_f32 v119, v122, v123
	s_nop 0
	v_cndmask_b32_e32 v114, v174, v114, vcc
	v_lshlrev_b32_e32 v131, 2, v114
	ds_bpermute_b32 v114, v131, v112
	ds_bpermute_b32 v115, v131, v113
	flat_store_dwordx4 v[166:167], v[116:119] offset:256
	s_mov_b32 s100, -1
	s_mov_b32 s101, 0
	s_mov_b32 s98, 0xffff0000
	s_mov_b32 s99, 0
	s_and_saveexec_b64 s[30:31], s[100:101]
	s_cbranch_execz .LBB0_809
	s_waitcnt lgkmcnt(0)
	v_add_f32_e32 v115, v113, v115
	v_add_f32_e32 v114, v112, v114
	v_lshl_add_u64 v[112:113], v[158:159], 3, s[14:15]
	v_cndmask_b32_e64 v114, v114, v115, s[98:99]
	v_cndmask_b32_e64 v115, 0, 4, s[98:99]
	v_or_b32_e32 v112, v112, v115
	v_mov_b32_e32 v250, v112
	v_mov_b32_e32 v251, v113
	v_mov_b32_e32 v252, v114

; DEVI unsigned pk2(float lo, float hi) { unsigned r; asm("v_cvt_pk_bf16_f32 %0, %1, %2" : "=v"(r) : "v"(lo), "v"(hi)); return r; }
;     DEVI void operator()(const f32x4 (&acc)[2][2][4][2], const pg8::Unit& u, int wr, int wc, int fr, int fq) const {
;     ...
;                         f32x4 zz = ALPHA * xv + acc[ai][bj][m][n];
;                         if (bias) zz += *(const f32x4*)(bias + col);
;                         *(f32x4*)(zdst + (size_t)row * DM + col) = zz;
;                         sum += zz[0] + zz[1] + zz[2] + zz[3]; sq += zz[0] * zz[0] + zz[1] * zz[1] + zz[2] * zz[2] + zz[3] * zz[3];
;                         z[n] = zz;
;                     }
;                     u32x4 o; o.x = pk2(z[0][0], z[0][1]); o.y = pk2(z[0][2], z[0][3]); o.z = pk2(z[1][0], z[1][1]); o.w = pk2(z[1][2], z[1][3]);
;                     if (zb) *(u32x4*)(zb + (size_t)row * DM + colb + bj * 128) = o;
;                 }
;                 sum += __shfl_xor(sum, 16); sq += __shfl_xor(sq, 16);
;                 sum += __shfl_xor(sum, 32); sq += __shfl_xor(sq, 32);
;                 if (fq == 0) { atomicAdd(stout + 2 * (size_t)row, sum); atomicAdd(stout + 2 * (size_t)row + 1, sq); }
.LBB0_820:
	v_add_f32_e32 v116, v108, v109
	v_mul_f32_e32 v109, v109, v109
	v_fmac_f32_e32 v109, v108, v108
	v_add_f32_e32 v108, v104, v105
	v_mul_f32_e32 v105, v105, v105
	v_fmac_f32_e32 v105, v104, v104
	v_fmac_f32_e32 v109, v110, v110
	v_fmac_f32_e32 v105, v106, v106
	v_add_f32_e32 v116, v110, v116
	v_fmac_f32_e32 v109, v111, v111
	v_fmac_f32_e32 v105, v107, v107
	v_add_f32_e32 v116, v111, v116
	v_add_f32_e32 v108, v106, v108
	v_add_f32_e32 v104, v109, v105
	v_add_f32_e32 v105, v100, v101
	v_add_f32_e32 v116, 0, v116
	v_add_f32_e32 v108, v107, v108
	v_add_f32_e32 v105, v102, v105
	v_add_f32_e32 v108, v116, v108
	v_add_f32_e32 v105, v103, v105
	v_add_f32_e32 v108, v108, v105
	v_mul_f32_e32 v105, v101, v101
	v_fmac_f32_e32 v105, v100, v100
	v_fmac_f32_e32 v105, v102, v102
	v_fmac_f32_e32 v105, v103, v103
	v_add_f32_e32 v109, v104, v105
	v_pk_fma_f32 v[104:105], v[112:113], s[26:27], v[96:97] op_sel_hi:[1,0,1]
	v_pk_fma_f32 v[106:107], v[114:115], s[26:27], v[98:99] op_sel_hi:[1,0,1]
	v_mul_f32_e32 v97, v105, v105
	v_add_f32_e32 v96, v104, v105
	v_fmac_f32_e32 v97, v104, v104
	v_add_f32_e32 v96, v106, v96
	v_fmac_f32_e32 v97, v106, v106
	v_add_f32_e32 v96, v107, v96
	v_fmac_f32_e32 v97, v107, v107
	v_add_f32_e32 v96, v108, v96
	v_add_f32_e32 v97, v109, v97
	ds_bpermute_b32 v98, v130, v96
	ds_bpermute_b32 v99, v130, v97
	global_store_dwordx4 v[122:123], v[104:107], off offset:528
	v_cvt_pk_bf16_f32 v100, v100, v101
	v_cvt_pk_bf16_f32 v101, v102, v103
	s_waitcnt lgkmcnt(0)
	v_add_f32_e32 v96, v96, v98
	v_add_f32_e32 v97, v97, v99
	ds_bpermute_b32 v98, v131, v96
	ds_bpermute_b32 v99, v131, v97
	v_cvt_pk_bf16_f32 v102, v104, v105
	v_cvt_pk_bf16_f32 v103, v106, v107
	flat_store_dwordx4 v[128:129], v[100:103] offset:256
	s_mov_b32 s100, -1
	s_mov_b32 s101, 0
	s_mov_b32 s98, 0xffff0000
	s_mov_b32 s99, 0
	s_and_saveexec_b64 s[30:31], s[100:101]
	s_cbranch_execz .LBB0_822
	s_waitcnt lgkmcnt(0)
	v_add_f32_e32 v99, v97, v99
	v_add_f32_e32 v98, v96, v98
	v_lshl_add_u64 v[96:97], v[120:121], 3, s[14:15]
	v_cndmask_b32_e64 v98, v98, v99, s[98:99]
	v_cndmask_b32_e64 v99, 0, 4, s[98:99]
	v_or_b32_e32 v96, v96, v99
	v_mov_b32_e32 v253, v98

; DEVI unsigned pk2(float lo, float hi) { unsigned r; asm("v_cvt_pk_bf16_f32 %0, %1, %2" : "=v"(r) : "v"(lo), "v"(hi)); return r; }
;     DEVI void operator()(const f32x4 (&acc)[2][2][4][2], const pg8::Unit& u, int wr, int wc, int fr, int fq) const {
;     ...
;                         f32x4 zz = ALPHA * xv + acc[ai][bj][m][n];
;                         if (bias) zz += *(const f32x4*)(bias + col);
;                         *(f32x4*)(zdst + (size_t)row * DM + col) = zz;
;                         sum += zz[0] + zz[1] + zz[2] + zz[3]; sq += zz[0] * zz[0] + zz[1] * zz[1] + zz[2] * zz[2] + zz[3] * zz[3];
;                         z[n] = zz;
;                     }
;                     u32x4 o; o.x = pk2(z[0][0], z[0][1]); o.y = pk2(z[0][2], z[0][3]); o.z = pk2(z[1][0], z[1][1]); o.w = pk2(z[1][2], z[1][3]);
;                     if (zb) *(u32x4*)(zb + (size_t)row * DM + colb + bj * 128) = o;
;                 }
;                 sum += __shfl_xor(sum, 16); sq += __shfl_xor(sq, 16);
;                 sum += __shfl_xor(sum, 32); sq += __shfl_xor(sq, 32);
;                 if (fq == 0) { atomicAdd(stout + 2 * (size_t)row, sum); atomicAdd(stout + 2 * (size_t)row + 1, sq); }
.LBB0_833:
	v_add_f32_e32 v100, v92, v93
	v_mul_f32_e32 v93, v93, v93
	v_fmac_f32_e32 v93, v92, v92
	v_add_f32_e32 v92, v88, v89
	v_mul_f32_e32 v89, v89, v89
	v_fmac_f32_e32 v89, v88, v88
	v_fmac_f32_e32 v93, v94, v94
	v_fmac_f32_e32 v89, v90, v90
	v_add_f32_e32 v100, v94, v100
	v_fmac_f32_e32 v93, v95, v95
	v_fmac_f32_e32 v89, v91, v91
	v_add_f32_e32 v100, v95, v100
	v_add_f32_e32 v92, v90, v92
	v_add_f32_e32 v88, v93, v89
	v_add_f32_e32 v89, v84, v85
	v_add_f32_e32 v100, 0, v100
	v_add_f32_e32 v92, v91, v92
	v_add_f32_e32 v89, v86, v89
	v_add_f32_e32 v92, v100, v92
	v_add_f32_e32 v89, v87, v89
	v_add_f32_e32 v92, v92, v89
	v_mul_f32_e32 v89, v85, v85
	v_fmac_f32_e32 v89, v84, v84
	v_fmac_f32_e32 v89, v86, v86
	v_fmac_f32_e32 v89, v87, v87
	v_add_f32_e32 v93, v88, v89
	v_pk_fma_f32 v[88:89], v[96:97], s[26:27], v[80:81] op_sel_hi:[1,0,1]
	v_pk_fma_f32 v[90:91], v[98:99], s[26:27], v[82:83] op_sel_hi:[1,0,1]
	v_mul_f32_e32 v81, v89, v89
	v_add_f32_e32 v80, v88, v89
	v_fmac_f32_e32 v81, v88, v88
	v_add_f32_e32 v80, v90, v80
	v_fmac_f32_e32 v81, v90, v90
	v_add_f32_e32 v80, v91, v80
	v_fmac_f32_e32 v81, v91, v91
	v_add_f32_e32 v80, v92, v80
	v_add_f32_e32 v81, v93, v81
	ds_bpermute_b32 v82, v130, v80
	ds_bpermute_b32 v83, v130, v81
	global_store_dwordx4 v[106:107], v[88:91], off offset:528
	v_cvt_pk_bf16_f32 v84, v84, v85
	v_cvt_pk_bf16_f32 v85, v86, v87
	s_waitcnt lgkmcnt(0)
	v_add_f32_e32 v80, v80, v82
	v_add_f32_e32 v81, v81, v83
	ds_bpermute_b32 v82, v131, v80
	ds_bpermute_b32 v83, v131, v81
	v_cvt_pk_bf16_f32 v86, v88, v89
	v_cvt_pk_bf16_f32 v87, v90, v91
	flat_store_dwordx4 v[112:113], v[84:87] offset:256
	s_mov_b32 s100, -1
	s_mov_b32 s101, 0
	s_mov_b32 s98, 0xffff0000
	s_mov_b32 s99, 0
	s_and_saveexec_b64 s[30:31], s[100:101]
	s_cbranch_execz .LBB0_835
	s_waitcnt lgkmcnt(0)
	v_add_f32_e32 v83, v81, v83
	v_add_f32_e32 v82, v80, v82
	v_lshl_add_u64 v[80:81], v[104:105], 3, s[14:15]
	v_cndmask_b32_e64 v82, v82, v83, s[98:99]
	v_cndmask_b32_e64 v83, 0, 4, s[98:99]
	v_or_b32_e32 v80, v80, v83
	v_mov_b32_e32 v254, v82

; DEVI unsigned pk2(float lo, float hi) { unsigned r; asm("v_cvt_pk_bf16_f32 %0, %1, %2" : "=v"(r) : "v"(lo), "v"(hi)); return r; }
;     DEVI void operator()(const f32x4 (&acc)[2][2][4][2], const pg8::Unit& u, int wr, int wc, int fr, int fq) const {
;     ...
;                         const int col = colb + bj * 128 + 4 * n;
;                         f32x4 xv = *(const f32x4*)(zsrc + (size_t)row * DM + col);
;                         if (stin) { const f32x4 gv = *(const f32x4*)(gin + col), bv = *(const f32x4*)(bin + col); xv = (xv - mu) * rs * gv + bv; }
;                         f32x4 zz = ALPHA * xv + acc[ai][bj][m][n];
;                         if (bias) zz += *(const f32x4*)(bias + col);
;                         *(f32x4*)(zdst + (size_t)row * DM + col) = zz;
;                         sum += zz[0] + zz[1] + zz[2] + zz[3]; sq += zz[0] * zz[0] + zz[1] * zz[1] + zz[2] * zz[2] + zz[3] * zz[3];
;                         z[n] = zz;
;                     }
;                     u32x4 o; o.x = pk2(z[0][0], z[0][1]); o.y = pk2(z[0][2], z[0][3]); o.z = pk2(z[1][0], z[1][1]); o.w = pk2(z[1][2], z[1][3]);
;                     if (zb) *(u32x4*)(zb + (size_t)row * DM + colb + bj * 128) = o;
;                 }
;                 sum += __shfl_xor(sum, 16); sq += __shfl_xor(sq, 16);
;                 sum += __shfl_xor(sum, 32); sq += __shfl_xor(sq, 32);
;                 if (fq == 0) { atomicAdd(stout + 2 * (size_t)row, sum); atomicAdd(stout + 2 * (size_t)row + 1, sq); }
.LBB0_846:
	v_add_f32_e32 v84, v76, v77
	v_mul_f32_e32 v77, v77, v77
	v_fmac_f32_e32 v77, v76, v76
	v_add_f32_e32 v76, v72, v73
	v_mul_f32_e32 v73, v73, v73
	v_fmac_f32_e32 v73, v72, v72
	v_fmac_f32_e32 v77, v78, v78
	v_fmac_f32_e32 v73, v74, v74
	v_add_f32_e32 v84, v78, v84
	v_fmac_f32_e32 v77, v79, v79
	v_fmac_f32_e32 v73, v75, v75
	v_add_f32_e32 v84, v79, v84
	v_add_f32_e32 v76, v74, v76
	v_add_f32_e32 v72, v77, v73
	v_add_f32_e32 v73, v68, v69
	v_add_f32_e32 v84, 0, v84
	v_add_f32_e32 v76, v75, v76
	v_add_f32_e32 v73, v70, v73
	v_add_f32_e32 v76, v84, v76
	v_add_f32_e32 v73, v71, v73
	v_add_f32_e32 v76, v76, v73
	v_mul_f32_e32 v73, v69, v69
	v_fmac_f32_e32 v73, v68, v68
	v_fmac_f32_e32 v73, v70, v70
	v_fmac_f32_e32 v73, v71, v71
	v_add_f32_e32 v77, v72, v73
	v_pk_fma_f32 v[72:73], v[80:81], s[26:27], v[64:65] op_sel_hi:[1,0,1]
	v_pk_fma_f32 v[74:75], v[82:83], s[26:27], v[66:67] op_sel_hi:[1,0,1]
	v_mul_f32_e32 v65, v73, v73
	v_add_f32_e32 v64, v72, v73
	v_fmac_f32_e32 v65, v72, v72
	v_add_f32_e32 v64, v74, v64
	v_fmac_f32_e32 v65, v74, v74
	v_add_f32_e32 v64, v75, v64
	v_fmac_f32_e32 v65, v75, v75
	v_add_f32_e32 v64, v76, v64
	v_add_f32_e32 v65, v77, v65
	ds_bpermute_b32 v66, v130, v64
	ds_bpermute_b32 v67, v130, v65
	global_store_dwordx4 v[90:91], v[72:75], off offset:528
	v_cvt_pk_bf16_f32 v68, v68, v69
	v_cvt_pk_bf16_f32 v69, v70, v71
	s_waitcnt lgkmcnt(0)
	v_add_f32_e32 v64, v64, v66
	v_add_f32_e32 v65, v65, v67
	ds_bpermute_b32 v66, v131, v64
	ds_bpermute_b32 v67, v131, v65
	v_cvt_pk_bf16_f32 v70, v72, v73
	v_cvt_pk_bf16_f32 v71, v74, v75
	flat_store_dwordx4 v[96:97], v[68:71] offset:256
	s_mov_b32 s100, -1
	s_mov_b32 s101, 0
	s_mov_b32 s98, 0xffff0000
	s_mov_b32 s99, 0
	s_and_saveexec_b64 s[30:31], s[100:101]
	s_cbranch_execz .LBB0_848
	s_waitcnt lgkmcnt(0)
	v_add_f32_e32 v67, v65, v67
	v_add_f32_e32 v66, v64, v66
	v_lshl_add_u64 v[64:65], v[88:89], 3, s[14:15]
	v_cndmask_b32_e64 v66, v66, v67, s[98:99]
	v_cndmask_b32_e64 v67, 0, 4, s[98:99]
	v_or_b32_e32 v64, v64, v67
	v_mov_b32_e32 v255, v66
	flat_atomic_add_f32 v[250:251], v252
	flat_atomic_add_f32 v[250:251], v253 offset:128
	flat_atomic_add_f32 v[250:251], v254 offset:256
	flat_atomic_add_f32 v[250:251], v255 offset:384

; DEVI unsigned pk2(float lo, float hi) { unsigned r; asm("v_cvt_pk_bf16_f32 %0, %1, %2" : "=v"(r) : "v"(lo), "v"(hi)); return r; }
;     DEVI void operator()(const f32x4 (&acc)[2][2][4][2], const pg8::Unit& u, int wr, int wc, int fr, int fq) const {
;     ...
;                         const int col = colb + bj * 128 + 4 * n;
;                         f32x4 xv = *(const f32x4*)(zsrc + (size_t)row * DM + col);
;                         if (stin) { const f32x4 gv = *(const f32x4*)(gin + col), bv = *(const f32x4*)(bin + col); xv = (xv - mu) * rs * gv + bv; }
;                         f32x4 zz = ALPHA * xv + acc[ai][bj][m][n];
;                         if (bias) zz += *(const f32x4*)(bias + col);
;                         *(f32x4*)(zdst + (size_t)row * DM + col) = zz;
;                         sum += zz[0] + zz[1] + zz[2] + zz[3]; sq += zz[0] * zz[0] + zz[1] * zz[1] + zz[2] * zz[2] + zz[3] * zz[3];
;                         z[n] = zz;
;                     }
;                     u32x4 o; o.x = pk2(z[0][0], z[0][1]); o.y = pk2(z[0][2], z[0][3]); o.z = pk2(z[1][0], z[1][1]); o.w = pk2(z[1][2], z[1][3]);
;                     if (zb) *(u32x4*)(zb + (size_t)row * DM + colb + bj * 128) = o;
;                 }
;                 sum += __shfl_xor(sum, 16); sq += __shfl_xor(sq, 16);
;                 sum += __shfl_xor(sum, 32); sq += __shfl_xor(sq, 32);
;                 if (fq == 0) { atomicAdd(stout + 2 * (size_t)row, sum); atomicAdd(stout + 2 * (size_t)row + 1, sq); }
.LBB0_859:
	v_add_f32_e32 v68, v60, v61
	v_mul_f32_e32 v61, v61, v61
	v_fmac_f32_e32 v61, v60, v60
	v_add_f32_e32 v60, v56, v57
	v_mul_f32_e32 v57, v57, v57
	v_fmac_f32_e32 v57, v56, v56
	v_fmac_f32_e32 v61, v62, v62
	v_fmac_f32_e32 v57, v58, v58
	v_add_f32_e32 v68, v62, v68
	v_fmac_f32_e32 v61, v63, v63
	v_fmac_f32_e32 v57, v59, v59
	v_add_f32_e32 v68, v63, v68
	v_add_f32_e32 v60, v58, v60
	v_add_f32_e32 v56, v61, v57
	v_add_f32_e32 v57, v52, v53
	v_add_f32_e32 v68, 0, v68
	v_add_f32_e32 v60, v59, v60
	v_add_f32_e32 v57, v54, v57
	v_add_f32_e32 v60, v68, v60
	v_add_f32_e32 v57, v55, v57
	v_add_f32_e32 v60, v60, v57
	v_mul_f32_e32 v57, v53, v53
	v_fmac_f32_e32 v57, v52, v52
	v_fmac_f32_e32 v57, v54, v54
	v_fmac_f32_e32 v57, v55, v55
	v_add_f32_e32 v61, v56, v57
	v_pk_fma_f32 v[56:57], v[64:65], s[26:27], v[48:49] op_sel_hi:[1,0,1]
	v_pk_fma_f32 v[58:59], v[66:67], s[26:27], v[50:51] op_sel_hi:[1,0,1]
	v_mul_f32_e32 v49, v57, v57
	v_add_f32_e32 v48, v56, v57
	v_fmac_f32_e32 v49, v56, v56
	v_add_f32_e32 v48, v58, v48
	v_fmac_f32_e32 v49, v58, v58
	v_add_f32_e32 v48, v59, v48
	v_fmac_f32_e32 v49, v59, v59
	v_add_f32_e32 v48, v60, v48
	v_add_f32_e32 v49, v61, v49
	ds_bpermute_b32 v50, v130, v48
	ds_bpermute_b32 v51, v130, v49
	global_store_dwordx4 v[74:75], v[56:59], off offset:528
	v_cvt_pk_bf16_f32 v52, v52, v53
	v_cvt_pk_bf16_f32 v53, v54, v55
	s_waitcnt lgkmcnt(0)
	v_add_f32_e32 v48, v48, v50
	v_add_f32_e32 v49, v49, v51
	ds_bpermute_b32 v50, v131, v48
	ds_bpermute_b32 v51, v131, v49
	v_cvt_pk_bf16_f32 v54, v56, v57
	v_cvt_pk_bf16_f32 v55, v58, v59
	flat_store_dwordx4 v[80:81], v[52:55] offset:256
	s_mov_b32 s100, -1
	s_mov_b32 s101, 0
	s_mov_b32 s98, 0xffff0000
	s_mov_b32 s99, 0
	s_and_saveexec_b64 s[30:31], s[100:101]
	s_cbranch_execz .LBB0_861
	s_waitcnt lgkmcnt(0)
	v_add_f32_e32 v51, v49, v51
	v_add_f32_e32 v50, v48, v50
	v_lshl_add_u64 v[48:49], v[72:73], 3, s[14:15]
	v_cndmask_b32_e64 v50, v50, v51, s[98:99]
	v_cndmask_b32_e64 v51, 0, 4, s[98:99]
	v_or_b32_e32 v48, v48, v51
	v_mov_b32_e32 v250, v48
	v_mov_b32_e32 v251, v49
	v_mov_b32_e32 v252, v50

; DEVI unsigned pk2(float lo, float hi) { unsigned r; asm("v_cvt_pk_bf16_f32 %0, %1, %2" : "=v"(r) : "v"(lo), "v"(hi)); return r; }
;     DEVI void operator()(const f32x4 (&acc)[2][2][4][2], const pg8::Unit& u, int wr, int wc, int fr, int fq) const {
;     ...
;                         const int col = colb + bj * 128 + 4 * n;
;                         f32x4 xv = *(const f32x4*)(zsrc + (size_t)row * DM + col);
;                         if (stin) { const f32x4 gv = *(const f32x4*)(gin + col), bv = *(const f32x4*)(bin + col); xv = (xv - mu) * rs * gv + bv; }
;                         f32x4 zz = ALPHA * xv + acc[ai][bj][m][n];
;                         if (bias) zz += *(const f32x4*)(bias + col);
;                         *(f32x4*)(zdst + (size_t)row * DM + col) = zz;
;                         sum += zz[0] + zz[1] + zz[2] + zz[3]; sq += zz[0] * zz[0] + zz[1] * zz[1] + zz[2] * zz[2] + zz[3] * zz[3];
;                         z[n] = zz;
;                     }
;                     u32x4 o; o.x = pk2(z[0][0], z[0][1]); o.y = pk2(z[0][2], z[0][3]); o.z = pk2(z[1][0], z[1][1]); o.w = pk2(z[1][2], z[1][3]);
;                     if (zb) *(u32x4*)(zb + (size_t)row * DM + colb + bj * 128) = o;
;                 }
;                 sum += __shfl_xor(sum, 16); sq += __shfl_xor(sq, 16);
;                 sum += __shfl_xor(sum, 32); sq += __shfl_xor(sq, 32);
;                 if (fq == 0) { atomicAdd(stout + 2 * (size_t)row, sum); atomicAdd(stout + 2 * (size_t)row + 1, sq); }
.LBB0_872:
	v_add_f32_e32 v52, v44, v45
	v_mul_f32_e32 v45, v45, v45
	v_fmac_f32_e32 v45, v44, v44
	v_add_f32_e32 v44, v40, v41
	v_mul_f32_e32 v41, v41, v41
	v_fmac_f32_e32 v41, v40, v40
	v_fmac_f32_e32 v45, v46, v46
	v_fmac_f32_e32 v41, v42, v42
	v_add_f32_e32 v52, v46, v52
	v_fmac_f32_e32 v45, v47, v47
	v_fmac_f32_e32 v41, v43, v43
	v_add_f32_e32 v52, v47, v52
	v_add_f32_e32 v44, v42, v44
	v_add_f32_e32 v40, v45, v41
	v_add_f32_e32 v41, v36, v37
	v_add_f32_e32 v52, 0, v52
	v_add_f32_e32 v44, v43, v44
	v_add_f32_e32 v41, v38, v41
	v_add_f32_e32 v44, v52, v44
	v_add_f32_e32 v41, v39, v41
	v_add_f32_e32 v44, v44, v41
	v_mul_f32_e32 v41, v37, v37
	v_fmac_f32_e32 v41, v36, v36
	v_fmac_f32_e32 v41, v38, v38
	v_fmac_f32_e32 v41, v39, v39
	v_add_f32_e32 v45, v40, v41
	v_pk_fma_f32 v[40:41], v[48:49], s[26:27], v[32:33] op_sel_hi:[1,0,1]
	v_pk_fma_f32 v[42:43], v[50:51], s[26:27], v[34:35] op_sel_hi:[1,0,1]
	v_mul_f32_e32 v33, v41, v41
	v_add_f32_e32 v32, v40, v41
	v_fmac_f32_e32 v33, v40, v40
	v_add_f32_e32 v32, v42, v32
	v_fmac_f32_e32 v33, v42, v42
	v_add_f32_e32 v32, v43, v32
	v_fmac_f32_e32 v33, v43, v43
	v_add_f32_e32 v32, v44, v32
	v_add_f32_e32 v33, v45, v33
	ds_bpermute_b32 v34, v130, v32
	ds_bpermute_b32 v35, v130, v33
	global_store_dwordx4 v[58:59], v[40:43], off offset:528
	v_cvt_pk_bf16_f32 v36, v36, v37
	v_cvt_pk_bf16_f32 v37, v38, v39
	s_waitcnt lgkmcnt(0)
	v_add_f32_e32 v32, v32, v34
	v_add_f32_e32 v33, v33, v35
	ds_bpermute_b32 v34, v131, v32
	ds_bpermute_b32 v35, v131, v33
	v_cvt_pk_bf16_f32 v38, v40, v41
	v_cvt_pk_bf16_f32 v39, v42, v43
	flat_store_dwordx4 v[64:65], v[36:39] offset:256
	s_mov_b32 s100, -1
	s_mov_b32 s101, 0
	s_mov_b32 s98, 0xffff0000
	s_mov_b32 s99, 0
	s_and_saveexec_b64 s[30:31], s[100:101]
	s_cbranch_execz .LBB0_874
	s_waitcnt lgkmcnt(0)
	v_add_f32_e32 v35, v33, v35
	v_add_f32_e32 v34, v32, v34
	v_lshl_add_u64 v[32:33], v[56:57], 3, s[14:15]
	v_cndmask_b32_e64 v34, v34, v35, s[98:99]
	v_cndmask_b32_e64 v35, 0, 4, s[98:99]
	v_or_b32_e32 v32, v32, v35
	v_mov_b32_e32 v253, v34

; DEVI unsigned pk2(float lo, float hi) { unsigned r; asm("v_cvt_pk_bf16_f32 %0, %1, %2" : "=v"(r) : "v"(lo), "v"(hi)); return r; }
;     DEVI void operator()(const f32x4 (&acc)[2][2][4][2], const pg8::Unit& u, int wr, int wc, int fr, int fq) const {
;     ...
;                         const int col = colb + bj * 128 + 4 * n;
;                         f32x4 xv = *(const f32x4*)(zsrc + (size_t)row * DM + col);
;                         if (stin) { const f32x4 gv = *(const f32x4*)(gin + col), bv = *(const f32x4*)(bin + col); xv = (xv - mu) * rs * gv + bv; }
;                         f32x4 zz = ALPHA * xv + acc[ai][bj][m][n];
;                         if (bias) zz += *(const f32x4*)(bias + col);
;                         *(f32x4*)(zdst + (size_t)row * DM + col) = zz;
;                         sum += zz[0] + zz[1] + zz[2] + zz[3]; sq += zz[0] * zz[0] + zz[1] * zz[1] + zz[2] * zz[2] + zz[3] * zz[3];
;                         z[n] = zz;
;                     }
;                     u32x4 o; o.x = pk2(z[0][0], z[0][1]); o.y = pk2(z[0][2], z[0][3]); o.z = pk2(z[1][0], z[1][1]); o.w = pk2(z[1][2], z[1][3]);
;                     if (zb) *(u32x4*)(zb + (size_t)row * DM + colb + bj * 128) = o;
;                 }
;                 sum += __shfl_xor(sum, 16); sq += __shfl_xor(sq, 16);
;                 sum += __shfl_xor(sum, 32); sq += __shfl_xor(sq, 32);
;                 if (fq == 0) { atomicAdd(stout + 2 * (size_t)row, sum); atomicAdd(stout + 2 * (size_t)row + 1, sq); }
.LBB0_885:
	v_add_f32_e32 v36, v28, v29
	v_mul_f32_e32 v29, v29, v29
	v_fmac_f32_e32 v29, v28, v28
	v_add_f32_e32 v28, v24, v25
	v_mul_f32_e32 v25, v25, v25
	v_fmac_f32_e32 v25, v24, v24
	v_fmac_f32_e32 v29, v30, v30
	v_fmac_f32_e32 v25, v26, v26
	v_add_f32_e32 v36, v30, v36
	v_fmac_f32_e32 v29, v31, v31
	v_fmac_f32_e32 v25, v27, v27
	v_add_f32_e32 v36, v31, v36
	v_add_f32_e32 v28, v26, v28
	v_add_f32_e32 v24, v29, v25
	v_add_f32_e32 v25, v20, v21
	v_add_f32_e32 v36, 0, v36
	v_add_f32_e32 v28, v27, v28
	v_add_f32_e32 v25, v22, v25
	v_add_f32_e32 v28, v36, v28
	v_add_f32_e32 v25, v23, v25
	v_add_f32_e32 v28, v28, v25
	v_mul_f32_e32 v25, v21, v21
	v_fmac_f32_e32 v25, v20, v20
	v_fmac_f32_e32 v25, v22, v22
	v_fmac_f32_e32 v25, v23, v23
	v_add_f32_e32 v29, v24, v25
	v_pk_fma_f32 v[24:25], v[32:33], s[26:27], v[16:17] op_sel_hi:[1,0,1]
	v_pk_fma_f32 v[26:27], v[34:35], s[26:27], v[18:19] op_sel_hi:[1,0,1]
	v_mul_f32_e32 v17, v25, v25
	v_add_f32_e32 v16, v24, v25
	v_fmac_f32_e32 v17, v24, v24
	v_add_f32_e32 v16, v26, v16
	v_fmac_f32_e32 v17, v26, v26
	v_add_f32_e32 v16, v27, v16
	v_fmac_f32_e32 v17, v27, v27
	v_add_f32_e32 v16, v28, v16
	v_add_f32_e32 v17, v29, v17
	ds_bpermute_b32 v18, v130, v16
	ds_bpermute_b32 v19, v130, v17
	global_store_dwordx4 v[42:43], v[24:27], off offset:528
	v_cvt_pk_bf16_f32 v20, v20, v21
	v_cvt_pk_bf16_f32 v21, v22, v23
	s_waitcnt lgkmcnt(0)
	v_add_f32_e32 v16, v16, v18
	v_add_f32_e32 v17, v17, v19
	ds_bpermute_b32 v18, v131, v16
	ds_bpermute_b32 v19, v131, v17
	v_cvt_pk_bf16_f32 v22, v24, v25
	v_cvt_pk_bf16_f32 v23, v26, v27
	flat_store_dwordx4 v[48:49], v[20:23] offset:256
	s_mov_b32 s100, -1
	s_mov_b32 s101, 0
	s_mov_b32 s98, 0xffff0000
	s_mov_b32 s99, 0
	s_and_saveexec_b64 s[30:31], s[100:101]
	s_cbranch_execz .LBB0_887
	s_waitcnt lgkmcnt(0)
	v_add_f32_e32 v19, v17, v19
	v_add_f32_e32 v18, v16, v18
	v_lshl_add_u64 v[16:17], v[40:41], 3, s[14:15]
	v_cndmask_b32_e64 v18, v18, v19, s[98:99]
	v_cndmask_b32_e64 v19, 0, 4, s[98:99]
	v_or_b32_e32 v16, v16, v19
	v_mov_b32_e32 v254, v18

; DEVI unsigned pk2(float lo, float hi) { unsigned r; asm("v_cvt_pk_bf16_f32 %0, %1, %2" : "=v"(r) : "v"(lo), "v"(hi)); return r; }
;     DEVI void operator()(const f32x4 (&acc)[2][2][4][2], const pg8::Unit& u, int wr, int wc, int fr, int fq) const {
;     ...
;                         const int col = colb + bj * 128 + 4 * n;
;                         f32x4 xv = *(const f32x4*)(zsrc + (size_t)row * DM + col);
;                         if (stin) { const f32x4 gv = *(const f32x4*)(gin + col), bv = *(const f32x4*)(bin + col); xv = (xv - mu) * rs * gv + bv; }
;                         f32x4 zz = ALPHA * xv + acc[ai][bj][m][n];
;                         if (bias) zz += *(const f32x4*)(bias + col);
;                         *(f32x4*)(zdst + (size_t)row * DM + col) = zz;
;                         sum += zz[0] + zz[1] + zz[2] + zz[3]; sq += zz[0] * zz[0] + zz[1] * zz[1] + zz[2] * zz[2] + zz[3] * zz[3];
;                         z[n] = zz;
;                     }
;                     u32x4 o; o.x = pk2(z[0][0], z[0][1]); o.y = pk2(z[0][2], z[0][3]); o.z = pk2(z[1][0], z[1][1]); o.w = pk2(z[1][2], z[1][3]);
;                     if (zb) *(u32x4*)(zb + (size_t)row * DM + colb + bj * 128) = o;
;                 }
;                 sum += __shfl_xor(sum, 16); sq += __shfl_xor(sq, 16);
;                 sum += __shfl_xor(sum, 32); sq += __shfl_xor(sq, 32);
;                 if (fq == 0) { atomicAdd(stout + 2 * (size_t)row, sum); atomicAdd(stout + 2 * (size_t)row + 1, sq); }
.LBB0_898:
	v_add_f32_e32 v20, v12, v13
	v_mul_f32_e32 v13, v13, v13
	v_fmac_f32_e32 v13, v12, v12
	v_add_f32_e32 v12, v8, v9
	v_mul_f32_e32 v9, v9, v9
	v_fmac_f32_e32 v9, v8, v8
	v_fmac_f32_e32 v13, v14, v14
	v_fmac_f32_e32 v9, v10, v10
	v_add_f32_e32 v20, v14, v20
	v_fmac_f32_e32 v13, v15, v15
	v_fmac_f32_e32 v9, v11, v11
	v_add_f32_e32 v20, v15, v20
	v_add_f32_e32 v12, v10, v12
	v_add_f32_e32 v8, v13, v9
	v_add_f32_e32 v9, v4, v5
	v_add_f32_e32 v20, 0, v20
	v_add_f32_e32 v12, v11, v12
	v_add_f32_e32 v9, v6, v9
	v_add_f32_e32 v12, v20, v12
	v_add_f32_e32 v9, v7, v9
	v_add_f32_e32 v12, v12, v9
	v_mul_f32_e32 v9, v5, v5
	v_fmac_f32_e32 v9, v4, v4
	v_fmac_f32_e32 v9, v6, v6
	v_fmac_f32_e32 v9, v7, v7
	v_add_f32_e32 v13, v8, v9
	v_pk_fma_f32 v[8:9], v[16:17], s[26:27], v[0:1] op_sel_hi:[1,0,1]
	v_pk_fma_f32 v[10:11], v[18:19], s[26:27], v[2:3] op_sel_hi:[1,0,1]
	v_mul_f32_e32 v1, v9, v9
	v_add_f32_e32 v0, v8, v9
	v_fmac_f32_e32 v1, v8, v8
	v_add_f32_e32 v0, v10, v0
	v_fmac_f32_e32 v1, v10, v10
	v_add_f32_e32 v0, v11, v0
	v_fmac_f32_e32 v1, v11, v11
	v_add_f32_e32 v0, v12, v0
	v_add_f32_e32 v1, v13, v1
	ds_bpermute_b32 v2, v130, v0
	ds_bpermute_b32 v3, v130, v1
	global_store_dwordx4 v[26:27], v[8:11], off offset:528
	v_cvt_pk_bf16_f32 v4, v4, v5
	v_cvt_pk_bf16_f32 v5, v6, v7
	s_waitcnt lgkmcnt(0)
	v_add_f32_e32 v0, v0, v2
	v_add_f32_e32 v1, v1, v3
	ds_bpermute_b32 v2, v131, v0
	ds_bpermute_b32 v3, v131, v1
	v_cvt_pk_bf16_f32 v6, v8, v9
	v_cvt_pk_bf16_f32 v7, v10, v11
	flat_store_dwordx4 v[32:33], v[4:7] offset:256
	s_mov_b32 s100, -1
	s_mov_b32 s101, 0
	s_mov_b32 s98, 0xffff0000
	s_mov_b32 s99, 0
	s_and_saveexec_b64 s[6:7], s[100:101]
	s_cbranch_execz .LBB0_900
	s_waitcnt lgkmcnt(0)
	v_add_f32_e32 v3, v1, v3
	v_add_f32_e32 v2, v0, v2
	v_lshl_add_u64 v[0:1], v[24:25], 3, s[14:15]
	v_cndmask_b32_e64 v2, v2, v3, s[98:99]
	v_cndmask_b32_e64 v3, 0, 4, s[98:99]
	v_or_b32_e32 v0, v0, v3
	v_mov_b32_e32 v255, v2
	flat_atomic_add_f32 v[250:251], v252
	flat_atomic_add_f32 v[250:251], v253 offset:128
	flat_atomic_add_f32 v[250:251], v254 offset:256
	flat_atomic_add_f32 v[250:251], v255 offset:384

; DEVI void row_stats(const float* stats, int row, float& mu, float& rs) {
;     if (stats) { const float2 st = *(const float2*)(stats + 2 * (size_t)row); mu = st.x * (1.0f / 1024.0f); const float var = st.y * (1.0f / 1024.0f) - mu * mu; rs = rsqrtf(fmaxf(var, 0.f) + LN_EPS); }
;     DEVI void operator()(const f32x4 (&acc)[2][2][4][2], const pg8::Unit& u, int wr, int wc, int fr, int fq) const {
;     ...
;                 const int row = row0 + ai * 128 + m * 16; float mu, rs; row_stats(stin, row, mu, rs);
;                 float sum = 0.f, sq = 0.f;
; #pragma unroll
;                 for (int bj = 0; bj < 2; ++bj) {
;                     f32x4 z[2];
; #pragma unroll
;                     for (int n = 0; n < 2; ++n) {
;                         const int col = colb + bj * 128 + 4 * n;
;                         f32x4 xv = *(const f32x4*)(zsrc + (size_t)row * DM + col);
;                         if (stin) { const f32x4 gv = *(const f32x4*)(gin + col), bv = *(const f32x4*)(bin + col); xv = (xv - mu) * rs * gv + bv; }
;                         f32x4 zz = ALPHA * xv + acc[ai][bj][m][n];
;                         if (bias) zz += *(const f32x4*)(bias + col);
;                         *(f32x4*)(zdst + (size_t)row * DM + col) = zz;
;                         sum += zz[0] + zz[1] + zz[2] + zz[3]; sq += zz[0] * zz[0] + zz[1] * zz[1] + zz[2] * zz[2] + zz[3] * zz[3];
.LBB0_1329:
	v_lshl_add_u32 v150, s30, 8, v162
	v_ashrrev_i32_e32 v151, 31, v150
	v_lshlrev_b64 v[156:157], 3, v[150:151]
	v_lshl_add_u64 v[144:145], s[6:7], 0, v[156:157]
	s_waitcnt vmcnt(0)
	flat_load_dwordx2 v[154:155], v[144:145]
	v_lshl_or_b32 v148, s34, 8, v164
	v_ashrrev_i32_e32 v149, 31, v148
	v_lshlrev_b64 v[144:145], 12, v[150:151]
	v_lshl_add_u64 v[144:145], s[46:47], 0, v[144:145]
	v_lshlrev_b64 v[152:153], 2, v[148:149]
	v_lshl_add_u64 v[158:159], v[144:145], 0, v[152:153]
	v_readlane_b32 s68, v249, 37
	global_load_dwordx4 v[170:173], v[158:159], off
	v_readlane_b32 s82, v249, 51
	v_readlane_b32 s83, v249, 52
	v_lshl_add_u64 v[146:147], s[44:45], 0, v[152:153]
	v_readlane_b32 s69, v249, 38
	v_lshl_add_u64 v[144:145], s[82:83], 0, v[152:153]
	global_load_dwordx4 v[174:177], v[144:145], off
	global_load_dwordx4 v[178:181], v[146:147], off
	v_lshl_add_u64 v[152:153], s[12:13], 0, v[152:153]
	global_load_dwordx4 v[182:185], v[152:153], off
	global_load_dwordx4 v[186:189], v[158:159], off offset:16
	v_readlane_b32 s70, v249, 39
	v_readlane_b32 s71, v249, 40
	v_readlane_b32 s72, v249, 41
	v_readlane_b32 s73, v249, 42
	v_readlane_b32 s74, v249, 43
	v_readlane_b32 s75, v249, 44
	v_readlane_b32 s76, v249, 45
	v_readlane_b32 s77, v249, 46
	v_readlane_b32 s78, v249, 47
	v_readlane_b32 s79, v249, 48
	v_readlane_b32 s80, v249, 49
	v_readlane_b32 s81, v249, 50
	s_waitcnt vmcnt(0) lgkmcnt(0)
	v_pk_mul_f32 v[160:161], v[154:155], s[18:19] op_sel:[1,0] op_sel_hi:[0,0]
	v_fma_f32 v154, -v161, v161, v160
	v_max_f32_e32 v154, 0, v154
	v_add_f32_e32 v154, 0x3727c5ac, v154
	v_mul_f32_e32 v160, 0x4b800000, v154
	v_cmp_gt_f32_e32 vcc, s64, v154
	v_sub_f32_e32 v155, v173, v161
	s_nop 0
	v_cndmask_b32_e32 v154, v154, v160, vcc
	v_rsq_f32_e32 v160, v154
	v_sub_f32_e32 v154, v172, v161
	v_sub_f32_e32 v171, v171, v161
	v_sub_f32_e32 v170, v170, v161
	v_mul_f32_e32 v169, 0x45800000, v160
	v_cndmask_b32_e32 v160, v160, v169, vcc
	v_pk_mul_f32 v[170:171], v[170:171], v[160:161] op_sel_hi:[1,0]
	v_pk_mul_f32 v[154:155], v[154:155], v[160:161] op_sel_hi:[1,0]
	v_pk_fma_f32 v[170:171], v[174:175], v[170:171], v[178:179]
	v_pk_fma_f32 v[154:155], v[176:177], v[154:155], v[180:181]
	v_pk_fma_f32 v[124:125], v[170:171], s[20:21], v[124:125] op_sel_hi:[1,0,1]
	v_pk_fma_f32 v[126:127], v[154:155], s[20:21], v[126:127] op_sel_hi:[1,0,1]
	v_pk_add_f32 v[124:125], v[182:183], v[124:125]
	v_pk_add_f32 v[126:127], v[184:185], v[126:127]
	global_store_dwordx4 v[158:159], v[124:127], off
	v_or_b32_e32 v154, 4, v148
	global_load_dwordx4 v[170:173], v[144:145], off offset:16
	global_load_dwordx4 v[174:177], v[146:147], off offset:16
	v_ashrrev_i32_e32 v155, 31, v154
	v_lshl_add_u64 v[154:155], v[154:155], 2, s[12:13]
	global_load_dwordx4 v[178:181], v[154:155], off
	v_lshlrev_b64 v[182:183], 11, v[150:151]
	v_lshl_add_u64 v[182:183], s[10:11], 0, v[182:183]
	v_lshl_add_u64 v[194:195], v[148:149], 1, v[182:183]
	v_sub_f32_e32 v183, v189, v161
	v_sub_f32_e32 v182, v188, v161
	v_sub_f32_e32 v185, v187, v161
	v_sub_f32_e32 v184, v186, v161
	v_pk_mul_f32 v[184:185], v[184:185], v[160:161] op_sel_hi:[1,0]
	v_pk_mul_f32 v[186:187], v[182:183], v[160:161] op_sel_hi:[1,0]
	v_cvt_pk_bf16_f32 v182, v124, v125
	v_cvt_pk_bf16_f32 v183, v126, v127
	s_waitcnt vmcnt(1)
	v_pk_fma_f32 v[170:171], v[170:171], v[184:185], v[174:175]
	v_pk_fma_f32 v[172:173], v[172:173], v[186:187], v[176:177]
	v_pk_fma_f32 v[120:121], v[170:171], s[20:21], v[120:121] op_sel_hi:[1,0,1]
	v_pk_fma_f32 v[122:123], v[172:173], s[20:21], v[122:123] op_sel_hi:[1,0,1]
	s_waitcnt vmcnt(0)
	v_pk_add_f32 v[170:171], v[178:179], v[120:121]
	v_pk_add_f32 v[172:173], v[180:181], v[122:123]
	global_store_dwordx4 v[158:159], v[170:173], off offset:16
	v_cvt_pk_bf16_f32 v184, v170, v171
	v_cvt_pk_bf16_f32 v185, v172, v173
	flat_store_dwordx4 v[194:195], v[182:185]
	global_load_dwordx4 v[174:177], v[158:159], off offset:512
	global_load_dwordx4 v[178:181], v[144:145], off offset:512
	s_nop 0
	global_load_dwordx4 v[182:185], v[146:147], off offset:512
	v_or_b32_e32 v120, 0x80, v148
	v_ashrrev_i32_e32 v121, 31, v120
	v_lshl_add_u64 v[120:121], v[120:121], 2, s[12:13]
	global_load_dwordx4 v[186:189], v[120:121], off
	global_load_dwordx4 v[190:193], v[158:159], off offset:528
	s_waitcnt vmcnt(0)
	v_sub_f32_e32 v123, v177, v161
	v_sub_f32_e32 v122, v176, v161
	v_sub_f32_e32 v175, v175, v161
	v_sub_f32_e32 v174, v174, v161
	v_pk_mul_f32 v[174:175], v[160:161], v[174:175] op_sel_hi:[0,1]
	v_pk_mul_f32 v[122:123], v[160:161], v[122:123] op_sel_hi:[0,1]
	v_pk_fma_f32 v[122:123], v[180:181], v[122:123], v[184:185]
	v_pk_fma_f32 v[174:175], v[178:179], v[174:175], v[182:183]
	v_pk_fma_f32 v[118:119], v[122:123], s[20:21], v[118:119] op_sel_hi:[1,0,1]
	v_pk_fma_f32 v[116:117], v[174:175], s[20:21], v[116:117] op_sel_hi:[1,0,1]
	v_pk_add_f32 v[176:177], v[188:189], v[118:119]
	v_pk_add_f32 v[174:175], v[186:187], v[116:117]
	global_store_dwordx4 v[158:159], v[174:177], off offset:512
	v_or_b32_e32 v116, 0x84, v148
	global_load_dwordx4 v[178:181], v[144:145], off offset:528
	global_load_dwordx4 v[182:185], v[146:147], off offset:528
	v_ashrrev_i32_e32 v117, 31, v116
	v_lshl_add_u64 v[116:117], v[116:117], 2, s[12:13]
	global_load_dwordx4 v[186:189], v[116:117], off
	v_and_b32_e32 v119, 64, v168
	v_xor_b32_e32 v118, 16, v168
	v_add_u32_e32 v119, 64, v119
	v_xor_b32_e32 v122, 32, v168
	v_cmp_lt_i32_e32 vcc, v118, v119
	v_mul_f32_e32 v123, v125, v125
	v_fmac_f32_e32 v123, v124, v124
	v_cndmask_b32_e32 v118, v168, v118, vcc
	v_cmp_lt_i32_e32 vcc, v122, v119
	v_fmac_f32_e32 v123, v126, v126
	v_fmac_f32_e32 v123, v127, v127
	v_cndmask_b32_e32 v119, v168, v122, vcc
	v_add_f32_e32 v122, v124, v125
	v_mul_f32_e32 v125, v171, v171
	v_add_f32_e32 v122, v126, v122
	v_add_f32_e32 v124, v170, v171
	v_fmac_f32_e32 v125, v170, v170
	v_add_f32_e32 v122, v127, v122
	v_add_f32_e32 v124, v172, v124
	v_fmac_f32_e32 v125, v172, v172
	v_add_f32_e32 v122, 0, v122
	v_add_f32_e32 v124, v173, v124
	v_fmac_f32_e32 v125, v173, v173
	v_add_f32_e32 v126, v124, v122
	v_add_f32_e32 v127, v123, v125
	v_sub_f32_e32 v125, v191, v161
	v_sub_f32_e32 v124, v190, v161
	v_sub_f32_e32 v123, v193, v161
	v_sub_f32_e32 v122, v192, v161
	v_pk_mul_f32 v[124:125], v[160:161], v[124:125] op_sel_hi:[0,1]
	v_pk_mul_f32 v[122:123], v[160:161], v[122:123] op_sel_hi:[0,1]
	v_mul_f32_e32 v160, v175, v175
	v_add_f32_e32 v151, v174, v175
	v_fmac_f32_e32 v160, v174, v174
	v_add_f32_e32 v151, v176, v151
	v_fmac_f32_e32 v160, v176, v176
	v_add_f32_e32 v151, v177, v151
	v_fmac_f32_e32 v160, v177, v177
	v_add_f32_e32 v126, v126, v151
	v_add_f32_e32 v127, v127, v160
	v_lshlrev_b32_e32 v118, 2, v118
	v_lshlrev_b32_e32 v119, 2, v119
	v_cvt_pk_bf16_f32 v170, v174, v175
	v_cvt_pk_bf16_f32 v171, v176, v177
	s_waitcnt vmcnt(0)
; DEVI unsigned pk2(float lo, float hi) { unsigned r; asm("v_cvt_pk_bf16_f32 %0, %1, %2" : "=v"(r) : "v"(lo), "v"(hi)); return r; }
;     DEVI void operator()(const f32x4 (&acc)[2][2][4][2], const pg8::Unit& u, int wr, int wc, int fr, int fq) const {
;     ...
;                 const int row = row0 + ai * 128 + m * 16; float mu, rs; row_stats(stin, row, mu, rs);
;                 float sum = 0.f, sq = 0.f;
; #pragma unroll
;                 for (int bj = 0; bj < 2; ++bj) {
;                     f32x4 z[2];
; #pragma unroll
;                     for (int n = 0; n < 2; ++n) {
;                         const int col = colb + bj * 128 + 4 * n;
;                         f32x4 xv = *(const f32x4*)(zsrc + (size_t)row * DM + col);
;                         if (stin) { const f32x4 gv = *(const f32x4*)(gin + col), bv = *(const f32x4*)(bin + col); xv = (xv - mu) * rs * gv + bv; }
;                         f32x4 zz = ALPHA * xv + acc[ai][bj][m][n];
;                         if (bias) zz += *(const f32x4*)(bias + col);
;                         *(f32x4*)(zdst + (size_t)row * DM + col) = zz;
;                         sum += zz[0] + zz[1] + zz[2] + zz[3]; sq += zz[0] * zz[0] + zz[1] * zz[1] + zz[2] * zz[2] + zz[3] * zz[3];
;                         z[n] = zz;
;                     }
;                     u32x4 o; o.x = pk2(z[0][0], z[0][1]); o.y = pk2(z[0][2], z[0][3]); o.z = pk2(z[1][0], z[1][1]); o.w = pk2(z[1][2], z[1][3]);
;                     if (zb) *(u32x4*)(zb + (size_t)row * DM + colb + bj * 128) = o;
;                 }
;                 sum += __shfl_xor(sum, 16); sq += __shfl_xor(sq, 16);
;                 sum += __shfl_xor(sum, 32); sq += __shfl_xor(sq, 32);
;                 if (fq == 0) { atomicAdd(stout + 2 * (size_t)row, sum); atomicAdd(stout + 2 * (size_t)row + 1, sq); }
	v_pk_fma_f32 v[124:125], v[178:179], v[124:125], v[182:183]
	v_pk_fma_f32 v[122:123], v[180:181], v[122:123], v[184:185]
	v_pk_fma_f32 v[112:113], v[124:125], s[20:21], v[112:113] op_sel_hi:[1,0,1]
	v_pk_fma_f32 v[114:115], v[122:123], s[20:21], v[114:115] op_sel_hi:[1,0,1]
	v_pk_add_f32 v[122:123], v[186:187], v[112:113]
	v_pk_add_f32 v[124:125], v[188:189], v[114:115]
	v_mul_f32_e32 v113, v123, v123
	v_add_f32_e32 v112, v122, v123
	v_fmac_f32_e32 v113, v122, v122
	v_add_f32_e32 v112, v124, v112
	v_fmac_f32_e32 v113, v124, v124
	v_add_f32_e32 v112, v125, v112
	v_fmac_f32_e32 v113, v125, v125
	v_add_f32_e32 v112, v126, v112
	v_add_f32_e32 v113, v127, v113
	ds_bpermute_b32 v114, v118, v112
	ds_bpermute_b32 v115, v118, v113
	global_store_dwordx4 v[158:159], v[122:125], off offset:528
	v_cvt_pk_bf16_f32 v172, v122, v123
	v_cvt_pk_bf16_f32 v173, v124, v125
	s_waitcnt lgkmcnt(0)
	v_add_f32_e32 v112, v112, v114
	v_add_f32_e32 v113, v113, v115
	ds_bpermute_b32 v114, v119, v112
	ds_bpermute_b32 v115, v119, v113
	flat_store_dwordx4 v[194:195], v[170:173] offset:256
	s_mov_b32 s100, -1
	s_mov_b32 s101, 0
	s_mov_b32 s98, 0xffff0000
	s_mov_b32 s99, 0
	s_and_saveexec_b64 s[30:31], s[100:101]
	s_cbranch_execz .LBB0_1331
	v_lshl_add_u64 v[122:123], s[8:9], 0, v[156:157]
	s_waitcnt lgkmcnt(0)
	v_add_f32_e32 v112, v112, v114
	v_add_f32_e32 v113, v113, v115
	v_cndmask_b32_e64 v112, v112, v113, s[98:99]
	v_cndmask_b32_e64 v113, 0, 4, s[98:99]
	v_or_b32_e32 v122, v122, v113
	v_mov_b32_e32 v250, v122
	v_mov_b32_e32 v251, v123
	v_mov_b32_e32 v252, v112
.LBB0_1331:
	s_or_b64 exec, exec, s[30:31]
	v_or_b32_e32 v126, 16, v150
	v_ashrrev_i32_e32 v127, 31, v126
	v_lshlrev_b64 v[112:113], 3, v[126:127]
	s_waitcnt lgkmcnt(0)
	v_lshl_add_u64 v[114:115], s[6:7], 0, v[112:113]
	flat_load_dwordx2 v[160:161], v[114:115]
	v_lshlrev_b64 v[114:115], 12, v[126:127]
	v_lshl_add_u64 v[114:115], s[46:47], 0, v[114:115]
	v_lshl_add_u64 v[114:115], v[148:149], 2, v[114:115]
	global_load_dwordx4 v[122:125], v[114:115], off
	global_load_dwordx4 v[156:159], v[144:145], off
	global_load_dwordx4 v[170:173], v[146:147], off
	global_load_dwordx4 v[174:177], v[152:153], off
	global_load_dwordx4 v[178:181], v[114:115], off offset:16
	v_lshlrev_b64 v[126:127], 11, v[126:127]
	v_lshl_add_u64 v[126:127], s[10:11], 0, v[126:127]
	v_lshl_add_u64 v[126:127], v[148:149], 1, v[126:127]
	s_waitcnt vmcnt(0) lgkmcnt(0)
	v_pk_mul_f32 v[160:161], v[160:161], s[18:19] op_sel:[1,0] op_sel_hi:[0,0]
	v_fma_f32 v151, -v161, v161, v160
	v_max_f32_e32 v151, 0, v151
	v_add_f32_e32 v151, 0x3727c5ac, v151
	v_mul_f32_e32 v160, 0x4b800000, v151
	v_cmp_gt_f32_e32 vcc, s64, v151
	v_sub_f32_e32 v125, v125, v161
	v_sub_f32_e32 v124, v124, v161
	v_cndmask_b32_e32 v151, v151, v160, vcc
	v_rsq_f32_e32 v151, v151
	v_sub_f32_e32 v123, v123, v161
	v_sub_f32_e32 v122, v122, v161
	v_mul_f32_e32 v160, 0x45800000, v151
	v_cndmask_b32_e32 v160, v151, v160, vcc
	v_pk_mul_f32 v[122:123], v[122:123], v[160:161] op_sel_hi:[1,0]
	v_pk_mul_f32 v[124:125], v[124:125], v[160:161] op_sel_hi:[1,0]
	v_pk_fma_f32 v[122:123], v[156:157], v[122:123], v[170:171]
	v_pk_fma_f32 v[124:125], v[158:159], v[124:125], v[172:173]
	v_pk_fma_f32 v[108:109], v[122:123], s[20:21], v[108:109] op_sel_hi:[1,0,1]
	v_pk_fma_f32 v[110:111], v[124:125], s[20:21], v[110:111] op_sel_hi:[1,0,1]
	v_pk_add_f32 v[108:109], v[174:175], v[108:109]
	v_pk_add_f32 v[110:111], v[176:177], v[110:111]
	global_store_dwordx4 v[114:115], v[108:111], off
	global_load_dwordx4 v[122:125], v[144:145], off offset:16
	global_load_dwordx4 v[156:159], v[146:147], off offset:16
	global_load_dwordx4 v[170:173], v[154:155], off
	v_sub_f32_e32 v175, v181, v161
	v_sub_f32_e32 v174, v180, v161
	v_sub_f32_e32 v177, v179, v161
	v_sub_f32_e32 v176, v178, v161
	v_pk_mul_f32 v[176:177], v[176:177], v[160:161] op_sel_hi:[1,0]
	v_pk_mul_f32 v[178:179], v[174:175], v[160:161] op_sel_hi:[1,0]
	v_cvt_pk_bf16_f32 v174, v108, v109
	v_cvt_pk_bf16_f32 v175, v110, v111
	v_add_f32_e32 v151, v108, v109
	v_mul_f32_e32 v109, v109, v109
	v_fmac_f32_e32 v109, v108, v108
	v_add_f32_e32 v151, v110, v151
	v_fmac_f32_e32 v109, v110, v110
	v_add_f32_e32 v108, v111, v151
	v_add_f32_e32 v108, 0, v108
	v_fmac_f32_e32 v109, v111, v111
	s_waitcnt vmcnt(1)
	v_pk_fma_f32 v[124:125], v[124:125], v[178:179], v[158:159]
	v_pk_fma_f32 v[122:123], v[122:123], v[176:177], v[156:157]
	v_pk_fma_f32 v[106:107], v[124:125], s[20:21], v[106:107] op_sel_hi:[1,0,1]
	v_pk_fma_f32 v[104:105], v[122:123], s[20:21], v[104:105] op_sel_hi:[1,0,1]
	s_waitcnt vmcnt(0)
	v_pk_add_f32 v[106:107], v[172:173], v[106:107]
	v_pk_add_f32 v[104:105], v[170:171], v[104:105]
	global_store_dwordx4 v[114:115], v[104:107], off offset:16
	v_cvt_pk_bf16_f32 v176, v104, v105
	v_cvt_pk_bf16_f32 v177, v106, v107
	flat_store_dwordx4 v[126:127], v[174:177]
	global_load_dwordx4 v[122:125], v[114:115], off offset:512
	global_load_dwordx4 v[156:159], v[144:145], off offset:512
	global_load_dwordx4 v[170:173], v[146:147], off offset:512
	s_nop 0
	global_load_dwordx4 v[174:177], v[120:121], off
	global_load_dwordx4 v[178:181], v[114:115], off offset:528
	v_add_f32_e32 v110, v104, v105
	v_mul_f32_e32 v105, v105, v105
	v_fmac_f32_e32 v105, v104, v104
	v_add_f32_e32 v110, v106, v110
	v_fmac_f32_e32 v105, v106, v106
	v_add_f32_e32 v104, v107, v110
	v_fmac_f32_e32 v105, v107, v107
	v_add_f32_e32 v108, v104, v108
	v_add_f32_e32 v109, v109, v105
	s_waitcnt vmcnt(0)
; DEVI unsigned pk2(float lo, float hi) { unsigned r; asm("v_cvt_pk_bf16_f32 %0, %1, %2" : "=v"(r) : "v"(lo), "v"(hi)); return r; }
;     DEVI void operator()(const f32x4 (&acc)[2][2][4][2], const pg8::Unit& u, int wr, int wc, int fr, int fq) const {
;     ...
;                 const int row = row0 + ai * 128 + m * 16; float mu, rs; row_stats(stin, row, mu, rs);
;                 float sum = 0.f, sq = 0.f;
; #pragma unroll
;                 for (int bj = 0; bj < 2; ++bj) {
;                     f32x4 z[2];
; #pragma unroll
;                     for (int n = 0; n < 2; ++n) {
;                         const int col = colb + bj * 128 + 4 * n;
;                         f32x4 xv = *(const f32x4*)(zsrc + (size_t)row * DM + col);
;                         if (stin) { const f32x4 gv = *(const f32x4*)(gin + col), bv = *(const f32x4*)(bin + col); xv = (xv - mu) * rs * gv + bv; }
;                         f32x4 zz = ALPHA * xv + acc[ai][bj][m][n];
;                         if (bias) zz += *(const f32x4*)(bias + col);
;                         *(f32x4*)(zdst + (size_t)row * DM + col) = zz;
;                         sum += zz[0] + zz[1] + zz[2] + zz[3]; sq += zz[0] * zz[0] + zz[1] * zz[1] + zz[2] * zz[2] + zz[3] * zz[3];
;                         z[n] = zz;
;                     }
;                     u32x4 o; o.x = pk2(z[0][0], z[0][1]); o.y = pk2(z[0][2], z[0][3]); o.z = pk2(z[1][0], z[1][1]); o.w = pk2(z[1][2], z[1][3]);
;                     if (zb) *(u32x4*)(zb + (size_t)row * DM + colb + bj * 128) = o;
;                 }
;                 sum += __shfl_xor(sum, 16); sq += __shfl_xor(sq, 16);
;                 sum += __shfl_xor(sum, 32); sq += __shfl_xor(sq, 32);
;                 if (fq == 0) { atomicAdd(stout + 2 * (size_t)row, sum); atomicAdd(stout + 2 * (size_t)row + 1, sq); }
	v_sub_f32_e32 v125, v125, v161
	v_sub_f32_e32 v124, v124, v161
	v_sub_f32_e32 v123, v123, v161
	v_sub_f32_e32 v122, v122, v161
	v_pk_mul_f32 v[122:123], v[160:161], v[122:123] op_sel_hi:[0,1]
	v_pk_mul_f32 v[124:125], v[160:161], v[124:125] op_sel_hi:[0,1]
	v_pk_fma_f32 v[124:125], v[158:159], v[124:125], v[172:173]
	v_pk_fma_f32 v[122:123], v[156:157], v[122:123], v[170:171]
	v_pk_fma_f32 v[102:103], v[124:125], s[20:21], v[102:103] op_sel_hi:[1,0,1]
	v_pk_fma_f32 v[100:101], v[122:123], s[20:21], v[100:101] op_sel_hi:[1,0,1]
	v_pk_add_f32 v[102:103], v[176:177], v[102:103]
	v_pk_add_f32 v[100:101], v[174:175], v[100:101]
	global_store_dwordx4 v[114:115], v[100:103], off offset:512
	global_load_dwordx4 v[122:125], v[144:145], off offset:528
	global_load_dwordx4 v[156:159], v[146:147], off offset:528
	global_load_dwordx4 v[170:173], v[116:117], off
	v_sub_f32_e32 v107, v179, v161
	v_sub_f32_e32 v106, v178, v161
	v_sub_f32_e32 v105, v181, v161
	v_sub_f32_e32 v104, v180, v161
	v_pk_mul_f32 v[106:107], v[160:161], v[106:107] op_sel_hi:[0,1]
	v_pk_mul_f32 v[104:105], v[160:161], v[104:105] op_sel_hi:[0,1]
	v_mul_f32_e32 v111, v101, v101
	v_add_f32_e32 v110, v100, v101
	v_fmac_f32_e32 v111, v100, v100
	v_add_f32_e32 v110, v102, v110
	v_fmac_f32_e32 v111, v102, v102
	v_add_f32_e32 v110, v103, v110
	v_fmac_f32_e32 v111, v103, v103
	v_add_f32_e32 v108, v108, v110
	v_add_f32_e32 v109, v109, v111
	v_cvt_pk_bf16_f32 v100, v100, v101
	v_cvt_pk_bf16_f32 v101, v102, v103
	s_waitcnt vmcnt(0)
	v_pk_fma_f32 v[106:107], v[122:123], v[106:107], v[156:157]
	v_pk_fma_f32 v[104:105], v[124:125], v[104:105], v[158:159]
	v_pk_fma_f32 v[96:97], v[106:107], s[20:21], v[96:97] op_sel_hi:[1,0,1]
	v_pk_fma_f32 v[98:99], v[104:105], s[20:21], v[98:99] op_sel_hi:[1,0,1]
	v_pk_add_f32 v[104:105], v[170:171], v[96:97]
	v_pk_add_f32 v[106:107], v[172:173], v[98:99]
	v_mul_f32_e32 v97, v105, v105
	v_add_f32_e32 v96, v104, v105
	v_fmac_f32_e32 v97, v104, v104
	v_add_f32_e32 v96, v106, v96
	v_fmac_f32_e32 v97, v106, v106
	v_add_f32_e32 v96, v107, v96
	v_fmac_f32_e32 v97, v107, v107
	v_add_f32_e32 v96, v108, v96
	v_add_f32_e32 v97, v109, v97
	ds_bpermute_b32 v98, v118, v96
	ds_bpermute_b32 v99, v118, v97
	global_store_dwordx4 v[114:115], v[104:107], off offset:528
	v_cvt_pk_bf16_f32 v102, v104, v105
	v_cvt_pk_bf16_f32 v103, v106, v107
	s_waitcnt lgkmcnt(0)
	v_add_f32_e32 v96, v96, v98
	v_add_f32_e32 v97, v97, v99
	ds_bpermute_b32 v98, v119, v96
	ds_bpermute_b32 v99, v119, v97
	flat_store_dwordx4 v[126:127], v[100:103] offset:256
	s_mov_b32 s100, -1
	s_mov_b32 s101, 0
	s_mov_b32 s98, 0xffff0000
	s_mov_b32 s99, 0
	s_and_saveexec_b64 s[30:31], s[100:101]
	s_cbranch_execz .LBB0_1333
	v_lshl_add_u64 v[100:101], s[8:9], 0, v[112:113]
	s_waitcnt lgkmcnt(0)
	v_add_f32_e32 v96, v96, v98
	v_add_f32_e32 v97, v97, v99
	v_cndmask_b32_e64 v96, v96, v97, s[98:99]
	v_cndmask_b32_e64 v97, 0, 4, s[98:99]
	v_or_b32_e32 v100, v100, v97
	v_mov_b32_e32 v253, v96
.LBB0_1333:
	s_or_b64 exec, exec, s[30:31]
	v_or_b32_e32 v126, 32, v150
	v_ashrrev_i32_e32 v127, 31, v126
	v_lshlrev_b64 v[96:97], 3, v[126:127]
	s_waitcnt lgkmcnt(0)
	v_lshl_add_u64 v[98:99], s[6:7], 0, v[96:97]
	flat_load_dwordx2 v[156:157], v[98:99]
	v_lshlrev_b64 v[98:99], 12, v[126:127]
	v_lshl_add_u64 v[98:99], s[46:47], 0, v[98:99]
	v_lshl_add_u64 v[98:99], v[148:149], 2, v[98:99]
	global_load_dwordx4 v[100:103], v[98:99], off
	global_load_dwordx4 v[104:107], v[144:145], off
	global_load_dwordx4 v[108:111], v[146:147], off
	global_load_dwordx4 v[112:115], v[152:153], off
	global_load_dwordx4 v[122:125], v[98:99], off offset:16
	s_waitcnt vmcnt(0) lgkmcnt(0)
	v_pk_mul_f32 v[156:157], v[156:157], s[18:19] op_sel:[1,0] op_sel_hi:[0,0]
	v_fma_f32 v151, -v157, v157, v156
	v_max_f32_e32 v151, 0, v151
	v_add_f32_e32 v151, 0x3727c5ac, v151
	v_mul_f32_e32 v156, 0x4b800000, v151
	v_cmp_gt_f32_e32 vcc, s64, v151
	v_sub_f32_e32 v103, v103, v157
	v_sub_f32_e32 v102, v102, v157
	v_cndmask_b32_e32 v151, v151, v156, vcc
	v_rsq_f32_e32 v151, v151
	v_sub_f32_e32 v101, v101, v157
	v_sub_f32_e32 v100, v100, v157
	v_mul_f32_e32 v156, 0x45800000, v151
	v_cndmask_b32_e32 v156, v151, v156, vcc
	v_pk_mul_f32 v[100:101], v[100:101], v[156:157] op_sel_hi:[1,0]
	v_pk_mul_f32 v[102:103], v[102:103], v[156:157] op_sel_hi:[1,0]
	v_pk_fma_f32 v[100:101], v[104:105], v[100:101], v[108:109]
	v_pk_fma_f32 v[102:103], v[106:107], v[102:103], v[110:111]
	v_pk_fma_f32 v[92:93], v[100:101], s[20:21], v[92:93] op_sel_hi:[1,0,1]
	v_pk_fma_f32 v[94:95], v[102:103], s[20:21], v[94:95] op_sel_hi:[1,0,1]
	v_pk_add_f32 v[92:93], v[112:113], v[92:93]
	v_pk_add_f32 v[94:95], v[114:115], v[94:95]
	global_store_dwordx4 v[98:99], v[92:95], off
	global_load_dwordx4 v[100:103], v[144:145], off offset:16
	global_load_dwordx4 v[104:107], v[146:147], off offset:16
	global_load_dwordx4 v[108:111], v[154:155], off
	v_lshlrev_b64 v[112:113], 11, v[126:127]
	v_lshl_add_u64 v[112:113], s[10:11], 0, v[112:113]
	v_lshl_add_u64 v[126:127], v[148:149], 1, v[112:113]
	v_sub_f32_e32 v113, v125, v157
	v_sub_f32_e32 v112, v124, v157
	v_sub_f32_e32 v115, v123, v157
	v_sub_f32_e32 v114, v122, v157
	v_pk_mul_f32 v[114:115], v[114:115], v[156:157] op_sel_hi:[1,0]
	v_pk_mul_f32 v[122:123], v[112:113], v[156:157] op_sel_hi:[1,0]
	v_cvt_pk_bf16_f32 v112, v92, v93
	v_cvt_pk_bf16_f32 v113, v94, v95
	s_waitcnt vmcnt(1)
	v_pk_fma_f32 v[100:101], v[100:101], v[114:115], v[104:105]
	v_pk_fma_f32 v[102:103], v[102:103], v[122:123], v[106:107]
	v_pk_fma_f32 v[88:89], v[100:101], s[20:21], v[88:89] op_sel_hi:[1,0,1]
	v_pk_fma_f32 v[90:91], v[102:103], s[20:21], v[90:91] op_sel_hi:[1,0,1]
	s_waitcnt vmcnt(0)
; DEVI unsigned pk2(float lo, float hi) { unsigned r; asm("v_cvt_pk_bf16_f32 %0, %1, %2" : "=v"(r) : "v"(lo), "v"(hi)); return r; }
;     DEVI void operator()(const f32x4 (&acc)[2][2][4][2], const pg8::Unit& u, int wr, int wc, int fr, int fq) const {
;     ...
;                 const int row = row0 + ai * 128 + m * 16; float mu, rs; row_stats(stin, row, mu, rs);
;                 float sum = 0.f, sq = 0.f;
; #pragma unroll
;                 for (int bj = 0; bj < 2; ++bj) {
;                     f32x4 z[2];
; #pragma unroll
;                     for (int n = 0; n < 2; ++n) {
;                         const int col = colb + bj * 128 + 4 * n;
;                         f32x4 xv = *(const f32x4*)(zsrc + (size_t)row * DM + col);
;                         if (stin) { const f32x4 gv = *(const f32x4*)(gin + col), bv = *(const f32x4*)(bin + col); xv = (xv - mu) * rs * gv + bv; }
;                         f32x4 zz = ALPHA * xv + acc[ai][bj][m][n];
;                         if (bias) zz += *(const f32x4*)(bias + col);
;                         *(f32x4*)(zdst + (size_t)row * DM + col) = zz;
;                         sum += zz[0] + zz[1] + zz[2] + zz[3]; sq += zz[0] * zz[0] + zz[1] * zz[1] + zz[2] * zz[2] + zz[3] * zz[3];
;                         z[n] = zz;
;                     }
;                     u32x4 o; o.x = pk2(z[0][0], z[0][1]); o.y = pk2(z[0][2], z[0][3]); o.z = pk2(z[1][0], z[1][1]); o.w = pk2(z[1][2], z[1][3]);
;                     if (zb) *(u32x4*)(zb + (size_t)row * DM + colb + bj * 128) = o;
;                 }
;                 sum += __shfl_xor(sum, 16); sq += __shfl_xor(sq, 16);
;                 sum += __shfl_xor(sum, 32); sq += __shfl_xor(sq, 32);
;                 if (fq == 0) { atomicAdd(stout + 2 * (size_t)row, sum); atomicAdd(stout + 2 * (size_t)row + 1, sq); }
	v_pk_add_f32 v[88:89], v[108:109], v[88:89]
	v_pk_add_f32 v[90:91], v[110:111], v[90:91]
	global_store_dwordx4 v[98:99], v[88:91], off offset:16
	v_cvt_pk_bf16_f32 v114, v88, v89
	v_cvt_pk_bf16_f32 v115, v90, v91
	flat_store_dwordx4 v[126:127], v[112:115]
	global_load_dwordx4 v[100:103], v[98:99], off offset:512
	global_load_dwordx4 v[104:107], v[144:145], off offset:512
	global_load_dwordx4 v[108:111], v[146:147], off offset:512
	s_nop 0
	global_load_dwordx4 v[112:115], v[120:121], off
	global_load_dwordx4 v[122:125], v[98:99], off offset:528
	s_waitcnt vmcnt(0)
	v_sub_f32_e32 v103, v103, v157
	v_sub_f32_e32 v102, v102, v157
	v_sub_f32_e32 v101, v101, v157
	v_sub_f32_e32 v100, v100, v157
	v_pk_mul_f32 v[100:101], v[156:157], v[100:101] op_sel_hi:[0,1]
	v_pk_mul_f32 v[102:103], v[156:157], v[102:103] op_sel_hi:[0,1]
	v_pk_fma_f32 v[102:103], v[106:107], v[102:103], v[110:111]
	v_pk_fma_f32 v[100:101], v[104:105], v[100:101], v[108:109]
	v_pk_fma_f32 v[86:87], v[102:103], s[20:21], v[86:87] op_sel_hi:[1,0,1]
	v_pk_fma_f32 v[84:85], v[100:101], s[20:21], v[84:85] op_sel_hi:[1,0,1]
	v_pk_add_f32 v[86:87], v[114:115], v[86:87]
	v_pk_add_f32 v[84:85], v[112:113], v[84:85]
	global_store_dwordx4 v[98:99], v[84:87], off offset:512
	global_load_dwordx4 v[100:103], v[144:145], off offset:528
	global_load_dwordx4 v[104:107], v[146:147], off offset:528
	global_load_dwordx4 v[108:111], v[116:117], off
	v_add_f32_e32 v112, v92, v93
	v_mul_f32_e32 v93, v93, v93
	v_fmac_f32_e32 v93, v92, v92
	v_add_f32_e32 v112, v94, v112
	v_fmac_f32_e32 v93, v94, v94
	v_add_f32_e32 v94, v88, v89
	v_mul_f32_e32 v89, v89, v89
	v_fmac_f32_e32 v89, v88, v88
	v_add_f32_e32 v92, v95, v112
	v_add_f32_e32 v94, v90, v94
	v_fmac_f32_e32 v89, v90, v90
	v_add_f32_e32 v92, 0, v92
	v_fmac_f32_e32 v93, v95, v95
	v_add_f32_e32 v88, v91, v94
	v_fmac_f32_e32 v89, v91, v91
	v_sub_f32_e32 v91, v123, v157
	v_sub_f32_e32 v90, v122, v157
	v_add_f32_e32 v92, v88, v92
	v_add_f32_e32 v93, v93, v89
	v_sub_f32_e32 v89, v125, v157
	v_sub_f32_e32 v88, v124, v157
	v_pk_mul_f32 v[90:91], v[156:157], v[90:91] op_sel_hi:[0,1]
	v_pk_mul_f32 v[88:89], v[156:157], v[88:89] op_sel_hi:[0,1]
	v_mul_f32_e32 v95, v85, v85
	v_add_f32_e32 v94, v84, v85
	v_fmac_f32_e32 v95, v84, v84
	v_add_f32_e32 v94, v86, v94
	v_fmac_f32_e32 v95, v86, v86
	v_add_f32_e32 v94, v87, v94
	v_fmac_f32_e32 v95, v87, v87
	v_add_f32_e32 v92, v92, v94
	v_add_f32_e32 v93, v93, v95
	v_cvt_pk_bf16_f32 v84, v84, v85
	v_cvt_pk_bf16_f32 v85, v86, v87
	s_waitcnt vmcnt(0)
	v_pk_fma_f32 v[90:91], v[100:101], v[90:91], v[104:105]
	v_pk_fma_f32 v[88:89], v[102:103], v[88:89], v[106:107]
	v_pk_fma_f32 v[80:81], v[90:91], s[20:21], v[80:81] op_sel_hi:[1,0,1]
	v_pk_fma_f32 v[82:83], v[88:89], s[20:21], v[82:83] op_sel_hi:[1,0,1]
	v_pk_add_f32 v[88:89], v[108:109], v[80:81]
	v_pk_add_f32 v[90:91], v[110:111], v[82:83]
	v_mul_f32_e32 v81, v89, v89
	v_add_f32_e32 v80, v88, v89
	v_fmac_f32_e32 v81, v88, v88
	v_add_f32_e32 v80, v90, v80
	v_fmac_f32_e32 v81, v90, v90
	v_add_f32_e32 v80, v91, v80
	v_fmac_f32_e32 v81, v91, v91
	v_add_f32_e32 v80, v92, v80
	v_add_f32_e32 v81, v93, v81
	ds_bpermute_b32 v82, v118, v80
	ds_bpermute_b32 v83, v118, v81
	global_store_dwordx4 v[98:99], v[88:91], off offset:528
	v_cvt_pk_bf16_f32 v86, v88, v89
	v_cvt_pk_bf16_f32 v87, v90, v91
	s_waitcnt lgkmcnt(0)
	v_add_f32_e32 v80, v80, v82
	v_add_f32_e32 v81, v81, v83
	ds_bpermute_b32 v82, v119, v80
	ds_bpermute_b32 v83, v119, v81
	flat_store_dwordx4 v[126:127], v[84:87] offset:256
	s_mov_b32 s100, -1
	s_mov_b32 s101, 0
	s_mov_b32 s98, 0xffff0000
	s_mov_b32 s99, 0
	s_and_saveexec_b64 s[30:31], s[100:101]
	s_cbranch_execz .LBB0_1335
	v_lshl_add_u64 v[84:85], s[8:9], 0, v[96:97]
	s_waitcnt lgkmcnt(0)
	v_add_f32_e32 v80, v80, v82
	v_add_f32_e32 v81, v81, v83
	v_cndmask_b32_e64 v80, v80, v81, s[98:99]
	v_cndmask_b32_e64 v81, 0, 4, s[98:99]
	v_or_b32_e32 v84, v84, v81
	v_mov_b32_e32 v254, v80
.LBB0_1335:
	s_or_b64 exec, exec, s[30:31]
	v_or_b32_e32 v104, 48, v150
	v_ashrrev_i32_e32 v105, 31, v104
	v_lshlrev_b64 v[80:81], 3, v[104:105]
	s_waitcnt lgkmcnt(0)
	v_lshl_add_u64 v[82:83], s[6:7], 0, v[80:81]
	flat_load_dwordx2 v[106:107], v[82:83]
	v_lshlrev_b64 v[82:83], 12, v[104:105]
	v_lshl_add_u64 v[82:83], s[46:47], 0, v[82:83]
	v_lshl_add_u64 v[82:83], v[148:149], 2, v[82:83]
	global_load_dwordx4 v[84:87], v[82:83], off
	global_load_dwordx4 v[88:91], v[144:145], off
	global_load_dwordx4 v[92:95], v[146:147], off
	global_load_dwordx4 v[96:99], v[152:153], off
	global_load_dwordx4 v[100:103], v[82:83], off offset:16
	s_waitcnt vmcnt(0) lgkmcnt(0)
	v_pk_mul_f32 v[106:107], v[106:107], s[18:19] op_sel:[1,0] op_sel_hi:[0,0]
	v_fma_f32 v106, -v107, v107, v106
	v_max_f32_e32 v106, 0, v106
	v_add_f32_e32 v106, 0x3727c5ac, v106
	v_mul_f32_e32 v108, 0x4b800000, v106
	v_cmp_gt_f32_e32 vcc, s64, v106
	v_sub_f32_e32 v87, v87, v107
	v_sub_f32_e32 v86, v86, v107
	v_cndmask_b32_e32 v106, v106, v108, vcc
	v_rsq_f32_e32 v106, v106
	v_sub_f32_e32 v85, v85, v107
	v_sub_f32_e32 v84, v84, v107
	v_mul_f32_e32 v108, 0x45800000, v106
	v_cndmask_b32_e32 v106, v106, v108, vcc
	v_pk_mul_f32 v[84:85], v[84:85], v[106:107] op_sel_hi:[1,0]
	v_pk_mul_f32 v[86:87], v[86:87], v[106:107] op_sel_hi:[1,0]
	v_pk_fma_f32 v[84:85], v[88:89], v[84:85], v[92:93]
	v_pk_fma_f32 v[86:87], v[90:91], v[86:87], v[94:95]
	v_pk_fma_f32 v[76:77], v[84:85], s[20:21], v[76:77] op_sel_hi:[1,0,1]
	v_pk_fma_f32 v[78:79], v[86:87], s[20:21], v[78:79] op_sel_hi:[1,0,1]
	v_pk_add_f32 v[76:77], v[96:97], v[76:77]
	v_pk_add_f32 v[78:79], v[98:99], v[78:79]
	global_store_dwordx4 v[82:83], v[76:79], off
	global_load_dwordx4 v[84:87], v[144:145], off offset:16
	global_load_dwordx4 v[88:91], v[146:147], off offset:16
	global_load_dwordx4 v[92:95], v[154:155], off
	v_lshlrev_b64 v[96:97], 11, v[104:105]
	v_lshl_add_u64 v[96:97], s[10:11], 0, v[96:97]
	v_lshl_add_u64 v[104:105], v[148:149], 1, v[96:97]
	v_sub_f32_e32 v97, v103, v107
	v_sub_f32_e32 v96, v102, v107
	v_sub_f32_e32 v99, v101, v107
	v_sub_f32_e32 v98, v100, v107
	v_pk_mul_f32 v[98:99], v[98:99], v[106:107] op_sel_hi:[1,0]
	v_pk_mul_f32 v[100:101], v[96:97], v[106:107] op_sel_hi:[1,0]
	v_cvt_pk_bf16_f32 v96, v76, v77
	v_cvt_pk_bf16_f32 v97, v78, v79
	s_waitcnt vmcnt(1)
; DEVI unsigned pk2(float lo, float hi) { unsigned r; asm("v_cvt_pk_bf16_f32 %0, %1, %2" : "=v"(r) : "v"(lo), "v"(hi)); return r; }
;     DEVI void operator()(const f32x4 (&acc)[2][2][4][2], const pg8::Unit& u, int wr, int wc, int fr, int fq) const {
;     ...
;                 const int row = row0 + ai * 128 + m * 16; float mu, rs; row_stats(stin, row, mu, rs);
;                 float sum = 0.f, sq = 0.f;
; #pragma unroll
;                 for (int bj = 0; bj < 2; ++bj) {
;                     f32x4 z[2];
; #pragma unroll
;                     for (int n = 0; n < 2; ++n) {
;                         const int col = colb + bj * 128 + 4 * n;
;                         f32x4 xv = *(const f32x4*)(zsrc + (size_t)row * DM + col);
;                         if (stin) { const f32x4 gv = *(const f32x4*)(gin + col), bv = *(const f32x4*)(bin + col); xv = (xv - mu) * rs * gv + bv; }
;                         f32x4 zz = ALPHA * xv + acc[ai][bj][m][n];
;                         if (bias) zz += *(const f32x4*)(bias + col);
;                         *(f32x4*)(zdst + (size_t)row * DM + col) = zz;
;                         sum += zz[0] + zz[1] + zz[2] + zz[3]; sq += zz[0] * zz[0] + zz[1] * zz[1] + zz[2] * zz[2] + zz[3] * zz[3];
;                         z[n] = zz;
;                     }
;                     u32x4 o; o.x = pk2(z[0][0], z[0][1]); o.y = pk2(z[0][2], z[0][3]); o.z = pk2(z[1][0], z[1][1]); o.w = pk2(z[1][2], z[1][3]);
;                     if (zb) *(u32x4*)(zb + (size_t)row * DM + colb + bj * 128) = o;
;                 }
;                 sum += __shfl_xor(sum, 16); sq += __shfl_xor(sq, 16);
;                 sum += __shfl_xor(sum, 32); sq += __shfl_xor(sq, 32);
;                 if (fq == 0) { atomicAdd(stout + 2 * (size_t)row, sum); atomicAdd(stout + 2 * (size_t)row + 1, sq); }
	v_pk_fma_f32 v[84:85], v[84:85], v[98:99], v[88:89]
	v_pk_fma_f32 v[86:87], v[86:87], v[100:101], v[90:91]
	v_pk_fma_f32 v[72:73], v[84:85], s[20:21], v[72:73] op_sel_hi:[1,0,1]
	v_pk_fma_f32 v[74:75], v[86:87], s[20:21], v[74:75] op_sel_hi:[1,0,1]
	s_waitcnt vmcnt(0)
	v_pk_add_f32 v[72:73], v[92:93], v[72:73]
	v_pk_add_f32 v[74:75], v[94:95], v[74:75]
	global_store_dwordx4 v[82:83], v[72:75], off offset:16
	v_cvt_pk_bf16_f32 v98, v72, v73
	v_cvt_pk_bf16_f32 v99, v74, v75
	flat_store_dwordx4 v[104:105], v[96:99]
	global_load_dwordx4 v[84:87], v[82:83], off offset:512
	global_load_dwordx4 v[88:91], v[144:145], off offset:512
	global_load_dwordx4 v[92:95], v[146:147], off offset:512
	s_nop 0
	global_load_dwordx4 v[96:99], v[120:121], off
	global_load_dwordx4 v[100:103], v[82:83], off offset:528
	s_waitcnt vmcnt(0)
	v_sub_f32_e32 v87, v87, v107
	v_sub_f32_e32 v86, v86, v107
	v_sub_f32_e32 v85, v85, v107
	v_sub_f32_e32 v84, v84, v107
	v_pk_mul_f32 v[84:85], v[106:107], v[84:85] op_sel_hi:[0,1]
	v_pk_mul_f32 v[86:87], v[106:107], v[86:87] op_sel_hi:[0,1]
	v_pk_fma_f32 v[86:87], v[90:91], v[86:87], v[94:95]
	v_pk_fma_f32 v[84:85], v[88:89], v[84:85], v[92:93]
	v_pk_fma_f32 v[70:71], v[86:87], s[20:21], v[70:71] op_sel_hi:[1,0,1]
	v_pk_fma_f32 v[68:69], v[84:85], s[20:21], v[68:69] op_sel_hi:[1,0,1]
	v_pk_add_f32 v[70:71], v[98:99], v[70:71]
	v_pk_add_f32 v[68:69], v[96:97], v[68:69]
	global_store_dwordx4 v[82:83], v[68:71], off offset:512
	global_load_dwordx4 v[84:87], v[144:145], off offset:528
	global_load_dwordx4 v[88:91], v[146:147], off offset:528
	global_load_dwordx4 v[92:95], v[116:117], off
	v_add_f32_e32 v96, v76, v77
	v_mul_f32_e32 v77, v77, v77
	v_fmac_f32_e32 v77, v76, v76
	v_add_f32_e32 v96, v78, v96
	v_fmac_f32_e32 v77, v78, v78
	v_add_f32_e32 v78, v72, v73
	v_mul_f32_e32 v73, v73, v73
	v_fmac_f32_e32 v73, v72, v72
	v_add_f32_e32 v76, v79, v96
	v_add_f32_e32 v78, v74, v78
	v_fmac_f32_e32 v73, v74, v74
	v_add_f32_e32 v76, 0, v76
	v_fmac_f32_e32 v77, v79, v79
	v_add_f32_e32 v72, v75, v78
	v_fmac_f32_e32 v73, v75, v75
	v_sub_f32_e32 v75, v101, v107
	v_sub_f32_e32 v74, v100, v107
	v_add_f32_e32 v76, v72, v76
	v_add_f32_e32 v77, v77, v73
	v_sub_f32_e32 v73, v103, v107
	v_sub_f32_e32 v72, v102, v107
	v_pk_mul_f32 v[74:75], v[106:107], v[74:75] op_sel_hi:[0,1]
	v_pk_mul_f32 v[72:73], v[106:107], v[72:73] op_sel_hi:[0,1]
	v_mul_f32_e32 v79, v69, v69
	v_add_f32_e32 v78, v68, v69
	v_fmac_f32_e32 v79, v68, v68
	v_add_f32_e32 v78, v70, v78
	v_fmac_f32_e32 v79, v70, v70
	v_add_f32_e32 v78, v71, v78
	v_fmac_f32_e32 v79, v71, v71
	v_add_f32_e32 v76, v76, v78
	v_add_f32_e32 v77, v77, v79
	v_cvt_pk_bf16_f32 v68, v68, v69
	v_cvt_pk_bf16_f32 v69, v70, v71
	s_waitcnt vmcnt(0)
	v_pk_fma_f32 v[74:75], v[84:85], v[74:75], v[88:89]
	v_pk_fma_f32 v[72:73], v[86:87], v[72:73], v[90:91]
	v_pk_fma_f32 v[64:65], v[74:75], s[20:21], v[64:65] op_sel_hi:[1,0,1]
	v_pk_fma_f32 v[66:67], v[72:73], s[20:21], v[66:67] op_sel_hi:[1,0,1]
	v_pk_add_f32 v[72:73], v[92:93], v[64:65]
	v_pk_add_f32 v[74:75], v[94:95], v[66:67]
	v_mul_f32_e32 v65, v73, v73
	v_add_f32_e32 v64, v72, v73
	v_fmac_f32_e32 v65, v72, v72
	v_add_f32_e32 v64, v74, v64
	v_fmac_f32_e32 v65, v74, v74
	v_add_f32_e32 v64, v75, v64
	v_fmac_f32_e32 v65, v75, v75
	v_add_f32_e32 v64, v76, v64
	v_add_f32_e32 v65, v77, v65
	ds_bpermute_b32 v66, v118, v64
	ds_bpermute_b32 v67, v118, v65
	global_store_dwordx4 v[82:83], v[72:75], off offset:528
	v_cvt_pk_bf16_f32 v70, v72, v73
	v_cvt_pk_bf16_f32 v71, v74, v75
	s_waitcnt lgkmcnt(0)
	v_add_f32_e32 v64, v64, v66
	v_add_f32_e32 v65, v65, v67
	ds_bpermute_b32 v66, v119, v64
	ds_bpermute_b32 v67, v119, v65
	flat_store_dwordx4 v[104:105], v[68:71] offset:256
	s_mov_b32 s100, -1
	s_mov_b32 s101, 0
	s_mov_b32 s98, 0xffff0000
	s_mov_b32 s99, 0
	s_and_saveexec_b64 s[30:31], s[100:101]
	s_cbranch_execz .LBB0_1337
	v_lshl_add_u64 v[68:69], s[8:9], 0, v[80:81]
	s_waitcnt lgkmcnt(0)
	v_add_f32_e32 v64, v64, v66
	v_add_f32_e32 v65, v65, v67
	v_cndmask_b32_e64 v64, v64, v65, s[98:99]
	v_cndmask_b32_e64 v65, 0, 4, s[98:99]
	v_or_b32_e32 v68, v68, v65
	v_mov_b32_e32 v255, v64
	flat_atomic_add_f32 v[250:251], v252
	flat_atomic_add_f32 v[250:251], v253 offset:128
	flat_atomic_add_f32 v[250:251], v254 offset:256
	flat_atomic_add_f32 v[250:251], v255 offset:384
; DEVI unsigned pk2(float lo, float hi) { unsigned r; asm("v_cvt_pk_bf16_f32 %0, %1, %2" : "=v"(r) : "v"(lo), "v"(hi)); return r; }
;     DEVI void operator()(const f32x4 (&acc)[2][2][4][2], const pg8::Unit& u, int wr, int wc, int fr, int fq) const {
;     ...
;                 const int row = row0 + ai * 128 + m * 16; float mu, rs; row_stats(stin, row, mu, rs);
;                 float sum = 0.f, sq = 0.f;
; #pragma unroll
;                 for (int bj = 0; bj < 2; ++bj) {
;                     f32x4 z[2];
; #pragma unroll
;                     for (int n = 0; n < 2; ++n) {
;                         const int col = colb + bj * 128 + 4 * n;
;                         f32x4 xv = *(const f32x4*)(zsrc + (size_t)row * DM + col);
;                         if (stin) { const f32x4 gv = *(const f32x4*)(gin + col), bv = *(const f32x4*)(bin + col); xv = (xv - mu) * rs * gv + bv; }
;                         f32x4 zz = ALPHA * xv + acc[ai][bj][m][n];
;                         if (bias) zz += *(const f32x4*)(bias + col);
;                         *(f32x4*)(zdst + (size_t)row * DM + col) = zz;
;                         sum += zz[0] + zz[1] + zz[2] + zz[3]; sq += zz[0] * zz[0] + zz[1] * zz[1] + zz[2] * zz[2] + zz[3] * zz[3];
;                         z[n] = zz;
;                     }
;                     u32x4 o; o.x = pk2(z[0][0], z[0][1]); o.y = pk2(z[0][2], z[0][3]); o.z = pk2(z[1][0], z[1][1]); o.w = pk2(z[1][2], z[1][3]);
;                     if (zb) *(u32x4*)(zb + (size_t)row * DM + colb + bj * 128) = o;
;                 }
;                 sum += __shfl_xor(sum, 16); sq += __shfl_xor(sq, 16);
;                 sum += __shfl_xor(sum, 32); sq += __shfl_xor(sq, 32);
;                 if (fq == 0) { atomicAdd(stout + 2 * (size_t)row, sum); atomicAdd(stout + 2 * (size_t)row + 1, sq); }
.LBB0_1337:
	s_or_b64 exec, exec, s[30:31]
	v_add_u32_e32 v88, 0x80, v150
	v_ashrrev_i32_e32 v89, 31, v88
	v_lshlrev_b64 v[64:65], 3, v[88:89]
	s_waitcnt lgkmcnt(0)
	v_lshl_add_u64 v[66:67], s[6:7], 0, v[64:65]
	flat_load_dwordx2 v[90:91], v[66:67]
	v_lshlrev_b64 v[66:67], 12, v[88:89]
	v_lshl_add_u64 v[66:67], s[46:47], 0, v[66:67]
	v_lshl_add_u64 v[66:67], v[148:149], 2, v[66:67]
	global_load_dwordx4 v[68:71], v[66:67], off
	global_load_dwordx4 v[72:75], v[144:145], off
	global_load_dwordx4 v[76:79], v[146:147], off
	global_load_dwordx4 v[80:83], v[152:153], off
	global_load_dwordx4 v[84:87], v[66:67], off offset:16
	s_waitcnt vmcnt(0) lgkmcnt(0)
	v_pk_mul_f32 v[90:91], v[90:91], s[18:19] op_sel:[1,0] op_sel_hi:[0,0]
	v_fma_f32 v90, -v91, v91, v90
	v_max_f32_e32 v90, 0, v90
	v_add_f32_e32 v90, 0x3727c5ac, v90
	v_mul_f32_e32 v92, 0x4b800000, v90
	v_cmp_gt_f32_e32 vcc, s64, v90
	v_sub_f32_e32 v71, v71, v91
	v_sub_f32_e32 v70, v70, v91
	v_cndmask_b32_e32 v90, v90, v92, vcc
	v_rsq_f32_e32 v90, v90
	v_sub_f32_e32 v69, v69, v91
	v_sub_f32_e32 v68, v68, v91
	v_mul_f32_e32 v92, 0x45800000, v90
	v_cndmask_b32_e32 v90, v90, v92, vcc
	v_pk_mul_f32 v[68:69], v[68:69], v[90:91] op_sel_hi:[1,0]
	v_pk_mul_f32 v[70:71], v[70:71], v[90:91] op_sel_hi:[1,0]
	v_pk_fma_f32 v[68:69], v[72:73], v[68:69], v[76:77]
	v_pk_fma_f32 v[70:71], v[74:75], v[70:71], v[78:79]
	v_pk_fma_f32 v[60:61], v[68:69], s[20:21], v[60:61] op_sel_hi:[1,0,1]
	v_pk_fma_f32 v[62:63], v[70:71], s[20:21], v[62:63] op_sel_hi:[1,0,1]
	v_pk_add_f32 v[60:61], v[80:81], v[60:61]
	v_pk_add_f32 v[62:63], v[82:83], v[62:63]
	global_store_dwordx4 v[66:67], v[60:63], off
	global_load_dwordx4 v[68:71], v[144:145], off offset:16
	global_load_dwordx4 v[72:75], v[146:147], off offset:16
	global_load_dwordx4 v[76:79], v[154:155], off
	v_lshlrev_b64 v[80:81], 11, v[88:89]
	v_lshl_add_u64 v[80:81], s[10:11], 0, v[80:81]
	v_lshl_add_u64 v[88:89], v[148:149], 1, v[80:81]
	v_sub_f32_e32 v81, v87, v91
	v_sub_f32_e32 v80, v86, v91
	v_sub_f32_e32 v83, v85, v91
	v_sub_f32_e32 v82, v84, v91
	v_pk_mul_f32 v[82:83], v[82:83], v[90:91] op_sel_hi:[1,0]
	v_pk_mul_f32 v[84:85], v[80:81], v[90:91] op_sel_hi:[1,0]
	v_cvt_pk_bf16_f32 v80, v60, v61
	v_cvt_pk_bf16_f32 v81, v62, v63
	s_waitcnt vmcnt(1)
	v_pk_fma_f32 v[68:69], v[68:69], v[82:83], v[72:73]
	v_pk_fma_f32 v[70:71], v[70:71], v[84:85], v[74:75]
	v_pk_fma_f32 v[56:57], v[68:69], s[20:21], v[56:57] op_sel_hi:[1,0,1]
	v_pk_fma_f32 v[58:59], v[70:71], s[20:21], v[58:59] op_sel_hi:[1,0,1]
	s_waitcnt vmcnt(0)
	v_pk_add_f32 v[56:57], v[76:77], v[56:57]
	v_pk_add_f32 v[58:59], v[78:79], v[58:59]
	global_store_dwordx4 v[66:67], v[56:59], off offset:16
	v_cvt_pk_bf16_f32 v82, v56, v57
	v_cvt_pk_bf16_f32 v83, v58, v59
	flat_store_dwordx4 v[88:89], v[80:83]
	global_load_dwordx4 v[68:71], v[66:67], off offset:512
	global_load_dwordx4 v[72:75], v[144:145], off offset:512
	global_load_dwordx4 v[76:79], v[146:147], off offset:512
	s_nop 0
	global_load_dwordx4 v[80:83], v[120:121], off
	global_load_dwordx4 v[84:87], v[66:67], off offset:528
	s_waitcnt vmcnt(0)
	v_sub_f32_e32 v71, v71, v91
	v_sub_f32_e32 v70, v70, v91
	v_sub_f32_e32 v69, v69, v91
	v_sub_f32_e32 v68, v68, v91
	v_pk_mul_f32 v[68:69], v[90:91], v[68:69] op_sel_hi:[0,1]
	v_pk_mul_f32 v[70:71], v[90:91], v[70:71] op_sel_hi:[0,1]
	v_pk_fma_f32 v[70:71], v[74:75], v[70:71], v[78:79]
	v_pk_fma_f32 v[68:69], v[72:73], v[68:69], v[76:77]
	v_pk_fma_f32 v[54:55], v[70:71], s[20:21], v[54:55] op_sel_hi:[1,0,1]
	v_pk_fma_f32 v[52:53], v[68:69], s[20:21], v[52:53] op_sel_hi:[1,0,1]
	v_pk_add_f32 v[54:55], v[82:83], v[54:55]
	v_pk_add_f32 v[52:53], v[80:81], v[52:53]
	global_store_dwordx4 v[66:67], v[52:55], off offset:512
	global_load_dwordx4 v[68:71], v[144:145], off offset:528
	global_load_dwordx4 v[72:75], v[146:147], off offset:528
	global_load_dwordx4 v[76:79], v[116:117], off
	v_add_f32_e32 v80, v60, v61
	v_mul_f32_e32 v61, v61, v61
	v_fmac_f32_e32 v61, v60, v60
	v_add_f32_e32 v80, v62, v80
	v_fmac_f32_e32 v61, v62, v62
	v_add_f32_e32 v62, v56, v57
	v_mul_f32_e32 v57, v57, v57
	v_fmac_f32_e32 v57, v56, v56
	v_add_f32_e32 v60, v63, v80
	v_add_f32_e32 v62, v58, v62
	v_fmac_f32_e32 v57, v58, v58
	v_add_f32_e32 v60, 0, v60
	v_fmac_f32_e32 v61, v63, v63
	v_add_f32_e32 v56, v59, v62
	v_fmac_f32_e32 v57, v59, v59
	v_sub_f32_e32 v59, v85, v91
	v_sub_f32_e32 v58, v84, v91
	v_add_f32_e32 v60, v56, v60
	v_add_f32_e32 v61, v61, v57
	v_sub_f32_e32 v57, v87, v91
	v_sub_f32_e32 v56, v86, v91
	v_pk_mul_f32 v[58:59], v[90:91], v[58:59] op_sel_hi:[0,1]
	v_pk_mul_f32 v[56:57], v[90:91], v[56:57] op_sel_hi:[0,1]
	v_mul_f32_e32 v63, v53, v53
	v_add_f32_e32 v62, v52, v53
	v_fmac_f32_e32 v63, v52, v52
	v_add_f32_e32 v62, v54, v62
	v_fmac_f32_e32 v63, v54, v54
	v_add_f32_e32 v62, v55, v62
	v_fmac_f32_e32 v63, v55, v55
	v_add_f32_e32 v60, v60, v62
	v_add_f32_e32 v61, v61, v63
	v_cvt_pk_bf16_f32 v52, v52, v53
	v_cvt_pk_bf16_f32 v53, v54, v55
	s_waitcnt vmcnt(0)
	v_pk_fma_f32 v[58:59], v[68:69], v[58:59], v[72:73]
	v_pk_fma_f32 v[56:57], v[70:71], v[56:57], v[74:75]
	v_pk_fma_f32 v[48:49], v[58:59], s[20:21], v[48:49] op_sel_hi:[1,0,1]
	v_pk_fma_f32 v[50:51], v[56:57], s[20:21], v[50:51] op_sel_hi:[1,0,1]
	v_pk_add_f32 v[56:57], v[76:77], v[48:49]
	v_pk_add_f32 v[58:59], v[78:79], v[50:51]
	v_mul_f32_e32 v49, v57, v57
	v_add_f32_e32 v48, v56, v57
	v_fmac_f32_e32 v49, v56, v56
	v_add_f32_e32 v48, v58, v48
	v_fmac_f32_e32 v49, v58, v58
	v_add_f32_e32 v48, v59, v48
	v_fmac_f32_e32 v49, v59, v59
	v_add_f32_e32 v48, v60, v48
	v_add_f32_e32 v49, v61, v49
	ds_bpermute_b32 v50, v118, v48
	ds_bpermute_b32 v51, v118, v49
	global_store_dwordx4 v[66:67], v[56:59], off offset:528
	v_cvt_pk_bf16_f32 v54, v56, v57
	v_cvt_pk_bf16_f32 v55, v58, v59
	s_waitcnt lgkmcnt(0)
	v_add_f32_e32 v48, v48, v50
	v_add_f32_e32 v49, v49, v51
	ds_bpermute_b32 v50, v119, v48
	ds_bpermute_b32 v51, v119, v49
	flat_store_dwordx4 v[88:89], v[52:55] offset:256
	s_mov_b32 s100, -1
	s_mov_b32 s101, 0
	s_mov_b32 s98, 0xffff0000
	s_mov_b32 s99, 0
	s_and_saveexec_b64 s[30:31], s[100:101]
	s_cbranch_execz .LBB0_1339
	v_lshl_add_u64 v[52:53], s[8:9], 0, v[64:65]
	s_waitcnt lgkmcnt(0)
	v_add_f32_e32 v48, v48, v50
	v_add_f32_e32 v49, v49, v51
	v_cndmask_b32_e64 v48, v48, v49, s[98:99]
	v_cndmask_b32_e64 v49, 0, 4, s[98:99]
	v_or_b32_e32 v52, v52, v49
	v_mov_b32_e32 v250, v52
	v_mov_b32_e32 v251, v53
	v_mov_b32_e32 v252, v48
; DEVI unsigned pk2(float lo, float hi) { unsigned r; asm("v_cvt_pk_bf16_f32 %0, %1, %2" : "=v"(r) : "v"(lo), "v"(hi)); return r; }
;     DEVI void operator()(const f32x4 (&acc)[2][2][4][2], const pg8::Unit& u, int wr, int wc, int fr, int fq) const {
;     ...
;                 const int row = row0 + ai * 128 + m * 16; float mu, rs; row_stats(stin, row, mu, rs);
;                 float sum = 0.f, sq = 0.f;
; #pragma unroll
;                 for (int bj = 0; bj < 2; ++bj) {
;                     f32x4 z[2];
; #pragma unroll
;                     for (int n = 0; n < 2; ++n) {
;                         const int col = colb + bj * 128 + 4 * n;
;                         f32x4 xv = *(const f32x4*)(zsrc + (size_t)row * DM + col);
;                         if (stin) { const f32x4 gv = *(const f32x4*)(gin + col), bv = *(const f32x4*)(bin + col); xv = (xv - mu) * rs * gv + bv; }
;                         f32x4 zz = ALPHA * xv + acc[ai][bj][m][n];
;                         if (bias) zz += *(const f32x4*)(bias + col);
;                         *(f32x4*)(zdst + (size_t)row * DM + col) = zz;
;                         sum += zz[0] + zz[1] + zz[2] + zz[3]; sq += zz[0] * zz[0] + zz[1] * zz[1] + zz[2] * zz[2] + zz[3] * zz[3];
;                         z[n] = zz;
;                     }
;                     u32x4 o; o.x = pk2(z[0][0], z[0][1]); o.y = pk2(z[0][2], z[0][3]); o.z = pk2(z[1][0], z[1][1]); o.w = pk2(z[1][2], z[1][3]);
;                     if (zb) *(u32x4*)(zb + (size_t)row * DM + colb + bj * 128) = o;
;                 }
;                 sum += __shfl_xor(sum, 16); sq += __shfl_xor(sq, 16);
;                 sum += __shfl_xor(sum, 32); sq += __shfl_xor(sq, 32);
;                 if (fq == 0) { atomicAdd(stout + 2 * (size_t)row, sum); atomicAdd(stout + 2 * (size_t)row + 1, sq); }
.LBB0_1339:
	s_or_b64 exec, exec, s[30:31]
	v_add_u32_e32 v72, 0x90, v150
	v_ashrrev_i32_e32 v73, 31, v72
	v_lshlrev_b64 v[48:49], 3, v[72:73]
	s_waitcnt lgkmcnt(0)
	v_lshl_add_u64 v[50:51], s[6:7], 0, v[48:49]
	flat_load_dwordx2 v[74:75], v[50:51]
	v_lshlrev_b64 v[50:51], 12, v[72:73]
	v_lshl_add_u64 v[50:51], s[46:47], 0, v[50:51]
	v_lshl_add_u64 v[50:51], v[148:149], 2, v[50:51]
	global_load_dwordx4 v[52:55], v[50:51], off
	global_load_dwordx4 v[56:59], v[144:145], off
	global_load_dwordx4 v[60:63], v[146:147], off
	global_load_dwordx4 v[64:67], v[152:153], off
	global_load_dwordx4 v[68:71], v[50:51], off offset:16
	s_waitcnt vmcnt(0) lgkmcnt(0)
	v_pk_mul_f32 v[74:75], v[74:75], s[18:19] op_sel:[1,0] op_sel_hi:[0,0]
	v_fma_f32 v74, -v75, v75, v74
	v_max_f32_e32 v74, 0, v74
	v_add_f32_e32 v74, 0x3727c5ac, v74
	v_mul_f32_e32 v76, 0x4b800000, v74
	v_cmp_gt_f32_e32 vcc, s64, v74
	v_sub_f32_e32 v55, v55, v75
	v_sub_f32_e32 v54, v54, v75
	v_cndmask_b32_e32 v74, v74, v76, vcc
	v_rsq_f32_e32 v74, v74
	v_sub_f32_e32 v53, v53, v75
	v_sub_f32_e32 v52, v52, v75
	v_mul_f32_e32 v76, 0x45800000, v74
	v_cndmask_b32_e32 v74, v74, v76, vcc
	v_pk_mul_f32 v[52:53], v[52:53], v[74:75] op_sel_hi:[1,0]
	v_pk_mul_f32 v[54:55], v[54:55], v[74:75] op_sel_hi:[1,0]
	v_pk_fma_f32 v[52:53], v[56:57], v[52:53], v[60:61]
	v_pk_fma_f32 v[54:55], v[58:59], v[54:55], v[62:63]
	v_pk_fma_f32 v[44:45], v[52:53], s[20:21], v[44:45] op_sel_hi:[1,0,1]
	v_pk_fma_f32 v[46:47], v[54:55], s[20:21], v[46:47] op_sel_hi:[1,0,1]
	v_pk_add_f32 v[44:45], v[64:65], v[44:45]
	v_pk_add_f32 v[46:47], v[66:67], v[46:47]
	global_store_dwordx4 v[50:51], v[44:47], off
	global_load_dwordx4 v[52:55], v[144:145], off offset:16
	global_load_dwordx4 v[56:59], v[146:147], off offset:16
	global_load_dwordx4 v[60:63], v[154:155], off
	v_lshlrev_b64 v[64:65], 11, v[72:73]
	v_lshl_add_u64 v[64:65], s[10:11], 0, v[64:65]
	v_lshl_add_u64 v[72:73], v[148:149], 1, v[64:65]
	v_sub_f32_e32 v65, v71, v75
	v_sub_f32_e32 v64, v70, v75
	v_sub_f32_e32 v67, v69, v75
	v_sub_f32_e32 v66, v68, v75
	v_pk_mul_f32 v[66:67], v[66:67], v[74:75] op_sel_hi:[1,0]
	v_pk_mul_f32 v[68:69], v[64:65], v[74:75] op_sel_hi:[1,0]
	v_cvt_pk_bf16_f32 v64, v44, v45
	v_cvt_pk_bf16_f32 v65, v46, v47
	s_waitcnt vmcnt(1)
	v_pk_fma_f32 v[52:53], v[52:53], v[66:67], v[56:57]
	v_pk_fma_f32 v[54:55], v[54:55], v[68:69], v[58:59]
	v_pk_fma_f32 v[40:41], v[52:53], s[20:21], v[40:41] op_sel_hi:[1,0,1]
	v_pk_fma_f32 v[42:43], v[54:55], s[20:21], v[42:43] op_sel_hi:[1,0,1]
	s_waitcnt vmcnt(0)
	v_pk_add_f32 v[40:41], v[60:61], v[40:41]
	v_pk_add_f32 v[42:43], v[62:63], v[42:43]
	global_store_dwordx4 v[50:51], v[40:43], off offset:16
	v_cvt_pk_bf16_f32 v66, v40, v41
	v_cvt_pk_bf16_f32 v67, v42, v43
	flat_store_dwordx4 v[72:73], v[64:67]
	global_load_dwordx4 v[52:55], v[50:51], off offset:512
	global_load_dwordx4 v[56:59], v[144:145], off offset:512
	global_load_dwordx4 v[60:63], v[146:147], off offset:512
	s_nop 0
	global_load_dwordx4 v[64:67], v[120:121], off
	global_load_dwordx4 v[68:71], v[50:51], off offset:528
	s_waitcnt vmcnt(0)
	v_sub_f32_e32 v55, v55, v75
	v_sub_f32_e32 v54, v54, v75
	v_sub_f32_e32 v53, v53, v75
	v_sub_f32_e32 v52, v52, v75
	v_pk_mul_f32 v[52:53], v[74:75], v[52:53] op_sel_hi:[0,1]
	v_pk_mul_f32 v[54:55], v[74:75], v[54:55] op_sel_hi:[0,1]
	v_pk_fma_f32 v[54:55], v[58:59], v[54:55], v[62:63]
	v_pk_fma_f32 v[52:53], v[56:57], v[52:53], v[60:61]
	v_pk_fma_f32 v[38:39], v[54:55], s[20:21], v[38:39] op_sel_hi:[1,0,1]
	v_pk_fma_f32 v[36:37], v[52:53], s[20:21], v[36:37] op_sel_hi:[1,0,1]
	v_pk_add_f32 v[38:39], v[66:67], v[38:39]
	v_pk_add_f32 v[36:37], v[64:65], v[36:37]
	global_store_dwordx4 v[50:51], v[36:39], off offset:512
	global_load_dwordx4 v[52:55], v[144:145], off offset:528
	global_load_dwordx4 v[56:59], v[146:147], off offset:528
	global_load_dwordx4 v[60:63], v[116:117], off
	v_add_f32_e32 v64, v44, v45
	v_mul_f32_e32 v45, v45, v45
	v_fmac_f32_e32 v45, v44, v44
	v_add_f32_e32 v64, v46, v64
	v_fmac_f32_e32 v45, v46, v46
	v_add_f32_e32 v46, v40, v41
	v_mul_f32_e32 v41, v41, v41
	v_fmac_f32_e32 v41, v40, v40
	v_add_f32_e32 v44, v47, v64
	v_add_f32_e32 v46, v42, v46
	v_fmac_f32_e32 v41, v42, v42
	v_add_f32_e32 v44, 0, v44
	v_fmac_f32_e32 v45, v47, v47
	v_add_f32_e32 v40, v43, v46
	v_fmac_f32_e32 v41, v43, v43
	v_sub_f32_e32 v43, v69, v75
	v_sub_f32_e32 v42, v68, v75
	v_add_f32_e32 v44, v40, v44
	v_add_f32_e32 v45, v45, v41
	v_sub_f32_e32 v41, v71, v75
	v_sub_f32_e32 v40, v70, v75
	v_pk_mul_f32 v[42:43], v[74:75], v[42:43] op_sel_hi:[0,1]
	v_pk_mul_f32 v[40:41], v[74:75], v[40:41] op_sel_hi:[0,1]
	v_mul_f32_e32 v47, v37, v37
	v_add_f32_e32 v46, v36, v37
	v_fmac_f32_e32 v47, v36, v36
	v_add_f32_e32 v46, v38, v46
	v_fmac_f32_e32 v47, v38, v38
	v_add_f32_e32 v46, v39, v46
	v_fmac_f32_e32 v47, v39, v39
	v_add_f32_e32 v44, v44, v46
	v_add_f32_e32 v45, v45, v47
	v_cvt_pk_bf16_f32 v36, v36, v37
	v_cvt_pk_bf16_f32 v37, v38, v39
	s_waitcnt vmcnt(0)
	v_pk_fma_f32 v[42:43], v[52:53], v[42:43], v[56:57]
	v_pk_fma_f32 v[40:41], v[54:55], v[40:41], v[58:59]
	v_pk_fma_f32 v[32:33], v[42:43], s[20:21], v[32:33] op_sel_hi:[1,0,1]
	v_pk_fma_f32 v[34:35], v[40:41], s[20:21], v[34:35] op_sel_hi:[1,0,1]
	v_pk_add_f32 v[40:41], v[60:61], v[32:33]
	v_pk_add_f32 v[42:43], v[62:63], v[34:35]
	v_mul_f32_e32 v33, v41, v41
	v_add_f32_e32 v32, v40, v41
	v_fmac_f32_e32 v33, v40, v40
	v_add_f32_e32 v32, v42, v32
	v_fmac_f32_e32 v33, v42, v42
	v_add_f32_e32 v32, v43, v32
	v_fmac_f32_e32 v33, v43, v43
	v_add_f32_e32 v32, v44, v32
	v_add_f32_e32 v33, v45, v33
	ds_bpermute_b32 v34, v118, v32
	ds_bpermute_b32 v35, v118, v33
	global_store_dwordx4 v[50:51], v[40:43], off offset:528
	v_cvt_pk_bf16_f32 v38, v40, v41
	v_cvt_pk_bf16_f32 v39, v42, v43
	s_waitcnt lgkmcnt(0)
	v_add_f32_e32 v32, v32, v34
	v_add_f32_e32 v33, v33, v35
	ds_bpermute_b32 v34, v119, v32
	ds_bpermute_b32 v35, v119, v33
	flat_store_dwordx4 v[72:73], v[36:39] offset:256
	s_mov_b32 s100, -1
	s_mov_b32 s101, 0
	s_mov_b32 s98, 0xffff0000
	s_mov_b32 s99, 0
	s_and_saveexec_b64 s[30:31], s[100:101]
	s_cbranch_execz .LBB0_1341
	v_lshl_add_u64 v[36:37], s[8:9], 0, v[48:49]
	s_waitcnt lgkmcnt(0)
	v_add_f32_e32 v32, v32, v34
	v_add_f32_e32 v33, v33, v35
	v_cndmask_b32_e64 v32, v32, v33, s[98:99]
	v_cndmask_b32_e64 v33, 0, 4, s[98:99]
	v_or_b32_e32 v36, v36, v33
	v_mov_b32_e32 v253, v32
; DEVI unsigned pk2(float lo, float hi) { unsigned r; asm("v_cvt_pk_bf16_f32 %0, %1, %2" : "=v"(r) : "v"(lo), "v"(hi)); return r; }
;     DEVI void operator()(const f32x4 (&acc)[2][2][4][2], const pg8::Unit& u, int wr, int wc, int fr, int fq) const {
;     ...
;                 const int row = row0 + ai * 128 + m * 16; float mu, rs; row_stats(stin, row, mu, rs);
;                 float sum = 0.f, sq = 0.f;
; #pragma unroll
;                 for (int bj = 0; bj < 2; ++bj) {
;                     f32x4 z[2];
; #pragma unroll
;                     for (int n = 0; n < 2; ++n) {
;                         const int col = colb + bj * 128 + 4 * n;
;                         f32x4 xv = *(const f32x4*)(zsrc + (size_t)row * DM + col);
;                         if (stin) { const f32x4 gv = *(const f32x4*)(gin + col), bv = *(const f32x4*)(bin + col); xv = (xv - mu) * rs * gv + bv; }
;                         f32x4 zz = ALPHA * xv + acc[ai][bj][m][n];
;                         if (bias) zz += *(const f32x4*)(bias + col);
;                         *(f32x4*)(zdst + (size_t)row * DM + col) = zz;
;                         sum += zz[0] + zz[1] + zz[2] + zz[3]; sq += zz[0] * zz[0] + zz[1] * zz[1] + zz[2] * zz[2] + zz[3] * zz[3];
;                         z[n] = zz;
;                     }
;                     u32x4 o; o.x = pk2(z[0][0], z[0][1]); o.y = pk2(z[0][2], z[0][3]); o.z = pk2(z[1][0], z[1][1]); o.w = pk2(z[1][2], z[1][3]);
;                     if (zb) *(u32x4*)(zb + (size_t)row * DM + colb + bj * 128) = o;
;                 }
;                 sum += __shfl_xor(sum, 16); sq += __shfl_xor(sq, 16);
;                 sum += __shfl_xor(sum, 32); sq += __shfl_xor(sq, 32);
;                 if (fq == 0) { atomicAdd(stout + 2 * (size_t)row, sum); atomicAdd(stout + 2 * (size_t)row + 1, sq); }
.LBB0_1341:
	s_or_b64 exec, exec, s[30:31]
	v_add_u32_e32 v56, 0xa0, v150
	v_ashrrev_i32_e32 v57, 31, v56
	v_lshlrev_b64 v[32:33], 3, v[56:57]
	s_waitcnt lgkmcnt(0)
	v_lshl_add_u64 v[34:35], s[6:7], 0, v[32:33]
	flat_load_dwordx2 v[58:59], v[34:35]
	v_lshlrev_b64 v[34:35], 12, v[56:57]
	v_lshl_add_u64 v[34:35], s[46:47], 0, v[34:35]
	v_lshl_add_u64 v[34:35], v[148:149], 2, v[34:35]
	global_load_dwordx4 v[36:39], v[34:35], off
	global_load_dwordx4 v[40:43], v[144:145], off
	global_load_dwordx4 v[44:47], v[146:147], off
	global_load_dwordx4 v[48:51], v[152:153], off
	global_load_dwordx4 v[52:55], v[34:35], off offset:16
	s_waitcnt vmcnt(0) lgkmcnt(0)
	v_pk_mul_f32 v[58:59], v[58:59], s[18:19] op_sel:[1,0] op_sel_hi:[0,0]
	v_fma_f32 v58, -v59, v59, v58
	v_max_f32_e32 v58, 0, v58
	v_add_f32_e32 v58, 0x3727c5ac, v58
	v_mul_f32_e32 v60, 0x4b800000, v58
	v_cmp_gt_f32_e32 vcc, s64, v58
	v_sub_f32_e32 v39, v39, v59
	v_sub_f32_e32 v38, v38, v59
	v_cndmask_b32_e32 v58, v58, v60, vcc
	v_rsq_f32_e32 v58, v58
	v_sub_f32_e32 v37, v37, v59
	v_sub_f32_e32 v36, v36, v59
	v_mul_f32_e32 v60, 0x45800000, v58
	v_cndmask_b32_e32 v58, v58, v60, vcc
	v_pk_mul_f32 v[36:37], v[36:37], v[58:59] op_sel_hi:[1,0]
	v_pk_mul_f32 v[38:39], v[38:39], v[58:59] op_sel_hi:[1,0]
	v_pk_fma_f32 v[36:37], v[40:41], v[36:37], v[44:45]
	v_pk_fma_f32 v[38:39], v[42:43], v[38:39], v[46:47]
	v_pk_fma_f32 v[28:29], v[36:37], s[20:21], v[28:29] op_sel_hi:[1,0,1]
	v_pk_fma_f32 v[30:31], v[38:39], s[20:21], v[30:31] op_sel_hi:[1,0,1]
	v_pk_add_f32 v[28:29], v[48:49], v[28:29]
	v_pk_add_f32 v[30:31], v[50:51], v[30:31]
	global_store_dwordx4 v[34:35], v[28:31], off
	global_load_dwordx4 v[36:39], v[144:145], off offset:16
	global_load_dwordx4 v[40:43], v[146:147], off offset:16
	global_load_dwordx4 v[44:47], v[154:155], off
	v_lshlrev_b64 v[48:49], 11, v[56:57]
	v_lshl_add_u64 v[48:49], s[10:11], 0, v[48:49]
	v_lshl_add_u64 v[56:57], v[148:149], 1, v[48:49]
	v_sub_f32_e32 v49, v55, v59
	v_sub_f32_e32 v48, v54, v59
	v_sub_f32_e32 v51, v53, v59
	v_sub_f32_e32 v50, v52, v59
	v_pk_mul_f32 v[50:51], v[50:51], v[58:59] op_sel_hi:[1,0]
	v_pk_mul_f32 v[52:53], v[48:49], v[58:59] op_sel_hi:[1,0]
	v_cvt_pk_bf16_f32 v48, v28, v29
	v_cvt_pk_bf16_f32 v49, v30, v31
	s_waitcnt vmcnt(1)
	v_pk_fma_f32 v[36:37], v[36:37], v[50:51], v[40:41]
	v_pk_fma_f32 v[38:39], v[38:39], v[52:53], v[42:43]
	v_pk_fma_f32 v[24:25], v[36:37], s[20:21], v[24:25] op_sel_hi:[1,0,1]
	v_pk_fma_f32 v[26:27], v[38:39], s[20:21], v[26:27] op_sel_hi:[1,0,1]
	s_waitcnt vmcnt(0)
	v_pk_add_f32 v[24:25], v[44:45], v[24:25]
	v_pk_add_f32 v[26:27], v[46:47], v[26:27]
	global_store_dwordx4 v[34:35], v[24:27], off offset:16
	v_cvt_pk_bf16_f32 v50, v24, v25
	v_cvt_pk_bf16_f32 v51, v26, v27
	flat_store_dwordx4 v[56:57], v[48:51]
	global_load_dwordx4 v[36:39], v[34:35], off offset:512
	global_load_dwordx4 v[40:43], v[144:145], off offset:512
	global_load_dwordx4 v[44:47], v[146:147], off offset:512
	s_nop 0
	global_load_dwordx4 v[48:51], v[120:121], off
	global_load_dwordx4 v[52:55], v[34:35], off offset:528
	s_waitcnt vmcnt(0)
	v_sub_f32_e32 v39, v39, v59
	v_sub_f32_e32 v38, v38, v59
	v_sub_f32_e32 v37, v37, v59
	v_sub_f32_e32 v36, v36, v59
	v_pk_mul_f32 v[36:37], v[58:59], v[36:37] op_sel_hi:[0,1]
	v_pk_mul_f32 v[38:39], v[58:59], v[38:39] op_sel_hi:[0,1]
	v_pk_fma_f32 v[38:39], v[42:43], v[38:39], v[46:47]
	v_pk_fma_f32 v[36:37], v[40:41], v[36:37], v[44:45]
	v_pk_fma_f32 v[22:23], v[38:39], s[20:21], v[22:23] op_sel_hi:[1,0,1]
	v_pk_fma_f32 v[20:21], v[36:37], s[20:21], v[20:21] op_sel_hi:[1,0,1]
	v_pk_add_f32 v[22:23], v[50:51], v[22:23]
	v_pk_add_f32 v[20:21], v[48:49], v[20:21]
	global_store_dwordx4 v[34:35], v[20:23], off offset:512
	global_load_dwordx4 v[36:39], v[144:145], off offset:528
	global_load_dwordx4 v[40:43], v[146:147], off offset:528
	global_load_dwordx4 v[44:47], v[116:117], off
	v_add_f32_e32 v48, v28, v29
	v_mul_f32_e32 v29, v29, v29
	v_fmac_f32_e32 v29, v28, v28
	v_add_f32_e32 v48, v30, v48
	v_fmac_f32_e32 v29, v30, v30
	v_add_f32_e32 v30, v24, v25
	v_mul_f32_e32 v25, v25, v25
	v_fmac_f32_e32 v25, v24, v24
	v_add_f32_e32 v28, v31, v48
	v_add_f32_e32 v30, v26, v30
	v_fmac_f32_e32 v25, v26, v26
	v_add_f32_e32 v28, 0, v28
	v_fmac_f32_e32 v29, v31, v31
	v_add_f32_e32 v24, v27, v30
	v_fmac_f32_e32 v25, v27, v27
	v_sub_f32_e32 v27, v53, v59
	v_sub_f32_e32 v26, v52, v59
	v_add_f32_e32 v28, v24, v28
	v_add_f32_e32 v29, v29, v25
	v_sub_f32_e32 v25, v55, v59
	v_sub_f32_e32 v24, v54, v59
	v_pk_mul_f32 v[26:27], v[58:59], v[26:27] op_sel_hi:[0,1]
	v_pk_mul_f32 v[24:25], v[58:59], v[24:25] op_sel_hi:[0,1]
	v_mul_f32_e32 v31, v21, v21
	v_add_f32_e32 v30, v20, v21
	v_fmac_f32_e32 v31, v20, v20
	v_add_f32_e32 v30, v22, v30
	v_fmac_f32_e32 v31, v22, v22
	v_add_f32_e32 v30, v23, v30
	v_fmac_f32_e32 v31, v23, v23
	v_add_f32_e32 v28, v28, v30
	v_add_f32_e32 v29, v29, v31
	v_cvt_pk_bf16_f32 v20, v20, v21
	v_cvt_pk_bf16_f32 v21, v22, v23
	s_waitcnt vmcnt(0)
	v_pk_fma_f32 v[26:27], v[36:37], v[26:27], v[40:41]
	v_pk_fma_f32 v[24:25], v[38:39], v[24:25], v[42:43]
	v_pk_fma_f32 v[16:17], v[26:27], s[20:21], v[16:17] op_sel_hi:[1,0,1]
	v_pk_fma_f32 v[18:19], v[24:25], s[20:21], v[18:19] op_sel_hi:[1,0,1]
	v_pk_add_f32 v[24:25], v[44:45], v[16:17]
	v_pk_add_f32 v[26:27], v[46:47], v[18:19]
	v_mul_f32_e32 v17, v25, v25
	v_add_f32_e32 v16, v24, v25
	v_fmac_f32_e32 v17, v24, v24
	v_add_f32_e32 v16, v26, v16
	v_fmac_f32_e32 v17, v26, v26
	v_add_f32_e32 v16, v27, v16
	v_fmac_f32_e32 v17, v27, v27
	v_add_f32_e32 v16, v28, v16
	v_add_f32_e32 v17, v29, v17
	ds_bpermute_b32 v18, v118, v16
	ds_bpermute_b32 v19, v118, v17
	global_store_dwordx4 v[34:35], v[24:27], off offset:528
	v_cvt_pk_bf16_f32 v22, v24, v25
	v_cvt_pk_bf16_f32 v23, v26, v27
	s_waitcnt lgkmcnt(0)
	v_add_f32_e32 v16, v16, v18
	v_add_f32_e32 v17, v17, v19
	ds_bpermute_b32 v18, v119, v16
	ds_bpermute_b32 v19, v119, v17
	flat_store_dwordx4 v[56:57], v[20:23] offset:256
	s_mov_b32 s100, -1
	s_mov_b32 s101, 0
	s_mov_b32 s98, 0xffff0000
	s_mov_b32 s99, 0
	s_and_saveexec_b64 s[30:31], s[100:101]
	s_cbranch_execz .LBB0_1343
	v_lshl_add_u64 v[20:21], s[8:9], 0, v[32:33]
	s_waitcnt lgkmcnt(0)
	v_add_f32_e32 v16, v16, v18
	v_add_f32_e32 v17, v17, v19
	v_cndmask_b32_e64 v16, v16, v17, s[98:99]
	v_cndmask_b32_e64 v17, 0, 4, s[98:99]
	v_or_b32_e32 v20, v20, v17
	v_mov_b32_e32 v254, v16
; DEVI unsigned pk2(float lo, float hi) { unsigned r; asm("v_cvt_pk_bf16_f32 %0, %1, %2" : "=v"(r) : "v"(lo), "v"(hi)); return r; }
;     DEVI void operator()(const f32x4 (&acc)[2][2][4][2], const pg8::Unit& u, int wr, int wc, int fr, int fq) const {
;     ...
;                 const int row = row0 + ai * 128 + m * 16; float mu, rs; row_stats(stin, row, mu, rs);
;                 float sum = 0.f, sq = 0.f;
; #pragma unroll
;                 for (int bj = 0; bj < 2; ++bj) {
;                     f32x4 z[2];
; #pragma unroll
;                     for (int n = 0; n < 2; ++n) {
;                         const int col = colb + bj * 128 + 4 * n;
;                         f32x4 xv = *(const f32x4*)(zsrc + (size_t)row * DM + col);
;                         if (stin) { const f32x4 gv = *(const f32x4*)(gin + col), bv = *(const f32x4*)(bin + col); xv = (xv - mu) * rs * gv + bv; }
;                         f32x4 zz = ALPHA * xv + acc[ai][bj][m][n];
;                         if (bias) zz += *(const f32x4*)(bias + col);
;                         *(f32x4*)(zdst + (size_t)row * DM + col) = zz;
;                         sum += zz[0] + zz[1] + zz[2] + zz[3]; sq += zz[0] * zz[0] + zz[1] * zz[1] + zz[2] * zz[2] + zz[3] * zz[3];
;                         z[n] = zz;
;                     }
;                     u32x4 o; o.x = pk2(z[0][0], z[0][1]); o.y = pk2(z[0][2], z[0][3]); o.z = pk2(z[1][0], z[1][1]); o.w = pk2(z[1][2], z[1][3]);
;                     if (zb) *(u32x4*)(zb + (size_t)row * DM + colb + bj * 128) = o;
;                 }
;                 sum += __shfl_xor(sum, 16); sq += __shfl_xor(sq, 16);
;                 sum += __shfl_xor(sum, 32); sq += __shfl_xor(sq, 32);
;                 if (fq == 0) { atomicAdd(stout + 2 * (size_t)row, sum); atomicAdd(stout + 2 * (size_t)row + 1, sq); }
.LBB0_1343:
	s_or_b64 exec, exec, s[30:31]
	v_add_u32_e32 v40, 0xb0, v150
	v_ashrrev_i32_e32 v41, 31, v40
	v_lshlrev_b64 v[16:17], 3, v[40:41]
	s_waitcnt lgkmcnt(0)
	v_lshl_add_u64 v[18:19], s[6:7], 0, v[16:17]
	flat_load_dwordx2 v[42:43], v[18:19]
	v_lshlrev_b64 v[18:19], 12, v[40:41]
	v_lshl_add_u64 v[18:19], s[46:47], 0, v[18:19]
	v_lshl_add_u64 v[18:19], v[148:149], 2, v[18:19]
	global_load_dwordx4 v[20:23], v[18:19], off
	global_load_dwordx4 v[24:27], v[144:145], off
	global_load_dwordx4 v[28:31], v[146:147], off
	global_load_dwordx4 v[32:35], v[152:153], off
	global_load_dwordx4 v[36:39], v[18:19], off offset:16
	s_waitcnt vmcnt(0) lgkmcnt(0)
	v_pk_mul_f32 v[42:43], v[42:43], s[18:19] op_sel:[1,0] op_sel_hi:[0,0]
	v_fma_f32 v42, -v43, v43, v42
	v_max_f32_e32 v42, 0, v42
	v_add_f32_e32 v42, 0x3727c5ac, v42
	v_mul_f32_e32 v44, 0x4b800000, v42
	v_cmp_gt_f32_e32 vcc, s64, v42
	v_sub_f32_e32 v23, v23, v43
	v_sub_f32_e32 v22, v22, v43
	v_cndmask_b32_e32 v42, v42, v44, vcc
	v_rsq_f32_e32 v42, v42
	v_sub_f32_e32 v21, v21, v43
	v_sub_f32_e32 v20, v20, v43
	v_mul_f32_e32 v44, 0x45800000, v42
	v_cndmask_b32_e32 v42, v42, v44, vcc
	v_pk_mul_f32 v[20:21], v[20:21], v[42:43] op_sel_hi:[1,0]
	v_pk_mul_f32 v[22:23], v[22:23], v[42:43] op_sel_hi:[1,0]
	v_pk_fma_f32 v[20:21], v[24:25], v[20:21], v[28:29]
	v_pk_fma_f32 v[22:23], v[26:27], v[22:23], v[30:31]
	v_pk_fma_f32 v[12:13], v[20:21], s[20:21], v[12:13] op_sel_hi:[1,0,1]
	v_pk_fma_f32 v[14:15], v[22:23], s[20:21], v[14:15] op_sel_hi:[1,0,1]
	v_pk_add_f32 v[12:13], v[32:33], v[12:13]
	v_pk_add_f32 v[14:15], v[34:35], v[14:15]
	global_store_dwordx4 v[18:19], v[12:15], off
	global_load_dwordx4 v[20:23], v[144:145], off offset:16
	global_load_dwordx4 v[24:27], v[146:147], off offset:16
	global_load_dwordx4 v[28:31], v[154:155], off
	v_lshlrev_b64 v[32:33], 11, v[40:41]
	v_lshl_add_u64 v[32:33], s[10:11], 0, v[32:33]
	v_lshl_add_u64 v[40:41], v[148:149], 1, v[32:33]
	v_sub_f32_e32 v33, v39, v43
	v_sub_f32_e32 v32, v38, v43
	v_sub_f32_e32 v35, v37, v43
	v_sub_f32_e32 v34, v36, v43
	v_pk_mul_f32 v[34:35], v[34:35], v[42:43] op_sel_hi:[1,0]
	v_pk_mul_f32 v[36:37], v[32:33], v[42:43] op_sel_hi:[1,0]
	v_cvt_pk_bf16_f32 v32, v12, v13
	v_cvt_pk_bf16_f32 v33, v14, v15
	s_waitcnt vmcnt(1)
	v_pk_fma_f32 v[20:21], v[20:21], v[34:35], v[24:25]
	v_pk_fma_f32 v[22:23], v[22:23], v[36:37], v[26:27]
	v_pk_fma_f32 v[8:9], v[20:21], s[20:21], v[8:9] op_sel_hi:[1,0,1]
	v_pk_fma_f32 v[10:11], v[22:23], s[20:21], v[10:11] op_sel_hi:[1,0,1]
	s_waitcnt vmcnt(0)
	v_pk_add_f32 v[8:9], v[28:29], v[8:9]
	v_pk_add_f32 v[10:11], v[30:31], v[10:11]
	global_store_dwordx4 v[18:19], v[8:11], off offset:16
	v_cvt_pk_bf16_f32 v34, v8, v9
	v_cvt_pk_bf16_f32 v35, v10, v11
	flat_store_dwordx4 v[40:41], v[32:35]
	global_load_dwordx4 v[20:23], v[18:19], off offset:512
	global_load_dwordx4 v[24:27], v[144:145], off offset:512
	global_load_dwordx4 v[28:31], v[146:147], off offset:512
	s_nop 0
	global_load_dwordx4 v[32:35], v[120:121], off
	global_load_dwordx4 v[36:39], v[18:19], off offset:528
	s_waitcnt vmcnt(0)
	v_sub_f32_e32 v23, v23, v43
	v_sub_f32_e32 v22, v22, v43
	v_sub_f32_e32 v21, v21, v43
	v_sub_f32_e32 v20, v20, v43
	v_pk_mul_f32 v[20:21], v[42:43], v[20:21] op_sel_hi:[0,1]
	v_pk_mul_f32 v[22:23], v[42:43], v[22:23] op_sel_hi:[0,1]
	v_pk_fma_f32 v[22:23], v[26:27], v[22:23], v[30:31]
	v_pk_fma_f32 v[20:21], v[24:25], v[20:21], v[28:29]
	v_pk_fma_f32 v[6:7], v[22:23], s[20:21], v[6:7] op_sel_hi:[1,0,1]
	v_pk_fma_f32 v[4:5], v[20:21], s[20:21], v[4:5] op_sel_hi:[1,0,1]
	v_pk_add_f32 v[6:7], v[34:35], v[6:7]
	v_pk_add_f32 v[4:5], v[32:33], v[4:5]
	global_store_dwordx4 v[18:19], v[4:7], off offset:512
	global_load_dwordx4 v[20:23], v[144:145], off offset:528
	global_load_dwordx4 v[24:27], v[146:147], off offset:528
	global_load_dwordx4 v[28:31], v[116:117], off
	v_add_f32_e32 v32, v12, v13
	v_mul_f32_e32 v13, v13, v13
	v_fmac_f32_e32 v13, v12, v12
	v_add_f32_e32 v32, v14, v32
	v_fmac_f32_e32 v13, v14, v14
	v_add_f32_e32 v14, v8, v9
	v_mul_f32_e32 v9, v9, v9
	v_fmac_f32_e32 v9, v8, v8
	v_add_f32_e32 v12, v15, v32
	v_add_f32_e32 v14, v10, v14
	v_fmac_f32_e32 v9, v10, v10
	v_add_f32_e32 v12, 0, v12
	v_fmac_f32_e32 v13, v15, v15
	v_add_f32_e32 v8, v11, v14
	v_fmac_f32_e32 v9, v11, v11
	v_sub_f32_e32 v11, v37, v43
	v_sub_f32_e32 v10, v36, v43
	v_add_f32_e32 v12, v8, v12
	v_add_f32_e32 v13, v13, v9
	v_sub_f32_e32 v9, v39, v43
	v_sub_f32_e32 v8, v38, v43
	v_pk_mul_f32 v[10:11], v[42:43], v[10:11] op_sel_hi:[0,1]
	v_pk_mul_f32 v[8:9], v[42:43], v[8:9] op_sel_hi:[0,1]
	v_mul_f32_e32 v15, v5, v5
	v_add_f32_e32 v14, v4, v5
	v_fmac_f32_e32 v15, v4, v4
	v_add_f32_e32 v14, v6, v14
	v_fmac_f32_e32 v15, v6, v6
	v_add_f32_e32 v14, v7, v14
	v_fmac_f32_e32 v15, v7, v7
	v_add_f32_e32 v12, v12, v14
	v_add_f32_e32 v13, v13, v15
	v_cvt_pk_bf16_f32 v4, v4, v5
	v_cvt_pk_bf16_f32 v5, v6, v7
	s_waitcnt vmcnt(0)
	v_pk_fma_f32 v[10:11], v[20:21], v[10:11], v[24:25]
	v_pk_fma_f32 v[8:9], v[22:23], v[8:9], v[26:27]
	v_pk_fma_f32 v[0:1], v[10:11], s[20:21], v[0:1] op_sel_hi:[1,0,1]
	v_pk_fma_f32 v[2:3], v[8:9], s[20:21], v[2:3] op_sel_hi:[1,0,1]
	v_pk_add_f32 v[8:9], v[28:29], v[0:1]
	v_pk_add_f32 v[10:11], v[30:31], v[2:3]
	v_mul_f32_e32 v1, v9, v9
	v_add_f32_e32 v0, v8, v9
	v_fmac_f32_e32 v1, v8, v8
	v_add_f32_e32 v0, v10, v0
	v_fmac_f32_e32 v1, v10, v10
	v_add_f32_e32 v0, v11, v0
	v_fmac_f32_e32 v1, v11, v11
	v_add_f32_e32 v0, v12, v0
	v_add_f32_e32 v1, v13, v1
	ds_bpermute_b32 v2, v118, v0
	ds_bpermute_b32 v3, v118, v1
	global_store_dwordx4 v[18:19], v[8:11], off offset:528
	v_cvt_pk_bf16_f32 v6, v8, v9
	v_cvt_pk_bf16_f32 v7, v10, v11
	s_waitcnt lgkmcnt(0)
	v_add_f32_e32 v0, v0, v2
	v_add_f32_e32 v1, v1, v3
	ds_bpermute_b32 v2, v119, v0
	ds_bpermute_b32 v3, v119, v1
	flat_store_dwordx4 v[40:41], v[4:7] offset:256
	s_mov_b32 s100, -1
	s_mov_b32 s101, 0
	s_mov_b32 s98, 0xffff0000
	s_mov_b32 s99, 0
	s_and_saveexec_b64 s[30:31], s[100:101]
	s_cbranch_execz .LBB0_1345
	v_lshl_add_u64 v[4:5], s[8:9], 0, v[16:17]
	s_waitcnt lgkmcnt(0)
	v_add_f32_e32 v0, v0, v2
	v_add_f32_e32 v1, v1, v3
	v_cndmask_b32_e64 v0, v0, v1, s[98:99]
	v_cndmask_b32_e64 v1, 0, 4, s[98:99]
	v_or_b32_e32 v4, v4, v1
	v_mov_b32_e32 v255, v0
	flat_atomic_add_f32 v[250:251], v252
	flat_atomic_add_f32 v[250:251], v253 offset:128
	flat_atomic_add_f32 v[250:251], v254 offset:256
	flat_atomic_add_f32 v[250:251], v255 offset:384

; DEVI void row_stats(const float* stats, int row, float& mu, float& rs) {
;     if (stats) { const float2 st = *(const float2*)(stats + 2 * (size_t)row); mu = st.x * (1.0f / 1024.0f); const float var = st.y * (1.0f / 1024.0f) - mu * mu; rs = rsqrtf(fmaxf(var, 0.f) + LN_EPS); }
;     DEVI void operator()(const f32x4 (&acc)[2][2][4][2], const pg8::Unit& u, int wr, int wc, int fr, int fq) const {
;     ...
;                 const int row = row0 + ai * 128 + m * 16; float mu, rs; row_stats(stin, row, mu, rs);
;                 float sum = 0.f, sq = 0.f;
; #pragma unroll
;                 for (int bj = 0; bj < 2; ++bj) {
;                     f32x4 z[2];
; #pragma unroll
;                     for (int n = 0; n < 2; ++n) {
;                         const int col = colb + bj * 128 + 4 * n;
;                         f32x4 xv = *(const f32x4*)(zsrc + (size_t)row * DM + col);
;                         if (stin) { const f32x4 gv = *(const f32x4*)(gin + col), bv = *(const f32x4*)(bin + col); xv = (xv - mu) * rs * gv + bv; }
;                         f32x4 zz = ALPHA * xv + acc[ai][bj][m][n];
;                         if (bias) zz += *(const f32x4*)(bias + col);
;                         *(f32x4*)(zdst + (size_t)row * DM + col) = zz;
.LBB0_1538:
	v_lshl_add_u32 v154, s64, 8, v162
	v_ashrrev_i32_e32 v155, 31, v154
	v_lshlrev_b64 v[156:157], 3, v[154:155]
	v_lshl_add_u64 v[146:147], s[12:13], 0, v[156:157]
	s_waitcnt vmcnt(0)
	flat_load_dwordx2 v[160:161], v[146:147]
	v_lshl_or_b32 v144, s65, 8, v164
	v_ashrrev_i32_e32 v145, 31, v144
	v_lshlrev_b64 v[146:147], 12, v[154:155]
	v_lshl_add_u64 v[146:147], s[46:47], 0, v[146:147]
	v_lshlrev_b64 v[148:149], 2, v[144:145]
	v_lshl_add_u64 v[158:159], v[146:147], 0, v[148:149]
	global_load_dwordx4 v[170:173], v[158:159], off
	v_lshl_add_u64 v[150:151], s[16:17], 0, v[148:149]
	v_lshl_add_u64 v[152:153], s[18:19], 0, v[148:149]
	global_load_dwordx4 v[174:177], v[150:151], off
	global_load_dwordx4 v[178:181], v[152:153], off
	global_load_dwordx4 v[182:185], v[158:159], off offset:16
	v_or_b32_e32 v146, 4, v144
	v_ashrrev_i32_e32 v147, 31, v146
	v_lshlrev_b64 v[148:149], 2, v[146:147]
	v_lshl_add_u64 v[146:147], s[16:17], 0, v[148:149]
	v_lshl_add_u64 v[148:149], s[18:19], 0, v[148:149]
	v_or_b32_e32 v186, 0x80, v144
	v_ashrrev_i32_e32 v187, 31, v186
	s_waitcnt vmcnt(0) lgkmcnt(0)
	v_pk_mul_f32 v[160:161], v[160:161], s[24:25] op_sel:[1,0] op_sel_hi:[0,0]
	v_fma_f32 v160, -v161, v161, v160
	v_max_f32_e32 v160, 0, v160
	v_add_f32_e32 v160, 0x3727c5ac, v160
	v_mul_f32_e32 v169, 0x4b800000, v160
	v_cmp_gt_f32_e32 vcc, s61, v160
	v_sub_f32_e32 v171, v171, v161
	s_nop 0
	v_cndmask_b32_e32 v160, v160, v169, vcc
	v_rsq_f32_e32 v160, v160
	v_sub_f32_e32 v170, v170, v161
	v_sub_f32_e32 v173, v173, v161
	v_sub_f32_e32 v172, v172, v161
	v_mul_f32_e32 v169, 0x45800000, v160
	v_cndmask_b32_e32 v160, v160, v169, vcc
	v_pk_mul_f32 v[172:173], v[172:173], v[160:161] op_sel_hi:[1,0]
	v_pk_mul_f32 v[170:171], v[170:171], v[160:161] op_sel_hi:[1,0]
	v_pk_fma_f32 v[172:173], v[176:177], v[172:173], v[180:181]
	v_pk_fma_f32 v[170:171], v[174:175], v[170:171], v[178:179]
	v_pk_fma_f32 v[172:173], v[172:173], s[26:27], v[126:127] op_sel_hi:[1,0,1]
	v_pk_fma_f32 v[170:171], v[170:171], s[26:27], v[124:125] op_sel_hi:[1,0,1]
	global_store_dwordx4 v[158:159], v[170:173], off
	global_load_dwordx4 v[124:127], v[146:147], off
	global_load_dwordx4 v[174:177], v[148:149], off
	v_lshlrev_b64 v[178:179], 11, v[154:155]
	v_lshl_add_u64 v[178:179], s[14:15], 0, v[178:179]
	v_lshl_add_u64 v[194:195], v[144:145], 1, v[178:179]
	v_sub_f32_e32 v179, v183, v161
	v_sub_f32_e32 v178, v182, v161
	v_sub_f32_e32 v181, v185, v161
	v_sub_f32_e32 v180, v184, v161
	v_pk_mul_f32 v[180:181], v[180:181], v[160:161] op_sel_hi:[1,0]
	v_pk_mul_f32 v[182:183], v[178:179], v[160:161] op_sel_hi:[1,0]
	v_cvt_pk_bf16_f32 v178, v170, v171
	v_cvt_pk_bf16_f32 v179, v172, v173
	s_waitcnt vmcnt(0)
	v_pk_fma_f32 v[126:127], v[126:127], v[180:181], v[176:177]
	v_pk_fma_f32 v[124:125], v[124:125], v[182:183], v[174:175]
	v_pk_fma_f32 v[176:177], v[126:127], s[26:27], v[122:123] op_sel_hi:[1,0,1]
	v_pk_fma_f32 v[174:175], v[124:125], s[26:27], v[120:121] op_sel_hi:[1,0,1]
	global_store_dwordx4 v[158:159], v[174:177], off offset:16
	v_cvt_pk_bf16_f32 v180, v174, v175
	v_cvt_pk_bf16_f32 v181, v176, v177
	flat_store_dwordx4 v[194:195], v[178:181]
	global_load_dwordx4 v[178:181], v[158:159], off offset:512
	v_lshlrev_b64 v[122:123], 2, v[186:187]
	v_lshl_add_u64 v[120:121], s[16:17], 0, v[122:123]
	v_lshl_add_u64 v[122:123], s[18:19], 0, v[122:123]
	global_load_dwordx4 v[182:185], v[120:121], off
	global_load_dwordx4 v[186:189], v[122:123], off
	global_load_dwordx4 v[190:193], v[158:159], off offset:528
	v_or_b32_e32 v124, 0x84, v144
	v_ashrrev_i32_e32 v125, 31, v124
	v_lshlrev_b64 v[126:127], 2, v[124:125]
	v_lshl_add_u64 v[124:125], s[16:17], 0, v[126:127]
	v_lshl_add_u64 v[126:127], s[18:19], 0, v[126:127]
	v_mul_f32_e32 v169, v175, v175
	v_add_f32_e32 v155, v174, v175
	v_fmac_f32_e32 v169, v174, v174
	v_add_f32_e32 v155, v176, v155
	v_fmac_f32_e32 v169, v176, v176
	v_add_f32_e32 v155, v177, v155
	v_fmac_f32_e32 v169, v177, v177
	s_waitcnt vmcnt(0)
	v_sub_f32_e32 v179, v179, v161
	v_sub_f32_e32 v178, v178, v161
	v_sub_f32_e32 v181, v181, v161
	v_sub_f32_e32 v180, v180, v161
	v_pk_mul_f32 v[180:181], v[160:161], v[180:181] op_sel_hi:[0,1]
	v_pk_mul_f32 v[178:179], v[160:161], v[178:179] op_sel_hi:[0,1]
	v_pk_fma_f32 v[178:179], v[182:183], v[178:179], v[186:187]
	v_pk_fma_f32 v[180:181], v[184:185], v[180:181], v[188:189]
	v_pk_fma_f32 v[178:179], v[178:179], s[26:27], v[116:117] op_sel_hi:[1,0,1]
	v_pk_fma_f32 v[180:181], v[180:181], s[26:27], v[118:119] op_sel_hi:[1,0,1]
	global_store_dwordx4 v[158:159], v[178:181], off offset:512
	global_load_dwordx4 v[182:185], v[124:125], off
	global_load_dwordx4 v[186:189], v[126:127], off
	v_and_b32_e32 v117, 64, v168
	v_xor_b32_e32 v116, 16, v168
	v_add_u32_e32 v117, 64, v117
	v_xor_b32_e32 v118, 32, v168
	v_cmp_lt_i32_e32 vcc, v116, v117
	v_mul_f32_e32 v119, v171, v171
	v_fmac_f32_e32 v119, v170, v170
	v_cndmask_b32_e32 v116, v168, v116, vcc
	v_cmp_lt_i32_e32 vcc, v118, v117
	v_fmac_f32_e32 v119, v172, v172
	v_fmac_f32_e32 v119, v173, v173
	v_cndmask_b32_e32 v117, v168, v118, vcc
	v_add_f32_e32 v118, v170, v171
	v_add_f32_e32 v118, v172, v118
	v_add_f32_e32 v118, v173, v118
	v_add_f32_e32 v118, 0, v118
	v_add_f32_e32 v155, v155, v118
	v_add_f32_e32 v169, v119, v169
	v_sub_f32_e32 v119, v191, v161
	v_sub_f32_e32 v118, v190, v161
	v_sub_f32_e32 v171, v193, v161
	v_sub_f32_e32 v170, v192, v161
	v_pk_mul_f32 v[170:171], v[160:161], v[170:171] op_sel_hi:[0,1]
	v_pk_mul_f32 v[118:119], v[160:161], v[118:119] op_sel_hi:[0,1]
	v_mul_f32_e32 v161, v179, v179
	v_add_f32_e32 v160, v178, v179
	v_fmac_f32_e32 v161, v178, v178
	v_add_f32_e32 v160, v180, v160
	v_fmac_f32_e32 v161, v180, v180
	v_add_f32_e32 v160, v181, v160
	v_fmac_f32_e32 v161, v181, v181
	v_add_f32_e32 v155, v155, v160
	v_add_f32_e32 v169, v169, v161
	v_lshlrev_b32_e32 v116, 2, v116
	v_lshlrev_b32_e32 v117, 2, v117
	v_cvt_pk_bf16_f32 v174, v178, v179
	v_cvt_pk_bf16_f32 v175, v180, v181
	s_waitcnt vmcnt(0)
; DEVI unsigned pk2(float lo, float hi) { unsigned r; asm("v_cvt_pk_bf16_f32 %0, %1, %2" : "=v"(r) : "v"(lo), "v"(hi)); return r; }
;     DEVI void operator()(const f32x4 (&acc)[2][2][4][2], const pg8::Unit& u, int wr, int wc, int fr, int fq) const {
;     ...
;                 const int row = row0 + ai * 128 + m * 16; float mu, rs; row_stats(stin, row, mu, rs);
;                 float sum = 0.f, sq = 0.f;
; #pragma unroll
;                 for (int bj = 0; bj < 2; ++bj) {
;                     f32x4 z[2];
; #pragma unroll
;                     for (int n = 0; n < 2; ++n) {
;                         const int col = colb + bj * 128 + 4 * n;
;                         f32x4 xv = *(const f32x4*)(zsrc + (size_t)row * DM + col);
;                         if (stin) { const f32x4 gv = *(const f32x4*)(gin + col), bv = *(const f32x4*)(bin + col); xv = (xv - mu) * rs * gv + bv; }
;                         f32x4 zz = ALPHA * xv + acc[ai][bj][m][n];
;                         if (bias) zz += *(const f32x4*)(bias + col);
;                         *(f32x4*)(zdst + (size_t)row * DM + col) = zz;
;                         sum += zz[0] + zz[1] + zz[2] + zz[3]; sq += zz[0] * zz[0] + zz[1] * zz[1] + zz[2] * zz[2] + zz[3] * zz[3];
;                         z[n] = zz;
;                     }
;                     u32x4 o; o.x = pk2(z[0][0], z[0][1]); o.y = pk2(z[0][2], z[0][3]); o.z = pk2(z[1][0], z[1][1]); o.w = pk2(z[1][2], z[1][3]);
;                     if (zb) *(u32x4*)(zb + (size_t)row * DM + colb + bj * 128) = o;
;                 }
;                 sum += __shfl_xor(sum, 16); sq += __shfl_xor(sq, 16);
;                 sum += __shfl_xor(sum, 32); sq += __shfl_xor(sq, 32);
;                 if (fq == 0) { atomicAdd(stout + 2 * (size_t)row, sum); atomicAdd(stout + 2 * (size_t)row + 1, sq); }
	v_pk_fma_f32 v[118:119], v[182:183], v[118:119], v[186:187]
	v_pk_fma_f32 v[160:161], v[184:185], v[170:171], v[188:189]
	v_pk_fma_f32 v[170:171], v[118:119], s[26:27], v[112:113] op_sel_hi:[1,0,1]
	v_pk_fma_f32 v[172:173], v[160:161], s[26:27], v[114:115] op_sel_hi:[1,0,1]
	v_mul_f32_e32 v113, v171, v171
	v_add_f32_e32 v112, v170, v171
	v_fmac_f32_e32 v113, v170, v170
	v_add_f32_e32 v112, v172, v112
	v_fmac_f32_e32 v113, v172, v172
	v_add_f32_e32 v112, v173, v112
	v_fmac_f32_e32 v113, v173, v173
	v_add_f32_e32 v112, v155, v112
	v_add_f32_e32 v113, v169, v113
	ds_bpermute_b32 v114, v116, v112
	ds_bpermute_b32 v115, v116, v113
	global_store_dwordx4 v[158:159], v[170:173], off offset:528
	v_cvt_pk_bf16_f32 v176, v170, v171
	v_cvt_pk_bf16_f32 v177, v172, v173
	s_waitcnt lgkmcnt(0)
	v_add_f32_e32 v112, v112, v114
	v_add_f32_e32 v113, v113, v115
	ds_bpermute_b32 v114, v117, v112
	ds_bpermute_b32 v115, v117, v113
	flat_store_dwordx4 v[194:195], v[174:177] offset:256
	s_mov_b32 s100, -1
	s_mov_b32 s101, 0
	s_mov_b32 s98, 0xffff0000
	s_mov_b32 s99, 0
	s_and_saveexec_b64 s[30:31], s[100:101]
	s_cbranch_execz .LBB0_1540
	v_lshl_add_u64 v[118:119], s[10:11], 0, v[156:157]
	s_waitcnt lgkmcnt(0)
	v_add_f32_e32 v112, v112, v114
	v_add_f32_e32 v113, v113, v115
	v_cndmask_b32_e64 v112, v112, v113, s[98:99]
	v_cndmask_b32_e64 v113, 0, 4, s[98:99]
	v_or_b32_e32 v118, v118, v113
	v_mov_b32_e32 v250, v118
	v_mov_b32_e32 v251, v119
	v_mov_b32_e32 v252, v112
.LBB0_1540:
	s_or_b64 exec, exec, s[30:31]
	v_or_b32_e32 v118, 16, v154
	v_ashrrev_i32_e32 v119, 31, v118
	v_lshlrev_b64 v[112:113], 3, v[118:119]
	s_waitcnt lgkmcnt(0)
	v_lshl_add_u64 v[114:115], s[12:13], 0, v[112:113]
	flat_load_dwordx2 v[160:161], v[114:115]
	v_lshlrev_b64 v[114:115], 12, v[118:119]
	v_lshl_add_u64 v[114:115], s[46:47], 0, v[114:115]
	v_lshl_add_u64 v[114:115], v[144:145], 2, v[114:115]
	global_load_dwordx4 v[156:159], v[114:115], off
	global_load_dwordx4 v[170:173], v[150:151], off
	global_load_dwordx4 v[174:177], v[152:153], off
	global_load_dwordx4 v[178:181], v[114:115], off offset:16
	v_lshlrev_b64 v[118:119], 11, v[118:119]
	v_lshl_add_u64 v[118:119], s[14:15], 0, v[118:119]
	v_lshl_add_u64 v[118:119], v[144:145], 1, v[118:119]
	s_waitcnt vmcnt(0) lgkmcnt(0)
	v_pk_mul_f32 v[160:161], v[160:161], s[24:25] op_sel:[1,0] op_sel_hi:[0,0]
	v_fma_f32 v155, -v161, v161, v160
	v_max_f32_e32 v155, 0, v155
	v_add_f32_e32 v155, 0x3727c5ac, v155
	v_mul_f32_e32 v160, 0x4b800000, v155
	v_cmp_gt_f32_e32 vcc, s61, v155
	v_sub_f32_e32 v157, v157, v161
	v_sub_f32_e32 v156, v156, v161
	v_cndmask_b32_e32 v155, v155, v160, vcc
	v_rsq_f32_e32 v155, v155
	v_sub_f32_e32 v159, v159, v161
	v_sub_f32_e32 v158, v158, v161
	v_mul_f32_e32 v160, 0x45800000, v155
	v_cndmask_b32_e32 v160, v155, v160, vcc
	v_pk_mul_f32 v[158:159], v[158:159], v[160:161] op_sel_hi:[1,0]
	v_pk_mul_f32 v[156:157], v[156:157], v[160:161] op_sel_hi:[1,0]
	v_pk_fma_f32 v[158:159], v[172:173], v[158:159], v[176:177]
	v_pk_fma_f32 v[156:157], v[170:171], v[156:157], v[174:175]
	v_pk_fma_f32 v[110:111], v[158:159], s[26:27], v[110:111] op_sel_hi:[1,0,1]
	v_pk_fma_f32 v[108:109], v[156:157], s[26:27], v[108:109] op_sel_hi:[1,0,1]
	global_store_dwordx4 v[114:115], v[108:111], off
	global_load_dwordx4 v[156:159], v[146:147], off
	global_load_dwordx4 v[170:173], v[148:149], off
	v_sub_f32_e32 v175, v179, v161
	v_sub_f32_e32 v174, v178, v161
	v_sub_f32_e32 v177, v181, v161
	v_sub_f32_e32 v176, v180, v161
	v_pk_mul_f32 v[176:177], v[176:177], v[160:161] op_sel_hi:[1,0]
	v_pk_mul_f32 v[178:179], v[174:175], v[160:161] op_sel_hi:[1,0]
	v_cvt_pk_bf16_f32 v174, v108, v109
	v_cvt_pk_bf16_f32 v175, v110, v111
	v_add_f32_e32 v155, v108, v109
	v_mul_f32_e32 v109, v109, v109
	v_fmac_f32_e32 v109, v108, v108
	v_add_f32_e32 v155, v110, v155
	v_fmac_f32_e32 v109, v110, v110
	v_add_f32_e32 v108, v111, v155
	v_add_f32_e32 v108, 0, v108
	v_fmac_f32_e32 v109, v111, v111
	s_waitcnt vmcnt(0)
	v_pk_fma_f32 v[156:157], v[156:157], v[178:179], v[170:171]
	v_pk_fma_f32 v[158:159], v[158:159], v[176:177], v[172:173]
	v_pk_fma_f32 v[104:105], v[156:157], s[26:27], v[104:105] op_sel_hi:[1,0,1]
	v_pk_fma_f32 v[106:107], v[158:159], s[26:27], v[106:107] op_sel_hi:[1,0,1]
	global_store_dwordx4 v[114:115], v[104:107], off offset:16
	v_cvt_pk_bf16_f32 v176, v104, v105
	v_cvt_pk_bf16_f32 v177, v106, v107
	flat_store_dwordx4 v[118:119], v[174:177]
	global_load_dwordx4 v[156:159], v[114:115], off offset:512
	global_load_dwordx4 v[170:173], v[120:121], off
	s_nop 0
	global_load_dwordx4 v[174:177], v[122:123], off
	global_load_dwordx4 v[178:181], v[114:115], off offset:528
	v_add_f32_e32 v110, v104, v105
	v_mul_f32_e32 v105, v105, v105
	v_fmac_f32_e32 v105, v104, v104
	v_add_f32_e32 v110, v106, v110
	v_fmac_f32_e32 v105, v106, v106
	v_add_f32_e32 v104, v107, v110
	v_fmac_f32_e32 v105, v107, v107
	v_add_f32_e32 v108, v104, v108
	v_add_f32_e32 v109, v109, v105
	s_waitcnt vmcnt(0)
	v_sub_f32_e32 v157, v157, v161
	v_sub_f32_e32 v156, v156, v161
	v_sub_f32_e32 v159, v159, v161
	v_sub_f32_e32 v158, v158, v161
	v_pk_mul_f32 v[158:159], v[160:161], v[158:159] op_sel_hi:[0,1]
	v_pk_mul_f32 v[156:157], v[160:161], v[156:157] op_sel_hi:[0,1]
	v_pk_fma_f32 v[156:157], v[170:171], v[156:157], v[174:175]
	v_pk_fma_f32 v[158:159], v[172:173], v[158:159], v[176:177]
	v_pk_fma_f32 v[100:101], v[156:157], s[26:27], v[100:101] op_sel_hi:[1,0,1]
	v_pk_fma_f32 v[102:103], v[158:159], s[26:27], v[102:103] op_sel_hi:[1,0,1]
	global_store_dwordx4 v[114:115], v[100:103], off offset:512
	global_load_dwordx4 v[156:159], v[124:125], off
	global_load_dwordx4 v[170:173], v[126:127], off
	v_sub_f32_e32 v105, v179, v161
	v_sub_f32_e32 v104, v178, v161
	v_pk_mul_f32 v[104:105], v[160:161], v[104:105] op_sel_hi:[0,1]
	v_sub_f32_e32 v107, v181, v161
	v_sub_f32_e32 v106, v180, v161
	v_pk_mul_f32 v[106:107], v[160:161], v[106:107] op_sel_hi:[0,1]
	v_mul_f32_e32 v111, v101, v101
	v_add_f32_e32 v110, v100, v101
	v_fmac_f32_e32 v111, v100, v100
	v_add_f32_e32 v110, v102, v110
	v_fmac_f32_e32 v111, v102, v102
	v_add_f32_e32 v110, v103, v110
	v_fmac_f32_e32 v111, v103, v103
	v_add_f32_e32 v108, v108, v110
	v_add_f32_e32 v109, v109, v111
	v_cvt_pk_bf16_f32 v100, v100, v101
	v_cvt_pk_bf16_f32 v101, v102, v103
	s_waitcnt vmcnt(0)
; DEVI unsigned pk2(float lo, float hi) { unsigned r; asm("v_cvt_pk_bf16_f32 %0, %1, %2" : "=v"(r) : "v"(lo), "v"(hi)); return r; }
;     DEVI void operator()(const f32x4 (&acc)[2][2][4][2], const pg8::Unit& u, int wr, int wc, int fr, int fq) const {
;     ...
;                 const int row = row0 + ai * 128 + m * 16; float mu, rs; row_stats(stin, row, mu, rs);
;                 float sum = 0.f, sq = 0.f;
; #pragma unroll
;                 for (int bj = 0; bj < 2; ++bj) {
;                     f32x4 z[2];
; #pragma unroll
;                     for (int n = 0; n < 2; ++n) {
;                         const int col = colb + bj * 128 + 4 * n;
;                         f32x4 xv = *(const f32x4*)(zsrc + (size_t)row * DM + col);
;                         if (stin) { const f32x4 gv = *(const f32x4*)(gin + col), bv = *(const f32x4*)(bin + col); xv = (xv - mu) * rs * gv + bv; }
;                         f32x4 zz = ALPHA * xv + acc[ai][bj][m][n];
;                         if (bias) zz += *(const f32x4*)(bias + col);
;                         *(f32x4*)(zdst + (size_t)row * DM + col) = zz;
;                         sum += zz[0] + zz[1] + zz[2] + zz[3]; sq += zz[0] * zz[0] + zz[1] * zz[1] + zz[2] * zz[2] + zz[3] * zz[3];
;                         z[n] = zz;
;                     }
;                     u32x4 o; o.x = pk2(z[0][0], z[0][1]); o.y = pk2(z[0][2], z[0][3]); o.z = pk2(z[1][0], z[1][1]); o.w = pk2(z[1][2], z[1][3]);
;                     if (zb) *(u32x4*)(zb + (size_t)row * DM + colb + bj * 128) = o;
;                 }
;                 sum += __shfl_xor(sum, 16); sq += __shfl_xor(sq, 16);
;                 sum += __shfl_xor(sum, 32); sq += __shfl_xor(sq, 32);
;                 if (fq == 0) { atomicAdd(stout + 2 * (size_t)row, sum); atomicAdd(stout + 2 * (size_t)row + 1, sq); }
	v_pk_fma_f32 v[104:105], v[156:157], v[104:105], v[170:171]
	s_nop 0
	v_pk_fma_f32 v[104:105], v[104:105], s[26:27], v[96:97] op_sel_hi:[1,0,1]
	v_pk_fma_f32 v[106:107], v[158:159], v[106:107], v[172:173]
	v_mul_f32_e32 v97, v105, v105
	v_pk_fma_f32 v[106:107], v[106:107], s[26:27], v[98:99] op_sel_hi:[1,0,1]
	v_add_f32_e32 v96, v104, v105
	v_fmac_f32_e32 v97, v104, v104
	v_add_f32_e32 v96, v106, v96
	v_fmac_f32_e32 v97, v106, v106
	v_add_f32_e32 v96, v107, v96
	v_fmac_f32_e32 v97, v107, v107
	v_add_f32_e32 v96, v108, v96
	v_add_f32_e32 v97, v109, v97
	ds_bpermute_b32 v98, v116, v96
	ds_bpermute_b32 v99, v116, v97
	global_store_dwordx4 v[114:115], v[104:107], off offset:528
	v_cvt_pk_bf16_f32 v102, v104, v105
	v_cvt_pk_bf16_f32 v103, v106, v107
	s_waitcnt lgkmcnt(0)
	v_add_f32_e32 v96, v96, v98
	v_add_f32_e32 v97, v97, v99
	ds_bpermute_b32 v98, v117, v96
	ds_bpermute_b32 v99, v117, v97
	flat_store_dwordx4 v[118:119], v[100:103] offset:256
	s_mov_b32 s100, -1
	s_mov_b32 s101, 0
	s_mov_b32 s98, 0xffff0000
	s_mov_b32 s99, 0
	s_and_saveexec_b64 s[30:31], s[100:101]
	s_cbranch_execz .LBB0_1542
	v_lshl_add_u64 v[100:101], s[10:11], 0, v[112:113]
	s_waitcnt lgkmcnt(0)
	v_add_f32_e32 v96, v96, v98
	v_add_f32_e32 v97, v97, v99
	v_cndmask_b32_e64 v96, v96, v97, s[98:99]
	v_cndmask_b32_e64 v97, 0, 4, s[98:99]
	v_or_b32_e32 v100, v100, v97
	v_mov_b32_e32 v253, v96
.LBB0_1542:
	s_or_b64 exec, exec, s[30:31]
	v_or_b32_e32 v118, 32, v154
	v_ashrrev_i32_e32 v119, 31, v118
	v_lshlrev_b64 v[96:97], 3, v[118:119]
	s_waitcnt lgkmcnt(0)
	v_lshl_add_u64 v[98:99], s[12:13], 0, v[96:97]
	flat_load_dwordx2 v[156:157], v[98:99]
	v_lshlrev_b64 v[98:99], 12, v[118:119]
	v_lshl_add_u64 v[98:99], s[46:47], 0, v[98:99]
	v_lshl_add_u64 v[98:99], v[144:145], 2, v[98:99]
	global_load_dwordx4 v[100:103], v[98:99], off
	global_load_dwordx4 v[104:107], v[150:151], off
	global_load_dwordx4 v[108:111], v[152:153], off
	global_load_dwordx4 v[112:115], v[98:99], off offset:16
	s_waitcnt vmcnt(0) lgkmcnt(0)
	v_pk_mul_f32 v[156:157], v[156:157], s[24:25] op_sel:[1,0] op_sel_hi:[0,0]
	v_fma_f32 v155, -v157, v157, v156
	v_max_f32_e32 v155, 0, v155
	v_add_f32_e32 v155, 0x3727c5ac, v155
	v_mul_f32_e32 v156, 0x4b800000, v155
	v_cmp_gt_f32_e32 vcc, s61, v155
	v_sub_f32_e32 v101, v101, v157
	v_sub_f32_e32 v100, v100, v157
	v_cndmask_b32_e32 v155, v155, v156, vcc
	v_rsq_f32_e32 v155, v155
	v_sub_f32_e32 v103, v103, v157
	v_sub_f32_e32 v102, v102, v157
	v_mul_f32_e32 v156, 0x45800000, v155
	v_cndmask_b32_e32 v156, v155, v156, vcc
	v_pk_mul_f32 v[102:103], v[102:103], v[156:157] op_sel_hi:[1,0]
	v_pk_mul_f32 v[100:101], v[100:101], v[156:157] op_sel_hi:[1,0]
	v_pk_fma_f32 v[102:103], v[106:107], v[102:103], v[110:111]
	v_pk_fma_f32 v[100:101], v[104:105], v[100:101], v[108:109]
	v_pk_fma_f32 v[94:95], v[102:103], s[26:27], v[94:95] op_sel_hi:[1,0,1]
	v_pk_fma_f32 v[92:93], v[100:101], s[26:27], v[92:93] op_sel_hi:[1,0,1]
	global_store_dwordx4 v[98:99], v[92:95], off
	global_load_dwordx4 v[100:103], v[146:147], off
	global_load_dwordx4 v[104:107], v[148:149], off
	v_lshlrev_b64 v[108:109], 11, v[118:119]
	v_lshl_add_u64 v[108:109], s[14:15], 0, v[108:109]
	v_lshl_add_u64 v[118:119], v[144:145], 1, v[108:109]
	v_sub_f32_e32 v109, v113, v157
	v_sub_f32_e32 v108, v112, v157
	v_sub_f32_e32 v111, v115, v157
	v_sub_f32_e32 v110, v114, v157
	v_pk_mul_f32 v[110:111], v[110:111], v[156:157] op_sel_hi:[1,0]
	v_pk_mul_f32 v[112:113], v[108:109], v[156:157] op_sel_hi:[1,0]
	v_cvt_pk_bf16_f32 v108, v92, v93
	v_cvt_pk_bf16_f32 v109, v94, v95
	s_waitcnt vmcnt(0)
	v_pk_fma_f32 v[102:103], v[102:103], v[110:111], v[106:107]
	v_pk_fma_f32 v[100:101], v[100:101], v[112:113], v[104:105]
	v_pk_fma_f32 v[90:91], v[102:103], s[26:27], v[90:91] op_sel_hi:[1,0,1]
	v_pk_fma_f32 v[88:89], v[100:101], s[26:27], v[88:89] op_sel_hi:[1,0,1]
	global_store_dwordx4 v[98:99], v[88:91], off offset:16
	v_cvt_pk_bf16_f32 v110, v88, v89
	v_cvt_pk_bf16_f32 v111, v90, v91
	flat_store_dwordx4 v[118:119], v[108:111]
	global_load_dwordx4 v[100:103], v[98:99], off offset:512
	global_load_dwordx4 v[104:107], v[120:121], off
	s_nop 0
	global_load_dwordx4 v[108:111], v[122:123], off
	global_load_dwordx4 v[112:115], v[98:99], off offset:528
	s_waitcnt vmcnt(0)
	v_sub_f32_e32 v101, v101, v157
	v_sub_f32_e32 v100, v100, v157
	v_sub_f32_e32 v103, v103, v157
	v_sub_f32_e32 v102, v102, v157
	v_pk_mul_f32 v[102:103], v[156:157], v[102:103] op_sel_hi:[0,1]
	v_pk_mul_f32 v[100:101], v[156:157], v[100:101] op_sel_hi:[0,1]
	v_pk_fma_f32 v[100:101], v[104:105], v[100:101], v[108:109]
	v_pk_fma_f32 v[102:103], v[106:107], v[102:103], v[110:111]
	v_pk_fma_f32 v[84:85], v[100:101], s[26:27], v[84:85] op_sel_hi:[1,0,1]
	v_pk_fma_f32 v[86:87], v[102:103], s[26:27], v[86:87] op_sel_hi:[1,0,1]
	global_store_dwordx4 v[98:99], v[84:87], off offset:512
	global_load_dwordx4 v[100:103], v[124:125], off
	global_load_dwordx4 v[104:107], v[126:127], off
	v_add_f32_e32 v108, v92, v93
	v_mul_f32_e32 v93, v93, v93
	v_fmac_f32_e32 v93, v92, v92
	v_add_f32_e32 v108, v94, v108
	v_fmac_f32_e32 v93, v94, v94
	v_add_f32_e32 v94, v88, v89
	v_mul_f32_e32 v89, v89, v89
	v_fmac_f32_e32 v89, v88, v88
	v_add_f32_e32 v92, v95, v108
	v_add_f32_e32 v94, v90, v94
	v_fmac_f32_e32 v89, v90, v90
	v_add_f32_e32 v92, 0, v92
	v_fmac_f32_e32 v93, v95, v95
	v_add_f32_e32 v88, v91, v94
	v_fmac_f32_e32 v89, v91, v91
	v_add_f32_e32 v92, v88, v92
	v_add_f32_e32 v93, v93, v89
	v_sub_f32_e32 v89, v113, v157
	v_sub_f32_e32 v88, v112, v157
	v_pk_mul_f32 v[88:89], v[156:157], v[88:89] op_sel_hi:[0,1]
	v_sub_f32_e32 v91, v115, v157
	v_sub_f32_e32 v90, v114, v157
	v_pk_mul_f32 v[90:91], v[156:157], v[90:91] op_sel_hi:[0,1]
	v_mul_f32_e32 v95, v85, v85
	v_add_f32_e32 v94, v84, v85
	v_fmac_f32_e32 v95, v84, v84
	v_add_f32_e32 v94, v86, v94
	v_fmac_f32_e32 v95, v86, v86
	v_add_f32_e32 v94, v87, v94
	v_fmac_f32_e32 v95, v87, v87
	v_add_f32_e32 v92, v92, v94
	v_add_f32_e32 v93, v93, v95
	v_cvt_pk_bf16_f32 v84, v84, v85
	v_cvt_pk_bf16_f32 v85, v86, v87
	s_waitcnt vmcnt(0)
; DEVI unsigned pk2(float lo, float hi) { unsigned r; asm("v_cvt_pk_bf16_f32 %0, %1, %2" : "=v"(r) : "v"(lo), "v"(hi)); return r; }
;     DEVI void operator()(const f32x4 (&acc)[2][2][4][2], const pg8::Unit& u, int wr, int wc, int fr, int fq) const {
;     ...
;                 const int row = row0 + ai * 128 + m * 16; float mu, rs; row_stats(stin, row, mu, rs);
;                 float sum = 0.f, sq = 0.f;
; #pragma unroll
;                 for (int bj = 0; bj < 2; ++bj) {
;                     f32x4 z[2];
; #pragma unroll
;                     for (int n = 0; n < 2; ++n) {
;                         const int col = colb + bj * 128 + 4 * n;
;                         f32x4 xv = *(const f32x4*)(zsrc + (size_t)row * DM + col);
;                         if (stin) { const f32x4 gv = *(const f32x4*)(gin + col), bv = *(const f32x4*)(bin + col); xv = (xv - mu) * rs * gv + bv; }
;                         f32x4 zz = ALPHA * xv + acc[ai][bj][m][n];
;                         if (bias) zz += *(const f32x4*)(bias + col);
;                         *(f32x4*)(zdst + (size_t)row * DM + col) = zz;
;                         sum += zz[0] + zz[1] + zz[2] + zz[3]; sq += zz[0] * zz[0] + zz[1] * zz[1] + zz[2] * zz[2] + zz[3] * zz[3];
;                         z[n] = zz;
;                     }
;                     u32x4 o; o.x = pk2(z[0][0], z[0][1]); o.y = pk2(z[0][2], z[0][3]); o.z = pk2(z[1][0], z[1][1]); o.w = pk2(z[1][2], z[1][3]);
;                     if (zb) *(u32x4*)(zb + (size_t)row * DM + colb + bj * 128) = o;
;                 }
;                 sum += __shfl_xor(sum, 16); sq += __shfl_xor(sq, 16);
;                 sum += __shfl_xor(sum, 32); sq += __shfl_xor(sq, 32);
;                 if (fq == 0) { atomicAdd(stout + 2 * (size_t)row, sum); atomicAdd(stout + 2 * (size_t)row + 1, sq); }
	v_pk_fma_f32 v[88:89], v[100:101], v[88:89], v[104:105]
	s_nop 0
	v_pk_fma_f32 v[88:89], v[88:89], s[26:27], v[80:81] op_sel_hi:[1,0,1]
	v_pk_fma_f32 v[90:91], v[102:103], v[90:91], v[106:107]
	v_mul_f32_e32 v81, v89, v89
	v_pk_fma_f32 v[90:91], v[90:91], s[26:27], v[82:83] op_sel_hi:[1,0,1]
	v_add_f32_e32 v80, v88, v89
	v_fmac_f32_e32 v81, v88, v88
	v_add_f32_e32 v80, v90, v80
	v_fmac_f32_e32 v81, v90, v90
	v_add_f32_e32 v80, v91, v80
	v_fmac_f32_e32 v81, v91, v91
	v_add_f32_e32 v80, v92, v80
	v_add_f32_e32 v81, v93, v81
	ds_bpermute_b32 v82, v116, v80
	ds_bpermute_b32 v83, v116, v81
	global_store_dwordx4 v[98:99], v[88:91], off offset:528
	v_cvt_pk_bf16_f32 v86, v88, v89
	v_cvt_pk_bf16_f32 v87, v90, v91
	s_waitcnt lgkmcnt(0)
	v_add_f32_e32 v80, v80, v82
	v_add_f32_e32 v81, v81, v83
	ds_bpermute_b32 v82, v117, v80
	ds_bpermute_b32 v83, v117, v81
	flat_store_dwordx4 v[118:119], v[84:87] offset:256
	s_mov_b32 s100, -1
	s_mov_b32 s101, 0
	s_mov_b32 s98, 0xffff0000
	s_mov_b32 s99, 0
	s_and_saveexec_b64 s[30:31], s[100:101]
	s_cbranch_execz .LBB0_1544
	v_lshl_add_u64 v[84:85], s[10:11], 0, v[96:97]
	s_waitcnt lgkmcnt(0)
	v_add_f32_e32 v80, v80, v82
	v_add_f32_e32 v81, v81, v83
	v_cndmask_b32_e64 v80, v80, v81, s[98:99]
	v_cndmask_b32_e64 v81, 0, 4, s[98:99]
	v_or_b32_e32 v84, v84, v81
	v_mov_b32_e32 v254, v80
.LBB0_1544:
	s_or_b64 exec, exec, s[30:31]
	v_or_b32_e32 v100, 48, v154
	v_ashrrev_i32_e32 v101, 31, v100
	v_lshlrev_b64 v[80:81], 3, v[100:101]
	s_waitcnt lgkmcnt(0)
	v_lshl_add_u64 v[82:83], s[12:13], 0, v[80:81]
	flat_load_dwordx2 v[102:103], v[82:83]
	v_lshlrev_b64 v[82:83], 12, v[100:101]
	v_lshl_add_u64 v[82:83], s[46:47], 0, v[82:83]
	v_lshl_add_u64 v[82:83], v[144:145], 2, v[82:83]
	global_load_dwordx4 v[84:87], v[82:83], off
	global_load_dwordx4 v[88:91], v[150:151], off
	global_load_dwordx4 v[92:95], v[152:153], off
	global_load_dwordx4 v[96:99], v[82:83], off offset:16
	s_waitcnt vmcnt(0) lgkmcnt(0)
	v_pk_mul_f32 v[102:103], v[102:103], s[24:25] op_sel:[1,0] op_sel_hi:[0,0]
	v_fma_f32 v102, -v103, v103, v102
	v_max_f32_e32 v102, 0, v102
	v_add_f32_e32 v102, 0x3727c5ac, v102
	v_mul_f32_e32 v104, 0x4b800000, v102
	v_cmp_gt_f32_e32 vcc, s61, v102
	v_sub_f32_e32 v85, v85, v103
	v_sub_f32_e32 v84, v84, v103
	v_cndmask_b32_e32 v102, v102, v104, vcc
	v_rsq_f32_e32 v102, v102
	v_sub_f32_e32 v87, v87, v103
	v_sub_f32_e32 v86, v86, v103
	v_mul_f32_e32 v104, 0x45800000, v102
	v_cndmask_b32_e32 v102, v102, v104, vcc
	v_pk_mul_f32 v[86:87], v[86:87], v[102:103] op_sel_hi:[1,0]
	v_pk_mul_f32 v[84:85], v[84:85], v[102:103] op_sel_hi:[1,0]
	v_pk_fma_f32 v[86:87], v[90:91], v[86:87], v[94:95]
	v_pk_fma_f32 v[84:85], v[88:89], v[84:85], v[92:93]
	v_pk_fma_f32 v[78:79], v[86:87], s[26:27], v[78:79] op_sel_hi:[1,0,1]
	v_pk_fma_f32 v[76:77], v[84:85], s[26:27], v[76:77] op_sel_hi:[1,0,1]
	global_store_dwordx4 v[82:83], v[76:79], off
	global_load_dwordx4 v[84:87], v[146:147], off
	global_load_dwordx4 v[88:91], v[148:149], off
	v_lshlrev_b64 v[92:93], 11, v[100:101]
	v_lshl_add_u64 v[92:93], s[14:15], 0, v[92:93]
	v_lshl_add_u64 v[100:101], v[144:145], 1, v[92:93]
	v_sub_f32_e32 v93, v97, v103
	v_sub_f32_e32 v92, v96, v103
	v_sub_f32_e32 v95, v99, v103
	v_sub_f32_e32 v94, v98, v103
	v_pk_mul_f32 v[94:95], v[94:95], v[102:103] op_sel_hi:[1,0]
	v_pk_mul_f32 v[96:97], v[92:93], v[102:103] op_sel_hi:[1,0]
	v_cvt_pk_bf16_f32 v92, v76, v77
	v_cvt_pk_bf16_f32 v93, v78, v79
	s_waitcnt vmcnt(0)
	v_pk_fma_f32 v[86:87], v[86:87], v[94:95], v[90:91]
	v_pk_fma_f32 v[84:85], v[84:85], v[96:97], v[88:89]
	v_pk_fma_f32 v[74:75], v[86:87], s[26:27], v[74:75] op_sel_hi:[1,0,1]
	v_pk_fma_f32 v[72:73], v[84:85], s[26:27], v[72:73] op_sel_hi:[1,0,1]
	global_store_dwordx4 v[82:83], v[72:75], off offset:16
	v_cvt_pk_bf16_f32 v94, v72, v73
	v_cvt_pk_bf16_f32 v95, v74, v75
	flat_store_dwordx4 v[100:101], v[92:95]
	global_load_dwordx4 v[84:87], v[82:83], off offset:512
	global_load_dwordx4 v[88:91], v[120:121], off
	s_nop 0
	global_load_dwordx4 v[92:95], v[122:123], off
	global_load_dwordx4 v[96:99], v[82:83], off offset:528
	s_waitcnt vmcnt(0)
	v_sub_f32_e32 v85, v85, v103
	v_sub_f32_e32 v84, v84, v103
	v_sub_f32_e32 v87, v87, v103
	v_sub_f32_e32 v86, v86, v103
	v_pk_mul_f32 v[86:87], v[102:103], v[86:87] op_sel_hi:[0,1]
	v_pk_mul_f32 v[84:85], v[102:103], v[84:85] op_sel_hi:[0,1]
	v_pk_fma_f32 v[84:85], v[88:89], v[84:85], v[92:93]
	v_pk_fma_f32 v[86:87], v[90:91], v[86:87], v[94:95]
	v_pk_fma_f32 v[68:69], v[84:85], s[26:27], v[68:69] op_sel_hi:[1,0,1]
	v_pk_fma_f32 v[70:71], v[86:87], s[26:27], v[70:71] op_sel_hi:[1,0,1]
	global_store_dwordx4 v[82:83], v[68:71], off offset:512
	global_load_dwordx4 v[84:87], v[124:125], off
	global_load_dwordx4 v[88:91], v[126:127], off
	v_add_f32_e32 v92, v76, v77
	v_mul_f32_e32 v77, v77, v77
	v_fmac_f32_e32 v77, v76, v76
	v_add_f32_e32 v92, v78, v92
	v_fmac_f32_e32 v77, v78, v78
	v_add_f32_e32 v78, v72, v73
	v_mul_f32_e32 v73, v73, v73
	v_fmac_f32_e32 v73, v72, v72
	v_add_f32_e32 v76, v79, v92
	v_add_f32_e32 v78, v74, v78
	v_fmac_f32_e32 v73, v74, v74
	v_add_f32_e32 v76, 0, v76
	v_fmac_f32_e32 v77, v79, v79
	v_add_f32_e32 v72, v75, v78
	v_fmac_f32_e32 v73, v75, v75
	v_add_f32_e32 v76, v72, v76
	v_add_f32_e32 v77, v77, v73
	v_sub_f32_e32 v73, v97, v103
	v_sub_f32_e32 v72, v96, v103
	v_pk_mul_f32 v[72:73], v[102:103], v[72:73] op_sel_hi:[0,1]
	v_sub_f32_e32 v75, v99, v103
	v_sub_f32_e32 v74, v98, v103
	v_pk_mul_f32 v[74:75], v[102:103], v[74:75] op_sel_hi:[0,1]
	v_mul_f32_e32 v79, v69, v69
	v_add_f32_e32 v78, v68, v69
	v_fmac_f32_e32 v79, v68, v68
	v_add_f32_e32 v78, v70, v78
	v_fmac_f32_e32 v79, v70, v70
	v_add_f32_e32 v78, v71, v78
	v_fmac_f32_e32 v79, v71, v71
	v_add_f32_e32 v76, v76, v78
	v_add_f32_e32 v77, v77, v79
	v_cvt_pk_bf16_f32 v68, v68, v69
	v_cvt_pk_bf16_f32 v69, v70, v71
	s_waitcnt vmcnt(0)
	v_pk_fma_f32 v[72:73], v[84:85], v[72:73], v[88:89]
	s_nop 0
	v_pk_fma_f32 v[72:73], v[72:73], s[26:27], v[64:65] op_sel_hi:[1,0,1]
	v_pk_fma_f32 v[74:75], v[86:87], v[74:75], v[90:91]
	v_mul_f32_e32 v65, v73, v73
	v_pk_fma_f32 v[74:75], v[74:75], s[26:27], v[66:67] op_sel_hi:[1,0,1]
	v_add_f32_e32 v64, v72, v73
	v_fmac_f32_e32 v65, v72, v72
	v_add_f32_e32 v64, v74, v64
	v_fmac_f32_e32 v65, v74, v74
	v_add_f32_e32 v64, v75, v64
	v_fmac_f32_e32 v65, v75, v75
	v_add_f32_e32 v64, v76, v64
	v_add_f32_e32 v65, v77, v65
	ds_bpermute_b32 v66, v116, v64
	ds_bpermute_b32 v67, v116, v65
	global_store_dwordx4 v[82:83], v[72:75], off offset:528
	v_cvt_pk_bf16_f32 v70, v72, v73
	v_cvt_pk_bf16_f32 v71, v74, v75
	s_waitcnt lgkmcnt(0)
	v_add_f32_e32 v64, v64, v66
	v_add_f32_e32 v65, v65, v67
	ds_bpermute_b32 v66, v117, v64
	ds_bpermute_b32 v67, v117, v65
	flat_store_dwordx4 v[100:101], v[68:71] offset:256
	s_mov_b32 s100, -1
	s_mov_b32 s101, 0
	s_mov_b32 s98, 0xffff0000
	s_mov_b32 s99, 0
	s_and_saveexec_b64 s[30:31], s[100:101]
	s_cbranch_execz .LBB0_1546
; DEVI unsigned pk2(float lo, float hi) { unsigned r; asm("v_cvt_pk_bf16_f32 %0, %1, %2" : "=v"(r) : "v"(lo), "v"(hi)); return r; }
;     DEVI void operator()(const f32x4 (&acc)[2][2][4][2], const pg8::Unit& u, int wr, int wc, int fr, int fq) const {
;     ...
;                 const int row = row0 + ai * 128 + m * 16; float mu, rs; row_stats(stin, row, mu, rs);
;                 float sum = 0.f, sq = 0.f;
; #pragma unroll
;                 for (int bj = 0; bj < 2; ++bj) {
;                     f32x4 z[2];
; #pragma unroll
;                     for (int n = 0; n < 2; ++n) {
;                         const int col = colb + bj * 128 + 4 * n;
;                         f32x4 xv = *(const f32x4*)(zsrc + (size_t)row * DM + col);
;                         if (stin) { const f32x4 gv = *(const f32x4*)(gin + col), bv = *(const f32x4*)(bin + col); xv = (xv - mu) * rs * gv + bv; }
;                         f32x4 zz = ALPHA * xv + acc[ai][bj][m][n];
;                         if (bias) zz += *(const f32x4*)(bias + col);
;                         *(f32x4*)(zdst + (size_t)row * DM + col) = zz;
;                         sum += zz[0] + zz[1] + zz[2] + zz[3]; sq += zz[0] * zz[0] + zz[1] * zz[1] + zz[2] * zz[2] + zz[3] * zz[3];
;                         z[n] = zz;
;                     }
;                     u32x4 o; o.x = pk2(z[0][0], z[0][1]); o.y = pk2(z[0][2], z[0][3]); o.z = pk2(z[1][0], z[1][1]); o.w = pk2(z[1][2], z[1][3]);
;                     if (zb) *(u32x4*)(zb + (size_t)row * DM + colb + bj * 128) = o;
;                 }
;                 sum += __shfl_xor(sum, 16); sq += __shfl_xor(sq, 16);
;                 sum += __shfl_xor(sum, 32); sq += __shfl_xor(sq, 32);
;                 if (fq == 0) { atomicAdd(stout + 2 * (size_t)row, sum); atomicAdd(stout + 2 * (size_t)row + 1, sq); }
	v_lshl_add_u64 v[68:69], s[10:11], 0, v[80:81]
	s_waitcnt lgkmcnt(0)
	v_add_f32_e32 v64, v64, v66
	v_add_f32_e32 v65, v65, v67
	v_cndmask_b32_e64 v64, v64, v65, s[98:99]
	v_cndmask_b32_e64 v65, 0, 4, s[98:99]
	v_or_b32_e32 v68, v68, v65
	v_mov_b32_e32 v255, v64
	flat_atomic_add_f32 v[250:251], v252
	flat_atomic_add_f32 v[250:251], v253 offset:128
	flat_atomic_add_f32 v[250:251], v254 offset:256
	flat_atomic_add_f32 v[250:251], v255 offset:384
.LBB0_1546:
	s_or_b64 exec, exec, s[30:31]
	v_add_u32_e32 v84, 0x80, v154
	v_ashrrev_i32_e32 v85, 31, v84
	v_lshlrev_b64 v[64:65], 3, v[84:85]
	s_waitcnt lgkmcnt(0)
	v_lshl_add_u64 v[66:67], s[12:13], 0, v[64:65]
	flat_load_dwordx2 v[86:87], v[66:67]
	v_lshlrev_b64 v[66:67], 12, v[84:85]
	v_lshl_add_u64 v[66:67], s[46:47], 0, v[66:67]
	v_lshl_add_u64 v[66:67], v[144:145], 2, v[66:67]
	global_load_dwordx4 v[68:71], v[66:67], off
	global_load_dwordx4 v[72:75], v[150:151], off
	global_load_dwordx4 v[76:79], v[152:153], off
	global_load_dwordx4 v[80:83], v[66:67], off offset:16
	s_waitcnt vmcnt(0) lgkmcnt(0)
	v_pk_mul_f32 v[86:87], v[86:87], s[24:25] op_sel:[1,0] op_sel_hi:[0,0]
	v_fma_f32 v86, -v87, v87, v86
	v_max_f32_e32 v86, 0, v86
	v_add_f32_e32 v86, 0x3727c5ac, v86
	v_mul_f32_e32 v88, 0x4b800000, v86
	v_cmp_gt_f32_e32 vcc, s61, v86
	v_sub_f32_e32 v69, v69, v87
	v_sub_f32_e32 v68, v68, v87
	v_cndmask_b32_e32 v86, v86, v88, vcc
	v_rsq_f32_e32 v86, v86
	v_sub_f32_e32 v71, v71, v87
	v_sub_f32_e32 v70, v70, v87
	v_mul_f32_e32 v88, 0x45800000, v86
	v_cndmask_b32_e32 v86, v86, v88, vcc
	v_pk_mul_f32 v[70:71], v[70:71], v[86:87] op_sel_hi:[1,0]
	v_pk_mul_f32 v[68:69], v[68:69], v[86:87] op_sel_hi:[1,0]
	v_pk_fma_f32 v[70:71], v[74:75], v[70:71], v[78:79]
	v_pk_fma_f32 v[68:69], v[72:73], v[68:69], v[76:77]
	v_pk_fma_f32 v[62:63], v[70:71], s[26:27], v[62:63] op_sel_hi:[1,0,1]
	v_pk_fma_f32 v[60:61], v[68:69], s[26:27], v[60:61] op_sel_hi:[1,0,1]
	global_store_dwordx4 v[66:67], v[60:63], off
	global_load_dwordx4 v[68:71], v[146:147], off
	global_load_dwordx4 v[72:75], v[148:149], off
	v_lshlrev_b64 v[76:77], 11, v[84:85]
	v_lshl_add_u64 v[76:77], s[14:15], 0, v[76:77]
	v_lshl_add_u64 v[84:85], v[144:145], 1, v[76:77]
	v_sub_f32_e32 v77, v81, v87
	v_sub_f32_e32 v76, v80, v87
	v_sub_f32_e32 v79, v83, v87
	v_sub_f32_e32 v78, v82, v87
	v_pk_mul_f32 v[78:79], v[78:79], v[86:87] op_sel_hi:[1,0]
	v_pk_mul_f32 v[80:81], v[76:77], v[86:87] op_sel_hi:[1,0]
	v_cvt_pk_bf16_f32 v76, v60, v61
	v_cvt_pk_bf16_f32 v77, v62, v63
	s_waitcnt vmcnt(0)
	v_pk_fma_f32 v[70:71], v[70:71], v[78:79], v[74:75]
	v_pk_fma_f32 v[68:69], v[68:69], v[80:81], v[72:73]
	v_pk_fma_f32 v[58:59], v[70:71], s[26:27], v[58:59] op_sel_hi:[1,0,1]
	v_pk_fma_f32 v[56:57], v[68:69], s[26:27], v[56:57] op_sel_hi:[1,0,1]
	global_store_dwordx4 v[66:67], v[56:59], off offset:16
	v_cvt_pk_bf16_f32 v78, v56, v57
	v_cvt_pk_bf16_f32 v79, v58, v59
	flat_store_dwordx4 v[84:85], v[76:79]
	global_load_dwordx4 v[68:71], v[66:67], off offset:512
	global_load_dwordx4 v[72:75], v[120:121], off
	s_nop 0
	global_load_dwordx4 v[76:79], v[122:123], off
	global_load_dwordx4 v[80:83], v[66:67], off offset:528
	s_waitcnt vmcnt(0)
	v_sub_f32_e32 v69, v69, v87
	v_sub_f32_e32 v68, v68, v87
	v_sub_f32_e32 v71, v71, v87
	v_sub_f32_e32 v70, v70, v87
	v_pk_mul_f32 v[70:71], v[86:87], v[70:71] op_sel_hi:[0,1]
	v_pk_mul_f32 v[68:69], v[86:87], v[68:69] op_sel_hi:[0,1]
	v_pk_fma_f32 v[68:69], v[72:73], v[68:69], v[76:77]
	v_pk_fma_f32 v[70:71], v[74:75], v[70:71], v[78:79]
	v_pk_fma_f32 v[52:53], v[68:69], s[26:27], v[52:53] op_sel_hi:[1,0,1]
	v_pk_fma_f32 v[54:55], v[70:71], s[26:27], v[54:55] op_sel_hi:[1,0,1]
	global_store_dwordx4 v[66:67], v[52:55], off offset:512
	global_load_dwordx4 v[68:71], v[124:125], off
	global_load_dwordx4 v[72:75], v[126:127], off
	v_add_f32_e32 v76, v60, v61
	v_mul_f32_e32 v61, v61, v61
	v_fmac_f32_e32 v61, v60, v60
	v_add_f32_e32 v76, v62, v76
	v_fmac_f32_e32 v61, v62, v62
	v_add_f32_e32 v62, v56, v57
	v_mul_f32_e32 v57, v57, v57
	v_fmac_f32_e32 v57, v56, v56
	v_add_f32_e32 v60, v63, v76
	v_add_f32_e32 v62, v58, v62
	v_fmac_f32_e32 v57, v58, v58
	v_add_f32_e32 v60, 0, v60
	v_fmac_f32_e32 v61, v63, v63
	v_add_f32_e32 v56, v59, v62
	v_fmac_f32_e32 v57, v59, v59
	v_add_f32_e32 v60, v56, v60
	v_add_f32_e32 v61, v61, v57
	v_sub_f32_e32 v57, v81, v87
	v_sub_f32_e32 v56, v80, v87
	v_pk_mul_f32 v[56:57], v[86:87], v[56:57] op_sel_hi:[0,1]
	v_sub_f32_e32 v59, v83, v87
	v_sub_f32_e32 v58, v82, v87
	v_pk_mul_f32 v[58:59], v[86:87], v[58:59] op_sel_hi:[0,1]
	v_mul_f32_e32 v63, v53, v53
	v_add_f32_e32 v62, v52, v53
	v_fmac_f32_e32 v63, v52, v52
	v_add_f32_e32 v62, v54, v62
	v_fmac_f32_e32 v63, v54, v54
	v_add_f32_e32 v62, v55, v62
	v_fmac_f32_e32 v63, v55, v55
	v_add_f32_e32 v60, v60, v62
	v_add_f32_e32 v61, v61, v63
	v_cvt_pk_bf16_f32 v52, v52, v53
	v_cvt_pk_bf16_f32 v53, v54, v55
	s_waitcnt vmcnt(0)
	v_pk_fma_f32 v[56:57], v[68:69], v[56:57], v[72:73]
	s_nop 0
	v_pk_fma_f32 v[56:57], v[56:57], s[26:27], v[48:49] op_sel_hi:[1,0,1]
	v_pk_fma_f32 v[58:59], v[70:71], v[58:59], v[74:75]
	v_mul_f32_e32 v49, v57, v57
	v_pk_fma_f32 v[58:59], v[58:59], s[26:27], v[50:51] op_sel_hi:[1,0,1]
	v_add_f32_e32 v48, v56, v57
	v_fmac_f32_e32 v49, v56, v56
	v_add_f32_e32 v48, v58, v48
	v_fmac_f32_e32 v49, v58, v58
	v_add_f32_e32 v48, v59, v48
	v_fmac_f32_e32 v49, v59, v59
	v_add_f32_e32 v48, v60, v48
	v_add_f32_e32 v49, v61, v49
	ds_bpermute_b32 v50, v116, v48
	ds_bpermute_b32 v51, v116, v49
	global_store_dwordx4 v[66:67], v[56:59], off offset:528
	v_cvt_pk_bf16_f32 v54, v56, v57
	v_cvt_pk_bf16_f32 v55, v58, v59
	s_waitcnt lgkmcnt(0)
	v_add_f32_e32 v48, v48, v50
	v_add_f32_e32 v49, v49, v51
	ds_bpermute_b32 v50, v117, v48
	ds_bpermute_b32 v51, v117, v49
	flat_store_dwordx4 v[84:85], v[52:55] offset:256
	s_mov_b32 s100, -1
	s_mov_b32 s101, 0
	s_mov_b32 s98, 0xffff0000
	s_mov_b32 s99, 0
	s_and_saveexec_b64 s[30:31], s[100:101]
	s_cbranch_execz .LBB0_1548
	v_lshl_add_u64 v[52:53], s[10:11], 0, v[64:65]
	s_waitcnt lgkmcnt(0)
	v_add_f32_e32 v48, v48, v50
	v_add_f32_e32 v49, v49, v51
	v_cndmask_b32_e64 v48, v48, v49, s[98:99]
	v_cndmask_b32_e64 v49, 0, 4, s[98:99]
	v_or_b32_e32 v52, v52, v49
	v_mov_b32_e32 v250, v52
	v_mov_b32_e32 v251, v53
	v_mov_b32_e32 v252, v48
; DEVI unsigned pk2(float lo, float hi) { unsigned r; asm("v_cvt_pk_bf16_f32 %0, %1, %2" : "=v"(r) : "v"(lo), "v"(hi)); return r; }
;     DEVI void operator()(const f32x4 (&acc)[2][2][4][2], const pg8::Unit& u, int wr, int wc, int fr, int fq) const {
;     ...
;                 const int row = row0 + ai * 128 + m * 16; float mu, rs; row_stats(stin, row, mu, rs);
;                 float sum = 0.f, sq = 0.f;
; #pragma unroll
;                 for (int bj = 0; bj < 2; ++bj) {
;                     f32x4 z[2];
; #pragma unroll
;                     for (int n = 0; n < 2; ++n) {
;                         const int col = colb + bj * 128 + 4 * n;
;                         f32x4 xv = *(const f32x4*)(zsrc + (size_t)row * DM + col);
;                         if (stin) { const f32x4 gv = *(const f32x4*)(gin + col), bv = *(const f32x4*)(bin + col); xv = (xv - mu) * rs * gv + bv; }
;                         f32x4 zz = ALPHA * xv + acc[ai][bj][m][n];
;                         if (bias) zz += *(const f32x4*)(bias + col);
;                         *(f32x4*)(zdst + (size_t)row * DM + col) = zz;
;                         sum += zz[0] + zz[1] + zz[2] + zz[3]; sq += zz[0] * zz[0] + zz[1] * zz[1] + zz[2] * zz[2] + zz[3] * zz[3];
;                         z[n] = zz;
;                     }
;                     u32x4 o; o.x = pk2(z[0][0], z[0][1]); o.y = pk2(z[0][2], z[0][3]); o.z = pk2(z[1][0], z[1][1]); o.w = pk2(z[1][2], z[1][3]);
;                     if (zb) *(u32x4*)(zb + (size_t)row * DM + colb + bj * 128) = o;
;                 }
;                 sum += __shfl_xor(sum, 16); sq += __shfl_xor(sq, 16);
;                 sum += __shfl_xor(sum, 32); sq += __shfl_xor(sq, 32);
;                 if (fq == 0) { atomicAdd(stout + 2 * (size_t)row, sum); atomicAdd(stout + 2 * (size_t)row + 1, sq); }
.LBB0_1548:
	s_or_b64 exec, exec, s[30:31]
	v_add_u32_e32 v68, 0x90, v154
	v_ashrrev_i32_e32 v69, 31, v68
	v_lshlrev_b64 v[48:49], 3, v[68:69]
	s_waitcnt lgkmcnt(0)
	v_lshl_add_u64 v[50:51], s[12:13], 0, v[48:49]
	flat_load_dwordx2 v[70:71], v[50:51]
	v_lshlrev_b64 v[50:51], 12, v[68:69]
	v_lshl_add_u64 v[50:51], s[46:47], 0, v[50:51]
	v_lshl_add_u64 v[50:51], v[144:145], 2, v[50:51]
	global_load_dwordx4 v[52:55], v[50:51], off
	global_load_dwordx4 v[56:59], v[150:151], off
	global_load_dwordx4 v[60:63], v[152:153], off
	global_load_dwordx4 v[64:67], v[50:51], off offset:16
	s_waitcnt vmcnt(0) lgkmcnt(0)
	v_pk_mul_f32 v[70:71], v[70:71], s[24:25] op_sel:[1,0] op_sel_hi:[0,0]
	v_fma_f32 v70, -v71, v71, v70
	v_max_f32_e32 v70, 0, v70
	v_add_f32_e32 v70, 0x3727c5ac, v70
	v_mul_f32_e32 v72, 0x4b800000, v70
	v_cmp_gt_f32_e32 vcc, s61, v70
	v_sub_f32_e32 v53, v53, v71
	v_sub_f32_e32 v52, v52, v71
	v_cndmask_b32_e32 v70, v70, v72, vcc
	v_rsq_f32_e32 v70, v70
	v_sub_f32_e32 v55, v55, v71
	v_sub_f32_e32 v54, v54, v71
	v_mul_f32_e32 v72, 0x45800000, v70
	v_cndmask_b32_e32 v70, v70, v72, vcc
	v_pk_mul_f32 v[54:55], v[54:55], v[70:71] op_sel_hi:[1,0]
	v_pk_mul_f32 v[52:53], v[52:53], v[70:71] op_sel_hi:[1,0]
	v_pk_fma_f32 v[54:55], v[58:59], v[54:55], v[62:63]
	v_pk_fma_f32 v[52:53], v[56:57], v[52:53], v[60:61]
	v_pk_fma_f32 v[46:47], v[54:55], s[26:27], v[46:47] op_sel_hi:[1,0,1]
	v_pk_fma_f32 v[44:45], v[52:53], s[26:27], v[44:45] op_sel_hi:[1,0,1]
	global_store_dwordx4 v[50:51], v[44:47], off
	global_load_dwordx4 v[52:55], v[146:147], off
	global_load_dwordx4 v[56:59], v[148:149], off
	v_lshlrev_b64 v[60:61], 11, v[68:69]
	v_lshl_add_u64 v[60:61], s[14:15], 0, v[60:61]
	v_lshl_add_u64 v[68:69], v[144:145], 1, v[60:61]
	v_sub_f32_e32 v61, v65, v71
	v_sub_f32_e32 v60, v64, v71
	v_sub_f32_e32 v63, v67, v71
	v_sub_f32_e32 v62, v66, v71
	v_pk_mul_f32 v[62:63], v[62:63], v[70:71] op_sel_hi:[1,0]
	v_pk_mul_f32 v[64:65], v[60:61], v[70:71] op_sel_hi:[1,0]
	v_cvt_pk_bf16_f32 v60, v44, v45
	v_cvt_pk_bf16_f32 v61, v46, v47
	s_waitcnt vmcnt(0)
	v_pk_fma_f32 v[54:55], v[54:55], v[62:63], v[58:59]
	v_pk_fma_f32 v[52:53], v[52:53], v[64:65], v[56:57]
	v_pk_fma_f32 v[42:43], v[54:55], s[26:27], v[42:43] op_sel_hi:[1,0,1]
	v_pk_fma_f32 v[40:41], v[52:53], s[26:27], v[40:41] op_sel_hi:[1,0,1]
	global_store_dwordx4 v[50:51], v[40:43], off offset:16
	v_cvt_pk_bf16_f32 v62, v40, v41
	v_cvt_pk_bf16_f32 v63, v42, v43
	flat_store_dwordx4 v[68:69], v[60:63]
	global_load_dwordx4 v[52:55], v[50:51], off offset:512
	global_load_dwordx4 v[56:59], v[120:121], off
	s_nop 0
	global_load_dwordx4 v[60:63], v[122:123], off
	global_load_dwordx4 v[64:67], v[50:51], off offset:528
	s_waitcnt vmcnt(0)
	v_sub_f32_e32 v53, v53, v71
	v_sub_f32_e32 v52, v52, v71
	v_sub_f32_e32 v55, v55, v71
	v_sub_f32_e32 v54, v54, v71
	v_pk_mul_f32 v[54:55], v[70:71], v[54:55] op_sel_hi:[0,1]
	v_pk_mul_f32 v[52:53], v[70:71], v[52:53] op_sel_hi:[0,1]
	v_pk_fma_f32 v[52:53], v[56:57], v[52:53], v[60:61]
	v_pk_fma_f32 v[54:55], v[58:59], v[54:55], v[62:63]
	v_pk_fma_f32 v[36:37], v[52:53], s[26:27], v[36:37] op_sel_hi:[1,0,1]
	v_pk_fma_f32 v[38:39], v[54:55], s[26:27], v[38:39] op_sel_hi:[1,0,1]
	global_store_dwordx4 v[50:51], v[36:39], off offset:512
	global_load_dwordx4 v[52:55], v[124:125], off
	global_load_dwordx4 v[56:59], v[126:127], off
	v_add_f32_e32 v60, v44, v45
	v_mul_f32_e32 v45, v45, v45
	v_fmac_f32_e32 v45, v44, v44
	v_add_f32_e32 v60, v46, v60
	v_fmac_f32_e32 v45, v46, v46
	v_add_f32_e32 v46, v40, v41
	v_mul_f32_e32 v41, v41, v41
	v_fmac_f32_e32 v41, v40, v40
	v_add_f32_e32 v44, v47, v60
	v_add_f32_e32 v46, v42, v46
	v_fmac_f32_e32 v41, v42, v42
	v_add_f32_e32 v44, 0, v44
	v_fmac_f32_e32 v45, v47, v47
	v_add_f32_e32 v40, v43, v46
	v_fmac_f32_e32 v41, v43, v43
	v_add_f32_e32 v44, v40, v44
	v_add_f32_e32 v45, v45, v41
	v_sub_f32_e32 v41, v65, v71
	v_sub_f32_e32 v40, v64, v71
	v_pk_mul_f32 v[40:41], v[70:71], v[40:41] op_sel_hi:[0,1]
	v_sub_f32_e32 v43, v67, v71
	v_sub_f32_e32 v42, v66, v71
	v_pk_mul_f32 v[42:43], v[70:71], v[42:43] op_sel_hi:[0,1]
	v_mul_f32_e32 v47, v37, v37
	v_add_f32_e32 v46, v36, v37
	v_fmac_f32_e32 v47, v36, v36
	v_add_f32_e32 v46, v38, v46
	v_fmac_f32_e32 v47, v38, v38
	v_add_f32_e32 v46, v39, v46
	v_fmac_f32_e32 v47, v39, v39
	v_add_f32_e32 v44, v44, v46
	v_add_f32_e32 v45, v45, v47
	v_cvt_pk_bf16_f32 v36, v36, v37
	v_cvt_pk_bf16_f32 v37, v38, v39
	s_waitcnt vmcnt(0)
	v_pk_fma_f32 v[40:41], v[52:53], v[40:41], v[56:57]
	s_nop 0
	v_pk_fma_f32 v[40:41], v[40:41], s[26:27], v[32:33] op_sel_hi:[1,0,1]
	v_pk_fma_f32 v[42:43], v[54:55], v[42:43], v[58:59]
	v_mul_f32_e32 v33, v41, v41
	v_pk_fma_f32 v[42:43], v[42:43], s[26:27], v[34:35] op_sel_hi:[1,0,1]
	v_add_f32_e32 v32, v40, v41
	v_fmac_f32_e32 v33, v40, v40
	v_add_f32_e32 v32, v42, v32
	v_fmac_f32_e32 v33, v42, v42
	v_add_f32_e32 v32, v43, v32
	v_fmac_f32_e32 v33, v43, v43
	v_add_f32_e32 v32, v44, v32
	v_add_f32_e32 v33, v45, v33
	ds_bpermute_b32 v34, v116, v32
	ds_bpermute_b32 v35, v116, v33
	global_store_dwordx4 v[50:51], v[40:43], off offset:528
	v_cvt_pk_bf16_f32 v38, v40, v41
	v_cvt_pk_bf16_f32 v39, v42, v43
	s_waitcnt lgkmcnt(0)
	v_add_f32_e32 v32, v32, v34
	v_add_f32_e32 v33, v33, v35
	ds_bpermute_b32 v34, v117, v32
	ds_bpermute_b32 v35, v117, v33
	flat_store_dwordx4 v[68:69], v[36:39] offset:256
	s_mov_b32 s100, -1
	s_mov_b32 s101, 0
	s_mov_b32 s98, 0xffff0000
	s_mov_b32 s99, 0
	s_and_saveexec_b64 s[30:31], s[100:101]
	s_cbranch_execz .LBB0_1550
	v_lshl_add_u64 v[36:37], s[10:11], 0, v[48:49]
	s_waitcnt lgkmcnt(0)
	v_add_f32_e32 v32, v32, v34
	v_add_f32_e32 v33, v33, v35
	v_cndmask_b32_e64 v32, v32, v33, s[98:99]
	v_cndmask_b32_e64 v33, 0, 4, s[98:99]
	v_or_b32_e32 v36, v36, v33
	v_mov_b32_e32 v253, v32
; DEVI unsigned pk2(float lo, float hi) { unsigned r; asm("v_cvt_pk_bf16_f32 %0, %1, %2" : "=v"(r) : "v"(lo), "v"(hi)); return r; }
;     DEVI void operator()(const f32x4 (&acc)[2][2][4][2], const pg8::Unit& u, int wr, int wc, int fr, int fq) const {
;     ...
;                 const int row = row0 + ai * 128 + m * 16; float mu, rs; row_stats(stin, row, mu, rs);
;                 float sum = 0.f, sq = 0.f;
; #pragma unroll
;                 for (int bj = 0; bj < 2; ++bj) {
;                     f32x4 z[2];
; #pragma unroll
;                     for (int n = 0; n < 2; ++n) {
;                         const int col = colb + bj * 128 + 4 * n;
;                         f32x4 xv = *(const f32x4*)(zsrc + (size_t)row * DM + col);
;                         if (stin) { const f32x4 gv = *(const f32x4*)(gin + col), bv = *(const f32x4*)(bin + col); xv = (xv - mu) * rs * gv + bv; }
;                         f32x4 zz = ALPHA * xv + acc[ai][bj][m][n];
;                         if (bias) zz += *(const f32x4*)(bias + col);
;                         *(f32x4*)(zdst + (size_t)row * DM + col) = zz;
;                         sum += zz[0] + zz[1] + zz[2] + zz[3]; sq += zz[0] * zz[0] + zz[1] * zz[1] + zz[2] * zz[2] + zz[3] * zz[3];
;                         z[n] = zz;
;                     }
;                     u32x4 o; o.x = pk2(z[0][0], z[0][1]); o.y = pk2(z[0][2], z[0][3]); o.z = pk2(z[1][0], z[1][1]); o.w = pk2(z[1][2], z[1][3]);
;                     if (zb) *(u32x4*)(zb + (size_t)row * DM + colb + bj * 128) = o;
;                 }
;                 sum += __shfl_xor(sum, 16); sq += __shfl_xor(sq, 16);
;                 sum += __shfl_xor(sum, 32); sq += __shfl_xor(sq, 32);
;                 if (fq == 0) { atomicAdd(stout + 2 * (size_t)row, sum); atomicAdd(stout + 2 * (size_t)row + 1, sq); }
.LBB0_1550:
	s_or_b64 exec, exec, s[30:31]
	v_add_u32_e32 v52, 0xa0, v154
	v_ashrrev_i32_e32 v53, 31, v52
	v_lshlrev_b64 v[32:33], 3, v[52:53]
	s_waitcnt lgkmcnt(0)
	v_lshl_add_u64 v[34:35], s[12:13], 0, v[32:33]
	flat_load_dwordx2 v[54:55], v[34:35]
	v_lshlrev_b64 v[34:35], 12, v[52:53]
	v_lshl_add_u64 v[34:35], s[46:47], 0, v[34:35]
	v_lshl_add_u64 v[34:35], v[144:145], 2, v[34:35]
	global_load_dwordx4 v[36:39], v[34:35], off
	global_load_dwordx4 v[40:43], v[150:151], off
	global_load_dwordx4 v[44:47], v[152:153], off
	global_load_dwordx4 v[48:51], v[34:35], off offset:16
	s_waitcnt vmcnt(0) lgkmcnt(0)
	v_pk_mul_f32 v[54:55], v[54:55], s[24:25] op_sel:[1,0] op_sel_hi:[0,0]
	v_fma_f32 v54, -v55, v55, v54
	v_max_f32_e32 v54, 0, v54
	v_add_f32_e32 v54, 0x3727c5ac, v54
	v_mul_f32_e32 v56, 0x4b800000, v54
	v_cmp_gt_f32_e32 vcc, s61, v54
	v_sub_f32_e32 v37, v37, v55
	v_sub_f32_e32 v36, v36, v55
	v_cndmask_b32_e32 v54, v54, v56, vcc
	v_rsq_f32_e32 v54, v54
	v_sub_f32_e32 v39, v39, v55
	v_sub_f32_e32 v38, v38, v55
	v_mul_f32_e32 v56, 0x45800000, v54
	v_cndmask_b32_e32 v54, v54, v56, vcc
	v_pk_mul_f32 v[38:39], v[38:39], v[54:55] op_sel_hi:[1,0]
	v_pk_mul_f32 v[36:37], v[36:37], v[54:55] op_sel_hi:[1,0]
	v_pk_fma_f32 v[38:39], v[42:43], v[38:39], v[46:47]
	v_pk_fma_f32 v[36:37], v[40:41], v[36:37], v[44:45]
	v_pk_fma_f32 v[30:31], v[38:39], s[26:27], v[30:31] op_sel_hi:[1,0,1]
	v_pk_fma_f32 v[28:29], v[36:37], s[26:27], v[28:29] op_sel_hi:[1,0,1]
	global_store_dwordx4 v[34:35], v[28:31], off
	global_load_dwordx4 v[36:39], v[146:147], off
	global_load_dwordx4 v[40:43], v[148:149], off
	v_lshlrev_b64 v[44:45], 11, v[52:53]
	v_lshl_add_u64 v[44:45], s[14:15], 0, v[44:45]
	v_lshl_add_u64 v[52:53], v[144:145], 1, v[44:45]
	v_sub_f32_e32 v45, v49, v55
	v_sub_f32_e32 v44, v48, v55
	v_sub_f32_e32 v47, v51, v55
	v_sub_f32_e32 v46, v50, v55
	v_pk_mul_f32 v[46:47], v[46:47], v[54:55] op_sel_hi:[1,0]
	v_pk_mul_f32 v[48:49], v[44:45], v[54:55] op_sel_hi:[1,0]
	v_cvt_pk_bf16_f32 v44, v28, v29
	v_cvt_pk_bf16_f32 v45, v30, v31
	s_waitcnt vmcnt(0)
	v_pk_fma_f32 v[38:39], v[38:39], v[46:47], v[42:43]
	v_pk_fma_f32 v[36:37], v[36:37], v[48:49], v[40:41]
	v_pk_fma_f32 v[26:27], v[38:39], s[26:27], v[26:27] op_sel_hi:[1,0,1]
	v_pk_fma_f32 v[24:25], v[36:37], s[26:27], v[24:25] op_sel_hi:[1,0,1]
	global_store_dwordx4 v[34:35], v[24:27], off offset:16
	v_cvt_pk_bf16_f32 v46, v24, v25
	v_cvt_pk_bf16_f32 v47, v26, v27
	flat_store_dwordx4 v[52:53], v[44:47]
	global_load_dwordx4 v[36:39], v[34:35], off offset:512
	global_load_dwordx4 v[40:43], v[120:121], off
	s_nop 0
	global_load_dwordx4 v[44:47], v[122:123], off
	global_load_dwordx4 v[48:51], v[34:35], off offset:528
	s_waitcnt vmcnt(0)
	v_sub_f32_e32 v37, v37, v55
	v_sub_f32_e32 v36, v36, v55
	v_sub_f32_e32 v39, v39, v55
	v_sub_f32_e32 v38, v38, v55
	v_pk_mul_f32 v[38:39], v[54:55], v[38:39] op_sel_hi:[0,1]
	v_pk_mul_f32 v[36:37], v[54:55], v[36:37] op_sel_hi:[0,1]
	v_pk_fma_f32 v[36:37], v[40:41], v[36:37], v[44:45]
	v_pk_fma_f32 v[38:39], v[42:43], v[38:39], v[46:47]
	v_pk_fma_f32 v[20:21], v[36:37], s[26:27], v[20:21] op_sel_hi:[1,0,1]
	v_pk_fma_f32 v[22:23], v[38:39], s[26:27], v[22:23] op_sel_hi:[1,0,1]
	global_store_dwordx4 v[34:35], v[20:23], off offset:512
	global_load_dwordx4 v[36:39], v[124:125], off
	global_load_dwordx4 v[40:43], v[126:127], off
	v_add_f32_e32 v44, v28, v29
	v_mul_f32_e32 v29, v29, v29
	v_fmac_f32_e32 v29, v28, v28
	v_add_f32_e32 v44, v30, v44
	v_fmac_f32_e32 v29, v30, v30
	v_add_f32_e32 v30, v24, v25
	v_mul_f32_e32 v25, v25, v25
	v_fmac_f32_e32 v25, v24, v24
	v_add_f32_e32 v28, v31, v44
	v_add_f32_e32 v30, v26, v30
	v_fmac_f32_e32 v25, v26, v26
	v_add_f32_e32 v28, 0, v28
	v_fmac_f32_e32 v29, v31, v31
	v_add_f32_e32 v24, v27, v30
	v_fmac_f32_e32 v25, v27, v27
	v_add_f32_e32 v28, v24, v28
	v_add_f32_e32 v29, v29, v25
	v_sub_f32_e32 v25, v49, v55
	v_sub_f32_e32 v24, v48, v55
	v_pk_mul_f32 v[24:25], v[54:55], v[24:25] op_sel_hi:[0,1]
	v_sub_f32_e32 v27, v51, v55
	v_sub_f32_e32 v26, v50, v55
	v_pk_mul_f32 v[26:27], v[54:55], v[26:27] op_sel_hi:[0,1]
	v_mul_f32_e32 v31, v21, v21
	v_add_f32_e32 v30, v20, v21
	v_fmac_f32_e32 v31, v20, v20
	v_add_f32_e32 v30, v22, v30
	v_fmac_f32_e32 v31, v22, v22
	v_add_f32_e32 v30, v23, v30
	v_fmac_f32_e32 v31, v23, v23
	v_add_f32_e32 v28, v28, v30
	v_add_f32_e32 v29, v29, v31
	v_cvt_pk_bf16_f32 v20, v20, v21
	v_cvt_pk_bf16_f32 v21, v22, v23
	s_waitcnt vmcnt(0)
	v_pk_fma_f32 v[24:25], v[36:37], v[24:25], v[40:41]
	s_nop 0
	v_pk_fma_f32 v[24:25], v[24:25], s[26:27], v[16:17] op_sel_hi:[1,0,1]
	v_pk_fma_f32 v[26:27], v[38:39], v[26:27], v[42:43]
	v_mul_f32_e32 v17, v25, v25
	v_pk_fma_f32 v[26:27], v[26:27], s[26:27], v[18:19] op_sel_hi:[1,0,1]
	v_add_f32_e32 v16, v24, v25
	v_fmac_f32_e32 v17, v24, v24
	v_add_f32_e32 v16, v26, v16
	v_fmac_f32_e32 v17, v26, v26
	v_add_f32_e32 v16, v27, v16
	v_fmac_f32_e32 v17, v27, v27
	v_add_f32_e32 v16, v28, v16
	v_add_f32_e32 v17, v29, v17
	ds_bpermute_b32 v18, v116, v16
	ds_bpermute_b32 v19, v116, v17
	global_store_dwordx4 v[34:35], v[24:27], off offset:528
	v_cvt_pk_bf16_f32 v22, v24, v25
	v_cvt_pk_bf16_f32 v23, v26, v27
	s_waitcnt lgkmcnt(0)
	v_add_f32_e32 v16, v16, v18
	v_add_f32_e32 v17, v17, v19
	ds_bpermute_b32 v18, v117, v16
	ds_bpermute_b32 v19, v117, v17
	flat_store_dwordx4 v[52:53], v[20:23] offset:256
	s_mov_b32 s100, -1
	s_mov_b32 s101, 0
	s_mov_b32 s98, 0xffff0000
	s_mov_b32 s99, 0
	s_and_saveexec_b64 s[30:31], s[100:101]
	s_cbranch_execz .LBB0_1552
	v_lshl_add_u64 v[20:21], s[10:11], 0, v[32:33]
	s_waitcnt lgkmcnt(0)
	v_add_f32_e32 v16, v16, v18
	v_add_f32_e32 v17, v17, v19
	v_cndmask_b32_e64 v16, v16, v17, s[98:99]
	v_cndmask_b32_e64 v17, 0, 4, s[98:99]
	v_or_b32_e32 v20, v20, v17
	v_mov_b32_e32 v254, v16
; DEVI unsigned pk2(float lo, float hi) { unsigned r; asm("v_cvt_pk_bf16_f32 %0, %1, %2" : "=v"(r) : "v"(lo), "v"(hi)); return r; }
;     DEVI void operator()(const f32x4 (&acc)[2][2][4][2], const pg8::Unit& u, int wr, int wc, int fr, int fq) const {
;     ...
;                 const int row = row0 + ai * 128 + m * 16; float mu, rs; row_stats(stin, row, mu, rs);
;                 float sum = 0.f, sq = 0.f;
; #pragma unroll
;                 for (int bj = 0; bj < 2; ++bj) {
;                     f32x4 z[2];
; #pragma unroll
;                     for (int n = 0; n < 2; ++n) {
;                         const int col = colb + bj * 128 + 4 * n;
;                         f32x4 xv = *(const f32x4*)(zsrc + (size_t)row * DM + col);
;                         if (stin) { const f32x4 gv = *(const f32x4*)(gin + col), bv = *(const f32x4*)(bin + col); xv = (xv - mu) * rs * gv + bv; }
;                         f32x4 zz = ALPHA * xv + acc[ai][bj][m][n];
;                         if (bias) zz += *(const f32x4*)(bias + col);
;                         *(f32x4*)(zdst + (size_t)row * DM + col) = zz;
;                         sum += zz[0] + zz[1] + zz[2] + zz[3]; sq += zz[0] * zz[0] + zz[1] * zz[1] + zz[2] * zz[2] + zz[3] * zz[3];
;                         z[n] = zz;
;                     }
;                     u32x4 o; o.x = pk2(z[0][0], z[0][1]); o.y = pk2(z[0][2], z[0][3]); o.z = pk2(z[1][0], z[1][1]); o.w = pk2(z[1][2], z[1][3]);
;                     if (zb) *(u32x4*)(zb + (size_t)row * DM + colb + bj * 128) = o;
;                 }
;                 sum += __shfl_xor(sum, 16); sq += __shfl_xor(sq, 16);
;                 sum += __shfl_xor(sum, 32); sq += __shfl_xor(sq, 32);
;                 if (fq == 0) { atomicAdd(stout + 2 * (size_t)row, sum); atomicAdd(stout + 2 * (size_t)row + 1, sq); }
.LBB0_1552:
	s_or_b64 exec, exec, s[30:31]
	v_add_u32_e32 v36, 0xb0, v154
	v_ashrrev_i32_e32 v37, 31, v36
	v_lshlrev_b64 v[16:17], 3, v[36:37]
	s_waitcnt lgkmcnt(0)
	v_lshl_add_u64 v[18:19], s[12:13], 0, v[16:17]
	flat_load_dwordx2 v[38:39], v[18:19]
	v_lshlrev_b64 v[18:19], 12, v[36:37]
	v_lshl_add_u64 v[18:19], s[46:47], 0, v[18:19]
	v_lshl_add_u64 v[18:19], v[144:145], 2, v[18:19]
	global_load_dwordx4 v[20:23], v[18:19], off
	global_load_dwordx4 v[24:27], v[150:151], off
	global_load_dwordx4 v[28:31], v[152:153], off
	global_load_dwordx4 v[32:35], v[18:19], off offset:16
	s_waitcnt vmcnt(0) lgkmcnt(0)
	v_pk_mul_f32 v[38:39], v[38:39], s[24:25] op_sel:[1,0] op_sel_hi:[0,0]
	v_fma_f32 v38, -v39, v39, v38
	v_max_f32_e32 v38, 0, v38
	v_add_f32_e32 v38, 0x3727c5ac, v38
	v_mul_f32_e32 v40, 0x4b800000, v38
	v_cmp_gt_f32_e32 vcc, s61, v38
	v_sub_f32_e32 v21, v21, v39
	v_sub_f32_e32 v20, v20, v39
	v_cndmask_b32_e32 v38, v38, v40, vcc
	v_rsq_f32_e32 v38, v38
	v_sub_f32_e32 v23, v23, v39
	v_sub_f32_e32 v22, v22, v39
	v_mul_f32_e32 v40, 0x45800000, v38
	v_cndmask_b32_e32 v38, v38, v40, vcc
	v_pk_mul_f32 v[22:23], v[22:23], v[38:39] op_sel_hi:[1,0]
	v_pk_mul_f32 v[20:21], v[20:21], v[38:39] op_sel_hi:[1,0]
	v_pk_fma_f32 v[22:23], v[26:27], v[22:23], v[30:31]
	v_pk_fma_f32 v[20:21], v[24:25], v[20:21], v[28:29]
	v_pk_fma_f32 v[14:15], v[22:23], s[26:27], v[14:15] op_sel_hi:[1,0,1]
	v_pk_fma_f32 v[12:13], v[20:21], s[26:27], v[12:13] op_sel_hi:[1,0,1]
	global_store_dwordx4 v[18:19], v[12:15], off
	global_load_dwordx4 v[20:23], v[146:147], off
	global_load_dwordx4 v[24:27], v[148:149], off
	v_lshlrev_b64 v[28:29], 11, v[36:37]
	v_lshl_add_u64 v[28:29], s[14:15], 0, v[28:29]
	v_lshl_add_u64 v[36:37], v[144:145], 1, v[28:29]
	v_sub_f32_e32 v29, v33, v39
	v_sub_f32_e32 v28, v32, v39
	v_sub_f32_e32 v31, v35, v39
	v_sub_f32_e32 v30, v34, v39
	v_pk_mul_f32 v[30:31], v[30:31], v[38:39] op_sel_hi:[1,0]
	v_pk_mul_f32 v[32:33], v[28:29], v[38:39] op_sel_hi:[1,0]
	v_cvt_pk_bf16_f32 v28, v12, v13
	v_cvt_pk_bf16_f32 v29, v14, v15
	s_waitcnt vmcnt(0)
	v_pk_fma_f32 v[22:23], v[22:23], v[30:31], v[26:27]
	v_pk_fma_f32 v[20:21], v[20:21], v[32:33], v[24:25]
	v_pk_fma_f32 v[10:11], v[22:23], s[26:27], v[10:11] op_sel_hi:[1,0,1]
	v_pk_fma_f32 v[8:9], v[20:21], s[26:27], v[8:9] op_sel_hi:[1,0,1]
	global_store_dwordx4 v[18:19], v[8:11], off offset:16
	v_cvt_pk_bf16_f32 v30, v8, v9
	v_cvt_pk_bf16_f32 v31, v10, v11
	flat_store_dwordx4 v[36:37], v[28:31]
	global_load_dwordx4 v[20:23], v[18:19], off offset:512
	global_load_dwordx4 v[24:27], v[120:121], off
	s_nop 0
	global_load_dwordx4 v[28:31], v[122:123], off
	global_load_dwordx4 v[32:35], v[18:19], off offset:528
	s_waitcnt vmcnt(0)
	v_sub_f32_e32 v21, v21, v39
	v_sub_f32_e32 v20, v20, v39
	v_sub_f32_e32 v23, v23, v39
	v_sub_f32_e32 v22, v22, v39
	v_pk_mul_f32 v[22:23], v[38:39], v[22:23] op_sel_hi:[0,1]
	v_pk_mul_f32 v[20:21], v[38:39], v[20:21] op_sel_hi:[0,1]
	v_pk_fma_f32 v[20:21], v[24:25], v[20:21], v[28:29]
	v_pk_fma_f32 v[22:23], v[26:27], v[22:23], v[30:31]
	v_pk_fma_f32 v[4:5], v[20:21], s[26:27], v[4:5] op_sel_hi:[1,0,1]
	v_pk_fma_f32 v[6:7], v[22:23], s[26:27], v[6:7] op_sel_hi:[1,0,1]
	global_store_dwordx4 v[18:19], v[4:7], off offset:512
	global_load_dwordx4 v[20:23], v[124:125], off
	global_load_dwordx4 v[24:27], v[126:127], off
	v_add_f32_e32 v28, v12, v13
	v_mul_f32_e32 v13, v13, v13
	v_fmac_f32_e32 v13, v12, v12
	v_add_f32_e32 v28, v14, v28
	v_fmac_f32_e32 v13, v14, v14
	v_add_f32_e32 v14, v8, v9
	v_mul_f32_e32 v9, v9, v9
	v_fmac_f32_e32 v9, v8, v8
	v_add_f32_e32 v12, v15, v28
	v_add_f32_e32 v14, v10, v14
	v_fmac_f32_e32 v9, v10, v10
	v_add_f32_e32 v12, 0, v12
	v_fmac_f32_e32 v13, v15, v15
	v_add_f32_e32 v8, v11, v14
	v_fmac_f32_e32 v9, v11, v11
	v_add_f32_e32 v12, v8, v12
	v_add_f32_e32 v13, v13, v9
	v_sub_f32_e32 v9, v33, v39
	v_sub_f32_e32 v8, v32, v39
	v_pk_mul_f32 v[8:9], v[38:39], v[8:9] op_sel_hi:[0,1]
	v_sub_f32_e32 v11, v35, v39
	v_sub_f32_e32 v10, v34, v39
	v_pk_mul_f32 v[10:11], v[38:39], v[10:11] op_sel_hi:[0,1]
	v_mul_f32_e32 v15, v5, v5
	v_add_f32_e32 v14, v4, v5
	v_fmac_f32_e32 v15, v4, v4
	v_add_f32_e32 v14, v6, v14
	v_fmac_f32_e32 v15, v6, v6
	v_add_f32_e32 v14, v7, v14
	v_fmac_f32_e32 v15, v7, v7
	v_add_f32_e32 v12, v12, v14
	v_add_f32_e32 v13, v13, v15
	v_cvt_pk_bf16_f32 v4, v4, v5
	v_cvt_pk_bf16_f32 v5, v6, v7
	s_waitcnt vmcnt(0)
	v_pk_fma_f32 v[8:9], v[20:21], v[8:9], v[24:25]
	s_nop 0
	v_pk_fma_f32 v[8:9], v[8:9], s[26:27], v[0:1] op_sel_hi:[1,0,1]
	v_pk_fma_f32 v[10:11], v[22:23], v[10:11], v[26:27]
	v_mul_f32_e32 v1, v9, v9
	v_pk_fma_f32 v[10:11], v[10:11], s[26:27], v[2:3] op_sel_hi:[1,0,1]
	v_add_f32_e32 v0, v8, v9
	v_fmac_f32_e32 v1, v8, v8
	v_add_f32_e32 v0, v10, v0
	v_fmac_f32_e32 v1, v10, v10
	v_add_f32_e32 v0, v11, v0
	v_fmac_f32_e32 v1, v11, v11
	v_add_f32_e32 v0, v12, v0
	v_add_f32_e32 v1, v13, v1
	ds_bpermute_b32 v2, v116, v0
	ds_bpermute_b32 v3, v116, v1
	global_store_dwordx4 v[18:19], v[8:11], off offset:528
	v_cvt_pk_bf16_f32 v6, v8, v9
	v_cvt_pk_bf16_f32 v7, v10, v11
	s_waitcnt lgkmcnt(0)
	v_add_f32_e32 v0, v0, v2
	v_add_f32_e32 v1, v1, v3
	ds_bpermute_b32 v2, v117, v0
	ds_bpermute_b32 v3, v117, v1
	flat_store_dwordx4 v[36:37], v[4:7] offset:256
	s_mov_b32 s100, -1
	s_mov_b32 s101, 0
	s_mov_b32 s98, 0xffff0000
	s_mov_b32 s99, 0
	s_and_saveexec_b64 s[30:31], s[100:101]
	s_cbranch_execz .LBB0_1554
	v_lshl_add_u64 v[4:5], s[10:11], 0, v[16:17]
	s_waitcnt lgkmcnt(0)
	v_add_f32_e32 v0, v0, v2
	v_add_f32_e32 v1, v1, v3
	v_cndmask_b32_e64 v0, v0, v1, s[98:99]
	v_cndmask_b32_e64 v1, 0, 4, s[98:99]
	v_or_b32_e32 v4, v4, v1
	v_mov_b32_e32 v255, v0
	flat_atomic_add_f32 v[250:251], v252
	flat_atomic_add_f32 v[250:251], v253 offset:128
	flat_atomic_add_f32 v[250:251], v254 offset:256
	flat_atomic_add_f32 v[250:251], v255 offset:384

; DEVI void row_stats(const float* stats, int row, float& mu, float& rs) {
;     if (stats) { const float2 st = *(const float2*)(stats + 2 * (size_t)row); mu = st.x * (1.0f / 1024.0f); const float var = st.y * (1.0f / 1024.0f) - mu * mu; rs = rsqrtf(fmaxf(var, 0.f) + LN_EPS); }
;     DEVI void operator()(const f32x4 (&acc)[2][2][4][2], const pg8::Unit& u, int wr, int wc, int fr, int fq) const {
;     ...
;                 const int row = row0 + ai * 128 + m * 16; float mu, rs; row_stats(stin, row, mu, rs);
;                 float sum = 0.f, sq = 0.f;
; #pragma unroll
;                 for (int bj = 0; bj < 2; ++bj) {
;                     f32x4 z[2];
; #pragma unroll
;                     for (int n = 0; n < 2; ++n) {
;                         const int col = colb + bj * 128 + 4 * n;
;                         f32x4 xv = *(const f32x4*)(zsrc + (size_t)row * DM + col);
;                         if (stin) { const f32x4 gv = *(const f32x4*)(gin + col), bv = *(const f32x4*)(bin + col); xv = (xv - mu) * rs * gv + bv; }
;                         f32x4 zz = ALPHA * xv + acc[ai][bj][m][n];
;                         if (bias) zz += *(const f32x4*)(bias + col);
;                         *(f32x4*)(zdst + (size_t)row * DM + col) = zz;
;                         sum += zz[0] + zz[1] + zz[2] + zz[3]; sq += zz[0] * zz[0] + zz[1] * zz[1] + zz[2] * zz[2] + zz[3] * zz[3];
.LBB0_1983:
	v_lshl_add_u32 v154, s36, 8, v168
	v_ashrrev_i32_e32 v155, 31, v154
	v_lshlrev_b64 v[162:163], 3, v[154:155]
	v_lshl_add_u64 v[146:147], s[6:7], 0, v[162:163]
	s_waitcnt vmcnt(0)
	flat_load_dwordx2 v[166:167], v[146:147]
	v_lshl_or_b32 v144, s38, 8, v170
	v_ashrrev_i32_e32 v145, 31, v144
	v_lshlrev_b64 v[146:147], 12, v[154:155]
	v_lshl_add_u64 v[146:147], s[46:47], 0, v[146:147]
	v_lshlrev_b64 v[148:149], 2, v[144:145]
	v_lshl_add_u64 v[164:165], v[146:147], 0, v[148:149]
	global_load_dwordx4 v[158:161], v[164:165], off
	v_lshl_add_u64 v[150:151], s[12:13], 0, v[148:149]
	v_lshl_add_u64 v[152:153], s[14:15], 0, v[148:149]
	global_load_dwordx4 v[176:179], v[150:151], off
	global_load_dwordx4 v[180:183], v[152:153], off
	v_lshl_add_u64 v[156:157], s[16:17], 0, v[148:149]
	global_load_dwordx4 v[184:187], v[156:157], off
	global_load_dwordx4 v[188:191], v[164:165], off offset:16
	v_or_b32_e32 v146, 4, v144
	v_ashrrev_i32_e32 v147, 31, v146
	v_lshlrev_b64 v[192:193], 2, v[146:147]
	v_lshl_add_u64 v[146:147], s[12:13], 0, v[192:193]
	v_lshl_add_u64 v[148:149], s[14:15], 0, v[192:193]
	s_waitcnt vmcnt(0) lgkmcnt(0)
	v_pk_mul_f32 v[166:167], v[166:167], s[22:23] op_sel:[1,0] op_sel_hi:[0,0]
	v_fma_f32 v166, -v167, v167, v166
	v_max_f32_e32 v166, 0, v166
	v_add_f32_e32 v166, 0x3727c5ac, v166
	v_mul_f32_e32 v175, 0x4b800000, v166
	v_cmp_gt_f32_e32 vcc, s72, v166
	v_sub_f32_e32 v161, v161, v167
	s_nop 0
	v_cndmask_b32_e32 v166, v166, v175, vcc
	v_rsq_f32_e32 v166, v166
	v_sub_f32_e32 v160, v160, v167
	v_sub_f32_e32 v159, v159, v167
	v_sub_f32_e32 v158, v158, v167
	v_mul_f32_e32 v175, 0x45800000, v166
	v_cndmask_b32_e32 v166, v166, v175, vcc
	v_pk_mul_f32 v[158:159], v[158:159], v[166:167] op_sel_hi:[1,0]
	v_pk_mul_f32 v[160:161], v[160:161], v[166:167] op_sel_hi:[1,0]
	v_pk_fma_f32 v[158:159], v[176:177], v[158:159], v[180:181]
	v_pk_fma_f32 v[160:161], v[178:179], v[160:161], v[182:183]
	v_pk_fma_f32 v[124:125], v[158:159], s[24:25], v[124:125] op_sel_hi:[1,0,1]
	v_pk_fma_f32 v[126:127], v[160:161], s[24:25], v[126:127] op_sel_hi:[1,0,1]
	v_pk_add_f32 v[176:177], v[184:185], v[124:125]
	v_pk_add_f32 v[178:179], v[186:187], v[126:127]
	global_store_dwordx4 v[164:165], v[176:179], off
	global_load_dwordx4 v[158:161], v[146:147], off
	global_load_dwordx4 v[180:183], v[148:149], off
	v_lshl_add_u64 v[124:125], s[16:17], 0, v[192:193]
	global_load_dwordx4 v[184:187], v[124:125], off
	v_lshlrev_b64 v[192:193], 11, v[154:155]
	v_lshl_add_u64 v[192:193], s[10:11], 0, v[192:193]
	v_sub_f32_e32 v191, v191, v167
	v_sub_f32_e32 v190, v190, v167
	v_sub_f32_e32 v189, v189, v167
	v_sub_f32_e32 v188, v188, v167
	v_lshl_add_u64 v[204:205], v[144:145], 1, v[192:193]
	v_pk_mul_f32 v[192:193], v[188:189], v[166:167] op_sel_hi:[1,0]
	v_pk_mul_f32 v[190:191], v[190:191], v[166:167] op_sel_hi:[1,0]
	v_or_b32_e32 v126, 0x80, v144
	v_cvt_pk_bf16_f32 v188, v176, v177
	v_cvt_pk_bf16_f32 v189, v178, v179
	v_ashrrev_i32_e32 v127, 31, v126
	v_xor_b32_e32 v155, 32, v174
	v_mul_f32_e32 v175, v177, v177
	v_fmac_f32_e32 v175, v176, v176
	v_fmac_f32_e32 v175, v178, v178
	v_fmac_f32_e32 v175, v179, v179
	s_waitcnt vmcnt(1)
	v_pk_fma_f32 v[160:161], v[160:161], v[190:191], v[182:183]
	v_pk_fma_f32 v[158:159], v[158:159], v[192:193], v[180:181]
	v_pk_fma_f32 v[122:123], v[160:161], s[24:25], v[122:123] op_sel_hi:[1,0,1]
	v_pk_fma_f32 v[120:121], v[158:159], s[24:25], v[120:121] op_sel_hi:[1,0,1]
	s_waitcnt vmcnt(0)
	v_pk_add_f32 v[182:183], v[186:187], v[122:123]
	v_pk_add_f32 v[180:181], v[184:185], v[120:121]
	global_store_dwordx4 v[164:165], v[180:183], off offset:16
	v_cvt_pk_bf16_f32 v190, v180, v181
	v_cvt_pk_bf16_f32 v191, v182, v183
	flat_store_dwordx4 v[204:205], v[188:191]
	global_load_dwordx4 v[184:187], v[164:165], off offset:512
	v_lshlrev_b64 v[120:121], 2, v[126:127]
	v_lshl_add_u64 v[126:127], s[12:13], 0, v[120:121]
	v_lshl_add_u64 v[158:159], s[14:15], 0, v[120:121]
	global_load_dwordx4 v[188:191], v[126:127], off
	global_load_dwordx4 v[192:195], v[158:159], off
	v_lshl_add_u64 v[160:161], s[16:17], 0, v[120:121]
	global_load_dwordx4 v[196:199], v[160:161], off
	global_load_dwordx4 v[200:203], v[164:165], off offset:528
	v_or_b32_e32 v120, 0x84, v144
	v_ashrrev_i32_e32 v121, 31, v120
	v_lshlrev_b64 v[206:207], 2, v[120:121]
	v_lshl_add_u64 v[120:121], s[12:13], 0, v[206:207]
	v_lshl_add_u64 v[122:123], s[14:15], 0, v[206:207]
	s_waitcnt vmcnt(0)
	v_sub_f32_e32 v187, v187, v167
	v_sub_f32_e32 v186, v186, v167
	v_sub_f32_e32 v185, v185, v167
	v_sub_f32_e32 v184, v184, v167
	v_pk_mul_f32 v[184:185], v[166:167], v[184:185] op_sel_hi:[0,1]
	v_pk_mul_f32 v[186:187], v[166:167], v[186:187] op_sel_hi:[0,1]
	v_pk_fma_f32 v[186:187], v[190:191], v[186:187], v[194:195]
	v_pk_fma_f32 v[184:185], v[188:189], v[184:185], v[192:193]
	v_pk_fma_f32 v[118:119], v[186:187], s[24:25], v[118:119] op_sel_hi:[1,0,1]
	v_pk_fma_f32 v[116:117], v[184:185], s[24:25], v[116:117] op_sel_hi:[1,0,1]
	v_pk_add_f32 v[186:187], v[198:199], v[118:119]
	v_pk_add_f32 v[184:185], v[196:197], v[116:117]
	global_store_dwordx4 v[164:165], v[184:187], off offset:512
	global_load_dwordx4 v[188:191], v[120:121], off
	global_load_dwordx4 v[192:195], v[122:123], off
	v_lshl_add_u64 v[116:117], s[16:17], 0, v[206:207]
	global_load_dwordx4 v[196:199], v[116:117], off
	v_and_b32_e32 v119, 64, v174
	v_xor_b32_e32 v118, 16, v174
	v_add_u32_e32 v119, 64, v119
	v_cmp_lt_i32_e32 vcc, v118, v119
	s_nop 1
	v_cndmask_b32_e32 v118, v174, v118, vcc
	v_cmp_lt_i32_e32 vcc, v155, v119
	v_lshlrev_b32_e32 v118, 2, v118
	s_nop 0
	v_cndmask_b32_e32 v119, v174, v155, vcc
	v_add_f32_e32 v155, v176, v177
	v_mul_f32_e32 v177, v181, v181
	v_add_f32_e32 v155, v178, v155
	v_add_f32_e32 v176, v180, v181
	v_fmac_f32_e32 v177, v180, v180
	v_add_f32_e32 v155, v179, v155
	v_add_f32_e32 v176, v182, v176
	v_fmac_f32_e32 v177, v182, v182
	v_add_f32_e32 v155, 0, v155
	v_add_f32_e32 v176, v183, v176
	v_fmac_f32_e32 v177, v183, v183
	v_add_f32_e32 v155, v176, v155
	v_add_f32_e32 v175, v175, v177
	v_sub_f32_e32 v177, v203, v167
	v_sub_f32_e32 v176, v202, v167
	v_sub_f32_e32 v179, v201, v167
	v_sub_f32_e32 v178, v200, v167
	v_pk_mul_f32 v[178:179], v[166:167], v[178:179] op_sel_hi:[0,1]
	v_pk_mul_f32 v[166:167], v[166:167], v[176:177] op_sel_hi:[0,1]
	v_mul_f32_e32 v177, v185, v185
	v_add_f32_e32 v176, v184, v185
	v_fmac_f32_e32 v177, v184, v184
	v_add_f32_e32 v176, v186, v176
	v_fmac_f32_e32 v177, v186, v186
	v_add_f32_e32 v176, v187, v176
	v_fmac_f32_e32 v177, v187, v187
	v_add_f32_e32 v155, v155, v176
	v_add_f32_e32 v175, v175, v177
	v_lshlrev_b32_e32 v119, 2, v119
	v_cvt_pk_bf16_f32 v180, v184, v185
	v_cvt_pk_bf16_f32 v181, v186, v187
	s_waitcnt vmcnt(0)
; DEVI unsigned pk2(float lo, float hi) { unsigned r; asm("v_cvt_pk_bf16_f32 %0, %1, %2" : "=v"(r) : "v"(lo), "v"(hi)); return r; }
;     DEVI void operator()(const f32x4 (&acc)[2][2][4][2], const pg8::Unit& u, int wr, int wc, int fr, int fq) const {
;     ...
;                 const int row = row0 + ai * 128 + m * 16; float mu, rs; row_stats(stin, row, mu, rs);
;                 float sum = 0.f, sq = 0.f;
; #pragma unroll
;                 for (int bj = 0; bj < 2; ++bj) {
;                     f32x4 z[2];
; #pragma unroll
;                     for (int n = 0; n < 2; ++n) {
;                         const int col = colb + bj * 128 + 4 * n;
;                         f32x4 xv = *(const f32x4*)(zsrc + (size_t)row * DM + col);
;                         if (stin) { const f32x4 gv = *(const f32x4*)(gin + col), bv = *(const f32x4*)(bin + col); xv = (xv - mu) * rs * gv + bv; }
;                         f32x4 zz = ALPHA * xv + acc[ai][bj][m][n];
;                         if (bias) zz += *(const f32x4*)(bias + col);
;                         *(f32x4*)(zdst + (size_t)row * DM + col) = zz;
;                         sum += zz[0] + zz[1] + zz[2] + zz[3]; sq += zz[0] * zz[0] + zz[1] * zz[1] + zz[2] * zz[2] + zz[3] * zz[3];
;                         z[n] = zz;
;                     }
;                     u32x4 o; o.x = pk2(z[0][0], z[0][1]); o.y = pk2(z[0][2], z[0][3]); o.z = pk2(z[1][0], z[1][1]); o.w = pk2(z[1][2], z[1][3]);
;                     if (zb) *(u32x4*)(zb + (size_t)row * DM + colb + bj * 128) = o;
;                 }
;                 sum += __shfl_xor(sum, 16); sq += __shfl_xor(sq, 16);
;                 sum += __shfl_xor(sum, 32); sq += __shfl_xor(sq, 32);
;                 if (fq == 0) { atomicAdd(stout + 2 * (size_t)row, sum); atomicAdd(stout + 2 * (size_t)row + 1, sq); }
	v_pk_fma_f32 v[176:177], v[188:189], v[178:179], v[192:193]
	s_nop 0
	v_pk_fma_f32 v[112:113], v[176:177], s[24:25], v[112:113] op_sel_hi:[1,0,1]
	v_pk_fma_f32 v[166:167], v[190:191], v[166:167], v[194:195]
	v_pk_add_f32 v[176:177], v[196:197], v[112:113]
	v_pk_fma_f32 v[114:115], v[166:167], s[24:25], v[114:115] op_sel_hi:[1,0,1]
	v_mul_f32_e32 v113, v177, v177
	v_pk_add_f32 v[178:179], v[198:199], v[114:115]
	v_add_f32_e32 v112, v176, v177
	v_fmac_f32_e32 v113, v176, v176
	v_add_f32_e32 v112, v178, v112
	v_fmac_f32_e32 v113, v178, v178
	v_add_f32_e32 v112, v179, v112
	v_fmac_f32_e32 v113, v179, v179
	v_add_f32_e32 v112, v155, v112
	v_add_f32_e32 v113, v175, v113
	ds_bpermute_b32 v114, v118, v112
	ds_bpermute_b32 v115, v118, v113
	global_store_dwordx4 v[164:165], v[176:179], off offset:528
	v_cvt_pk_bf16_f32 v182, v176, v177
	v_cvt_pk_bf16_f32 v183, v178, v179
	s_waitcnt lgkmcnt(0)
	v_add_f32_e32 v112, v112, v114
	v_add_f32_e32 v113, v113, v115
	ds_bpermute_b32 v114, v119, v112
	ds_bpermute_b32 v115, v119, v113
	flat_store_dwordx4 v[204:205], v[180:183] offset:256
	s_mov_b32 s100, -1
	s_mov_b32 s101, 0
	s_mov_b32 s98, 0xffff0000
	s_mov_b32 s99, 0
	s_and_saveexec_b64 s[36:37], s[100:101]
	s_cbranch_execz .LBB0_1985
	s_waitcnt lgkmcnt(0)
	v_add_f32_e32 v115, v113, v115
	v_add_f32_e32 v114, v112, v114
	v_lshl_add_u64 v[112:113], s[8:9], 0, v[162:163]
	v_cndmask_b32_e64 v114, v114, v115, s[98:99]
	v_cndmask_b32_e64 v115, 0, 4, s[98:99]
	v_or_b32_e32 v112, v112, v115
	v_mov_b32_e32 v250, v112
	v_mov_b32_e32 v251, v113
	v_mov_b32_e32 v252, v114
.LBB0_1985:
	s_or_b64 exec, exec, s[36:37]
	v_or_b32_e32 v166, 16, v154
	v_ashrrev_i32_e32 v167, 31, v166
	v_lshlrev_b64 v[112:113], 3, v[166:167]
	s_waitcnt lgkmcnt(0)
	v_lshl_add_u64 v[114:115], s[6:7], 0, v[112:113]
	flat_load_dwordx2 v[192:193], v[114:115]
	v_lshlrev_b64 v[114:115], 12, v[166:167]
	v_lshl_add_u64 v[114:115], s[46:47], 0, v[114:115]
	v_lshl_add_u64 v[114:115], v[144:145], 2, v[114:115]
	global_load_dwordx4 v[162:165], v[114:115], off
	global_load_dwordx4 v[176:179], v[150:151], off
	global_load_dwordx4 v[180:183], v[152:153], off
	global_load_dwordx4 v[184:187], v[156:157], off
	global_load_dwordx4 v[188:191], v[114:115], off offset:16
	v_lshlrev_b64 v[166:167], 11, v[166:167]
	v_lshl_add_u64 v[166:167], s[10:11], 0, v[166:167]
	v_lshl_add_u64 v[166:167], v[144:145], 1, v[166:167]
	s_waitcnt vmcnt(0) lgkmcnt(0)
	v_pk_mul_f32 v[192:193], v[192:193], s[22:23] op_sel:[1,0] op_sel_hi:[0,0]
	v_fma_f32 v155, -v193, v193, v192
	v_max_f32_e32 v155, 0, v155
	v_add_f32_e32 v155, 0x3727c5ac, v155
	v_mul_f32_e32 v175, 0x4b800000, v155
	v_cmp_gt_f32_e32 vcc, s72, v155
	v_sub_f32_e32 v165, v165, v193
	v_sub_f32_e32 v164, v164, v193
	v_cndmask_b32_e32 v155, v155, v175, vcc
	v_rsq_f32_e32 v155, v155
	v_sub_f32_e32 v163, v163, v193
	v_sub_f32_e32 v162, v162, v193
	v_mul_f32_e32 v175, 0x45800000, v155
	v_cndmask_b32_e32 v192, v155, v175, vcc
	v_pk_mul_f32 v[162:163], v[162:163], v[192:193] op_sel_hi:[1,0]
	v_pk_mul_f32 v[164:165], v[164:165], v[192:193] op_sel_hi:[1,0]
	v_pk_fma_f32 v[162:163], v[176:177], v[162:163], v[180:181]
	v_pk_fma_f32 v[164:165], v[178:179], v[164:165], v[182:183]
	v_pk_fma_f32 v[108:109], v[162:163], s[24:25], v[108:109] op_sel_hi:[1,0,1]
	v_pk_fma_f32 v[110:111], v[164:165], s[24:25], v[110:111] op_sel_hi:[1,0,1]
	v_pk_add_f32 v[108:109], v[184:185], v[108:109]
	v_pk_add_f32 v[110:111], v[186:187], v[110:111]
	global_store_dwordx4 v[114:115], v[108:111], off
	global_load_dwordx4 v[162:165], v[146:147], off
	global_load_dwordx4 v[176:179], v[148:149], off
	global_load_dwordx4 v[180:183], v[124:125], off
	v_sub_f32_e32 v185, v191, v193
	v_sub_f32_e32 v184, v190, v193
	v_sub_f32_e32 v187, v189, v193
	v_sub_f32_e32 v186, v188, v193
	v_pk_mul_f32 v[186:187], v[186:187], v[192:193] op_sel_hi:[1,0]
	v_pk_mul_f32 v[188:189], v[184:185], v[192:193] op_sel_hi:[1,0]
	v_cvt_pk_bf16_f32 v184, v108, v109
	v_cvt_pk_bf16_f32 v185, v110, v111
	v_add_f32_e32 v155, v108, v109
	v_mul_f32_e32 v109, v109, v109
	v_fmac_f32_e32 v109, v108, v108
	v_add_f32_e32 v155, v110, v155
	v_fmac_f32_e32 v109, v110, v110
	v_add_f32_e32 v108, v111, v155
	v_add_f32_e32 v108, 0, v108
	v_fmac_f32_e32 v109, v111, v111
	s_waitcnt vmcnt(1)
	v_pk_fma_f32 v[164:165], v[164:165], v[188:189], v[178:179]
	v_pk_fma_f32 v[162:163], v[162:163], v[186:187], v[176:177]
	v_pk_fma_f32 v[106:107], v[164:165], s[24:25], v[106:107] op_sel_hi:[1,0,1]
	v_pk_fma_f32 v[104:105], v[162:163], s[24:25], v[104:105] op_sel_hi:[1,0,1]
	s_waitcnt vmcnt(0)
	v_pk_add_f32 v[106:107], v[182:183], v[106:107]
	v_pk_add_f32 v[104:105], v[180:181], v[104:105]
	global_store_dwordx4 v[114:115], v[104:107], off offset:16
	v_cvt_pk_bf16_f32 v186, v104, v105
	v_cvt_pk_bf16_f32 v187, v106, v107
	flat_store_dwordx4 v[166:167], v[184:187]
	global_load_dwordx4 v[162:165], v[114:115], off offset:512
	global_load_dwordx4 v[176:179], v[126:127], off
	global_load_dwordx4 v[180:183], v[158:159], off
	s_nop 0
	global_load_dwordx4 v[184:187], v[160:161], off
	global_load_dwordx4 v[188:191], v[114:115], off offset:528
	v_add_f32_e32 v110, v104, v105
	v_mul_f32_e32 v105, v105, v105
	v_fmac_f32_e32 v105, v104, v104
	v_add_f32_e32 v110, v106, v110
	v_fmac_f32_e32 v105, v106, v106
	v_add_f32_e32 v104, v107, v110
	v_fmac_f32_e32 v105, v107, v107
	v_add_f32_e32 v108, v104, v108
	v_add_f32_e32 v109, v109, v105
	s_waitcnt vmcnt(0)
; DEVI unsigned pk2(float lo, float hi) { unsigned r; asm("v_cvt_pk_bf16_f32 %0, %1, %2" : "=v"(r) : "v"(lo), "v"(hi)); return r; }
;     DEVI void operator()(const f32x4 (&acc)[2][2][4][2], const pg8::Unit& u, int wr, int wc, int fr, int fq) const {
;     ...
;                 const int row = row0 + ai * 128 + m * 16; float mu, rs; row_stats(stin, row, mu, rs);
;                 float sum = 0.f, sq = 0.f;
; #pragma unroll
;                 for (int bj = 0; bj < 2; ++bj) {
;                     f32x4 z[2];
; #pragma unroll
;                     for (int n = 0; n < 2; ++n) {
;                         const int col = colb + bj * 128 + 4 * n;
;                         f32x4 xv = *(const f32x4*)(zsrc + (size_t)row * DM + col);
;                         if (stin) { const f32x4 gv = *(const f32x4*)(gin + col), bv = *(const f32x4*)(bin + col); xv = (xv - mu) * rs * gv + bv; }
;                         f32x4 zz = ALPHA * xv + acc[ai][bj][m][n];
;                         if (bias) zz += *(const f32x4*)(bias + col);
;                         *(f32x4*)(zdst + (size_t)row * DM + col) = zz;
;                         sum += zz[0] + zz[1] + zz[2] + zz[3]; sq += zz[0] * zz[0] + zz[1] * zz[1] + zz[2] * zz[2] + zz[3] * zz[3];
;                         z[n] = zz;
;                     }
;                     u32x4 o; o.x = pk2(z[0][0], z[0][1]); o.y = pk2(z[0][2], z[0][3]); o.z = pk2(z[1][0], z[1][1]); o.w = pk2(z[1][2], z[1][3]);
;                     if (zb) *(u32x4*)(zb + (size_t)row * DM + colb + bj * 128) = o;
;                 }
;                 sum += __shfl_xor(sum, 16); sq += __shfl_xor(sq, 16);
;                 sum += __shfl_xor(sum, 32); sq += __shfl_xor(sq, 32);
;                 if (fq == 0) { atomicAdd(stout + 2 * (size_t)row, sum); atomicAdd(stout + 2 * (size_t)row + 1, sq); }
	v_sub_f32_e32 v165, v165, v193
	v_sub_f32_e32 v164, v164, v193
	v_sub_f32_e32 v163, v163, v193
	v_sub_f32_e32 v162, v162, v193
	v_pk_mul_f32 v[162:163], v[192:193], v[162:163] op_sel_hi:[0,1]
	v_pk_mul_f32 v[164:165], v[192:193], v[164:165] op_sel_hi:[0,1]
	v_pk_fma_f32 v[164:165], v[178:179], v[164:165], v[182:183]
	v_pk_fma_f32 v[162:163], v[176:177], v[162:163], v[180:181]
	v_pk_fma_f32 v[102:103], v[164:165], s[24:25], v[102:103] op_sel_hi:[1,0,1]
	v_pk_fma_f32 v[100:101], v[162:163], s[24:25], v[100:101] op_sel_hi:[1,0,1]
	v_pk_add_f32 v[102:103], v[186:187], v[102:103]
	v_pk_add_f32 v[100:101], v[184:185], v[100:101]
	global_store_dwordx4 v[114:115], v[100:103], off offset:512
	global_load_dwordx4 v[162:165], v[120:121], off
	global_load_dwordx4 v[176:179], v[122:123], off
	global_load_dwordx4 v[180:183], v[116:117], off
	v_sub_f32_e32 v107, v189, v193
	v_sub_f32_e32 v106, v188, v193
	v_sub_f32_e32 v105, v191, v193
	v_sub_f32_e32 v104, v190, v193
	v_pk_mul_f32 v[106:107], v[192:193], v[106:107] op_sel_hi:[0,1]
	v_pk_mul_f32 v[104:105], v[192:193], v[104:105] op_sel_hi:[0,1]
	v_mul_f32_e32 v111, v101, v101
	v_add_f32_e32 v110, v100, v101
	v_fmac_f32_e32 v111, v100, v100
	v_add_f32_e32 v110, v102, v110
	v_fmac_f32_e32 v111, v102, v102
	v_add_f32_e32 v110, v103, v110
	v_fmac_f32_e32 v111, v103, v103
	v_add_f32_e32 v108, v108, v110
	v_add_f32_e32 v109, v109, v111
	v_cvt_pk_bf16_f32 v100, v100, v101
	v_cvt_pk_bf16_f32 v101, v102, v103
	s_waitcnt vmcnt(0)
	v_pk_fma_f32 v[106:107], v[162:163], v[106:107], v[176:177]
	v_pk_fma_f32 v[104:105], v[164:165], v[104:105], v[178:179]
	v_pk_fma_f32 v[96:97], v[106:107], s[24:25], v[96:97] op_sel_hi:[1,0,1]
	v_pk_fma_f32 v[98:99], v[104:105], s[24:25], v[98:99] op_sel_hi:[1,0,1]
	v_pk_add_f32 v[104:105], v[180:181], v[96:97]
	v_pk_add_f32 v[106:107], v[182:183], v[98:99]
	v_mul_f32_e32 v97, v105, v105
	v_add_f32_e32 v96, v104, v105
	v_fmac_f32_e32 v97, v104, v104
	v_add_f32_e32 v96, v106, v96
	v_fmac_f32_e32 v97, v106, v106
	v_add_f32_e32 v96, v107, v96
	v_fmac_f32_e32 v97, v107, v107
	v_add_f32_e32 v96, v108, v96
	v_add_f32_e32 v97, v109, v97
	ds_bpermute_b32 v98, v118, v96
	ds_bpermute_b32 v99, v118, v97
	global_store_dwordx4 v[114:115], v[104:107], off offset:528
	v_cvt_pk_bf16_f32 v102, v104, v105
	v_cvt_pk_bf16_f32 v103, v106, v107
	s_waitcnt lgkmcnt(0)
	v_add_f32_e32 v96, v96, v98
	v_add_f32_e32 v97, v97, v99
	ds_bpermute_b32 v98, v119, v96
	ds_bpermute_b32 v99, v119, v97
	flat_store_dwordx4 v[166:167], v[100:103] offset:256
	s_mov_b32 s100, -1
	s_mov_b32 s101, 0
	s_mov_b32 s98, 0xffff0000
	s_mov_b32 s99, 0
	s_and_saveexec_b64 s[36:37], s[100:101]
	s_cbranch_execz .LBB0_1987
	s_waitcnt lgkmcnt(0)
	v_add_f32_e32 v99, v97, v99
	v_add_f32_e32 v98, v96, v98
	v_lshl_add_u64 v[96:97], s[8:9], 0, v[112:113]
	v_cndmask_b32_e64 v98, v98, v99, s[98:99]
	v_cndmask_b32_e64 v99, 0, 4, s[98:99]
	v_or_b32_e32 v96, v96, v99
	v_mov_b32_e32 v253, v98
.LBB0_1987:
	s_or_b64 exec, exec, s[36:37]
	v_or_b32_e32 v166, 32, v154
	v_ashrrev_i32_e32 v167, 31, v166
	v_lshlrev_b64 v[96:97], 3, v[166:167]
	s_waitcnt lgkmcnt(0)
	v_lshl_add_u64 v[98:99], s[6:7], 0, v[96:97]
	flat_load_dwordx2 v[176:177], v[98:99]
	v_lshlrev_b64 v[98:99], 12, v[166:167]
	v_lshl_add_u64 v[98:99], s[46:47], 0, v[98:99]
	v_lshl_add_u64 v[98:99], v[144:145], 2, v[98:99]
	global_load_dwordx4 v[100:103], v[98:99], off
	global_load_dwordx4 v[104:107], v[150:151], off
	global_load_dwordx4 v[108:111], v[152:153], off
	global_load_dwordx4 v[112:115], v[156:157], off
	global_load_dwordx4 v[162:165], v[98:99], off offset:16
	s_waitcnt vmcnt(0) lgkmcnt(0)
	v_pk_mul_f32 v[176:177], v[176:177], s[22:23] op_sel:[1,0] op_sel_hi:[0,0]
	v_fma_f32 v155, -v177, v177, v176
	v_max_f32_e32 v155, 0, v155
	v_add_f32_e32 v155, 0x3727c5ac, v155
	v_mul_f32_e32 v175, 0x4b800000, v155
	v_cmp_gt_f32_e32 vcc, s72, v155
	v_sub_f32_e32 v103, v103, v177
	v_sub_f32_e32 v102, v102, v177
	v_cndmask_b32_e32 v155, v155, v175, vcc
	v_rsq_f32_e32 v155, v155
	v_sub_f32_e32 v101, v101, v177
	v_sub_f32_e32 v100, v100, v177
	v_mul_f32_e32 v175, 0x45800000, v155
	v_cndmask_b32_e32 v176, v155, v175, vcc
	v_pk_mul_f32 v[100:101], v[100:101], v[176:177] op_sel_hi:[1,0]
	v_pk_mul_f32 v[102:103], v[102:103], v[176:177] op_sel_hi:[1,0]
	v_pk_fma_f32 v[100:101], v[104:105], v[100:101], v[108:109]
	v_pk_fma_f32 v[102:103], v[106:107], v[102:103], v[110:111]
	v_pk_fma_f32 v[92:93], v[100:101], s[24:25], v[92:93] op_sel_hi:[1,0,1]
	v_pk_fma_f32 v[94:95], v[102:103], s[24:25], v[94:95] op_sel_hi:[1,0,1]
	v_pk_add_f32 v[92:93], v[112:113], v[92:93]
	v_pk_add_f32 v[94:95], v[114:115], v[94:95]
	global_store_dwordx4 v[98:99], v[92:95], off
	global_load_dwordx4 v[100:103], v[146:147], off
	global_load_dwordx4 v[104:107], v[148:149], off
	global_load_dwordx4 v[108:111], v[124:125], off
	v_lshlrev_b64 v[112:113], 11, v[166:167]
	v_lshl_add_u64 v[112:113], s[10:11], 0, v[112:113]
	v_lshl_add_u64 v[166:167], v[144:145], 1, v[112:113]
	v_sub_f32_e32 v113, v165, v177
	v_sub_f32_e32 v112, v164, v177
	v_sub_f32_e32 v115, v163, v177
	v_sub_f32_e32 v114, v162, v177
	v_pk_mul_f32 v[114:115], v[114:115], v[176:177] op_sel_hi:[1,0]
	v_pk_mul_f32 v[162:163], v[112:113], v[176:177] op_sel_hi:[1,0]
	v_cvt_pk_bf16_f32 v112, v92, v93
	v_cvt_pk_bf16_f32 v113, v94, v95
	s_waitcnt vmcnt(1)
	v_pk_fma_f32 v[100:101], v[100:101], v[114:115], v[104:105]
	v_pk_fma_f32 v[102:103], v[102:103], v[162:163], v[106:107]
	v_pk_fma_f32 v[88:89], v[100:101], s[24:25], v[88:89] op_sel_hi:[1,0,1]
	v_pk_fma_f32 v[90:91], v[102:103], s[24:25], v[90:91] op_sel_hi:[1,0,1]
	s_waitcnt vmcnt(0)
; DEVI unsigned pk2(float lo, float hi) { unsigned r; asm("v_cvt_pk_bf16_f32 %0, %1, %2" : "=v"(r) : "v"(lo), "v"(hi)); return r; }
;     DEVI void operator()(const f32x4 (&acc)[2][2][4][2], const pg8::Unit& u, int wr, int wc, int fr, int fq) const {
;     ...
;                 const int row = row0 + ai * 128 + m * 16; float mu, rs; row_stats(stin, row, mu, rs);
;                 float sum = 0.f, sq = 0.f;
; #pragma unroll
;                 for (int bj = 0; bj < 2; ++bj) {
;                     f32x4 z[2];
; #pragma unroll
;                     for (int n = 0; n < 2; ++n) {
;                         const int col = colb + bj * 128 + 4 * n;
;                         f32x4 xv = *(const f32x4*)(zsrc + (size_t)row * DM + col);
;                         if (stin) { const f32x4 gv = *(const f32x4*)(gin + col), bv = *(const f32x4*)(bin + col); xv = (xv - mu) * rs * gv + bv; }
;                         f32x4 zz = ALPHA * xv + acc[ai][bj][m][n];
;                         if (bias) zz += *(const f32x4*)(bias + col);
;                         *(f32x4*)(zdst + (size_t)row * DM + col) = zz;
;                         sum += zz[0] + zz[1] + zz[2] + zz[3]; sq += zz[0] * zz[0] + zz[1] * zz[1] + zz[2] * zz[2] + zz[3] * zz[3];
;                         z[n] = zz;
;                     }
;                     u32x4 o; o.x = pk2(z[0][0], z[0][1]); o.y = pk2(z[0][2], z[0][3]); o.z = pk2(z[1][0], z[1][1]); o.w = pk2(z[1][2], z[1][3]);
;                     if (zb) *(u32x4*)(zb + (size_t)row * DM + colb + bj * 128) = o;
;                 }
;                 sum += __shfl_xor(sum, 16); sq += __shfl_xor(sq, 16);
;                 sum += __shfl_xor(sum, 32); sq += __shfl_xor(sq, 32);
;                 if (fq == 0) { atomicAdd(stout + 2 * (size_t)row, sum); atomicAdd(stout + 2 * (size_t)row + 1, sq); }
	v_pk_add_f32 v[88:89], v[108:109], v[88:89]
	v_pk_add_f32 v[90:91], v[110:111], v[90:91]
	global_store_dwordx4 v[98:99], v[88:91], off offset:16
	v_cvt_pk_bf16_f32 v114, v88, v89
	v_cvt_pk_bf16_f32 v115, v90, v91
	flat_store_dwordx4 v[166:167], v[112:115]
	global_load_dwordx4 v[100:103], v[98:99], off offset:512
	global_load_dwordx4 v[104:107], v[126:127], off
	global_load_dwordx4 v[108:111], v[158:159], off
	s_nop 0
	global_load_dwordx4 v[112:115], v[160:161], off
	global_load_dwordx4 v[162:165], v[98:99], off offset:528
	s_waitcnt vmcnt(0)
	v_sub_f32_e32 v103, v103, v177
	v_sub_f32_e32 v102, v102, v177
	v_sub_f32_e32 v101, v101, v177
	v_sub_f32_e32 v100, v100, v177
	v_pk_mul_f32 v[100:101], v[176:177], v[100:101] op_sel_hi:[0,1]
	v_pk_mul_f32 v[102:103], v[176:177], v[102:103] op_sel_hi:[0,1]
	v_pk_fma_f32 v[102:103], v[106:107], v[102:103], v[110:111]
	v_pk_fma_f32 v[100:101], v[104:105], v[100:101], v[108:109]
	v_pk_fma_f32 v[86:87], v[102:103], s[24:25], v[86:87] op_sel_hi:[1,0,1]
	v_pk_fma_f32 v[84:85], v[100:101], s[24:25], v[84:85] op_sel_hi:[1,0,1]
	v_pk_add_f32 v[86:87], v[114:115], v[86:87]
	v_pk_add_f32 v[84:85], v[112:113], v[84:85]
	global_store_dwordx4 v[98:99], v[84:87], off offset:512
	global_load_dwordx4 v[100:103], v[120:121], off
	global_load_dwordx4 v[104:107], v[122:123], off
	global_load_dwordx4 v[108:111], v[116:117], off
	v_add_f32_e32 v112, v92, v93
	v_mul_f32_e32 v93, v93, v93
	v_fmac_f32_e32 v93, v92, v92
	v_add_f32_e32 v112, v94, v112
	v_fmac_f32_e32 v93, v94, v94
	v_add_f32_e32 v94, v88, v89
	v_mul_f32_e32 v89, v89, v89
	v_fmac_f32_e32 v89, v88, v88
	v_add_f32_e32 v92, v95, v112
	v_add_f32_e32 v94, v90, v94
	v_fmac_f32_e32 v89, v90, v90
	v_add_f32_e32 v92, 0, v92
	v_fmac_f32_e32 v93, v95, v95
	v_add_f32_e32 v88, v91, v94
	v_fmac_f32_e32 v89, v91, v91
	v_sub_f32_e32 v91, v163, v177
	v_sub_f32_e32 v90, v162, v177
	v_add_f32_e32 v92, v88, v92
	v_add_f32_e32 v93, v93, v89
	v_sub_f32_e32 v89, v165, v177
	v_sub_f32_e32 v88, v164, v177
	v_pk_mul_f32 v[90:91], v[176:177], v[90:91] op_sel_hi:[0,1]
	v_pk_mul_f32 v[88:89], v[176:177], v[88:89] op_sel_hi:[0,1]
	v_mul_f32_e32 v95, v85, v85
	v_add_f32_e32 v94, v84, v85
	v_fmac_f32_e32 v95, v84, v84
	v_add_f32_e32 v94, v86, v94
	v_fmac_f32_e32 v95, v86, v86
	v_add_f32_e32 v94, v87, v94
	v_fmac_f32_e32 v95, v87, v87
	v_add_f32_e32 v92, v92, v94
	v_add_f32_e32 v93, v93, v95
	v_cvt_pk_bf16_f32 v84, v84, v85
	v_cvt_pk_bf16_f32 v85, v86, v87
	s_waitcnt vmcnt(0)
	v_pk_fma_f32 v[90:91], v[100:101], v[90:91], v[104:105]
	v_pk_fma_f32 v[88:89], v[102:103], v[88:89], v[106:107]
	v_pk_fma_f32 v[80:81], v[90:91], s[24:25], v[80:81] op_sel_hi:[1,0,1]
	v_pk_fma_f32 v[82:83], v[88:89], s[24:25], v[82:83] op_sel_hi:[1,0,1]
	v_pk_add_f32 v[88:89], v[108:109], v[80:81]
	v_pk_add_f32 v[90:91], v[110:111], v[82:83]
	v_mul_f32_e32 v81, v89, v89
	v_add_f32_e32 v80, v88, v89
	v_fmac_f32_e32 v81, v88, v88
	v_add_f32_e32 v80, v90, v80
	v_fmac_f32_e32 v81, v90, v90
	v_add_f32_e32 v80, v91, v80
	v_fmac_f32_e32 v81, v91, v91
	v_add_f32_e32 v80, v92, v80
	v_add_f32_e32 v81, v93, v81
	ds_bpermute_b32 v82, v118, v80
	ds_bpermute_b32 v83, v118, v81
	global_store_dwordx4 v[98:99], v[88:91], off offset:528
	v_cvt_pk_bf16_f32 v86, v88, v89
	v_cvt_pk_bf16_f32 v87, v90, v91
	s_waitcnt lgkmcnt(0)
	v_add_f32_e32 v80, v80, v82
	v_add_f32_e32 v81, v81, v83
	ds_bpermute_b32 v82, v119, v80
	ds_bpermute_b32 v83, v119, v81
	flat_store_dwordx4 v[166:167], v[84:87] offset:256
	s_mov_b32 s100, -1
	s_mov_b32 s101, 0
	s_mov_b32 s98, 0xffff0000
	s_mov_b32 s99, 0
	s_and_saveexec_b64 s[36:37], s[100:101]
	s_cbranch_execz .LBB0_1989
	s_waitcnt lgkmcnt(0)
	v_add_f32_e32 v83, v81, v83
	v_add_f32_e32 v82, v80, v82
	v_lshl_add_u64 v[80:81], s[8:9], 0, v[96:97]
	v_cndmask_b32_e64 v82, v82, v83, s[98:99]
	v_cndmask_b32_e64 v83, 0, 4, s[98:99]
	v_or_b32_e32 v80, v80, v83
	v_mov_b32_e32 v254, v82
.LBB0_1989:
	s_or_b64 exec, exec, s[36:37]
	v_or_b32_e32 v104, 48, v154
	v_ashrrev_i32_e32 v105, 31, v104
	v_lshlrev_b64 v[80:81], 3, v[104:105]
	s_waitcnt lgkmcnt(0)
	v_lshl_add_u64 v[82:83], s[6:7], 0, v[80:81]
	flat_load_dwordx2 v[106:107], v[82:83]
	v_lshlrev_b64 v[82:83], 12, v[104:105]
	v_lshl_add_u64 v[82:83], s[46:47], 0, v[82:83]
	v_lshl_add_u64 v[82:83], v[144:145], 2, v[82:83]
	global_load_dwordx4 v[84:87], v[82:83], off
	global_load_dwordx4 v[88:91], v[150:151], off
	global_load_dwordx4 v[92:95], v[152:153], off
	global_load_dwordx4 v[96:99], v[156:157], off
	global_load_dwordx4 v[100:103], v[82:83], off offset:16
	s_waitcnt vmcnt(0) lgkmcnt(0)
	v_pk_mul_f32 v[106:107], v[106:107], s[22:23] op_sel:[1,0] op_sel_hi:[0,0]
	v_fma_f32 v106, -v107, v107, v106
	v_max_f32_e32 v106, 0, v106
	v_add_f32_e32 v106, 0x3727c5ac, v106
	v_mul_f32_e32 v108, 0x4b800000, v106
	v_cmp_gt_f32_e32 vcc, s72, v106
	v_sub_f32_e32 v87, v87, v107
	v_sub_f32_e32 v86, v86, v107
	v_cndmask_b32_e32 v106, v106, v108, vcc
	v_rsq_f32_e32 v106, v106
	v_sub_f32_e32 v85, v85, v107
	v_sub_f32_e32 v84, v84, v107
	v_mul_f32_e32 v108, 0x45800000, v106
	v_cndmask_b32_e32 v106, v106, v108, vcc
	v_pk_mul_f32 v[84:85], v[84:85], v[106:107] op_sel_hi:[1,0]
	v_pk_mul_f32 v[86:87], v[86:87], v[106:107] op_sel_hi:[1,0]
	v_pk_fma_f32 v[84:85], v[88:89], v[84:85], v[92:93]
	v_pk_fma_f32 v[86:87], v[90:91], v[86:87], v[94:95]
	v_pk_fma_f32 v[76:77], v[84:85], s[24:25], v[76:77] op_sel_hi:[1,0,1]
	v_pk_fma_f32 v[78:79], v[86:87], s[24:25], v[78:79] op_sel_hi:[1,0,1]
	v_pk_add_f32 v[76:77], v[96:97], v[76:77]
	v_pk_add_f32 v[78:79], v[98:99], v[78:79]
	global_store_dwordx4 v[82:83], v[76:79], off
	global_load_dwordx4 v[84:87], v[146:147], off
	global_load_dwordx4 v[88:91], v[148:149], off
	global_load_dwordx4 v[92:95], v[124:125], off
	v_lshlrev_b64 v[96:97], 11, v[104:105]
	v_lshl_add_u64 v[96:97], s[10:11], 0, v[96:97]
	v_lshl_add_u64 v[104:105], v[144:145], 1, v[96:97]
	v_sub_f32_e32 v97, v103, v107
	v_sub_f32_e32 v96, v102, v107
	v_sub_f32_e32 v99, v101, v107
	v_sub_f32_e32 v98, v100, v107
	v_pk_mul_f32 v[98:99], v[98:99], v[106:107] op_sel_hi:[1,0]
	v_pk_mul_f32 v[100:101], v[96:97], v[106:107] op_sel_hi:[1,0]
	v_cvt_pk_bf16_f32 v96, v76, v77
	v_cvt_pk_bf16_f32 v97, v78, v79
	s_waitcnt vmcnt(1)
; DEVI unsigned pk2(float lo, float hi) { unsigned r; asm("v_cvt_pk_bf16_f32 %0, %1, %2" : "=v"(r) : "v"(lo), "v"(hi)); return r; }
;     DEVI void operator()(const f32x4 (&acc)[2][2][4][2], const pg8::Unit& u, int wr, int wc, int fr, int fq) const {
;     ...
;                 const int row = row0 + ai * 128 + m * 16; float mu, rs; row_stats(stin, row, mu, rs);
;                 float sum = 0.f, sq = 0.f;
; #pragma unroll
;                 for (int bj = 0; bj < 2; ++bj) {
;                     f32x4 z[2];
; #pragma unroll
;                     for (int n = 0; n < 2; ++n) {
;                         const int col = colb + bj * 128 + 4 * n;
;                         f32x4 xv = *(const f32x4*)(zsrc + (size_t)row * DM + col);
;                         if (stin) { const f32x4 gv = *(const f32x4*)(gin + col), bv = *(const f32x4*)(bin + col); xv = (xv - mu) * rs * gv + bv; }
;                         f32x4 zz = ALPHA * xv + acc[ai][bj][m][n];
;                         if (bias) zz += *(const f32x4*)(bias + col);
;                         *(f32x4*)(zdst + (size_t)row * DM + col) = zz;
;                         sum += zz[0] + zz[1] + zz[2] + zz[3]; sq += zz[0] * zz[0] + zz[1] * zz[1] + zz[2] * zz[2] + zz[3] * zz[3];
;                         z[n] = zz;
;                     }
;                     u32x4 o; o.x = pk2(z[0][0], z[0][1]); o.y = pk2(z[0][2], z[0][3]); o.z = pk2(z[1][0], z[1][1]); o.w = pk2(z[1][2], z[1][3]);
;                     if (zb) *(u32x4*)(zb + (size_t)row * DM + colb + bj * 128) = o;
;                 }
;                 sum += __shfl_xor(sum, 16); sq += __shfl_xor(sq, 16);
;                 sum += __shfl_xor(sum, 32); sq += __shfl_xor(sq, 32);
;                 if (fq == 0) { atomicAdd(stout + 2 * (size_t)row, sum); atomicAdd(stout + 2 * (size_t)row + 1, sq); }
	v_pk_fma_f32 v[84:85], v[84:85], v[98:99], v[88:89]
	v_pk_fma_f32 v[86:87], v[86:87], v[100:101], v[90:91]
	v_pk_fma_f32 v[72:73], v[84:85], s[24:25], v[72:73] op_sel_hi:[1,0,1]
	v_pk_fma_f32 v[74:75], v[86:87], s[24:25], v[74:75] op_sel_hi:[1,0,1]
	s_waitcnt vmcnt(0)
	v_pk_add_f32 v[72:73], v[92:93], v[72:73]
	v_pk_add_f32 v[74:75], v[94:95], v[74:75]
	global_store_dwordx4 v[82:83], v[72:75], off offset:16
	v_cvt_pk_bf16_f32 v98, v72, v73
	v_cvt_pk_bf16_f32 v99, v74, v75
	flat_store_dwordx4 v[104:105], v[96:99]
	global_load_dwordx4 v[84:87], v[82:83], off offset:512
	global_load_dwordx4 v[88:91], v[126:127], off
	global_load_dwordx4 v[92:95], v[158:159], off
	s_nop 0
	global_load_dwordx4 v[96:99], v[160:161], off
	global_load_dwordx4 v[100:103], v[82:83], off offset:528
	s_waitcnt vmcnt(0)
	v_sub_f32_e32 v87, v87, v107
	v_sub_f32_e32 v86, v86, v107
	v_sub_f32_e32 v85, v85, v107
	v_sub_f32_e32 v84, v84, v107
	v_pk_mul_f32 v[84:85], v[106:107], v[84:85] op_sel_hi:[0,1]
	v_pk_mul_f32 v[86:87], v[106:107], v[86:87] op_sel_hi:[0,1]
	v_pk_fma_f32 v[86:87], v[90:91], v[86:87], v[94:95]
	v_pk_fma_f32 v[84:85], v[88:89], v[84:85], v[92:93]
	v_pk_fma_f32 v[70:71], v[86:87], s[24:25], v[70:71] op_sel_hi:[1,0,1]
	v_pk_fma_f32 v[68:69], v[84:85], s[24:25], v[68:69] op_sel_hi:[1,0,1]
	v_pk_add_f32 v[70:71], v[98:99], v[70:71]
	v_pk_add_f32 v[68:69], v[96:97], v[68:69]
	global_store_dwordx4 v[82:83], v[68:71], off offset:512
	global_load_dwordx4 v[84:87], v[120:121], off
	global_load_dwordx4 v[88:91], v[122:123], off
	global_load_dwordx4 v[92:95], v[116:117], off
	v_add_f32_e32 v96, v76, v77
	v_mul_f32_e32 v77, v77, v77
	v_fmac_f32_e32 v77, v76, v76
	v_add_f32_e32 v96, v78, v96
	v_fmac_f32_e32 v77, v78, v78
	v_add_f32_e32 v78, v72, v73
	v_mul_f32_e32 v73, v73, v73
	v_fmac_f32_e32 v73, v72, v72
	v_add_f32_e32 v76, v79, v96
	v_add_f32_e32 v78, v74, v78
	v_fmac_f32_e32 v73, v74, v74
	v_add_f32_e32 v76, 0, v76
	v_fmac_f32_e32 v77, v79, v79
	v_add_f32_e32 v72, v75, v78
	v_fmac_f32_e32 v73, v75, v75
	v_sub_f32_e32 v75, v101, v107
	v_sub_f32_e32 v74, v100, v107
	v_add_f32_e32 v76, v72, v76
	v_add_f32_e32 v77, v77, v73
	v_sub_f32_e32 v73, v103, v107
	v_sub_f32_e32 v72, v102, v107
	v_pk_mul_f32 v[74:75], v[106:107], v[74:75] op_sel_hi:[0,1]
	v_pk_mul_f32 v[72:73], v[106:107], v[72:73] op_sel_hi:[0,1]
	v_mul_f32_e32 v79, v69, v69
	v_add_f32_e32 v78, v68, v69
	v_fmac_f32_e32 v79, v68, v68
	v_add_f32_e32 v78, v70, v78
	v_fmac_f32_e32 v79, v70, v70
	v_add_f32_e32 v78, v71, v78
	v_fmac_f32_e32 v79, v71, v71
	v_add_f32_e32 v76, v76, v78
	v_add_f32_e32 v77, v77, v79
	v_cvt_pk_bf16_f32 v68, v68, v69
	v_cvt_pk_bf16_f32 v69, v70, v71
	s_waitcnt vmcnt(0)
	v_pk_fma_f32 v[74:75], v[84:85], v[74:75], v[88:89]
	v_pk_fma_f32 v[72:73], v[86:87], v[72:73], v[90:91]
	v_pk_fma_f32 v[64:65], v[74:75], s[24:25], v[64:65] op_sel_hi:[1,0,1]
	v_pk_fma_f32 v[66:67], v[72:73], s[24:25], v[66:67] op_sel_hi:[1,0,1]
	v_pk_add_f32 v[72:73], v[92:93], v[64:65]
	v_pk_add_f32 v[74:75], v[94:95], v[66:67]
	v_mul_f32_e32 v65, v73, v73
	v_add_f32_e32 v64, v72, v73
	v_fmac_f32_e32 v65, v72, v72
	v_add_f32_e32 v64, v74, v64
	v_fmac_f32_e32 v65, v74, v74
	v_add_f32_e32 v64, v75, v64
	v_fmac_f32_e32 v65, v75, v75
	v_add_f32_e32 v64, v76, v64
	v_add_f32_e32 v65, v77, v65
	ds_bpermute_b32 v66, v118, v64
	ds_bpermute_b32 v67, v118, v65
	global_store_dwordx4 v[82:83], v[72:75], off offset:528
	v_cvt_pk_bf16_f32 v70, v72, v73
	v_cvt_pk_bf16_f32 v71, v74, v75
	s_waitcnt lgkmcnt(0)
	v_add_f32_e32 v64, v64, v66
	v_add_f32_e32 v65, v65, v67
	ds_bpermute_b32 v66, v119, v64
	ds_bpermute_b32 v67, v119, v65
	flat_store_dwordx4 v[104:105], v[68:71] offset:256
	s_mov_b32 s100, -1
	s_mov_b32 s101, 0
	s_mov_b32 s98, 0xffff0000
	s_mov_b32 s99, 0
	s_and_saveexec_b64 s[36:37], s[100:101]
	s_cbranch_execz .LBB0_1991
	s_waitcnt lgkmcnt(0)
	v_add_f32_e32 v67, v65, v67
	v_add_f32_e32 v66, v64, v66
	v_lshl_add_u64 v[64:65], s[8:9], 0, v[80:81]
	v_cndmask_b32_e64 v66, v66, v67, s[98:99]
	v_cndmask_b32_e64 v67, 0, 4, s[98:99]
	v_or_b32_e32 v64, v64, v67
	v_mov_b32_e32 v255, v66
	flat_atomic_add_f32 v[250:251], v252
	flat_atomic_add_f32 v[250:251], v253 offset:128
	flat_atomic_add_f32 v[250:251], v254 offset:256
	flat_atomic_add_f32 v[250:251], v255 offset:384
; DEVI unsigned pk2(float lo, float hi) { unsigned r; asm("v_cvt_pk_bf16_f32 %0, %1, %2" : "=v"(r) : "v"(lo), "v"(hi)); return r; }
;     DEVI void operator()(const f32x4 (&acc)[2][2][4][2], const pg8::Unit& u, int wr, int wc, int fr, int fq) const {
;     ...
;                 const int row = row0 + ai * 128 + m * 16; float mu, rs; row_stats(stin, row, mu, rs);
;                 float sum = 0.f, sq = 0.f;
; #pragma unroll
;                 for (int bj = 0; bj < 2; ++bj) {
;                     f32x4 z[2];
; #pragma unroll
;                     for (int n = 0; n < 2; ++n) {
;                         const int col = colb + bj * 128 + 4 * n;
;                         f32x4 xv = *(const f32x4*)(zsrc + (size_t)row * DM + col);
;                         if (stin) { const f32x4 gv = *(const f32x4*)(gin + col), bv = *(const f32x4*)(bin + col); xv = (xv - mu) * rs * gv + bv; }
;                         f32x4 zz = ALPHA * xv + acc[ai][bj][m][n];
;                         if (bias) zz += *(const f32x4*)(bias + col);
;                         *(f32x4*)(zdst + (size_t)row * DM + col) = zz;
;                         sum += zz[0] + zz[1] + zz[2] + zz[3]; sq += zz[0] * zz[0] + zz[1] * zz[1] + zz[2] * zz[2] + zz[3] * zz[3];
;                         z[n] = zz;
;                     }
;                     u32x4 o; o.x = pk2(z[0][0], z[0][1]); o.y = pk2(z[0][2], z[0][3]); o.z = pk2(z[1][0], z[1][1]); o.w = pk2(z[1][2], z[1][3]);
;                     if (zb) *(u32x4*)(zb + (size_t)row * DM + colb + bj * 128) = o;
;                 }
;                 sum += __shfl_xor(sum, 16); sq += __shfl_xor(sq, 16);
;                 sum += __shfl_xor(sum, 32); sq += __shfl_xor(sq, 32);
;                 if (fq == 0) { atomicAdd(stout + 2 * (size_t)row, sum); atomicAdd(stout + 2 * (size_t)row + 1, sq); }
.LBB0_1991:
	s_or_b64 exec, exec, s[36:37]
	v_add_u32_e32 v88, 0x80, v154
	v_ashrrev_i32_e32 v89, 31, v88
	v_lshlrev_b64 v[64:65], 3, v[88:89]
	s_waitcnt lgkmcnt(0)
	v_lshl_add_u64 v[66:67], s[6:7], 0, v[64:65]
	flat_load_dwordx2 v[90:91], v[66:67]
	v_lshlrev_b64 v[66:67], 12, v[88:89]
	v_lshl_add_u64 v[66:67], s[46:47], 0, v[66:67]
	v_lshl_add_u64 v[66:67], v[144:145], 2, v[66:67]
	global_load_dwordx4 v[68:71], v[66:67], off
	global_load_dwordx4 v[72:75], v[150:151], off
	global_load_dwordx4 v[76:79], v[152:153], off
	global_load_dwordx4 v[80:83], v[156:157], off
	global_load_dwordx4 v[84:87], v[66:67], off offset:16
	s_waitcnt vmcnt(0) lgkmcnt(0)
	v_pk_mul_f32 v[90:91], v[90:91], s[22:23] op_sel:[1,0] op_sel_hi:[0,0]
	v_fma_f32 v90, -v91, v91, v90
	v_max_f32_e32 v90, 0, v90
	v_add_f32_e32 v90, 0x3727c5ac, v90
	v_mul_f32_e32 v92, 0x4b800000, v90
	v_cmp_gt_f32_e32 vcc, s72, v90
	v_sub_f32_e32 v71, v71, v91
	v_sub_f32_e32 v70, v70, v91
	v_cndmask_b32_e32 v90, v90, v92, vcc
	v_rsq_f32_e32 v90, v90
	v_sub_f32_e32 v69, v69, v91
	v_sub_f32_e32 v68, v68, v91
	v_mul_f32_e32 v92, 0x45800000, v90
	v_cndmask_b32_e32 v90, v90, v92, vcc
	v_pk_mul_f32 v[68:69], v[68:69], v[90:91] op_sel_hi:[1,0]
	v_pk_mul_f32 v[70:71], v[70:71], v[90:91] op_sel_hi:[1,0]
	v_pk_fma_f32 v[68:69], v[72:73], v[68:69], v[76:77]
	v_pk_fma_f32 v[70:71], v[74:75], v[70:71], v[78:79]
	v_pk_fma_f32 v[60:61], v[68:69], s[24:25], v[60:61] op_sel_hi:[1,0,1]
	v_pk_fma_f32 v[62:63], v[70:71], s[24:25], v[62:63] op_sel_hi:[1,0,1]
	v_pk_add_f32 v[60:61], v[80:81], v[60:61]
	v_pk_add_f32 v[62:63], v[82:83], v[62:63]
	global_store_dwordx4 v[66:67], v[60:63], off
	global_load_dwordx4 v[68:71], v[146:147], off
	global_load_dwordx4 v[72:75], v[148:149], off
	global_load_dwordx4 v[76:79], v[124:125], off
	v_lshlrev_b64 v[80:81], 11, v[88:89]
	v_lshl_add_u64 v[80:81], s[10:11], 0, v[80:81]
	v_lshl_add_u64 v[88:89], v[144:145], 1, v[80:81]
	v_sub_f32_e32 v81, v87, v91
	v_sub_f32_e32 v80, v86, v91
	v_sub_f32_e32 v83, v85, v91
	v_sub_f32_e32 v82, v84, v91
	v_pk_mul_f32 v[82:83], v[82:83], v[90:91] op_sel_hi:[1,0]
	v_pk_mul_f32 v[84:85], v[80:81], v[90:91] op_sel_hi:[1,0]
	v_cvt_pk_bf16_f32 v80, v60, v61
	v_cvt_pk_bf16_f32 v81, v62, v63
	s_waitcnt vmcnt(1)
	v_pk_fma_f32 v[68:69], v[68:69], v[82:83], v[72:73]
	v_pk_fma_f32 v[70:71], v[70:71], v[84:85], v[74:75]
	v_pk_fma_f32 v[56:57], v[68:69], s[24:25], v[56:57] op_sel_hi:[1,0,1]
	v_pk_fma_f32 v[58:59], v[70:71], s[24:25], v[58:59] op_sel_hi:[1,0,1]
	s_waitcnt vmcnt(0)
	v_pk_add_f32 v[56:57], v[76:77], v[56:57]
	v_pk_add_f32 v[58:59], v[78:79], v[58:59]
	global_store_dwordx4 v[66:67], v[56:59], off offset:16
	v_cvt_pk_bf16_f32 v82, v56, v57
	v_cvt_pk_bf16_f32 v83, v58, v59
	flat_store_dwordx4 v[88:89], v[80:83]
	global_load_dwordx4 v[68:71], v[66:67], off offset:512
	global_load_dwordx4 v[72:75], v[126:127], off
	global_load_dwordx4 v[76:79], v[158:159], off
	s_nop 0
	global_load_dwordx4 v[80:83], v[160:161], off
	global_load_dwordx4 v[84:87], v[66:67], off offset:528
	s_waitcnt vmcnt(0)
	v_sub_f32_e32 v71, v71, v91
	v_sub_f32_e32 v70, v70, v91
	v_sub_f32_e32 v69, v69, v91
	v_sub_f32_e32 v68, v68, v91
	v_pk_mul_f32 v[68:69], v[90:91], v[68:69] op_sel_hi:[0,1]
	v_pk_mul_f32 v[70:71], v[90:91], v[70:71] op_sel_hi:[0,1]
	v_pk_fma_f32 v[70:71], v[74:75], v[70:71], v[78:79]
	v_pk_fma_f32 v[68:69], v[72:73], v[68:69], v[76:77]
	v_pk_fma_f32 v[54:55], v[70:71], s[24:25], v[54:55] op_sel_hi:[1,0,1]
	v_pk_fma_f32 v[52:53], v[68:69], s[24:25], v[52:53] op_sel_hi:[1,0,1]
	v_pk_add_f32 v[54:55], v[82:83], v[54:55]
	v_pk_add_f32 v[52:53], v[80:81], v[52:53]
	global_store_dwordx4 v[66:67], v[52:55], off offset:512
	global_load_dwordx4 v[68:71], v[120:121], off
	global_load_dwordx4 v[72:75], v[122:123], off
	global_load_dwordx4 v[76:79], v[116:117], off
	v_add_f32_e32 v80, v60, v61
	v_mul_f32_e32 v61, v61, v61
	v_fmac_f32_e32 v61, v60, v60
	v_add_f32_e32 v80, v62, v80
	v_fmac_f32_e32 v61, v62, v62
	v_add_f32_e32 v62, v56, v57
	v_mul_f32_e32 v57, v57, v57
	v_fmac_f32_e32 v57, v56, v56
	v_add_f32_e32 v60, v63, v80
	v_add_f32_e32 v62, v58, v62
	v_fmac_f32_e32 v57, v58, v58
	v_add_f32_e32 v60, 0, v60
	v_fmac_f32_e32 v61, v63, v63
	v_add_f32_e32 v56, v59, v62
	v_fmac_f32_e32 v57, v59, v59
	v_sub_f32_e32 v59, v85, v91
	v_sub_f32_e32 v58, v84, v91
	v_add_f32_e32 v60, v56, v60
	v_add_f32_e32 v61, v61, v57
	v_sub_f32_e32 v57, v87, v91
	v_sub_f32_e32 v56, v86, v91
	v_pk_mul_f32 v[58:59], v[90:91], v[58:59] op_sel_hi:[0,1]
	v_pk_mul_f32 v[56:57], v[90:91], v[56:57] op_sel_hi:[0,1]
	v_mul_f32_e32 v63, v53, v53
	v_add_f32_e32 v62, v52, v53
	v_fmac_f32_e32 v63, v52, v52
	v_add_f32_e32 v62, v54, v62
	v_fmac_f32_e32 v63, v54, v54
	v_add_f32_e32 v62, v55, v62
	v_fmac_f32_e32 v63, v55, v55
	v_add_f32_e32 v60, v60, v62
	v_add_f32_e32 v61, v61, v63
	v_cvt_pk_bf16_f32 v52, v52, v53
	v_cvt_pk_bf16_f32 v53, v54, v55
	s_waitcnt vmcnt(0)
	v_pk_fma_f32 v[58:59], v[68:69], v[58:59], v[72:73]
	v_pk_fma_f32 v[56:57], v[70:71], v[56:57], v[74:75]
	v_pk_fma_f32 v[48:49], v[58:59], s[24:25], v[48:49] op_sel_hi:[1,0,1]
	v_pk_fma_f32 v[50:51], v[56:57], s[24:25], v[50:51] op_sel_hi:[1,0,1]
	v_pk_add_f32 v[56:57], v[76:77], v[48:49]
	v_pk_add_f32 v[58:59], v[78:79], v[50:51]
	v_mul_f32_e32 v49, v57, v57
	v_add_f32_e32 v48, v56, v57
	v_fmac_f32_e32 v49, v56, v56
	v_add_f32_e32 v48, v58, v48
	v_fmac_f32_e32 v49, v58, v58
	v_add_f32_e32 v48, v59, v48
	v_fmac_f32_e32 v49, v59, v59
	v_add_f32_e32 v48, v60, v48
	v_add_f32_e32 v49, v61, v49
	ds_bpermute_b32 v50, v118, v48
	ds_bpermute_b32 v51, v118, v49
	global_store_dwordx4 v[66:67], v[56:59], off offset:528
	v_cvt_pk_bf16_f32 v54, v56, v57
	v_cvt_pk_bf16_f32 v55, v58, v59
	s_waitcnt lgkmcnt(0)
	v_add_f32_e32 v48, v48, v50
	v_add_f32_e32 v49, v49, v51
	ds_bpermute_b32 v50, v119, v48
	ds_bpermute_b32 v51, v119, v49
	flat_store_dwordx4 v[88:89], v[52:55] offset:256
	s_mov_b32 s100, -1
	s_mov_b32 s101, 0
	s_mov_b32 s98, 0xffff0000
	s_mov_b32 s99, 0
	s_and_saveexec_b64 s[36:37], s[100:101]
	s_cbranch_execz .LBB0_1993
	s_waitcnt lgkmcnt(0)
	v_add_f32_e32 v51, v49, v51
	v_add_f32_e32 v50, v48, v50
	v_lshl_add_u64 v[48:49], s[8:9], 0, v[64:65]
	v_cndmask_b32_e64 v50, v50, v51, s[98:99]
	v_cndmask_b32_e64 v51, 0, 4, s[98:99]
	v_or_b32_e32 v48, v48, v51
	v_mov_b32_e32 v250, v48
	v_mov_b32_e32 v251, v49
	v_mov_b32_e32 v252, v50
; DEVI unsigned pk2(float lo, float hi) { unsigned r; asm("v_cvt_pk_bf16_f32 %0, %1, %2" : "=v"(r) : "v"(lo), "v"(hi)); return r; }
;     DEVI void operator()(const f32x4 (&acc)[2][2][4][2], const pg8::Unit& u, int wr, int wc, int fr, int fq) const {
;     ...
;                 const int row = row0 + ai * 128 + m * 16; float mu, rs; row_stats(stin, row, mu, rs);
;                 float sum = 0.f, sq = 0.f;
; #pragma unroll
;                 for (int bj = 0; bj < 2; ++bj) {
;                     f32x4 z[2];
; #pragma unroll
;                     for (int n = 0; n < 2; ++n) {
;                         const int col = colb + bj * 128 + 4 * n;
;                         f32x4 xv = *(const f32x4*)(zsrc + (size_t)row * DM + col);
;                         if (stin) { const f32x4 gv = *(const f32x4*)(gin + col), bv = *(const f32x4*)(bin + col); xv = (xv - mu) * rs * gv + bv; }
;                         f32x4 zz = ALPHA * xv + acc[ai][bj][m][n];
;                         if (bias) zz += *(const f32x4*)(bias + col);
;                         *(f32x4*)(zdst + (size_t)row * DM + col) = zz;
;                         sum += zz[0] + zz[1] + zz[2] + zz[3]; sq += zz[0] * zz[0] + zz[1] * zz[1] + zz[2] * zz[2] + zz[3] * zz[3];
;                         z[n] = zz;
;                     }
;                     u32x4 o; o.x = pk2(z[0][0], z[0][1]); o.y = pk2(z[0][2], z[0][3]); o.z = pk2(z[1][0], z[1][1]); o.w = pk2(z[1][2], z[1][3]);
;                     if (zb) *(u32x4*)(zb + (size_t)row * DM + colb + bj * 128) = o;
;                 }
;                 sum += __shfl_xor(sum, 16); sq += __shfl_xor(sq, 16);
;                 sum += __shfl_xor(sum, 32); sq += __shfl_xor(sq, 32);
;                 if (fq == 0) { atomicAdd(stout + 2 * (size_t)row, sum); atomicAdd(stout + 2 * (size_t)row + 1, sq); }
.LBB0_1993:
	s_or_b64 exec, exec, s[36:37]
	v_add_u32_e32 v72, 0x90, v154
	v_ashrrev_i32_e32 v73, 31, v72
	v_lshlrev_b64 v[48:49], 3, v[72:73]
	s_waitcnt lgkmcnt(0)
	v_lshl_add_u64 v[50:51], s[6:7], 0, v[48:49]
	flat_load_dwordx2 v[74:75], v[50:51]
	v_lshlrev_b64 v[50:51], 12, v[72:73]
	v_lshl_add_u64 v[50:51], s[46:47], 0, v[50:51]
	v_lshl_add_u64 v[50:51], v[144:145], 2, v[50:51]
	global_load_dwordx4 v[52:55], v[50:51], off
	global_load_dwordx4 v[56:59], v[150:151], off
	global_load_dwordx4 v[60:63], v[152:153], off
	global_load_dwordx4 v[64:67], v[156:157], off
	global_load_dwordx4 v[68:71], v[50:51], off offset:16
	s_waitcnt vmcnt(0) lgkmcnt(0)
	v_pk_mul_f32 v[74:75], v[74:75], s[22:23] op_sel:[1,0] op_sel_hi:[0,0]
	v_fma_f32 v74, -v75, v75, v74
	v_max_f32_e32 v74, 0, v74
	v_add_f32_e32 v74, 0x3727c5ac, v74
	v_mul_f32_e32 v76, 0x4b800000, v74
	v_cmp_gt_f32_e32 vcc, s72, v74
	v_sub_f32_e32 v55, v55, v75
	v_sub_f32_e32 v54, v54, v75
	v_cndmask_b32_e32 v74, v74, v76, vcc
	v_rsq_f32_e32 v74, v74
	v_sub_f32_e32 v53, v53, v75
	v_sub_f32_e32 v52, v52, v75
	v_mul_f32_e32 v76, 0x45800000, v74
	v_cndmask_b32_e32 v74, v74, v76, vcc
	v_pk_mul_f32 v[52:53], v[52:53], v[74:75] op_sel_hi:[1,0]
	v_pk_mul_f32 v[54:55], v[54:55], v[74:75] op_sel_hi:[1,0]
	v_pk_fma_f32 v[52:53], v[56:57], v[52:53], v[60:61]
	v_pk_fma_f32 v[54:55], v[58:59], v[54:55], v[62:63]
	v_pk_fma_f32 v[44:45], v[52:53], s[24:25], v[44:45] op_sel_hi:[1,0,1]
	v_pk_fma_f32 v[46:47], v[54:55], s[24:25], v[46:47] op_sel_hi:[1,0,1]
	v_pk_add_f32 v[44:45], v[64:65], v[44:45]
	v_pk_add_f32 v[46:47], v[66:67], v[46:47]
	global_store_dwordx4 v[50:51], v[44:47], off
	global_load_dwordx4 v[52:55], v[146:147], off
	global_load_dwordx4 v[56:59], v[148:149], off
	global_load_dwordx4 v[60:63], v[124:125], off
	v_lshlrev_b64 v[64:65], 11, v[72:73]
	v_lshl_add_u64 v[64:65], s[10:11], 0, v[64:65]
	v_lshl_add_u64 v[72:73], v[144:145], 1, v[64:65]
	v_sub_f32_e32 v65, v71, v75
	v_sub_f32_e32 v64, v70, v75
	v_sub_f32_e32 v67, v69, v75
	v_sub_f32_e32 v66, v68, v75
	v_pk_mul_f32 v[66:67], v[66:67], v[74:75] op_sel_hi:[1,0]
	v_pk_mul_f32 v[68:69], v[64:65], v[74:75] op_sel_hi:[1,0]
	v_cvt_pk_bf16_f32 v64, v44, v45
	v_cvt_pk_bf16_f32 v65, v46, v47
	s_waitcnt vmcnt(1)
	v_pk_fma_f32 v[52:53], v[52:53], v[66:67], v[56:57]
	v_pk_fma_f32 v[54:55], v[54:55], v[68:69], v[58:59]
	v_pk_fma_f32 v[40:41], v[52:53], s[24:25], v[40:41] op_sel_hi:[1,0,1]
	v_pk_fma_f32 v[42:43], v[54:55], s[24:25], v[42:43] op_sel_hi:[1,0,1]
	s_waitcnt vmcnt(0)
	v_pk_add_f32 v[40:41], v[60:61], v[40:41]
	v_pk_add_f32 v[42:43], v[62:63], v[42:43]
	global_store_dwordx4 v[50:51], v[40:43], off offset:16
	v_cvt_pk_bf16_f32 v66, v40, v41
	v_cvt_pk_bf16_f32 v67, v42, v43
	flat_store_dwordx4 v[72:73], v[64:67]
	global_load_dwordx4 v[52:55], v[50:51], off offset:512
	global_load_dwordx4 v[56:59], v[126:127], off
	global_load_dwordx4 v[60:63], v[158:159], off
	s_nop 0
	global_load_dwordx4 v[64:67], v[160:161], off
	global_load_dwordx4 v[68:71], v[50:51], off offset:528
	s_waitcnt vmcnt(0)
	v_sub_f32_e32 v55, v55, v75
	v_sub_f32_e32 v54, v54, v75
	v_sub_f32_e32 v53, v53, v75
	v_sub_f32_e32 v52, v52, v75
	v_pk_mul_f32 v[52:53], v[74:75], v[52:53] op_sel_hi:[0,1]
	v_pk_mul_f32 v[54:55], v[74:75], v[54:55] op_sel_hi:[0,1]
	v_pk_fma_f32 v[54:55], v[58:59], v[54:55], v[62:63]
	v_pk_fma_f32 v[52:53], v[56:57], v[52:53], v[60:61]
	v_pk_fma_f32 v[38:39], v[54:55], s[24:25], v[38:39] op_sel_hi:[1,0,1]
	v_pk_fma_f32 v[36:37], v[52:53], s[24:25], v[36:37] op_sel_hi:[1,0,1]
	v_pk_add_f32 v[38:39], v[66:67], v[38:39]
	v_pk_add_f32 v[36:37], v[64:65], v[36:37]
	global_store_dwordx4 v[50:51], v[36:39], off offset:512
	global_load_dwordx4 v[52:55], v[120:121], off
	global_load_dwordx4 v[56:59], v[122:123], off
	global_load_dwordx4 v[60:63], v[116:117], off
	v_add_f32_e32 v64, v44, v45
	v_mul_f32_e32 v45, v45, v45
	v_fmac_f32_e32 v45, v44, v44
	v_add_f32_e32 v64, v46, v64
	v_fmac_f32_e32 v45, v46, v46
	v_add_f32_e32 v46, v40, v41
	v_mul_f32_e32 v41, v41, v41
	v_fmac_f32_e32 v41, v40, v40
	v_add_f32_e32 v44, v47, v64
	v_add_f32_e32 v46, v42, v46
	v_fmac_f32_e32 v41, v42, v42
	v_add_f32_e32 v44, 0, v44
	v_fmac_f32_e32 v45, v47, v47
	v_add_f32_e32 v40, v43, v46
	v_fmac_f32_e32 v41, v43, v43
	v_sub_f32_e32 v43, v69, v75
	v_sub_f32_e32 v42, v68, v75
	v_add_f32_e32 v44, v40, v44
	v_add_f32_e32 v45, v45, v41
	v_sub_f32_e32 v41, v71, v75
	v_sub_f32_e32 v40, v70, v75
	v_pk_mul_f32 v[42:43], v[74:75], v[42:43] op_sel_hi:[0,1]
	v_pk_mul_f32 v[40:41], v[74:75], v[40:41] op_sel_hi:[0,1]
	v_mul_f32_e32 v47, v37, v37
	v_add_f32_e32 v46, v36, v37
	v_fmac_f32_e32 v47, v36, v36
	v_add_f32_e32 v46, v38, v46
	v_fmac_f32_e32 v47, v38, v38
	v_add_f32_e32 v46, v39, v46
	v_fmac_f32_e32 v47, v39, v39
	v_add_f32_e32 v44, v44, v46
	v_add_f32_e32 v45, v45, v47
	v_cvt_pk_bf16_f32 v36, v36, v37
	v_cvt_pk_bf16_f32 v37, v38, v39
	s_waitcnt vmcnt(0)
	v_pk_fma_f32 v[42:43], v[52:53], v[42:43], v[56:57]
	v_pk_fma_f32 v[40:41], v[54:55], v[40:41], v[58:59]
	v_pk_fma_f32 v[32:33], v[42:43], s[24:25], v[32:33] op_sel_hi:[1,0,1]
	v_pk_fma_f32 v[34:35], v[40:41], s[24:25], v[34:35] op_sel_hi:[1,0,1]
	v_pk_add_f32 v[40:41], v[60:61], v[32:33]
	v_pk_add_f32 v[42:43], v[62:63], v[34:35]
	v_mul_f32_e32 v33, v41, v41
	v_add_f32_e32 v32, v40, v41
	v_fmac_f32_e32 v33, v40, v40
	v_add_f32_e32 v32, v42, v32
	v_fmac_f32_e32 v33, v42, v42
	v_add_f32_e32 v32, v43, v32
	v_fmac_f32_e32 v33, v43, v43
	v_add_f32_e32 v32, v44, v32
	v_add_f32_e32 v33, v45, v33
	ds_bpermute_b32 v34, v118, v32
	ds_bpermute_b32 v35, v118, v33
	global_store_dwordx4 v[50:51], v[40:43], off offset:528
	v_cvt_pk_bf16_f32 v38, v40, v41
	v_cvt_pk_bf16_f32 v39, v42, v43
	s_waitcnt lgkmcnt(0)
	v_add_f32_e32 v32, v32, v34
	v_add_f32_e32 v33, v33, v35
	ds_bpermute_b32 v34, v119, v32
	ds_bpermute_b32 v35, v119, v33
	flat_store_dwordx4 v[72:73], v[36:39] offset:256
	s_mov_b32 s100, -1
	s_mov_b32 s101, 0
	s_mov_b32 s98, 0xffff0000
	s_mov_b32 s99, 0
	s_and_saveexec_b64 s[36:37], s[100:101]
	s_cbranch_execz .LBB0_1995
	s_waitcnt lgkmcnt(0)
	v_add_f32_e32 v35, v33, v35
	v_add_f32_e32 v34, v32, v34
	v_lshl_add_u64 v[32:33], s[8:9], 0, v[48:49]
	v_cndmask_b32_e64 v34, v34, v35, s[98:99]
	v_cndmask_b32_e64 v35, 0, 4, s[98:99]
	v_or_b32_e32 v32, v32, v35
	v_mov_b32_e32 v253, v34
; DEVI unsigned pk2(float lo, float hi) { unsigned r; asm("v_cvt_pk_bf16_f32 %0, %1, %2" : "=v"(r) : "v"(lo), "v"(hi)); return r; }
;     DEVI void operator()(const f32x4 (&acc)[2][2][4][2], const pg8::Unit& u, int wr, int wc, int fr, int fq) const {
;     ...
;                 const int row = row0 + ai * 128 + m * 16; float mu, rs; row_stats(stin, row, mu, rs);
;                 float sum = 0.f, sq = 0.f;
; #pragma unroll
;                 for (int bj = 0; bj < 2; ++bj) {
;                     f32x4 z[2];
; #pragma unroll
;                     for (int n = 0; n < 2; ++n) {
;                         const int col = colb + bj * 128 + 4 * n;
;                         f32x4 xv = *(const f32x4*)(zsrc + (size_t)row * DM + col);
;                         if (stin) { const f32x4 gv = *(const f32x4*)(gin + col), bv = *(const f32x4*)(bin + col); xv = (xv - mu) * rs * gv + bv; }
;                         f32x4 zz = ALPHA * xv + acc[ai][bj][m][n];
;                         if (bias) zz += *(const f32x4*)(bias + col);
;                         *(f32x4*)(zdst + (size_t)row * DM + col) = zz;
;                         sum += zz[0] + zz[1] + zz[2] + zz[3]; sq += zz[0] * zz[0] + zz[1] * zz[1] + zz[2] * zz[2] + zz[3] * zz[3];
;                         z[n] = zz;
;                     }
;                     u32x4 o; o.x = pk2(z[0][0], z[0][1]); o.y = pk2(z[0][2], z[0][3]); o.z = pk2(z[1][0], z[1][1]); o.w = pk2(z[1][2], z[1][3]);
;                     if (zb) *(u32x4*)(zb + (size_t)row * DM + colb + bj * 128) = o;
;                 }
;                 sum += __shfl_xor(sum, 16); sq += __shfl_xor(sq, 16);
;                 sum += __shfl_xor(sum, 32); sq += __shfl_xor(sq, 32);
;                 if (fq == 0) { atomicAdd(stout + 2 * (size_t)row, sum); atomicAdd(stout + 2 * (size_t)row + 1, sq); }
.LBB0_1995:
	s_or_b64 exec, exec, s[36:37]
	v_add_u32_e32 v56, 0xa0, v154
	v_ashrrev_i32_e32 v57, 31, v56
	v_lshlrev_b64 v[32:33], 3, v[56:57]
	s_waitcnt lgkmcnt(0)
	v_lshl_add_u64 v[34:35], s[6:7], 0, v[32:33]
	flat_load_dwordx2 v[58:59], v[34:35]
	v_lshlrev_b64 v[34:35], 12, v[56:57]
	v_lshl_add_u64 v[34:35], s[46:47], 0, v[34:35]
	v_lshl_add_u64 v[34:35], v[144:145], 2, v[34:35]
	global_load_dwordx4 v[36:39], v[34:35], off
	global_load_dwordx4 v[40:43], v[150:151], off
	global_load_dwordx4 v[44:47], v[152:153], off
	global_load_dwordx4 v[48:51], v[156:157], off
	global_load_dwordx4 v[52:55], v[34:35], off offset:16
	s_waitcnt vmcnt(0) lgkmcnt(0)
	v_pk_mul_f32 v[58:59], v[58:59], s[22:23] op_sel:[1,0] op_sel_hi:[0,0]
	v_fma_f32 v58, -v59, v59, v58
	v_max_f32_e32 v58, 0, v58
	v_add_f32_e32 v58, 0x3727c5ac, v58
	v_mul_f32_e32 v60, 0x4b800000, v58
	v_cmp_gt_f32_e32 vcc, s72, v58
	v_sub_f32_e32 v39, v39, v59
	v_sub_f32_e32 v38, v38, v59
	v_cndmask_b32_e32 v58, v58, v60, vcc
	v_rsq_f32_e32 v58, v58
	v_sub_f32_e32 v37, v37, v59
	v_sub_f32_e32 v36, v36, v59
	v_mul_f32_e32 v60, 0x45800000, v58
	v_cndmask_b32_e32 v58, v58, v60, vcc
	v_pk_mul_f32 v[36:37], v[36:37], v[58:59] op_sel_hi:[1,0]
	v_pk_mul_f32 v[38:39], v[38:39], v[58:59] op_sel_hi:[1,0]
	v_pk_fma_f32 v[36:37], v[40:41], v[36:37], v[44:45]
	v_pk_fma_f32 v[38:39], v[42:43], v[38:39], v[46:47]
	v_pk_fma_f32 v[28:29], v[36:37], s[24:25], v[28:29] op_sel_hi:[1,0,1]
	v_pk_fma_f32 v[30:31], v[38:39], s[24:25], v[30:31] op_sel_hi:[1,0,1]
	v_pk_add_f32 v[28:29], v[48:49], v[28:29]
	v_pk_add_f32 v[30:31], v[50:51], v[30:31]
	global_store_dwordx4 v[34:35], v[28:31], off
	global_load_dwordx4 v[36:39], v[146:147], off
	global_load_dwordx4 v[40:43], v[148:149], off
	global_load_dwordx4 v[44:47], v[124:125], off
	v_lshlrev_b64 v[48:49], 11, v[56:57]
	v_lshl_add_u64 v[48:49], s[10:11], 0, v[48:49]
	v_lshl_add_u64 v[56:57], v[144:145], 1, v[48:49]
	v_sub_f32_e32 v49, v55, v59
	v_sub_f32_e32 v48, v54, v59
	v_sub_f32_e32 v51, v53, v59
	v_sub_f32_e32 v50, v52, v59
	v_pk_mul_f32 v[50:51], v[50:51], v[58:59] op_sel_hi:[1,0]
	v_pk_mul_f32 v[52:53], v[48:49], v[58:59] op_sel_hi:[1,0]
	v_cvt_pk_bf16_f32 v48, v28, v29
	v_cvt_pk_bf16_f32 v49, v30, v31
	s_waitcnt vmcnt(1)
	v_pk_fma_f32 v[36:37], v[36:37], v[50:51], v[40:41]
	v_pk_fma_f32 v[38:39], v[38:39], v[52:53], v[42:43]
	v_pk_fma_f32 v[24:25], v[36:37], s[24:25], v[24:25] op_sel_hi:[1,0,1]
	v_pk_fma_f32 v[26:27], v[38:39], s[24:25], v[26:27] op_sel_hi:[1,0,1]
	s_waitcnt vmcnt(0)
	v_pk_add_f32 v[24:25], v[44:45], v[24:25]
	v_pk_add_f32 v[26:27], v[46:47], v[26:27]
	global_store_dwordx4 v[34:35], v[24:27], off offset:16
	v_cvt_pk_bf16_f32 v50, v24, v25
	v_cvt_pk_bf16_f32 v51, v26, v27
	flat_store_dwordx4 v[56:57], v[48:51]
	global_load_dwordx4 v[36:39], v[34:35], off offset:512
	global_load_dwordx4 v[40:43], v[126:127], off
	global_load_dwordx4 v[44:47], v[158:159], off
	s_nop 0
	global_load_dwordx4 v[48:51], v[160:161], off
	global_load_dwordx4 v[52:55], v[34:35], off offset:528
	s_waitcnt vmcnt(0)
	v_sub_f32_e32 v39, v39, v59
	v_sub_f32_e32 v38, v38, v59
	v_sub_f32_e32 v37, v37, v59
	v_sub_f32_e32 v36, v36, v59
	v_pk_mul_f32 v[36:37], v[58:59], v[36:37] op_sel_hi:[0,1]
	v_pk_mul_f32 v[38:39], v[58:59], v[38:39] op_sel_hi:[0,1]
	v_pk_fma_f32 v[38:39], v[42:43], v[38:39], v[46:47]
	v_pk_fma_f32 v[36:37], v[40:41], v[36:37], v[44:45]
	v_pk_fma_f32 v[22:23], v[38:39], s[24:25], v[22:23] op_sel_hi:[1,0,1]
	v_pk_fma_f32 v[20:21], v[36:37], s[24:25], v[20:21] op_sel_hi:[1,0,1]
	v_pk_add_f32 v[22:23], v[50:51], v[22:23]
	v_pk_add_f32 v[20:21], v[48:49], v[20:21]
	global_store_dwordx4 v[34:35], v[20:23], off offset:512
	global_load_dwordx4 v[36:39], v[120:121], off
	global_load_dwordx4 v[40:43], v[122:123], off
	global_load_dwordx4 v[44:47], v[116:117], off
	v_add_f32_e32 v48, v28, v29
	v_mul_f32_e32 v29, v29, v29
	v_fmac_f32_e32 v29, v28, v28
	v_add_f32_e32 v48, v30, v48
	v_fmac_f32_e32 v29, v30, v30
	v_add_f32_e32 v30, v24, v25
	v_mul_f32_e32 v25, v25, v25
	v_fmac_f32_e32 v25, v24, v24
	v_add_f32_e32 v28, v31, v48
	v_add_f32_e32 v30, v26, v30
	v_fmac_f32_e32 v25, v26, v26
	v_add_f32_e32 v28, 0, v28
	v_fmac_f32_e32 v29, v31, v31
	v_add_f32_e32 v24, v27, v30
	v_fmac_f32_e32 v25, v27, v27
	v_sub_f32_e32 v27, v53, v59
	v_sub_f32_e32 v26, v52, v59
	v_add_f32_e32 v28, v24, v28
	v_add_f32_e32 v29, v29, v25
	v_sub_f32_e32 v25, v55, v59
	v_sub_f32_e32 v24, v54, v59
	v_pk_mul_f32 v[26:27], v[58:59], v[26:27] op_sel_hi:[0,1]
	v_pk_mul_f32 v[24:25], v[58:59], v[24:25] op_sel_hi:[0,1]
	v_mul_f32_e32 v31, v21, v21
	v_add_f32_e32 v30, v20, v21
	v_fmac_f32_e32 v31, v20, v20
	v_add_f32_e32 v30, v22, v30
	v_fmac_f32_e32 v31, v22, v22
	v_add_f32_e32 v30, v23, v30
	v_fmac_f32_e32 v31, v23, v23
	v_add_f32_e32 v28, v28, v30
	v_add_f32_e32 v29, v29, v31
	v_cvt_pk_bf16_f32 v20, v20, v21
	v_cvt_pk_bf16_f32 v21, v22, v23
	s_waitcnt vmcnt(0)
	v_pk_fma_f32 v[26:27], v[36:37], v[26:27], v[40:41]
	v_pk_fma_f32 v[24:25], v[38:39], v[24:25], v[42:43]
	v_pk_fma_f32 v[16:17], v[26:27], s[24:25], v[16:17] op_sel_hi:[1,0,1]
	v_pk_fma_f32 v[18:19], v[24:25], s[24:25], v[18:19] op_sel_hi:[1,0,1]
	v_pk_add_f32 v[24:25], v[44:45], v[16:17]
	v_pk_add_f32 v[26:27], v[46:47], v[18:19]
	v_mul_f32_e32 v17, v25, v25
	v_add_f32_e32 v16, v24, v25
	v_fmac_f32_e32 v17, v24, v24
	v_add_f32_e32 v16, v26, v16
	v_fmac_f32_e32 v17, v26, v26
	v_add_f32_e32 v16, v27, v16
	v_fmac_f32_e32 v17, v27, v27
	v_add_f32_e32 v16, v28, v16
	v_add_f32_e32 v17, v29, v17
	ds_bpermute_b32 v18, v118, v16
	ds_bpermute_b32 v19, v118, v17
	global_store_dwordx4 v[34:35], v[24:27], off offset:528
	v_cvt_pk_bf16_f32 v22, v24, v25
	v_cvt_pk_bf16_f32 v23, v26, v27
	s_waitcnt lgkmcnt(0)
	v_add_f32_e32 v16, v16, v18
	v_add_f32_e32 v17, v17, v19
	ds_bpermute_b32 v18, v119, v16
	ds_bpermute_b32 v19, v119, v17
	flat_store_dwordx4 v[56:57], v[20:23] offset:256
	s_mov_b32 s100, -1
	s_mov_b32 s101, 0
	s_mov_b32 s98, 0xffff0000
	s_mov_b32 s99, 0
	s_and_saveexec_b64 s[36:37], s[100:101]
	s_cbranch_execz .LBB0_1997
	s_waitcnt lgkmcnt(0)
	v_add_f32_e32 v19, v17, v19
	v_add_f32_e32 v18, v16, v18
	v_lshl_add_u64 v[16:17], s[8:9], 0, v[32:33]
	v_cndmask_b32_e64 v18, v18, v19, s[98:99]
	v_cndmask_b32_e64 v19, 0, 4, s[98:99]
	v_or_b32_e32 v16, v16, v19
	v_mov_b32_e32 v254, v18
; DEVI unsigned pk2(float lo, float hi) { unsigned r; asm("v_cvt_pk_bf16_f32 %0, %1, %2" : "=v"(r) : "v"(lo), "v"(hi)); return r; }
;     DEVI void operator()(const f32x4 (&acc)[2][2][4][2], const pg8::Unit& u, int wr, int wc, int fr, int fq) const {
;     ...
;                 const int row = row0 + ai * 128 + m * 16; float mu, rs; row_stats(stin, row, mu, rs);
;                 float sum = 0.f, sq = 0.f;
; #pragma unroll
;                 for (int bj = 0; bj < 2; ++bj) {
;                     f32x4 z[2];
; #pragma unroll
;                     for (int n = 0; n < 2; ++n) {
;                         const int col = colb + bj * 128 + 4 * n;
;                         f32x4 xv = *(const f32x4*)(zsrc + (size_t)row * DM + col);
;                         if (stin) { const f32x4 gv = *(const f32x4*)(gin + col), bv = *(const f32x4*)(bin + col); xv = (xv - mu) * rs * gv + bv; }
;                         f32x4 zz = ALPHA * xv + acc[ai][bj][m][n];
;                         if (bias) zz += *(const f32x4*)(bias + col);
;                         *(f32x4*)(zdst + (size_t)row * DM + col) = zz;
;                         sum += zz[0] + zz[1] + zz[2] + zz[3]; sq += zz[0] * zz[0] + zz[1] * zz[1] + zz[2] * zz[2] + zz[3] * zz[3];
;                         z[n] = zz;
;                     }
;                     u32x4 o; o.x = pk2(z[0][0], z[0][1]); o.y = pk2(z[0][2], z[0][3]); o.z = pk2(z[1][0], z[1][1]); o.w = pk2(z[1][2], z[1][3]);
;                     if (zb) *(u32x4*)(zb + (size_t)row * DM + colb + bj * 128) = o;
;                 }
;                 sum += __shfl_xor(sum, 16); sq += __shfl_xor(sq, 16);
;                 sum += __shfl_xor(sum, 32); sq += __shfl_xor(sq, 32);
;                 if (fq == 0) { atomicAdd(stout + 2 * (size_t)row, sum); atomicAdd(stout + 2 * (size_t)row + 1, sq); }
.LBB0_1997:
	s_or_b64 exec, exec, s[36:37]
	v_add_u32_e32 v40, 0xb0, v154
	v_ashrrev_i32_e32 v41, 31, v40
	v_lshlrev_b64 v[16:17], 3, v[40:41]
	s_waitcnt lgkmcnt(0)
	v_lshl_add_u64 v[18:19], s[6:7], 0, v[16:17]
	flat_load_dwordx2 v[42:43], v[18:19]
	v_lshlrev_b64 v[18:19], 12, v[40:41]
	v_lshl_add_u64 v[18:19], s[46:47], 0, v[18:19]
	v_lshl_add_u64 v[18:19], v[144:145], 2, v[18:19]
	global_load_dwordx4 v[20:23], v[18:19], off
	global_load_dwordx4 v[24:27], v[150:151], off
	global_load_dwordx4 v[28:31], v[152:153], off
	global_load_dwordx4 v[32:35], v[156:157], off
	global_load_dwordx4 v[36:39], v[18:19], off offset:16
	s_waitcnt vmcnt(0) lgkmcnt(0)
	v_pk_mul_f32 v[42:43], v[42:43], s[22:23] op_sel:[1,0] op_sel_hi:[0,0]
	v_fma_f32 v42, -v43, v43, v42
	v_max_f32_e32 v42, 0, v42
	v_add_f32_e32 v42, 0x3727c5ac, v42
	v_mul_f32_e32 v44, 0x4b800000, v42
	v_cmp_gt_f32_e32 vcc, s72, v42
	v_sub_f32_e32 v23, v23, v43
	v_sub_f32_e32 v22, v22, v43
	v_cndmask_b32_e32 v42, v42, v44, vcc
	v_rsq_f32_e32 v42, v42
	v_sub_f32_e32 v21, v21, v43
	v_sub_f32_e32 v20, v20, v43
	v_mul_f32_e32 v44, 0x45800000, v42
	v_cndmask_b32_e32 v42, v42, v44, vcc
	v_pk_mul_f32 v[20:21], v[20:21], v[42:43] op_sel_hi:[1,0]
	v_pk_mul_f32 v[22:23], v[22:23], v[42:43] op_sel_hi:[1,0]
	v_pk_fma_f32 v[20:21], v[24:25], v[20:21], v[28:29]
	v_pk_fma_f32 v[22:23], v[26:27], v[22:23], v[30:31]
	v_pk_fma_f32 v[12:13], v[20:21], s[24:25], v[12:13] op_sel_hi:[1,0,1]
	v_pk_fma_f32 v[14:15], v[22:23], s[24:25], v[14:15] op_sel_hi:[1,0,1]
	v_pk_add_f32 v[12:13], v[32:33], v[12:13]
	v_pk_add_f32 v[14:15], v[34:35], v[14:15]
	global_store_dwordx4 v[18:19], v[12:15], off
	global_load_dwordx4 v[20:23], v[146:147], off
	global_load_dwordx4 v[24:27], v[148:149], off
	global_load_dwordx4 v[28:31], v[124:125], off
	v_lshlrev_b64 v[32:33], 11, v[40:41]
	v_lshl_add_u64 v[32:33], s[10:11], 0, v[32:33]
	v_lshl_add_u64 v[40:41], v[144:145], 1, v[32:33]
	v_sub_f32_e32 v33, v39, v43
	v_sub_f32_e32 v32, v38, v43
	v_sub_f32_e32 v35, v37, v43
	v_sub_f32_e32 v34, v36, v43
	v_pk_mul_f32 v[34:35], v[34:35], v[42:43] op_sel_hi:[1,0]
	v_pk_mul_f32 v[36:37], v[32:33], v[42:43] op_sel_hi:[1,0]
	v_cvt_pk_bf16_f32 v32, v12, v13
	v_cvt_pk_bf16_f32 v33, v14, v15
	s_waitcnt vmcnt(1)
	v_pk_fma_f32 v[20:21], v[20:21], v[34:35], v[24:25]
	v_pk_fma_f32 v[22:23], v[22:23], v[36:37], v[26:27]
	v_pk_fma_f32 v[8:9], v[20:21], s[24:25], v[8:9] op_sel_hi:[1,0,1]
	v_pk_fma_f32 v[10:11], v[22:23], s[24:25], v[10:11] op_sel_hi:[1,0,1]
	s_waitcnt vmcnt(0)
	v_pk_add_f32 v[8:9], v[28:29], v[8:9]
	v_pk_add_f32 v[10:11], v[30:31], v[10:11]
	global_store_dwordx4 v[18:19], v[8:11], off offset:16
	v_cvt_pk_bf16_f32 v34, v8, v9
	v_cvt_pk_bf16_f32 v35, v10, v11
	flat_store_dwordx4 v[40:41], v[32:35]
	global_load_dwordx4 v[20:23], v[18:19], off offset:512
	global_load_dwordx4 v[24:27], v[126:127], off
	global_load_dwordx4 v[28:31], v[158:159], off
	s_nop 0
	global_load_dwordx4 v[32:35], v[160:161], off
	global_load_dwordx4 v[36:39], v[18:19], off offset:528
	s_waitcnt vmcnt(0)
	v_sub_f32_e32 v23, v23, v43
	v_sub_f32_e32 v22, v22, v43
	v_sub_f32_e32 v21, v21, v43
	v_sub_f32_e32 v20, v20, v43
	v_pk_mul_f32 v[20:21], v[42:43], v[20:21] op_sel_hi:[0,1]
	v_pk_mul_f32 v[22:23], v[42:43], v[22:23] op_sel_hi:[0,1]
	v_pk_fma_f32 v[22:23], v[26:27], v[22:23], v[30:31]
	v_pk_fma_f32 v[20:21], v[24:25], v[20:21], v[28:29]
	v_pk_fma_f32 v[6:7], v[22:23], s[24:25], v[6:7] op_sel_hi:[1,0,1]
	v_pk_fma_f32 v[4:5], v[20:21], s[24:25], v[4:5] op_sel_hi:[1,0,1]
	v_pk_add_f32 v[6:7], v[34:35], v[6:7]
	v_pk_add_f32 v[4:5], v[32:33], v[4:5]
	global_store_dwordx4 v[18:19], v[4:7], off offset:512
	global_load_dwordx4 v[20:23], v[120:121], off
	global_load_dwordx4 v[24:27], v[122:123], off
	global_load_dwordx4 v[28:31], v[116:117], off
	v_add_f32_e32 v32, v12, v13
	v_mul_f32_e32 v13, v13, v13
	v_fmac_f32_e32 v13, v12, v12
	v_add_f32_e32 v32, v14, v32
	v_fmac_f32_e32 v13, v14, v14
	v_add_f32_e32 v14, v8, v9
	v_mul_f32_e32 v9, v9, v9
	v_fmac_f32_e32 v9, v8, v8
	v_add_f32_e32 v12, v15, v32
	v_add_f32_e32 v14, v10, v14
	v_fmac_f32_e32 v9, v10, v10
	v_add_f32_e32 v12, 0, v12
	v_fmac_f32_e32 v13, v15, v15
	v_add_f32_e32 v8, v11, v14
	v_fmac_f32_e32 v9, v11, v11
	v_sub_f32_e32 v11, v37, v43
	v_sub_f32_e32 v10, v36, v43
	v_add_f32_e32 v12, v8, v12
	v_add_f32_e32 v13, v13, v9
	v_sub_f32_e32 v9, v39, v43
	v_sub_f32_e32 v8, v38, v43
	v_pk_mul_f32 v[10:11], v[42:43], v[10:11] op_sel_hi:[0,1]
	v_pk_mul_f32 v[8:9], v[42:43], v[8:9] op_sel_hi:[0,1]
	v_mul_f32_e32 v15, v5, v5
	v_add_f32_e32 v14, v4, v5
	v_fmac_f32_e32 v15, v4, v4
	v_add_f32_e32 v14, v6, v14
	v_fmac_f32_e32 v15, v6, v6
	v_add_f32_e32 v14, v7, v14
	v_fmac_f32_e32 v15, v7, v7
	v_add_f32_e32 v12, v12, v14
	v_add_f32_e32 v13, v13, v15
	v_cvt_pk_bf16_f32 v4, v4, v5
	v_cvt_pk_bf16_f32 v5, v6, v7
	s_waitcnt vmcnt(0)
	v_pk_fma_f32 v[10:11], v[20:21], v[10:11], v[24:25]
	v_pk_fma_f32 v[8:9], v[22:23], v[8:9], v[26:27]
	v_pk_fma_f32 v[0:1], v[10:11], s[24:25], v[0:1] op_sel_hi:[1,0,1]
	v_pk_fma_f32 v[2:3], v[8:9], s[24:25], v[2:3] op_sel_hi:[1,0,1]
	v_pk_add_f32 v[8:9], v[28:29], v[0:1]
	v_pk_add_f32 v[10:11], v[30:31], v[2:3]
	v_mul_f32_e32 v1, v9, v9
	v_add_f32_e32 v0, v8, v9
	v_fmac_f32_e32 v1, v8, v8
	v_add_f32_e32 v0, v10, v0
	v_fmac_f32_e32 v1, v10, v10
	v_add_f32_e32 v0, v11, v0
	v_fmac_f32_e32 v1, v11, v11
	v_add_f32_e32 v0, v12, v0
	v_add_f32_e32 v1, v13, v1
	ds_bpermute_b32 v2, v118, v0
	ds_bpermute_b32 v3, v118, v1
	global_store_dwordx4 v[18:19], v[8:11], off offset:528
	v_cvt_pk_bf16_f32 v6, v8, v9
	v_cvt_pk_bf16_f32 v7, v10, v11
	s_waitcnt lgkmcnt(0)
	v_add_f32_e32 v0, v0, v2
	v_add_f32_e32 v1, v1, v3
	ds_bpermute_b32 v2, v119, v0
	ds_bpermute_b32 v3, v119, v1
	flat_store_dwordx4 v[40:41], v[4:7] offset:256
	s_mov_b32 s100, -1
	s_mov_b32 s101, 0
	s_mov_b32 s98, 0xffff0000
	s_mov_b32 s99, 0
	s_and_saveexec_b64 s[36:37], s[100:101]
	s_cbranch_execz .LBB0_1999
	s_waitcnt lgkmcnt(0)
	v_add_f32_e32 v3, v1, v3
	v_add_f32_e32 v2, v0, v2
	v_lshl_add_u64 v[0:1], s[8:9], 0, v[16:17]
	v_cndmask_b32_e64 v2, v2, v3, s[98:99]
	v_cndmask_b32_e64 v3, 0, 4, s[98:99]
	v_or_b32_e32 v0, v0, v3
	v_mov_b32_e32 v255, v2
	flat_atomic_add_f32 v[250:251], v252
	flat_atomic_add_f32 v[250:251], v253 offset:128
	flat_atomic_add_f32 v[250:251], v254 offset:256
	flat_atomic_add_f32 v[250:251], v255 offset:384

;     DEVI void operator()(const f32x4 (&acc)[2][2][4][2], const pg8::Unit& u, int wr, int wc, int fr, int fq) const {
;         const int row0 = u.pm * 256 + wr * 64 + fr, colb = u.pn * 256 + wc * 32 + 8 * fq;
; #pragma unroll
;         for (int ai = 0; ai < 2; ++ai)
; #pragma unroll
;             for (int m = 0; m < 4; ++m) {
;                 const int row = row0 + ai * 128 + m * 16; float mu, rs; row_stats(stin, row, mu, rs);
;                 float sum = 0.f, sq = 0.f;
; #pragma unroll
;                 for (int bj = 0; bj < 2; ++bj) {
;                     f32x4 z[2];
; #pragma unroll
;                     for (int n = 0; n < 2; ++n) {
;                         const int col = colb + bj * 128 + 4 * n;
;                         f32x4 xv = *(const f32x4*)(zsrc + (size_t)row * DM + col);
;                         if (stin) { const f32x4 gv = *(const f32x4*)(gin + col), bv = *(const f32x4*)(bin + col); xv = (xv - mu) * rs * gv + bv; }
;                         f32x4 zz = ALPHA * xv + acc[ai][bj][m][n];
;                         if (bias) zz += *(const f32x4*)(bias + col);
;                         *(f32x4*)(zdst + (size_t)row * DM + col) = zz;
.LBB0_2192:
	v_lshl_add_u32 v154, s64, 8, v162
	v_ashrrev_i32_e32 v155, 31, v154
	v_lshlrev_b64 v[156:157], 3, v[154:155]
	v_lshl_add_u64 v[146:147], s[12:13], 0, v[156:157]
	s_waitcnt vmcnt(0)
	flat_load_dwordx2 v[160:161], v[146:147]
	v_lshl_or_b32 v144, s65, 8, v164
	v_ashrrev_i32_e32 v145, 31, v144
	v_lshlrev_b64 v[146:147], 12, v[154:155]
	v_lshl_add_u64 v[146:147], s[46:47], 0, v[146:147]
	v_lshlrev_b64 v[148:149], 2, v[144:145]
	v_lshl_add_u64 v[158:159], v[146:147], 0, v[148:149]
	global_load_dwordx4 v[170:173], v[158:159], off
	v_lshl_add_u64 v[150:151], s[16:17], 0, v[148:149]
	v_lshl_add_u64 v[152:153], s[18:19], 0, v[148:149]
	global_load_dwordx4 v[174:177], v[150:151], off
	global_load_dwordx4 v[178:181], v[152:153], off
	global_load_dwordx4 v[182:185], v[158:159], off offset:16
	v_or_b32_e32 v146, 4, v144
	v_ashrrev_i32_e32 v147, 31, v146
	v_lshlrev_b64 v[148:149], 2, v[146:147]
	v_lshl_add_u64 v[146:147], s[16:17], 0, v[148:149]
	v_lshl_add_u64 v[148:149], s[18:19], 0, v[148:149]
	v_or_b32_e32 v186, 0x80, v144
	v_ashrrev_i32_e32 v187, 31, v186
	s_waitcnt vmcnt(0) lgkmcnt(0)
	v_pk_mul_f32 v[160:161], v[160:161], s[24:25] op_sel:[1,0] op_sel_hi:[0,0]
	v_fma_f32 v160, -v161, v161, v160
	v_max_f32_e32 v160, 0, v160
	v_add_f32_e32 v160, 0x3727c5ac, v160
	v_mul_f32_e32 v169, 0x4b800000, v160
	v_cmp_gt_f32_e32 vcc, s61, v160
	v_sub_f32_e32 v171, v171, v161
	s_nop 0
	v_cndmask_b32_e32 v160, v160, v169, vcc
	v_rsq_f32_e32 v160, v160
	v_sub_f32_e32 v170, v170, v161
	v_sub_f32_e32 v173, v173, v161
	v_sub_f32_e32 v172, v172, v161
	v_mul_f32_e32 v169, 0x45800000, v160
	v_cndmask_b32_e32 v160, v160, v169, vcc
	v_pk_mul_f32 v[172:173], v[172:173], v[160:161] op_sel_hi:[1,0]
	v_pk_mul_f32 v[170:171], v[170:171], v[160:161] op_sel_hi:[1,0]
	v_pk_fma_f32 v[172:173], v[176:177], v[172:173], v[180:181]
	v_pk_fma_f32 v[170:171], v[174:175], v[170:171], v[178:179]
	v_pk_fma_f32 v[172:173], v[172:173], s[26:27], v[126:127] op_sel_hi:[1,0,1]
	v_pk_fma_f32 v[170:171], v[170:171], s[26:27], v[124:125] op_sel_hi:[1,0,1]
	global_store_dwordx4 v[158:159], v[170:173], off
	global_load_dwordx4 v[124:127], v[146:147], off
	global_load_dwordx4 v[174:177], v[148:149], off
	v_lshlrev_b64 v[178:179], 11, v[154:155]
	v_lshl_add_u64 v[178:179], s[14:15], 0, v[178:179]
	v_lshl_add_u64 v[194:195], v[144:145], 1, v[178:179]
	v_sub_f32_e32 v179, v183, v161
	v_sub_f32_e32 v178, v182, v161
	v_sub_f32_e32 v181, v185, v161
	v_sub_f32_e32 v180, v184, v161
	v_pk_mul_f32 v[180:181], v[180:181], v[160:161] op_sel_hi:[1,0]
	v_pk_mul_f32 v[182:183], v[178:179], v[160:161] op_sel_hi:[1,0]
	v_cvt_pk_bf16_f32 v178, v170, v171
	v_cvt_pk_bf16_f32 v179, v172, v173
	s_waitcnt vmcnt(0)
	v_pk_fma_f32 v[126:127], v[126:127], v[180:181], v[176:177]
	v_pk_fma_f32 v[124:125], v[124:125], v[182:183], v[174:175]
	v_pk_fma_f32 v[176:177], v[126:127], s[26:27], v[122:123] op_sel_hi:[1,0,1]
	v_pk_fma_f32 v[174:175], v[124:125], s[26:27], v[120:121] op_sel_hi:[1,0,1]
	global_store_dwordx4 v[158:159], v[174:177], off offset:16
	v_cvt_pk_bf16_f32 v180, v174, v175
	v_cvt_pk_bf16_f32 v181, v176, v177
	flat_store_dwordx4 v[194:195], v[178:181]
	global_load_dwordx4 v[178:181], v[158:159], off offset:512
	v_lshlrev_b64 v[122:123], 2, v[186:187]
	v_lshl_add_u64 v[120:121], s[16:17], 0, v[122:123]
	v_lshl_add_u64 v[122:123], s[18:19], 0, v[122:123]
	global_load_dwordx4 v[182:185], v[120:121], off
	global_load_dwordx4 v[186:189], v[122:123], off
	global_load_dwordx4 v[190:193], v[158:159], off offset:528
	v_or_b32_e32 v124, 0x84, v144
	v_ashrrev_i32_e32 v125, 31, v124
	v_lshlrev_b64 v[126:127], 2, v[124:125]
	v_lshl_add_u64 v[124:125], s[16:17], 0, v[126:127]
	v_lshl_add_u64 v[126:127], s[18:19], 0, v[126:127]
	v_mul_f32_e32 v169, v175, v175
	v_add_f32_e32 v155, v174, v175
	v_fmac_f32_e32 v169, v174, v174
	v_add_f32_e32 v155, v176, v155
	v_fmac_f32_e32 v169, v176, v176
	v_add_f32_e32 v155, v177, v155
	v_fmac_f32_e32 v169, v177, v177
	s_waitcnt vmcnt(0)
	v_sub_f32_e32 v179, v179, v161
	v_sub_f32_e32 v178, v178, v161
	v_sub_f32_e32 v181, v181, v161
	v_sub_f32_e32 v180, v180, v161
	v_pk_mul_f32 v[180:181], v[160:161], v[180:181] op_sel_hi:[0,1]
	v_pk_mul_f32 v[178:179], v[160:161], v[178:179] op_sel_hi:[0,1]
	v_pk_fma_f32 v[178:179], v[182:183], v[178:179], v[186:187]
	v_pk_fma_f32 v[180:181], v[184:185], v[180:181], v[188:189]
	v_pk_fma_f32 v[178:179], v[178:179], s[26:27], v[116:117] op_sel_hi:[1,0,1]
	v_pk_fma_f32 v[180:181], v[180:181], s[26:27], v[118:119] op_sel_hi:[1,0,1]
	global_store_dwordx4 v[158:159], v[178:181], off offset:512
	global_load_dwordx4 v[182:185], v[124:125], off
	global_load_dwordx4 v[186:189], v[126:127], off
	v_and_b32_e32 v117, 64, v168
	v_xor_b32_e32 v116, 16, v168
	v_add_u32_e32 v117, 64, v117
	v_xor_b32_e32 v118, 32, v168
	v_cmp_lt_i32_e32 vcc, v116, v117
	v_mul_f32_e32 v119, v171, v171
	v_fmac_f32_e32 v119, v170, v170
	v_cndmask_b32_e32 v116, v168, v116, vcc
	v_cmp_lt_i32_e32 vcc, v118, v117
	v_fmac_f32_e32 v119, v172, v172
	v_fmac_f32_e32 v119, v173, v173
	v_cndmask_b32_e32 v117, v168, v118, vcc
	v_add_f32_e32 v118, v170, v171
	v_add_f32_e32 v118, v172, v118
	v_add_f32_e32 v118, v173, v118
	v_add_f32_e32 v118, 0, v118
	v_add_f32_e32 v155, v155, v118
	v_add_f32_e32 v169, v119, v169
	v_sub_f32_e32 v119, v191, v161
	v_sub_f32_e32 v118, v190, v161
	v_sub_f32_e32 v171, v193, v161
	v_sub_f32_e32 v170, v192, v161
	v_pk_mul_f32 v[170:171], v[160:161], v[170:171] op_sel_hi:[0,1]
	v_pk_mul_f32 v[118:119], v[160:161], v[118:119] op_sel_hi:[0,1]
	v_mul_f32_e32 v161, v179, v179
	v_add_f32_e32 v160, v178, v179
	v_fmac_f32_e32 v161, v178, v178
	v_add_f32_e32 v160, v180, v160
	v_fmac_f32_e32 v161, v180, v180
	v_add_f32_e32 v160, v181, v160
	v_fmac_f32_e32 v161, v181, v181
	v_add_f32_e32 v155, v155, v160
	v_add_f32_e32 v169, v169, v161
	v_lshlrev_b32_e32 v116, 2, v116
	v_lshlrev_b32_e32 v117, 2, v117
	v_cvt_pk_bf16_f32 v174, v178, v179
	v_cvt_pk_bf16_f32 v175, v180, v181
	s_waitcnt vmcnt(0)
; DEVI unsigned pk2(float lo, float hi) { unsigned r; asm("v_cvt_pk_bf16_f32 %0, %1, %2" : "=v"(r) : "v"(lo), "v"(hi)); return r; }
;     DEVI void operator()(const f32x4 (&acc)[2][2][4][2], const pg8::Unit& u, int wr, int wc, int fr, int fq) const {
;     ...
;                 const int row = row0 + ai * 128 + m * 16; float mu, rs; row_stats(stin, row, mu, rs);
;                 float sum = 0.f, sq = 0.f;
; #pragma unroll
;                 for (int bj = 0; bj < 2; ++bj) {
;                     f32x4 z[2];
; #pragma unroll
;                     for (int n = 0; n < 2; ++n) {
;                         const int col = colb + bj * 128 + 4 * n;
;                         f32x4 xv = *(const f32x4*)(zsrc + (size_t)row * DM + col);
;                         if (stin) { const f32x4 gv = *(const f32x4*)(gin + col), bv = *(const f32x4*)(bin + col); xv = (xv - mu) * rs * gv + bv; }
;                         f32x4 zz = ALPHA * xv + acc[ai][bj][m][n];
;                         if (bias) zz += *(const f32x4*)(bias + col);
;                         *(f32x4*)(zdst + (size_t)row * DM + col) = zz;
;                         sum += zz[0] + zz[1] + zz[2] + zz[3]; sq += zz[0] * zz[0] + zz[1] * zz[1] + zz[2] * zz[2] + zz[3] * zz[3];
;                         z[n] = zz;
;                     }
;                     u32x4 o; o.x = pk2(z[0][0], z[0][1]); o.y = pk2(z[0][2], z[0][3]); o.z = pk2(z[1][0], z[1][1]); o.w = pk2(z[1][2], z[1][3]);
;                     if (zb) *(u32x4*)(zb + (size_t)row * DM + colb + bj * 128) = o;
;                 }
;                 sum += __shfl_xor(sum, 16); sq += __shfl_xor(sq, 16);
;                 sum += __shfl_xor(sum, 32); sq += __shfl_xor(sq, 32);
;                 if (fq == 0) { atomicAdd(stout + 2 * (size_t)row, sum); atomicAdd(stout + 2 * (size_t)row + 1, sq); }
	v_pk_fma_f32 v[118:119], v[182:183], v[118:119], v[186:187]
	v_pk_fma_f32 v[160:161], v[184:185], v[170:171], v[188:189]
	v_pk_fma_f32 v[170:171], v[118:119], s[26:27], v[112:113] op_sel_hi:[1,0,1]
	v_pk_fma_f32 v[172:173], v[160:161], s[26:27], v[114:115] op_sel_hi:[1,0,1]
	v_mul_f32_e32 v113, v171, v171
	v_add_f32_e32 v112, v170, v171
	v_fmac_f32_e32 v113, v170, v170
	v_add_f32_e32 v112, v172, v112
	v_fmac_f32_e32 v113, v172, v172
	v_add_f32_e32 v112, v173, v112
	v_fmac_f32_e32 v113, v173, v173
	v_add_f32_e32 v112, v155, v112
	v_add_f32_e32 v113, v169, v113
	ds_bpermute_b32 v114, v116, v112
	ds_bpermute_b32 v115, v116, v113
	global_store_dwordx4 v[158:159], v[170:173], off offset:528
	v_cvt_pk_bf16_f32 v176, v170, v171
	v_cvt_pk_bf16_f32 v177, v172, v173
	s_waitcnt lgkmcnt(0)
	v_add_f32_e32 v112, v112, v114
	v_add_f32_e32 v113, v113, v115
	ds_bpermute_b32 v114, v117, v112
	ds_bpermute_b32 v115, v117, v113
	flat_store_dwordx4 v[194:195], v[174:177] offset:256
	s_mov_b32 s100, -1
	s_mov_b32 s101, 0
	s_mov_b32 s98, 0xffff0000
	s_mov_b32 s99, 0
	s_and_saveexec_b64 s[30:31], s[100:101]
	s_cbranch_execz .LBB0_2194
	s_waitcnt lgkmcnt(0)
	v_add_f32_e32 v115, v113, v115
	v_add_f32_e32 v114, v112, v114
	v_lshl_add_u64 v[112:113], s[10:11], 0, v[156:157]
	v_cndmask_b32_e64 v114, v114, v115, s[98:99]
	v_cndmask_b32_e64 v115, 0, 4, s[98:99]
	v_or_b32_e32 v112, v112, v115
	v_mov_b32_e32 v250, v112
	v_mov_b32_e32 v251, v113
	v_mov_b32_e32 v252, v114
.LBB0_2194:
	s_or_b64 exec, exec, s[30:31]
	v_or_b32_e32 v118, 16, v154
	v_ashrrev_i32_e32 v119, 31, v118
	v_lshlrev_b64 v[112:113], 3, v[118:119]
	s_waitcnt lgkmcnt(0)
	v_lshl_add_u64 v[114:115], s[12:13], 0, v[112:113]
	flat_load_dwordx2 v[160:161], v[114:115]
	v_lshlrev_b64 v[114:115], 12, v[118:119]
	v_lshl_add_u64 v[114:115], s[46:47], 0, v[114:115]
	v_lshl_add_u64 v[114:115], v[144:145], 2, v[114:115]
	global_load_dwordx4 v[156:159], v[114:115], off
	global_load_dwordx4 v[170:173], v[150:151], off
	global_load_dwordx4 v[174:177], v[152:153], off
	global_load_dwordx4 v[178:181], v[114:115], off offset:16
	v_lshlrev_b64 v[118:119], 11, v[118:119]
	v_lshl_add_u64 v[118:119], s[14:15], 0, v[118:119]
	v_lshl_add_u64 v[118:119], v[144:145], 1, v[118:119]
	s_waitcnt vmcnt(0) lgkmcnt(0)
	v_pk_mul_f32 v[160:161], v[160:161], s[24:25] op_sel:[1,0] op_sel_hi:[0,0]
	v_fma_f32 v155, -v161, v161, v160
	v_max_f32_e32 v155, 0, v155
	v_add_f32_e32 v155, 0x3727c5ac, v155
	v_mul_f32_e32 v160, 0x4b800000, v155
	v_cmp_gt_f32_e32 vcc, s61, v155
	v_sub_f32_e32 v157, v157, v161
	v_sub_f32_e32 v156, v156, v161
	v_cndmask_b32_e32 v155, v155, v160, vcc
	v_rsq_f32_e32 v155, v155
	v_sub_f32_e32 v159, v159, v161
	v_sub_f32_e32 v158, v158, v161
	v_mul_f32_e32 v160, 0x45800000, v155
	v_cndmask_b32_e32 v160, v155, v160, vcc
	v_pk_mul_f32 v[158:159], v[158:159], v[160:161] op_sel_hi:[1,0]
	v_pk_mul_f32 v[156:157], v[156:157], v[160:161] op_sel_hi:[1,0]
	v_pk_fma_f32 v[158:159], v[172:173], v[158:159], v[176:177]
	v_pk_fma_f32 v[156:157], v[170:171], v[156:157], v[174:175]
	v_pk_fma_f32 v[110:111], v[158:159], s[26:27], v[110:111] op_sel_hi:[1,0,1]
	v_pk_fma_f32 v[108:109], v[156:157], s[26:27], v[108:109] op_sel_hi:[1,0,1]
	global_store_dwordx4 v[114:115], v[108:111], off
	global_load_dwordx4 v[156:159], v[146:147], off
	global_load_dwordx4 v[170:173], v[148:149], off
	v_sub_f32_e32 v175, v179, v161
	v_sub_f32_e32 v174, v178, v161
	v_sub_f32_e32 v177, v181, v161
	v_sub_f32_e32 v176, v180, v161
	v_pk_mul_f32 v[176:177], v[176:177], v[160:161] op_sel_hi:[1,0]
	v_pk_mul_f32 v[178:179], v[174:175], v[160:161] op_sel_hi:[1,0]
	v_cvt_pk_bf16_f32 v174, v108, v109
	v_cvt_pk_bf16_f32 v175, v110, v111
	v_add_f32_e32 v155, v108, v109
	v_mul_f32_e32 v109, v109, v109
	v_fmac_f32_e32 v109, v108, v108
	v_add_f32_e32 v155, v110, v155
	v_fmac_f32_e32 v109, v110, v110
	v_add_f32_e32 v108, v111, v155
	v_add_f32_e32 v108, 0, v108
	v_fmac_f32_e32 v109, v111, v111
	s_waitcnt vmcnt(0)
	v_pk_fma_f32 v[156:157], v[156:157], v[178:179], v[170:171]
	v_pk_fma_f32 v[158:159], v[158:159], v[176:177], v[172:173]
	v_pk_fma_f32 v[104:105], v[156:157], s[26:27], v[104:105] op_sel_hi:[1,0,1]
	v_pk_fma_f32 v[106:107], v[158:159], s[26:27], v[106:107] op_sel_hi:[1,0,1]
	global_store_dwordx4 v[114:115], v[104:107], off offset:16
	v_cvt_pk_bf16_f32 v176, v104, v105
	v_cvt_pk_bf16_f32 v177, v106, v107
	flat_store_dwordx4 v[118:119], v[174:177]
	global_load_dwordx4 v[156:159], v[114:115], off offset:512
	global_load_dwordx4 v[170:173], v[120:121], off
	s_nop 0
	global_load_dwordx4 v[174:177], v[122:123], off
	global_load_dwordx4 v[178:181], v[114:115], off offset:528
	v_add_f32_e32 v110, v104, v105
	v_mul_f32_e32 v105, v105, v105
	v_fmac_f32_e32 v105, v104, v104
	v_add_f32_e32 v110, v106, v110
	v_fmac_f32_e32 v105, v106, v106
	v_add_f32_e32 v104, v107, v110
	v_fmac_f32_e32 v105, v107, v107
	v_add_f32_e32 v108, v104, v108
	v_add_f32_e32 v109, v109, v105
	s_waitcnt vmcnt(0)
	v_sub_f32_e32 v157, v157, v161
	v_sub_f32_e32 v156, v156, v161
	v_sub_f32_e32 v159, v159, v161
	v_sub_f32_e32 v158, v158, v161
	v_pk_mul_f32 v[158:159], v[160:161], v[158:159] op_sel_hi:[0,1]
	v_pk_mul_f32 v[156:157], v[160:161], v[156:157] op_sel_hi:[0,1]
	v_pk_fma_f32 v[156:157], v[170:171], v[156:157], v[174:175]
	v_pk_fma_f32 v[158:159], v[172:173], v[158:159], v[176:177]
	v_pk_fma_f32 v[100:101], v[156:157], s[26:27], v[100:101] op_sel_hi:[1,0,1]
	v_pk_fma_f32 v[102:103], v[158:159], s[26:27], v[102:103] op_sel_hi:[1,0,1]
	global_store_dwordx4 v[114:115], v[100:103], off offset:512
	global_load_dwordx4 v[156:159], v[124:125], off
	global_load_dwordx4 v[170:173], v[126:127], off
	v_sub_f32_e32 v105, v179, v161
	v_sub_f32_e32 v104, v178, v161
	v_pk_mul_f32 v[104:105], v[160:161], v[104:105] op_sel_hi:[0,1]
	v_sub_f32_e32 v107, v181, v161
	v_sub_f32_e32 v106, v180, v161
	v_pk_mul_f32 v[106:107], v[160:161], v[106:107] op_sel_hi:[0,1]
	v_mul_f32_e32 v111, v101, v101
	v_add_f32_e32 v110, v100, v101
	v_fmac_f32_e32 v111, v100, v100
	v_add_f32_e32 v110, v102, v110
	v_fmac_f32_e32 v111, v102, v102
	v_add_f32_e32 v110, v103, v110
	v_fmac_f32_e32 v111, v103, v103
	v_add_f32_e32 v108, v108, v110
	v_add_f32_e32 v109, v109, v111
	v_cvt_pk_bf16_f32 v100, v100, v101
	v_cvt_pk_bf16_f32 v101, v102, v103
	s_waitcnt vmcnt(0)
; DEVI unsigned pk2(float lo, float hi) { unsigned r; asm("v_cvt_pk_bf16_f32 %0, %1, %2" : "=v"(r) : "v"(lo), "v"(hi)); return r; }
;     DEVI void operator()(const f32x4 (&acc)[2][2][4][2], const pg8::Unit& u, int wr, int wc, int fr, int fq) const {
;     ...
;                 const int row = row0 + ai * 128 + m * 16; float mu, rs; row_stats(stin, row, mu, rs);
;                 float sum = 0.f, sq = 0.f;
; #pragma unroll
;                 for (int bj = 0; bj < 2; ++bj) {
;                     f32x4 z[2];
; #pragma unroll
;                     for (int n = 0; n < 2; ++n) {
;                         const int col = colb + bj * 128 + 4 * n;
;                         f32x4 xv = *(const f32x4*)(zsrc + (size_t)row * DM + col);
;                         if (stin) { const f32x4 gv = *(const f32x4*)(gin + col), bv = *(const f32x4*)(bin + col); xv = (xv - mu) * rs * gv + bv; }
;                         f32x4 zz = ALPHA * xv + acc[ai][bj][m][n];
;                         if (bias) zz += *(const f32x4*)(bias + col);
;                         *(f32x4*)(zdst + (size_t)row * DM + col) = zz;
;                         sum += zz[0] + zz[1] + zz[2] + zz[3]; sq += zz[0] * zz[0] + zz[1] * zz[1] + zz[2] * zz[2] + zz[3] * zz[3];
;                         z[n] = zz;
;                     }
;                     u32x4 o; o.x = pk2(z[0][0], z[0][1]); o.y = pk2(z[0][2], z[0][3]); o.z = pk2(z[1][0], z[1][1]); o.w = pk2(z[1][2], z[1][3]);
;                     if (zb) *(u32x4*)(zb + (size_t)row * DM + colb + bj * 128) = o;
;                 }
;                 sum += __shfl_xor(sum, 16); sq += __shfl_xor(sq, 16);
;                 sum += __shfl_xor(sum, 32); sq += __shfl_xor(sq, 32);
;                 if (fq == 0) { atomicAdd(stout + 2 * (size_t)row, sum); atomicAdd(stout + 2 * (size_t)row + 1, sq); }
	v_pk_fma_f32 v[104:105], v[156:157], v[104:105], v[170:171]
	s_nop 0
	v_pk_fma_f32 v[104:105], v[104:105], s[26:27], v[96:97] op_sel_hi:[1,0,1]
	v_pk_fma_f32 v[106:107], v[158:159], v[106:107], v[172:173]
	v_mul_f32_e32 v97, v105, v105
	v_pk_fma_f32 v[106:107], v[106:107], s[26:27], v[98:99] op_sel_hi:[1,0,1]
	v_add_f32_e32 v96, v104, v105
	v_fmac_f32_e32 v97, v104, v104
	v_add_f32_e32 v96, v106, v96
	v_fmac_f32_e32 v97, v106, v106
	v_add_f32_e32 v96, v107, v96
	v_fmac_f32_e32 v97, v107, v107
	v_add_f32_e32 v96, v108, v96
	v_add_f32_e32 v97, v109, v97
	ds_bpermute_b32 v98, v116, v96
	ds_bpermute_b32 v99, v116, v97
	global_store_dwordx4 v[114:115], v[104:107], off offset:528
	v_cvt_pk_bf16_f32 v102, v104, v105
	v_cvt_pk_bf16_f32 v103, v106, v107
	s_waitcnt lgkmcnt(0)
	v_add_f32_e32 v96, v96, v98
	v_add_f32_e32 v97, v97, v99
	ds_bpermute_b32 v98, v117, v96
	ds_bpermute_b32 v99, v117, v97
	flat_store_dwordx4 v[118:119], v[100:103] offset:256
	s_mov_b32 s100, -1
	s_mov_b32 s101, 0
	s_mov_b32 s98, 0xffff0000
	s_mov_b32 s99, 0
	s_and_saveexec_b64 s[30:31], s[100:101]
	s_cbranch_execz .LBB0_2196
	s_waitcnt lgkmcnt(0)
	v_add_f32_e32 v99, v97, v99
	v_add_f32_e32 v98, v96, v98
	v_lshl_add_u64 v[96:97], s[10:11], 0, v[112:113]
	v_cndmask_b32_e64 v98, v98, v99, s[98:99]
	v_cndmask_b32_e64 v99, 0, 4, s[98:99]
	v_or_b32_e32 v96, v96, v99
	v_mov_b32_e32 v253, v98
.LBB0_2196:
	s_or_b64 exec, exec, s[30:31]
	v_or_b32_e32 v118, 32, v154
	v_ashrrev_i32_e32 v119, 31, v118
	v_lshlrev_b64 v[96:97], 3, v[118:119]
	s_waitcnt lgkmcnt(0)
	v_lshl_add_u64 v[98:99], s[12:13], 0, v[96:97]
	flat_load_dwordx2 v[156:157], v[98:99]
	v_lshlrev_b64 v[98:99], 12, v[118:119]
	v_lshl_add_u64 v[98:99], s[46:47], 0, v[98:99]
	v_lshl_add_u64 v[98:99], v[144:145], 2, v[98:99]
	global_load_dwordx4 v[100:103], v[98:99], off
	global_load_dwordx4 v[104:107], v[150:151], off
	global_load_dwordx4 v[108:111], v[152:153], off
	global_load_dwordx4 v[112:115], v[98:99], off offset:16
	s_waitcnt vmcnt(0) lgkmcnt(0)
	v_pk_mul_f32 v[156:157], v[156:157], s[24:25] op_sel:[1,0] op_sel_hi:[0,0]
	v_fma_f32 v155, -v157, v157, v156
	v_max_f32_e32 v155, 0, v155
	v_add_f32_e32 v155, 0x3727c5ac, v155
	v_mul_f32_e32 v156, 0x4b800000, v155
	v_cmp_gt_f32_e32 vcc, s61, v155
	v_sub_f32_e32 v101, v101, v157
	v_sub_f32_e32 v100, v100, v157
	v_cndmask_b32_e32 v155, v155, v156, vcc
	v_rsq_f32_e32 v155, v155
	v_sub_f32_e32 v103, v103, v157
	v_sub_f32_e32 v102, v102, v157
	v_mul_f32_e32 v156, 0x45800000, v155
	v_cndmask_b32_e32 v156, v155, v156, vcc
	v_pk_mul_f32 v[102:103], v[102:103], v[156:157] op_sel_hi:[1,0]
	v_pk_mul_f32 v[100:101], v[100:101], v[156:157] op_sel_hi:[1,0]
	v_pk_fma_f32 v[102:103], v[106:107], v[102:103], v[110:111]
	v_pk_fma_f32 v[100:101], v[104:105], v[100:101], v[108:109]
	v_pk_fma_f32 v[94:95], v[102:103], s[26:27], v[94:95] op_sel_hi:[1,0,1]
	v_pk_fma_f32 v[92:93], v[100:101], s[26:27], v[92:93] op_sel_hi:[1,0,1]
	global_store_dwordx4 v[98:99], v[92:95], off
	global_load_dwordx4 v[100:103], v[146:147], off
	global_load_dwordx4 v[104:107], v[148:149], off
	v_lshlrev_b64 v[108:109], 11, v[118:119]
	v_lshl_add_u64 v[108:109], s[14:15], 0, v[108:109]
	v_lshl_add_u64 v[118:119], v[144:145], 1, v[108:109]
	v_sub_f32_e32 v109, v113, v157
	v_sub_f32_e32 v108, v112, v157
	v_sub_f32_e32 v111, v115, v157
	v_sub_f32_e32 v110, v114, v157
	v_pk_mul_f32 v[110:111], v[110:111], v[156:157] op_sel_hi:[1,0]
	v_pk_mul_f32 v[112:113], v[108:109], v[156:157] op_sel_hi:[1,0]
	v_cvt_pk_bf16_f32 v108, v92, v93
	v_cvt_pk_bf16_f32 v109, v94, v95
	s_waitcnt vmcnt(0)
	v_pk_fma_f32 v[102:103], v[102:103], v[110:111], v[106:107]
	v_pk_fma_f32 v[100:101], v[100:101], v[112:113], v[104:105]
	v_pk_fma_f32 v[90:91], v[102:103], s[26:27], v[90:91] op_sel_hi:[1,0,1]
	v_pk_fma_f32 v[88:89], v[100:101], s[26:27], v[88:89] op_sel_hi:[1,0,1]
	global_store_dwordx4 v[98:99], v[88:91], off offset:16
	v_cvt_pk_bf16_f32 v110, v88, v89
	v_cvt_pk_bf16_f32 v111, v90, v91
	flat_store_dwordx4 v[118:119], v[108:111]
	global_load_dwordx4 v[100:103], v[98:99], off offset:512
	global_load_dwordx4 v[104:107], v[120:121], off
	s_nop 0
	global_load_dwordx4 v[108:111], v[122:123], off
	global_load_dwordx4 v[112:115], v[98:99], off offset:528
	s_waitcnt vmcnt(0)
	v_sub_f32_e32 v101, v101, v157
	v_sub_f32_e32 v100, v100, v157
	v_sub_f32_e32 v103, v103, v157
	v_sub_f32_e32 v102, v102, v157
	v_pk_mul_f32 v[102:103], v[156:157], v[102:103] op_sel_hi:[0,1]
	v_pk_mul_f32 v[100:101], v[156:157], v[100:101] op_sel_hi:[0,1]
	v_pk_fma_f32 v[100:101], v[104:105], v[100:101], v[108:109]
	v_pk_fma_f32 v[102:103], v[106:107], v[102:103], v[110:111]
	v_pk_fma_f32 v[84:85], v[100:101], s[26:27], v[84:85] op_sel_hi:[1,0,1]
	v_pk_fma_f32 v[86:87], v[102:103], s[26:27], v[86:87] op_sel_hi:[1,0,1]
	global_store_dwordx4 v[98:99], v[84:87], off offset:512
	global_load_dwordx4 v[100:103], v[124:125], off
	global_load_dwordx4 v[104:107], v[126:127], off
	v_add_f32_e32 v108, v92, v93
	v_mul_f32_e32 v93, v93, v93
	v_fmac_f32_e32 v93, v92, v92
	v_add_f32_e32 v108, v94, v108
	v_fmac_f32_e32 v93, v94, v94
	v_add_f32_e32 v94, v88, v89
	v_mul_f32_e32 v89, v89, v89
	v_fmac_f32_e32 v89, v88, v88
	v_add_f32_e32 v92, v95, v108
	v_add_f32_e32 v94, v90, v94
	v_fmac_f32_e32 v89, v90, v90
	v_add_f32_e32 v92, 0, v92
	v_fmac_f32_e32 v93, v95, v95
	v_add_f32_e32 v88, v91, v94
	v_fmac_f32_e32 v89, v91, v91
	v_add_f32_e32 v92, v88, v92
	v_add_f32_e32 v93, v93, v89
	v_sub_f32_e32 v89, v113, v157
	v_sub_f32_e32 v88, v112, v157
	v_pk_mul_f32 v[88:89], v[156:157], v[88:89] op_sel_hi:[0,1]
	v_sub_f32_e32 v91, v115, v157
	v_sub_f32_e32 v90, v114, v157
	v_pk_mul_f32 v[90:91], v[156:157], v[90:91] op_sel_hi:[0,1]
	v_mul_f32_e32 v95, v85, v85
	v_add_f32_e32 v94, v84, v85
	v_fmac_f32_e32 v95, v84, v84
	v_add_f32_e32 v94, v86, v94
	v_fmac_f32_e32 v95, v86, v86
	v_add_f32_e32 v94, v87, v94
	v_fmac_f32_e32 v95, v87, v87
	v_add_f32_e32 v92, v92, v94
	v_add_f32_e32 v93, v93, v95
	v_cvt_pk_bf16_f32 v84, v84, v85
	v_cvt_pk_bf16_f32 v85, v86, v87
	s_waitcnt vmcnt(0)
; DEVI unsigned pk2(float lo, float hi) { unsigned r; asm("v_cvt_pk_bf16_f32 %0, %1, %2" : "=v"(r) : "v"(lo), "v"(hi)); return r; }
;     DEVI void operator()(const f32x4 (&acc)[2][2][4][2], const pg8::Unit& u, int wr, int wc, int fr, int fq) const {
;     ...
;                 const int row = row0 + ai * 128 + m * 16; float mu, rs; row_stats(stin, row, mu, rs);
;                 float sum = 0.f, sq = 0.f;
; #pragma unroll
;                 for (int bj = 0; bj < 2; ++bj) {
;                     f32x4 z[2];
; #pragma unroll
;                     for (int n = 0; n < 2; ++n) {
;                         const int col = colb + bj * 128 + 4 * n;
;                         f32x4 xv = *(const f32x4*)(zsrc + (size_t)row * DM + col);
;                         if (stin) { const f32x4 gv = *(const f32x4*)(gin + col), bv = *(const f32x4*)(bin + col); xv = (xv - mu) * rs * gv + bv; }
;                         f32x4 zz = ALPHA * xv + acc[ai][bj][m][n];
;                         if (bias) zz += *(const f32x4*)(bias + col);
;                         *(f32x4*)(zdst + (size_t)row * DM + col) = zz;
;                         sum += zz[0] + zz[1] + zz[2] + zz[3]; sq += zz[0] * zz[0] + zz[1] * zz[1] + zz[2] * zz[2] + zz[3] * zz[3];
;                         z[n] = zz;
;                     }
;                     u32x4 o; o.x = pk2(z[0][0], z[0][1]); o.y = pk2(z[0][2], z[0][3]); o.z = pk2(z[1][0], z[1][1]); o.w = pk2(z[1][2], z[1][3]);
;                     if (zb) *(u32x4*)(zb + (size_t)row * DM + colb + bj * 128) = o;
;                 }
;                 sum += __shfl_xor(sum, 16); sq += __shfl_xor(sq, 16);
;                 sum += __shfl_xor(sum, 32); sq += __shfl_xor(sq, 32);
;                 if (fq == 0) { atomicAdd(stout + 2 * (size_t)row, sum); atomicAdd(stout + 2 * (size_t)row + 1, sq); }
	v_pk_fma_f32 v[88:89], v[100:101], v[88:89], v[104:105]
	s_nop 0
	v_pk_fma_f32 v[88:89], v[88:89], s[26:27], v[80:81] op_sel_hi:[1,0,1]
	v_pk_fma_f32 v[90:91], v[102:103], v[90:91], v[106:107]
	v_mul_f32_e32 v81, v89, v89
	v_pk_fma_f32 v[90:91], v[90:91], s[26:27], v[82:83] op_sel_hi:[1,0,1]
	v_add_f32_e32 v80, v88, v89
	v_fmac_f32_e32 v81, v88, v88
	v_add_f32_e32 v80, v90, v80
	v_fmac_f32_e32 v81, v90, v90
	v_add_f32_e32 v80, v91, v80
	v_fmac_f32_e32 v81, v91, v91
	v_add_f32_e32 v80, v92, v80
	v_add_f32_e32 v81, v93, v81
	ds_bpermute_b32 v82, v116, v80
	ds_bpermute_b32 v83, v116, v81
	global_store_dwordx4 v[98:99], v[88:91], off offset:528
	v_cvt_pk_bf16_f32 v86, v88, v89
	v_cvt_pk_bf16_f32 v87, v90, v91
	s_waitcnt lgkmcnt(0)
	v_add_f32_e32 v80, v80, v82
	v_add_f32_e32 v81, v81, v83
	ds_bpermute_b32 v82, v117, v80
	ds_bpermute_b32 v83, v117, v81
	flat_store_dwordx4 v[118:119], v[84:87] offset:256
	s_mov_b32 s100, -1
	s_mov_b32 s101, 0
	s_mov_b32 s98, 0xffff0000
	s_mov_b32 s99, 0
	s_and_saveexec_b64 s[30:31], s[100:101]
	s_cbranch_execz .LBB0_2198
	s_waitcnt lgkmcnt(0)
	v_add_f32_e32 v83, v81, v83
	v_add_f32_e32 v82, v80, v82
	v_lshl_add_u64 v[80:81], s[10:11], 0, v[96:97]
	v_cndmask_b32_e64 v82, v82, v83, s[98:99]
	v_cndmask_b32_e64 v83, 0, 4, s[98:99]
	v_or_b32_e32 v80, v80, v83
	v_mov_b32_e32 v254, v82
.LBB0_2198:
	s_or_b64 exec, exec, s[30:31]
	v_or_b32_e32 v100, 48, v154
	v_ashrrev_i32_e32 v101, 31, v100
	v_lshlrev_b64 v[80:81], 3, v[100:101]
	s_waitcnt lgkmcnt(0)
	v_lshl_add_u64 v[82:83], s[12:13], 0, v[80:81]
	flat_load_dwordx2 v[102:103], v[82:83]
	v_lshlrev_b64 v[82:83], 12, v[100:101]
	v_lshl_add_u64 v[82:83], s[46:47], 0, v[82:83]
	v_lshl_add_u64 v[82:83], v[144:145], 2, v[82:83]
	global_load_dwordx4 v[84:87], v[82:83], off
	global_load_dwordx4 v[88:91], v[150:151], off
	global_load_dwordx4 v[92:95], v[152:153], off
	global_load_dwordx4 v[96:99], v[82:83], off offset:16
	s_waitcnt vmcnt(0) lgkmcnt(0)
	v_pk_mul_f32 v[102:103], v[102:103], s[24:25] op_sel:[1,0] op_sel_hi:[0,0]
	v_fma_f32 v102, -v103, v103, v102
	v_max_f32_e32 v102, 0, v102
	v_add_f32_e32 v102, 0x3727c5ac, v102
	v_mul_f32_e32 v104, 0x4b800000, v102
	v_cmp_gt_f32_e32 vcc, s61, v102
	v_sub_f32_e32 v85, v85, v103
	v_sub_f32_e32 v84, v84, v103
	v_cndmask_b32_e32 v102, v102, v104, vcc
	v_rsq_f32_e32 v102, v102
	v_sub_f32_e32 v87, v87, v103
	v_sub_f32_e32 v86, v86, v103
	v_mul_f32_e32 v104, 0x45800000, v102
	v_cndmask_b32_e32 v102, v102, v104, vcc
	v_pk_mul_f32 v[86:87], v[86:87], v[102:103] op_sel_hi:[1,0]
	v_pk_mul_f32 v[84:85], v[84:85], v[102:103] op_sel_hi:[1,0]
	v_pk_fma_f32 v[86:87], v[90:91], v[86:87], v[94:95]
	v_pk_fma_f32 v[84:85], v[88:89], v[84:85], v[92:93]
	v_pk_fma_f32 v[78:79], v[86:87], s[26:27], v[78:79] op_sel_hi:[1,0,1]
	v_pk_fma_f32 v[76:77], v[84:85], s[26:27], v[76:77] op_sel_hi:[1,0,1]
	global_store_dwordx4 v[82:83], v[76:79], off
	global_load_dwordx4 v[84:87], v[146:147], off
	global_load_dwordx4 v[88:91], v[148:149], off
	v_lshlrev_b64 v[92:93], 11, v[100:101]
	v_lshl_add_u64 v[92:93], s[14:15], 0, v[92:93]
	v_lshl_add_u64 v[100:101], v[144:145], 1, v[92:93]
	v_sub_f32_e32 v93, v97, v103
	v_sub_f32_e32 v92, v96, v103
	v_sub_f32_e32 v95, v99, v103
	v_sub_f32_e32 v94, v98, v103
	v_pk_mul_f32 v[94:95], v[94:95], v[102:103] op_sel_hi:[1,0]
	v_pk_mul_f32 v[96:97], v[92:93], v[102:103] op_sel_hi:[1,0]
	v_cvt_pk_bf16_f32 v92, v76, v77
	v_cvt_pk_bf16_f32 v93, v78, v79
	s_waitcnt vmcnt(0)
	v_pk_fma_f32 v[86:87], v[86:87], v[94:95], v[90:91]
	v_pk_fma_f32 v[84:85], v[84:85], v[96:97], v[88:89]
	v_pk_fma_f32 v[74:75], v[86:87], s[26:27], v[74:75] op_sel_hi:[1,0,1]
	v_pk_fma_f32 v[72:73], v[84:85], s[26:27], v[72:73] op_sel_hi:[1,0,1]
	global_store_dwordx4 v[82:83], v[72:75], off offset:16
	v_cvt_pk_bf16_f32 v94, v72, v73
	v_cvt_pk_bf16_f32 v95, v74, v75
	flat_store_dwordx4 v[100:101], v[92:95]
	global_load_dwordx4 v[84:87], v[82:83], off offset:512
	global_load_dwordx4 v[88:91], v[120:121], off
	s_nop 0
	global_load_dwordx4 v[92:95], v[122:123], off
	global_load_dwordx4 v[96:99], v[82:83], off offset:528
	s_waitcnt vmcnt(0)
	v_sub_f32_e32 v85, v85, v103
	v_sub_f32_e32 v84, v84, v103
	v_sub_f32_e32 v87, v87, v103
	v_sub_f32_e32 v86, v86, v103
	v_pk_mul_f32 v[86:87], v[102:103], v[86:87] op_sel_hi:[0,1]
	v_pk_mul_f32 v[84:85], v[102:103], v[84:85] op_sel_hi:[0,1]
	v_pk_fma_f32 v[84:85], v[88:89], v[84:85], v[92:93]
	v_pk_fma_f32 v[86:87], v[90:91], v[86:87], v[94:95]
	v_pk_fma_f32 v[68:69], v[84:85], s[26:27], v[68:69] op_sel_hi:[1,0,1]
	v_pk_fma_f32 v[70:71], v[86:87], s[26:27], v[70:71] op_sel_hi:[1,0,1]
	global_store_dwordx4 v[82:83], v[68:71], off offset:512
	global_load_dwordx4 v[84:87], v[124:125], off
	global_load_dwordx4 v[88:91], v[126:127], off
	v_add_f32_e32 v92, v76, v77
	v_mul_f32_e32 v77, v77, v77
	v_fmac_f32_e32 v77, v76, v76
	v_add_f32_e32 v92, v78, v92
	v_fmac_f32_e32 v77, v78, v78
	v_add_f32_e32 v78, v72, v73
	v_mul_f32_e32 v73, v73, v73
	v_fmac_f32_e32 v73, v72, v72
	v_add_f32_e32 v76, v79, v92
	v_add_f32_e32 v78, v74, v78
	v_fmac_f32_e32 v73, v74, v74
	v_add_f32_e32 v76, 0, v76
	v_fmac_f32_e32 v77, v79, v79
	v_add_f32_e32 v72, v75, v78
	v_fmac_f32_e32 v73, v75, v75
	v_add_f32_e32 v76, v72, v76
	v_add_f32_e32 v77, v77, v73
	v_sub_f32_e32 v73, v97, v103
	v_sub_f32_e32 v72, v96, v103
	v_pk_mul_f32 v[72:73], v[102:103], v[72:73] op_sel_hi:[0,1]
	v_sub_f32_e32 v75, v99, v103
	v_sub_f32_e32 v74, v98, v103
	v_pk_mul_f32 v[74:75], v[102:103], v[74:75] op_sel_hi:[0,1]
	v_mul_f32_e32 v79, v69, v69
	v_add_f32_e32 v78, v68, v69
	v_fmac_f32_e32 v79, v68, v68
	v_add_f32_e32 v78, v70, v78
	v_fmac_f32_e32 v79, v70, v70
	v_add_f32_e32 v78, v71, v78
	v_fmac_f32_e32 v79, v71, v71
	v_add_f32_e32 v76, v76, v78
	v_add_f32_e32 v77, v77, v79
	v_cvt_pk_bf16_f32 v68, v68, v69
	v_cvt_pk_bf16_f32 v69, v70, v71
	s_waitcnt vmcnt(0)
	v_pk_fma_f32 v[72:73], v[84:85], v[72:73], v[88:89]
	s_nop 0
	v_pk_fma_f32 v[72:73], v[72:73], s[26:27], v[64:65] op_sel_hi:[1,0,1]
	v_pk_fma_f32 v[74:75], v[86:87], v[74:75], v[90:91]
	v_mul_f32_e32 v65, v73, v73
	v_pk_fma_f32 v[74:75], v[74:75], s[26:27], v[66:67] op_sel_hi:[1,0,1]
	v_add_f32_e32 v64, v72, v73
	v_fmac_f32_e32 v65, v72, v72
	v_add_f32_e32 v64, v74, v64
	v_fmac_f32_e32 v65, v74, v74
	v_add_f32_e32 v64, v75, v64
	v_fmac_f32_e32 v65, v75, v75
	v_add_f32_e32 v64, v76, v64
	v_add_f32_e32 v65, v77, v65
	ds_bpermute_b32 v66, v116, v64
	ds_bpermute_b32 v67, v116, v65
	global_store_dwordx4 v[82:83], v[72:75], off offset:528
	v_cvt_pk_bf16_f32 v70, v72, v73
	v_cvt_pk_bf16_f32 v71, v74, v75
	s_waitcnt lgkmcnt(0)
	v_add_f32_e32 v64, v64, v66
	v_add_f32_e32 v65, v65, v67
	ds_bpermute_b32 v66, v117, v64
	ds_bpermute_b32 v67, v117, v65
	flat_store_dwordx4 v[100:101], v[68:71] offset:256
	s_mov_b32 s100, -1
	s_mov_b32 s101, 0
	s_mov_b32 s98, 0xffff0000
	s_mov_b32 s99, 0
	s_and_saveexec_b64 s[30:31], s[100:101]
	s_cbranch_execz .LBB0_2200
; DEVI unsigned pk2(float lo, float hi) { unsigned r; asm("v_cvt_pk_bf16_f32 %0, %1, %2" : "=v"(r) : "v"(lo), "v"(hi)); return r; }
;     DEVI void operator()(const f32x4 (&acc)[2][2][4][2], const pg8::Unit& u, int wr, int wc, int fr, int fq) const {
;     ...
;                 const int row = row0 + ai * 128 + m * 16; float mu, rs; row_stats(stin, row, mu, rs);
;                 float sum = 0.f, sq = 0.f;
; #pragma unroll
;                 for (int bj = 0; bj < 2; ++bj) {
;                     f32x4 z[2];
; #pragma unroll
;                     for (int n = 0; n < 2; ++n) {
;                         const int col = colb + bj * 128 + 4 * n;
;                         f32x4 xv = *(const f32x4*)(zsrc + (size_t)row * DM + col);
;                         if (stin) { const f32x4 gv = *(const f32x4*)(gin + col), bv = *(const f32x4*)(bin + col); xv = (xv - mu) * rs * gv + bv; }
;                         f32x4 zz = ALPHA * xv + acc[ai][bj][m][n];
;                         if (bias) zz += *(const f32x4*)(bias + col);
;                         *(f32x4*)(zdst + (size_t)row * DM + col) = zz;
;                         sum += zz[0] + zz[1] + zz[2] + zz[3]; sq += zz[0] * zz[0] + zz[1] * zz[1] + zz[2] * zz[2] + zz[3] * zz[3];
;                         z[n] = zz;
;                     }
;                     u32x4 o; o.x = pk2(z[0][0], z[0][1]); o.y = pk2(z[0][2], z[0][3]); o.z = pk2(z[1][0], z[1][1]); o.w = pk2(z[1][2], z[1][3]);
;                     if (zb) *(u32x4*)(zb + (size_t)row * DM + colb + bj * 128) = o;
;                 }
;                 sum += __shfl_xor(sum, 16); sq += __shfl_xor(sq, 16);
;                 sum += __shfl_xor(sum, 32); sq += __shfl_xor(sq, 32);
;                 if (fq == 0) { atomicAdd(stout + 2 * (size_t)row, sum); atomicAdd(stout + 2 * (size_t)row + 1, sq); }
	s_waitcnt lgkmcnt(0)
	v_add_f32_e32 v67, v65, v67
	v_add_f32_e32 v66, v64, v66
	v_lshl_add_u64 v[64:65], s[10:11], 0, v[80:81]
	v_cndmask_b32_e64 v66, v66, v67, s[98:99]
	v_cndmask_b32_e64 v67, 0, 4, s[98:99]
	v_or_b32_e32 v64, v64, v67
	v_mov_b32_e32 v255, v66
	flat_atomic_add_f32 v[250:251], v252
	flat_atomic_add_f32 v[250:251], v253 offset:128
	flat_atomic_add_f32 v[250:251], v254 offset:256
	flat_atomic_add_f32 v[250:251], v255 offset:384
.LBB0_2200:
	s_or_b64 exec, exec, s[30:31]
	v_add_u32_e32 v84, 0x80, v154
	v_ashrrev_i32_e32 v85, 31, v84
	v_lshlrev_b64 v[64:65], 3, v[84:85]
	s_waitcnt lgkmcnt(0)
	v_lshl_add_u64 v[66:67], s[12:13], 0, v[64:65]
	flat_load_dwordx2 v[86:87], v[66:67]
	v_lshlrev_b64 v[66:67], 12, v[84:85]
	v_lshl_add_u64 v[66:67], s[46:47], 0, v[66:67]
	v_lshl_add_u64 v[66:67], v[144:145], 2, v[66:67]
	global_load_dwordx4 v[68:71], v[66:67], off
	global_load_dwordx4 v[72:75], v[150:151], off
	global_load_dwordx4 v[76:79], v[152:153], off
	global_load_dwordx4 v[80:83], v[66:67], off offset:16
	s_waitcnt vmcnt(0) lgkmcnt(0)
	v_pk_mul_f32 v[86:87], v[86:87], s[24:25] op_sel:[1,0] op_sel_hi:[0,0]
	v_fma_f32 v86, -v87, v87, v86
	v_max_f32_e32 v86, 0, v86
	v_add_f32_e32 v86, 0x3727c5ac, v86
	v_mul_f32_e32 v88, 0x4b800000, v86
	v_cmp_gt_f32_e32 vcc, s61, v86
	v_sub_f32_e32 v69, v69, v87
	v_sub_f32_e32 v68, v68, v87
	v_cndmask_b32_e32 v86, v86, v88, vcc
	v_rsq_f32_e32 v86, v86
	v_sub_f32_e32 v71, v71, v87
	v_sub_f32_e32 v70, v70, v87
	v_mul_f32_e32 v88, 0x45800000, v86
	v_cndmask_b32_e32 v86, v86, v88, vcc
	v_pk_mul_f32 v[70:71], v[70:71], v[86:87] op_sel_hi:[1,0]
	v_pk_mul_f32 v[68:69], v[68:69], v[86:87] op_sel_hi:[1,0]
	v_pk_fma_f32 v[70:71], v[74:75], v[70:71], v[78:79]
	v_pk_fma_f32 v[68:69], v[72:73], v[68:69], v[76:77]
	v_pk_fma_f32 v[62:63], v[70:71], s[26:27], v[62:63] op_sel_hi:[1,0,1]
	v_pk_fma_f32 v[60:61], v[68:69], s[26:27], v[60:61] op_sel_hi:[1,0,1]
	global_store_dwordx4 v[66:67], v[60:63], off
	global_load_dwordx4 v[68:71], v[146:147], off
	global_load_dwordx4 v[72:75], v[148:149], off
	v_lshlrev_b64 v[76:77], 11, v[84:85]
	v_lshl_add_u64 v[76:77], s[14:15], 0, v[76:77]
	v_lshl_add_u64 v[84:85], v[144:145], 1, v[76:77]
	v_sub_f32_e32 v77, v81, v87
	v_sub_f32_e32 v76, v80, v87
	v_sub_f32_e32 v79, v83, v87
	v_sub_f32_e32 v78, v82, v87
	v_pk_mul_f32 v[78:79], v[78:79], v[86:87] op_sel_hi:[1,0]
	v_pk_mul_f32 v[80:81], v[76:77], v[86:87] op_sel_hi:[1,0]
	v_cvt_pk_bf16_f32 v76, v60, v61
	v_cvt_pk_bf16_f32 v77, v62, v63
	s_waitcnt vmcnt(0)
	v_pk_fma_f32 v[70:71], v[70:71], v[78:79], v[74:75]
	v_pk_fma_f32 v[68:69], v[68:69], v[80:81], v[72:73]
	v_pk_fma_f32 v[58:59], v[70:71], s[26:27], v[58:59] op_sel_hi:[1,0,1]
	v_pk_fma_f32 v[56:57], v[68:69], s[26:27], v[56:57] op_sel_hi:[1,0,1]
	global_store_dwordx4 v[66:67], v[56:59], off offset:16
	v_cvt_pk_bf16_f32 v78, v56, v57
	v_cvt_pk_bf16_f32 v79, v58, v59
	flat_store_dwordx4 v[84:85], v[76:79]
	global_load_dwordx4 v[68:71], v[66:67], off offset:512
	global_load_dwordx4 v[72:75], v[120:121], off
	s_nop 0
	global_load_dwordx4 v[76:79], v[122:123], off
	global_load_dwordx4 v[80:83], v[66:67], off offset:528
	s_waitcnt vmcnt(0)
	v_sub_f32_e32 v69, v69, v87
	v_sub_f32_e32 v68, v68, v87
	v_sub_f32_e32 v71, v71, v87
	v_sub_f32_e32 v70, v70, v87
	v_pk_mul_f32 v[70:71], v[86:87], v[70:71] op_sel_hi:[0,1]
	v_pk_mul_f32 v[68:69], v[86:87], v[68:69] op_sel_hi:[0,1]
	v_pk_fma_f32 v[68:69], v[72:73], v[68:69], v[76:77]
	v_pk_fma_f32 v[70:71], v[74:75], v[70:71], v[78:79]
	v_pk_fma_f32 v[52:53], v[68:69], s[26:27], v[52:53] op_sel_hi:[1,0,1]
	v_pk_fma_f32 v[54:55], v[70:71], s[26:27], v[54:55] op_sel_hi:[1,0,1]
	global_store_dwordx4 v[66:67], v[52:55], off offset:512
	global_load_dwordx4 v[68:71], v[124:125], off
	global_load_dwordx4 v[72:75], v[126:127], off
	v_add_f32_e32 v76, v60, v61
	v_mul_f32_e32 v61, v61, v61
	v_fmac_f32_e32 v61, v60, v60
	v_add_f32_e32 v76, v62, v76
	v_fmac_f32_e32 v61, v62, v62
	v_add_f32_e32 v62, v56, v57
	v_mul_f32_e32 v57, v57, v57
	v_fmac_f32_e32 v57, v56, v56
	v_add_f32_e32 v60, v63, v76
	v_add_f32_e32 v62, v58, v62
	v_fmac_f32_e32 v57, v58, v58
	v_add_f32_e32 v60, 0, v60
	v_fmac_f32_e32 v61, v63, v63
	v_add_f32_e32 v56, v59, v62
	v_fmac_f32_e32 v57, v59, v59
	v_add_f32_e32 v60, v56, v60
	v_add_f32_e32 v61, v61, v57
	v_sub_f32_e32 v57, v81, v87
	v_sub_f32_e32 v56, v80, v87
	v_pk_mul_f32 v[56:57], v[86:87], v[56:57] op_sel_hi:[0,1]
	v_sub_f32_e32 v59, v83, v87
	v_sub_f32_e32 v58, v82, v87
	v_pk_mul_f32 v[58:59], v[86:87], v[58:59] op_sel_hi:[0,1]
	v_mul_f32_e32 v63, v53, v53
	v_add_f32_e32 v62, v52, v53
	v_fmac_f32_e32 v63, v52, v52
	v_add_f32_e32 v62, v54, v62
	v_fmac_f32_e32 v63, v54, v54
	v_add_f32_e32 v62, v55, v62
	v_fmac_f32_e32 v63, v55, v55
	v_add_f32_e32 v60, v60, v62
	v_add_f32_e32 v61, v61, v63
	v_cvt_pk_bf16_f32 v52, v52, v53
	v_cvt_pk_bf16_f32 v53, v54, v55
	s_waitcnt vmcnt(0)
	v_pk_fma_f32 v[56:57], v[68:69], v[56:57], v[72:73]
	s_nop 0
	v_pk_fma_f32 v[56:57], v[56:57], s[26:27], v[48:49] op_sel_hi:[1,0,1]
	v_pk_fma_f32 v[58:59], v[70:71], v[58:59], v[74:75]
	v_mul_f32_e32 v49, v57, v57
	v_pk_fma_f32 v[58:59], v[58:59], s[26:27], v[50:51] op_sel_hi:[1,0,1]
	v_add_f32_e32 v48, v56, v57
	v_fmac_f32_e32 v49, v56, v56
	v_add_f32_e32 v48, v58, v48
	v_fmac_f32_e32 v49, v58, v58
	v_add_f32_e32 v48, v59, v48
	v_fmac_f32_e32 v49, v59, v59
	v_add_f32_e32 v48, v60, v48
	v_add_f32_e32 v49, v61, v49
	ds_bpermute_b32 v50, v116, v48
	ds_bpermute_b32 v51, v116, v49
	global_store_dwordx4 v[66:67], v[56:59], off offset:528
	v_cvt_pk_bf16_f32 v54, v56, v57
	v_cvt_pk_bf16_f32 v55, v58, v59
	s_waitcnt lgkmcnt(0)
	v_add_f32_e32 v48, v48, v50
	v_add_f32_e32 v49, v49, v51
	ds_bpermute_b32 v50, v117, v48
	ds_bpermute_b32 v51, v117, v49
	flat_store_dwordx4 v[84:85], v[52:55] offset:256
	s_mov_b32 s100, -1
	s_mov_b32 s101, 0
	s_mov_b32 s98, 0xffff0000
	s_mov_b32 s99, 0
	s_and_saveexec_b64 s[30:31], s[100:101]
	s_cbranch_execz .LBB0_2202
	s_waitcnt lgkmcnt(0)
	v_add_f32_e32 v51, v49, v51
	v_add_f32_e32 v50, v48, v50
	v_lshl_add_u64 v[48:49], s[10:11], 0, v[64:65]
	v_cndmask_b32_e64 v50, v50, v51, s[98:99]
	v_cndmask_b32_e64 v51, 0, 4, s[98:99]
	v_or_b32_e32 v48, v48, v51
	v_mov_b32_e32 v250, v48
	v_mov_b32_e32 v251, v49
	v_mov_b32_e32 v252, v50
; DEVI unsigned pk2(float lo, float hi) { unsigned r; asm("v_cvt_pk_bf16_f32 %0, %1, %2" : "=v"(r) : "v"(lo), "v"(hi)); return r; }
;     DEVI void operator()(const f32x4 (&acc)[2][2][4][2], const pg8::Unit& u, int wr, int wc, int fr, int fq) const {
;     ...
;                 const int row = row0 + ai * 128 + m * 16; float mu, rs; row_stats(stin, row, mu, rs);
;                 float sum = 0.f, sq = 0.f;
; #pragma unroll
;                 for (int bj = 0; bj < 2; ++bj) {
;                     f32x4 z[2];
; #pragma unroll
;                     for (int n = 0; n < 2; ++n) {
;                         const int col = colb + bj * 128 + 4 * n;
;                         f32x4 xv = *(const f32x4*)(zsrc + (size_t)row * DM + col);
;                         if (stin) { const f32x4 gv = *(const f32x4*)(gin + col), bv = *(const f32x4*)(bin + col); xv = (xv - mu) * rs * gv + bv; }
;                         f32x4 zz = ALPHA * xv + acc[ai][bj][m][n];
;                         if (bias) zz += *(const f32x4*)(bias + col);
;                         *(f32x4*)(zdst + (size_t)row * DM + col) = zz;
;                         sum += zz[0] + zz[1] + zz[2] + zz[3]; sq += zz[0] * zz[0] + zz[1] * zz[1] + zz[2] * zz[2] + zz[3] * zz[3];
;                         z[n] = zz;
;                     }
;                     u32x4 o; o.x = pk2(z[0][0], z[0][1]); o.y = pk2(z[0][2], z[0][3]); o.z = pk2(z[1][0], z[1][1]); o.w = pk2(z[1][2], z[1][3]);
;                     if (zb) *(u32x4*)(zb + (size_t)row * DM + colb + bj * 128) = o;
;                 }
;                 sum += __shfl_xor(sum, 16); sq += __shfl_xor(sq, 16);
;                 sum += __shfl_xor(sum, 32); sq += __shfl_xor(sq, 32);
;                 if (fq == 0) { atomicAdd(stout + 2 * (size_t)row, sum); atomicAdd(stout + 2 * (size_t)row + 1, sq); }
.LBB0_2202:
	s_or_b64 exec, exec, s[30:31]
	v_add_u32_e32 v68, 0x90, v154
	v_ashrrev_i32_e32 v69, 31, v68
	v_lshlrev_b64 v[48:49], 3, v[68:69]
	s_waitcnt lgkmcnt(0)
	v_lshl_add_u64 v[50:51], s[12:13], 0, v[48:49]
	flat_load_dwordx2 v[70:71], v[50:51]
	v_lshlrev_b64 v[50:51], 12, v[68:69]
	v_lshl_add_u64 v[50:51], s[46:47], 0, v[50:51]
	v_lshl_add_u64 v[50:51], v[144:145], 2, v[50:51]
	global_load_dwordx4 v[52:55], v[50:51], off
	global_load_dwordx4 v[56:59], v[150:151], off
	global_load_dwordx4 v[60:63], v[152:153], off
	global_load_dwordx4 v[64:67], v[50:51], off offset:16
	s_waitcnt vmcnt(0) lgkmcnt(0)
	v_pk_mul_f32 v[70:71], v[70:71], s[24:25] op_sel:[1,0] op_sel_hi:[0,0]
	v_fma_f32 v70, -v71, v71, v70
	v_max_f32_e32 v70, 0, v70
	v_add_f32_e32 v70, 0x3727c5ac, v70
	v_mul_f32_e32 v72, 0x4b800000, v70
	v_cmp_gt_f32_e32 vcc, s61, v70
	v_sub_f32_e32 v53, v53, v71
	v_sub_f32_e32 v52, v52, v71
	v_cndmask_b32_e32 v70, v70, v72, vcc
	v_rsq_f32_e32 v70, v70
	v_sub_f32_e32 v55, v55, v71
	v_sub_f32_e32 v54, v54, v71
	v_mul_f32_e32 v72, 0x45800000, v70
	v_cndmask_b32_e32 v70, v70, v72, vcc
	v_pk_mul_f32 v[54:55], v[54:55], v[70:71] op_sel_hi:[1,0]
	v_pk_mul_f32 v[52:53], v[52:53], v[70:71] op_sel_hi:[1,0]
	v_pk_fma_f32 v[54:55], v[58:59], v[54:55], v[62:63]
	v_pk_fma_f32 v[52:53], v[56:57], v[52:53], v[60:61]
	v_pk_fma_f32 v[46:47], v[54:55], s[26:27], v[46:47] op_sel_hi:[1,0,1]
	v_pk_fma_f32 v[44:45], v[52:53], s[26:27], v[44:45] op_sel_hi:[1,0,1]
	global_store_dwordx4 v[50:51], v[44:47], off
	global_load_dwordx4 v[52:55], v[146:147], off
	global_load_dwordx4 v[56:59], v[148:149], off
	v_lshlrev_b64 v[60:61], 11, v[68:69]
	v_lshl_add_u64 v[60:61], s[14:15], 0, v[60:61]
	v_lshl_add_u64 v[68:69], v[144:145], 1, v[60:61]
	v_sub_f32_e32 v61, v65, v71
	v_sub_f32_e32 v60, v64, v71
	v_sub_f32_e32 v63, v67, v71
	v_sub_f32_e32 v62, v66, v71
	v_pk_mul_f32 v[62:63], v[62:63], v[70:71] op_sel_hi:[1,0]
	v_pk_mul_f32 v[64:65], v[60:61], v[70:71] op_sel_hi:[1,0]
	v_cvt_pk_bf16_f32 v60, v44, v45
	v_cvt_pk_bf16_f32 v61, v46, v47
	s_waitcnt vmcnt(0)
	v_pk_fma_f32 v[54:55], v[54:55], v[62:63], v[58:59]
	v_pk_fma_f32 v[52:53], v[52:53], v[64:65], v[56:57]
	v_pk_fma_f32 v[42:43], v[54:55], s[26:27], v[42:43] op_sel_hi:[1,0,1]
	v_pk_fma_f32 v[40:41], v[52:53], s[26:27], v[40:41] op_sel_hi:[1,0,1]
	global_store_dwordx4 v[50:51], v[40:43], off offset:16
	v_cvt_pk_bf16_f32 v62, v40, v41
	v_cvt_pk_bf16_f32 v63, v42, v43
	flat_store_dwordx4 v[68:69], v[60:63]
	global_load_dwordx4 v[52:55], v[50:51], off offset:512
	global_load_dwordx4 v[56:59], v[120:121], off
	s_nop 0
	global_load_dwordx4 v[60:63], v[122:123], off
	global_load_dwordx4 v[64:67], v[50:51], off offset:528
	s_waitcnt vmcnt(0)
	v_sub_f32_e32 v53, v53, v71
	v_sub_f32_e32 v52, v52, v71
	v_sub_f32_e32 v55, v55, v71
	v_sub_f32_e32 v54, v54, v71
	v_pk_mul_f32 v[54:55], v[70:71], v[54:55] op_sel_hi:[0,1]
	v_pk_mul_f32 v[52:53], v[70:71], v[52:53] op_sel_hi:[0,1]
	v_pk_fma_f32 v[52:53], v[56:57], v[52:53], v[60:61]
	v_pk_fma_f32 v[54:55], v[58:59], v[54:55], v[62:63]
	v_pk_fma_f32 v[36:37], v[52:53], s[26:27], v[36:37] op_sel_hi:[1,0,1]
	v_pk_fma_f32 v[38:39], v[54:55], s[26:27], v[38:39] op_sel_hi:[1,0,1]
	global_store_dwordx4 v[50:51], v[36:39], off offset:512
	global_load_dwordx4 v[52:55], v[124:125], off
	global_load_dwordx4 v[56:59], v[126:127], off
	v_add_f32_e32 v60, v44, v45
	v_mul_f32_e32 v45, v45, v45
	v_fmac_f32_e32 v45, v44, v44
	v_add_f32_e32 v60, v46, v60
	v_fmac_f32_e32 v45, v46, v46
	v_add_f32_e32 v46, v40, v41
	v_mul_f32_e32 v41, v41, v41
	v_fmac_f32_e32 v41, v40, v40
	v_add_f32_e32 v44, v47, v60
	v_add_f32_e32 v46, v42, v46
	v_fmac_f32_e32 v41, v42, v42
	v_add_f32_e32 v44, 0, v44
	v_fmac_f32_e32 v45, v47, v47
	v_add_f32_e32 v40, v43, v46
	v_fmac_f32_e32 v41, v43, v43
	v_add_f32_e32 v44, v40, v44
	v_add_f32_e32 v45, v45, v41
	v_sub_f32_e32 v41, v65, v71
	v_sub_f32_e32 v40, v64, v71
	v_pk_mul_f32 v[40:41], v[70:71], v[40:41] op_sel_hi:[0,1]
	v_sub_f32_e32 v43, v67, v71
	v_sub_f32_e32 v42, v66, v71
	v_pk_mul_f32 v[42:43], v[70:71], v[42:43] op_sel_hi:[0,1]
	v_mul_f32_e32 v47, v37, v37
	v_add_f32_e32 v46, v36, v37
	v_fmac_f32_e32 v47, v36, v36
	v_add_f32_e32 v46, v38, v46
	v_fmac_f32_e32 v47, v38, v38
	v_add_f32_e32 v46, v39, v46
	v_fmac_f32_e32 v47, v39, v39
	v_add_f32_e32 v44, v44, v46
	v_add_f32_e32 v45, v45, v47
	v_cvt_pk_bf16_f32 v36, v36, v37
	v_cvt_pk_bf16_f32 v37, v38, v39
	s_waitcnt vmcnt(0)
	v_pk_fma_f32 v[40:41], v[52:53], v[40:41], v[56:57]
	s_nop 0
	v_pk_fma_f32 v[40:41], v[40:41], s[26:27], v[32:33] op_sel_hi:[1,0,1]
	v_pk_fma_f32 v[42:43], v[54:55], v[42:43], v[58:59]
	v_mul_f32_e32 v33, v41, v41
	v_pk_fma_f32 v[42:43], v[42:43], s[26:27], v[34:35] op_sel_hi:[1,0,1]
	v_add_f32_e32 v32, v40, v41
	v_fmac_f32_e32 v33, v40, v40
	v_add_f32_e32 v32, v42, v32
	v_fmac_f32_e32 v33, v42, v42
	v_add_f32_e32 v32, v43, v32
	v_fmac_f32_e32 v33, v43, v43
	v_add_f32_e32 v32, v44, v32
	v_add_f32_e32 v33, v45, v33
	ds_bpermute_b32 v34, v116, v32
	ds_bpermute_b32 v35, v116, v33
	global_store_dwordx4 v[50:51], v[40:43], off offset:528
	v_cvt_pk_bf16_f32 v38, v40, v41
	v_cvt_pk_bf16_f32 v39, v42, v43
	s_waitcnt lgkmcnt(0)
	v_add_f32_e32 v32, v32, v34
	v_add_f32_e32 v33, v33, v35
	ds_bpermute_b32 v34, v117, v32
	ds_bpermute_b32 v35, v117, v33
	flat_store_dwordx4 v[68:69], v[36:39] offset:256
	s_mov_b32 s100, -1
	s_mov_b32 s101, 0
	s_mov_b32 s98, 0xffff0000
	s_mov_b32 s99, 0
	s_and_saveexec_b64 s[30:31], s[100:101]
	s_cbranch_execz .LBB0_2204
	s_waitcnt lgkmcnt(0)
	v_add_f32_e32 v35, v33, v35
	v_add_f32_e32 v34, v32, v34
	v_lshl_add_u64 v[32:33], s[10:11], 0, v[48:49]
	v_cndmask_b32_e64 v34, v34, v35, s[98:99]
	v_cndmask_b32_e64 v35, 0, 4, s[98:99]
	v_or_b32_e32 v32, v32, v35
	v_mov_b32_e32 v253, v34
; DEVI unsigned pk2(float lo, float hi) { unsigned r; asm("v_cvt_pk_bf16_f32 %0, %1, %2" : "=v"(r) : "v"(lo), "v"(hi)); return r; }
;     DEVI void operator()(const f32x4 (&acc)[2][2][4][2], const pg8::Unit& u, int wr, int wc, int fr, int fq) const {
;     ...
;                 const int row = row0 + ai * 128 + m * 16; float mu, rs; row_stats(stin, row, mu, rs);
;                 float sum = 0.f, sq = 0.f;
; #pragma unroll
;                 for (int bj = 0; bj < 2; ++bj) {
;                     f32x4 z[2];
; #pragma unroll
;                     for (int n = 0; n < 2; ++n) {
;                         const int col = colb + bj * 128 + 4 * n;
;                         f32x4 xv = *(const f32x4*)(zsrc + (size_t)row * DM + col);
;                         if (stin) { const f32x4 gv = *(const f32x4*)(gin + col), bv = *(const f32x4*)(bin + col); xv = (xv - mu) * rs * gv + bv; }
;                         f32x4 zz = ALPHA * xv + acc[ai][bj][m][n];
;                         if (bias) zz += *(const f32x4*)(bias + col);
;                         *(f32x4*)(zdst + (size_t)row * DM + col) = zz;
;                         sum += zz[0] + zz[1] + zz[2] + zz[3]; sq += zz[0] * zz[0] + zz[1] * zz[1] + zz[2] * zz[2] + zz[3] * zz[3];
;                         z[n] = zz;
;                     }
;                     u32x4 o; o.x = pk2(z[0][0], z[0][1]); o.y = pk2(z[0][2], z[0][3]); o.z = pk2(z[1][0], z[1][1]); o.w = pk2(z[1][2], z[1][3]);
;                     if (zb) *(u32x4*)(zb + (size_t)row * DM + colb + bj * 128) = o;
;                 }
;                 sum += __shfl_xor(sum, 16); sq += __shfl_xor(sq, 16);
;                 sum += __shfl_xor(sum, 32); sq += __shfl_xor(sq, 32);
;                 if (fq == 0) { atomicAdd(stout + 2 * (size_t)row, sum); atomicAdd(stout + 2 * (size_t)row + 1, sq); }
.LBB0_2204:
	s_or_b64 exec, exec, s[30:31]
	v_add_u32_e32 v52, 0xa0, v154
	v_ashrrev_i32_e32 v53, 31, v52
	v_lshlrev_b64 v[32:33], 3, v[52:53]
	s_waitcnt lgkmcnt(0)
	v_lshl_add_u64 v[34:35], s[12:13], 0, v[32:33]
	flat_load_dwordx2 v[54:55], v[34:35]
	v_lshlrev_b64 v[34:35], 12, v[52:53]
	v_lshl_add_u64 v[34:35], s[46:47], 0, v[34:35]
	v_lshl_add_u64 v[34:35], v[144:145], 2, v[34:35]
	global_load_dwordx4 v[36:39], v[34:35], off
	global_load_dwordx4 v[40:43], v[150:151], off
	global_load_dwordx4 v[44:47], v[152:153], off
	global_load_dwordx4 v[48:51], v[34:35], off offset:16
	s_waitcnt vmcnt(0) lgkmcnt(0)
	v_pk_mul_f32 v[54:55], v[54:55], s[24:25] op_sel:[1,0] op_sel_hi:[0,0]
	v_fma_f32 v54, -v55, v55, v54
	v_max_f32_e32 v54, 0, v54
	v_add_f32_e32 v54, 0x3727c5ac, v54
	v_mul_f32_e32 v56, 0x4b800000, v54
	v_cmp_gt_f32_e32 vcc, s61, v54
	v_sub_f32_e32 v37, v37, v55
	v_sub_f32_e32 v36, v36, v55
	v_cndmask_b32_e32 v54, v54, v56, vcc
	v_rsq_f32_e32 v54, v54
	v_sub_f32_e32 v39, v39, v55
	v_sub_f32_e32 v38, v38, v55
	v_mul_f32_e32 v56, 0x45800000, v54
	v_cndmask_b32_e32 v54, v54, v56, vcc
	v_pk_mul_f32 v[38:39], v[38:39], v[54:55] op_sel_hi:[1,0]
	v_pk_mul_f32 v[36:37], v[36:37], v[54:55] op_sel_hi:[1,0]
	v_pk_fma_f32 v[38:39], v[42:43], v[38:39], v[46:47]
	v_pk_fma_f32 v[36:37], v[40:41], v[36:37], v[44:45]
	v_pk_fma_f32 v[30:31], v[38:39], s[26:27], v[30:31] op_sel_hi:[1,0,1]
	v_pk_fma_f32 v[28:29], v[36:37], s[26:27], v[28:29] op_sel_hi:[1,0,1]
	global_store_dwordx4 v[34:35], v[28:31], off
	global_load_dwordx4 v[36:39], v[146:147], off
	global_load_dwordx4 v[40:43], v[148:149], off
	v_lshlrev_b64 v[44:45], 11, v[52:53]
	v_lshl_add_u64 v[44:45], s[14:15], 0, v[44:45]
	v_lshl_add_u64 v[52:53], v[144:145], 1, v[44:45]
	v_sub_f32_e32 v45, v49, v55
	v_sub_f32_e32 v44, v48, v55
	v_sub_f32_e32 v47, v51, v55
	v_sub_f32_e32 v46, v50, v55
	v_pk_mul_f32 v[46:47], v[46:47], v[54:55] op_sel_hi:[1,0]
	v_pk_mul_f32 v[48:49], v[44:45], v[54:55] op_sel_hi:[1,0]
	v_cvt_pk_bf16_f32 v44, v28, v29
	v_cvt_pk_bf16_f32 v45, v30, v31
	s_waitcnt vmcnt(0)
	v_pk_fma_f32 v[38:39], v[38:39], v[46:47], v[42:43]
	v_pk_fma_f32 v[36:37], v[36:37], v[48:49], v[40:41]
	v_pk_fma_f32 v[26:27], v[38:39], s[26:27], v[26:27] op_sel_hi:[1,0,1]
	v_pk_fma_f32 v[24:25], v[36:37], s[26:27], v[24:25] op_sel_hi:[1,0,1]
	global_store_dwordx4 v[34:35], v[24:27], off offset:16
	v_cvt_pk_bf16_f32 v46, v24, v25
	v_cvt_pk_bf16_f32 v47, v26, v27
	flat_store_dwordx4 v[52:53], v[44:47]
	global_load_dwordx4 v[36:39], v[34:35], off offset:512
	global_load_dwordx4 v[40:43], v[120:121], off
	s_nop 0
	global_load_dwordx4 v[44:47], v[122:123], off
	global_load_dwordx4 v[48:51], v[34:35], off offset:528
	s_waitcnt vmcnt(0)
	v_sub_f32_e32 v37, v37, v55
	v_sub_f32_e32 v36, v36, v55
	v_sub_f32_e32 v39, v39, v55
	v_sub_f32_e32 v38, v38, v55
	v_pk_mul_f32 v[38:39], v[54:55], v[38:39] op_sel_hi:[0,1]
	v_pk_mul_f32 v[36:37], v[54:55], v[36:37] op_sel_hi:[0,1]
	v_pk_fma_f32 v[36:37], v[40:41], v[36:37], v[44:45]
	v_pk_fma_f32 v[38:39], v[42:43], v[38:39], v[46:47]
	v_pk_fma_f32 v[20:21], v[36:37], s[26:27], v[20:21] op_sel_hi:[1,0,1]
	v_pk_fma_f32 v[22:23], v[38:39], s[26:27], v[22:23] op_sel_hi:[1,0,1]
	global_store_dwordx4 v[34:35], v[20:23], off offset:512
	global_load_dwordx4 v[36:39], v[124:125], off
	global_load_dwordx4 v[40:43], v[126:127], off
	v_add_f32_e32 v44, v28, v29
	v_mul_f32_e32 v29, v29, v29
	v_fmac_f32_e32 v29, v28, v28
	v_add_f32_e32 v44, v30, v44
	v_fmac_f32_e32 v29, v30, v30
	v_add_f32_e32 v30, v24, v25
	v_mul_f32_e32 v25, v25, v25
	v_fmac_f32_e32 v25, v24, v24
	v_add_f32_e32 v28, v31, v44
	v_add_f32_e32 v30, v26, v30
	v_fmac_f32_e32 v25, v26, v26
	v_add_f32_e32 v28, 0, v28
	v_fmac_f32_e32 v29, v31, v31
	v_add_f32_e32 v24, v27, v30
	v_fmac_f32_e32 v25, v27, v27
	v_add_f32_e32 v28, v24, v28
	v_add_f32_e32 v29, v29, v25
	v_sub_f32_e32 v25, v49, v55
	v_sub_f32_e32 v24, v48, v55
	v_pk_mul_f32 v[24:25], v[54:55], v[24:25] op_sel_hi:[0,1]
	v_sub_f32_e32 v27, v51, v55
	v_sub_f32_e32 v26, v50, v55
	v_pk_mul_f32 v[26:27], v[54:55], v[26:27] op_sel_hi:[0,1]
	v_mul_f32_e32 v31, v21, v21
	v_add_f32_e32 v30, v20, v21
	v_fmac_f32_e32 v31, v20, v20
	v_add_f32_e32 v30, v22, v30
	v_fmac_f32_e32 v31, v22, v22
	v_add_f32_e32 v30, v23, v30
	v_fmac_f32_e32 v31, v23, v23
	v_add_f32_e32 v28, v28, v30
	v_add_f32_e32 v29, v29, v31
	v_cvt_pk_bf16_f32 v20, v20, v21
	v_cvt_pk_bf16_f32 v21, v22, v23
	s_waitcnt vmcnt(0)
	v_pk_fma_f32 v[24:25], v[36:37], v[24:25], v[40:41]
	s_nop 0
	v_pk_fma_f32 v[24:25], v[24:25], s[26:27], v[16:17] op_sel_hi:[1,0,1]
	v_pk_fma_f32 v[26:27], v[38:39], v[26:27], v[42:43]
	v_mul_f32_e32 v17, v25, v25
	v_pk_fma_f32 v[26:27], v[26:27], s[26:27], v[18:19] op_sel_hi:[1,0,1]
	v_add_f32_e32 v16, v24, v25
	v_fmac_f32_e32 v17, v24, v24
	v_add_f32_e32 v16, v26, v16
	v_fmac_f32_e32 v17, v26, v26
	v_add_f32_e32 v16, v27, v16
	v_fmac_f32_e32 v17, v27, v27
	v_add_f32_e32 v16, v28, v16
	v_add_f32_e32 v17, v29, v17
	ds_bpermute_b32 v18, v116, v16
	ds_bpermute_b32 v19, v116, v17
	global_store_dwordx4 v[34:35], v[24:27], off offset:528
	v_cvt_pk_bf16_f32 v22, v24, v25
	v_cvt_pk_bf16_f32 v23, v26, v27
	s_waitcnt lgkmcnt(0)
	v_add_f32_e32 v16, v16, v18
	v_add_f32_e32 v17, v17, v19
	ds_bpermute_b32 v18, v117, v16
	ds_bpermute_b32 v19, v117, v17
	flat_store_dwordx4 v[52:53], v[20:23] offset:256
	s_mov_b32 s100, -1
	s_mov_b32 s101, 0
	s_mov_b32 s98, 0xffff0000
	s_mov_b32 s99, 0
	s_and_saveexec_b64 s[30:31], s[100:101]
	s_cbranch_execz .LBB0_2206
	s_waitcnt lgkmcnt(0)
	v_add_f32_e32 v19, v17, v19
	v_add_f32_e32 v18, v16, v18
	v_lshl_add_u64 v[16:17], s[10:11], 0, v[32:33]
	v_cndmask_b32_e64 v18, v18, v19, s[98:99]
	v_cndmask_b32_e64 v19, 0, 4, s[98:99]
	v_or_b32_e32 v16, v16, v19
	v_mov_b32_e32 v254, v18
; DEVI unsigned pk2(float lo, float hi) { unsigned r; asm("v_cvt_pk_bf16_f32 %0, %1, %2" : "=v"(r) : "v"(lo), "v"(hi)); return r; }
;     DEVI void operator()(const f32x4 (&acc)[2][2][4][2], const pg8::Unit& u, int wr, int wc, int fr, int fq) const {
;     ...
;                 const int row = row0 + ai * 128 + m * 16; float mu, rs; row_stats(stin, row, mu, rs);
;                 float sum = 0.f, sq = 0.f;
; #pragma unroll
;                 for (int bj = 0; bj < 2; ++bj) {
;                     f32x4 z[2];
; #pragma unroll
;                     for (int n = 0; n < 2; ++n) {
;                         const int col = colb + bj * 128 + 4 * n;
;                         f32x4 xv = *(const f32x4*)(zsrc + (size_t)row * DM + col);
;                         if (stin) { const f32x4 gv = *(const f32x4*)(gin + col), bv = *(const f32x4*)(bin + col); xv = (xv - mu) * rs * gv + bv; }
;                         f32x4 zz = ALPHA * xv + acc[ai][bj][m][n];
;                         if (bias) zz += *(const f32x4*)(bias + col);
;                         *(f32x4*)(zdst + (size_t)row * DM + col) = zz;
;                         sum += zz[0] + zz[1] + zz[2] + zz[3]; sq += zz[0] * zz[0] + zz[1] * zz[1] + zz[2] * zz[2] + zz[3] * zz[3];
;                         z[n] = zz;
;                     }
;                     u32x4 o; o.x = pk2(z[0][0], z[0][1]); o.y = pk2(z[0][2], z[0][3]); o.z = pk2(z[1][0], z[1][1]); o.w = pk2(z[1][2], z[1][3]);
;                     if (zb) *(u32x4*)(zb + (size_t)row * DM + colb + bj * 128) = o;
;                 }
;                 sum += __shfl_xor(sum, 16); sq += __shfl_xor(sq, 16);
;                 sum += __shfl_xor(sum, 32); sq += __shfl_xor(sq, 32);
;                 if (fq == 0) { atomicAdd(stout + 2 * (size_t)row, sum); atomicAdd(stout + 2 * (size_t)row + 1, sq); }
.LBB0_2206:
	s_or_b64 exec, exec, s[30:31]
	v_add_u32_e32 v36, 0xb0, v154
	v_ashrrev_i32_e32 v37, 31, v36
	v_lshlrev_b64 v[16:17], 3, v[36:37]
	s_waitcnt lgkmcnt(0)
	v_lshl_add_u64 v[18:19], s[12:13], 0, v[16:17]
	flat_load_dwordx2 v[38:39], v[18:19]
	v_lshlrev_b64 v[18:19], 12, v[36:37]
	v_lshl_add_u64 v[18:19], s[46:47], 0, v[18:19]
	v_lshl_add_u64 v[18:19], v[144:145], 2, v[18:19]
	global_load_dwordx4 v[20:23], v[18:19], off
	global_load_dwordx4 v[24:27], v[150:151], off
	global_load_dwordx4 v[28:31], v[152:153], off
	global_load_dwordx4 v[32:35], v[18:19], off offset:16
	s_waitcnt vmcnt(0) lgkmcnt(0)
	v_pk_mul_f32 v[38:39], v[38:39], s[24:25] op_sel:[1,0] op_sel_hi:[0,0]
	v_fma_f32 v38, -v39, v39, v38
	v_max_f32_e32 v38, 0, v38
	v_add_f32_e32 v38, 0x3727c5ac, v38
	v_mul_f32_e32 v40, 0x4b800000, v38
	v_cmp_gt_f32_e32 vcc, s61, v38
	v_sub_f32_e32 v21, v21, v39
	v_sub_f32_e32 v20, v20, v39
	v_cndmask_b32_e32 v38, v38, v40, vcc
	v_rsq_f32_e32 v38, v38
	v_sub_f32_e32 v23, v23, v39
	v_sub_f32_e32 v22, v22, v39
	v_mul_f32_e32 v40, 0x45800000, v38
	v_cndmask_b32_e32 v38, v38, v40, vcc
	v_pk_mul_f32 v[22:23], v[22:23], v[38:39] op_sel_hi:[1,0]
	v_pk_mul_f32 v[20:21], v[20:21], v[38:39] op_sel_hi:[1,0]
	v_pk_fma_f32 v[22:23], v[26:27], v[22:23], v[30:31]
	v_pk_fma_f32 v[20:21], v[24:25], v[20:21], v[28:29]
	v_pk_fma_f32 v[14:15], v[22:23], s[26:27], v[14:15] op_sel_hi:[1,0,1]
	v_pk_fma_f32 v[12:13], v[20:21], s[26:27], v[12:13] op_sel_hi:[1,0,1]
	global_store_dwordx4 v[18:19], v[12:15], off
	global_load_dwordx4 v[20:23], v[146:147], off
	global_load_dwordx4 v[24:27], v[148:149], off
	v_lshlrev_b64 v[28:29], 11, v[36:37]
	v_lshl_add_u64 v[28:29], s[14:15], 0, v[28:29]
	v_lshl_add_u64 v[36:37], v[144:145], 1, v[28:29]
	v_sub_f32_e32 v29, v33, v39
	v_sub_f32_e32 v28, v32, v39
	v_sub_f32_e32 v31, v35, v39
	v_sub_f32_e32 v30, v34, v39
	v_pk_mul_f32 v[30:31], v[30:31], v[38:39] op_sel_hi:[1,0]
	v_pk_mul_f32 v[32:33], v[28:29], v[38:39] op_sel_hi:[1,0]
	v_cvt_pk_bf16_f32 v28, v12, v13
	v_cvt_pk_bf16_f32 v29, v14, v15
	s_waitcnt vmcnt(0)
	v_pk_fma_f32 v[22:23], v[22:23], v[30:31], v[26:27]
	v_pk_fma_f32 v[20:21], v[20:21], v[32:33], v[24:25]
	v_pk_fma_f32 v[10:11], v[22:23], s[26:27], v[10:11] op_sel_hi:[1,0,1]
	v_pk_fma_f32 v[8:9], v[20:21], s[26:27], v[8:9] op_sel_hi:[1,0,1]
	global_store_dwordx4 v[18:19], v[8:11], off offset:16
	v_cvt_pk_bf16_f32 v30, v8, v9
	v_cvt_pk_bf16_f32 v31, v10, v11
	flat_store_dwordx4 v[36:37], v[28:31]
	global_load_dwordx4 v[20:23], v[18:19], off offset:512
	global_load_dwordx4 v[24:27], v[120:121], off
	s_nop 0
	global_load_dwordx4 v[28:31], v[122:123], off
	global_load_dwordx4 v[32:35], v[18:19], off offset:528
	s_waitcnt vmcnt(0)
	v_sub_f32_e32 v21, v21, v39
	v_sub_f32_e32 v20, v20, v39
	v_sub_f32_e32 v23, v23, v39
	v_sub_f32_e32 v22, v22, v39
	v_pk_mul_f32 v[22:23], v[38:39], v[22:23] op_sel_hi:[0,1]
	v_pk_mul_f32 v[20:21], v[38:39], v[20:21] op_sel_hi:[0,1]
	v_pk_fma_f32 v[20:21], v[24:25], v[20:21], v[28:29]
	v_pk_fma_f32 v[22:23], v[26:27], v[22:23], v[30:31]
	v_pk_fma_f32 v[4:5], v[20:21], s[26:27], v[4:5] op_sel_hi:[1,0,1]
	v_pk_fma_f32 v[6:7], v[22:23], s[26:27], v[6:7] op_sel_hi:[1,0,1]
	global_store_dwordx4 v[18:19], v[4:7], off offset:512
	global_load_dwordx4 v[20:23], v[124:125], off
	global_load_dwordx4 v[24:27], v[126:127], off
	v_add_f32_e32 v28, v12, v13
	v_mul_f32_e32 v13, v13, v13
	v_fmac_f32_e32 v13, v12, v12
	v_add_f32_e32 v28, v14, v28
	v_fmac_f32_e32 v13, v14, v14
	v_add_f32_e32 v14, v8, v9
	v_mul_f32_e32 v9, v9, v9
	v_fmac_f32_e32 v9, v8, v8
	v_add_f32_e32 v12, v15, v28
	v_add_f32_e32 v14, v10, v14
	v_fmac_f32_e32 v9, v10, v10
	v_add_f32_e32 v12, 0, v12
	v_fmac_f32_e32 v13, v15, v15
	v_add_f32_e32 v8, v11, v14
	v_fmac_f32_e32 v9, v11, v11
	v_add_f32_e32 v12, v8, v12
	v_add_f32_e32 v13, v13, v9
	v_sub_f32_e32 v9, v33, v39
	v_sub_f32_e32 v8, v32, v39
	v_pk_mul_f32 v[8:9], v[38:39], v[8:9] op_sel_hi:[0,1]
	v_sub_f32_e32 v11, v35, v39
	v_sub_f32_e32 v10, v34, v39
	v_pk_mul_f32 v[10:11], v[38:39], v[10:11] op_sel_hi:[0,1]
	v_mul_f32_e32 v15, v5, v5
	v_add_f32_e32 v14, v4, v5
	v_fmac_f32_e32 v15, v4, v4
	v_add_f32_e32 v14, v6, v14
	v_fmac_f32_e32 v15, v6, v6
	v_add_f32_e32 v14, v7, v14
	v_fmac_f32_e32 v15, v7, v7
	v_add_f32_e32 v12, v12, v14
	v_add_f32_e32 v13, v13, v15
	v_cvt_pk_bf16_f32 v4, v4, v5
	v_cvt_pk_bf16_f32 v5, v6, v7
	s_waitcnt vmcnt(0)
	v_pk_fma_f32 v[8:9], v[20:21], v[8:9], v[24:25]
	s_nop 0
	v_pk_fma_f32 v[8:9], v[8:9], s[26:27], v[0:1] op_sel_hi:[1,0,1]
	v_pk_fma_f32 v[10:11], v[22:23], v[10:11], v[26:27]
	v_mul_f32_e32 v1, v9, v9
	v_pk_fma_f32 v[10:11], v[10:11], s[26:27], v[2:3] op_sel_hi:[1,0,1]
	v_add_f32_e32 v0, v8, v9
	v_fmac_f32_e32 v1, v8, v8
	v_add_f32_e32 v0, v10, v0
	v_fmac_f32_e32 v1, v10, v10
	v_add_f32_e32 v0, v11, v0
	v_fmac_f32_e32 v1, v11, v11
	v_add_f32_e32 v0, v12, v0
	v_add_f32_e32 v1, v13, v1
	ds_bpermute_b32 v2, v116, v0
	ds_bpermute_b32 v3, v116, v1
	global_store_dwordx4 v[18:19], v[8:11], off offset:528
	v_cvt_pk_bf16_f32 v6, v8, v9
	v_cvt_pk_bf16_f32 v7, v10, v11
	s_waitcnt lgkmcnt(0)
	v_add_f32_e32 v0, v0, v2
	v_add_f32_e32 v1, v1, v3
	ds_bpermute_b32 v2, v117, v0
	ds_bpermute_b32 v3, v117, v1
	flat_store_dwordx4 v[36:37], v[4:7] offset:256
	s_mov_b32 s100, -1
	s_mov_b32 s101, 0
	s_mov_b32 s98, 0xffff0000
	s_mov_b32 s99, 0
	s_and_saveexec_b64 s[30:31], s[100:101]
	s_cbranch_execz .LBB0_2208
	s_waitcnt lgkmcnt(0)
	v_add_f32_e32 v3, v1, v3
	v_add_f32_e32 v2, v0, v2
	v_lshl_add_u64 v[0:1], s[10:11], 0, v[16:17]
	v_cndmask_b32_e64 v2, v2, v3, s[98:99]
	v_cndmask_b32_e64 v3, 0, 4, s[98:99]
	v_or_b32_e32 v0, v0, v3
	v_mov_b32_e32 v255, v2
	flat_atomic_add_f32 v[250:251], v252
	flat_atomic_add_f32 v[250:251], v253 offset:128
	flat_atomic_add_f32 v[250:251], v254 offset:256
	flat_atomic_add_f32 v[250:251], v255 offset:384

;     DEVI void operator()(const f32x4 (&acc)[2][2][4][2], const pg8::Unit& u, int wr, int wc, int fr, int fq) const {
;         const int row0 = u.pm * 256 + wr * 64 + fr, colb = u.pn * 256 + wc * 32 + 8 * fq;
; #pragma unroll
;         for (int ai = 0; ai < 2; ++ai)
; #pragma unroll
;             for (int m = 0; m < 4; ++m) {
;                 const int row = row0 + ai * 128 + m * 16; float mu, rs; row_stats(stin, row, mu, rs);
;                 float sum = 0.f, sq = 0.f;
; #pragma unroll
;                 for (int bj = 0; bj < 2; ++bj) {
;                     f32x4 z[2];
; #pragma unroll
;                     for (int n = 0; n < 2; ++n) {
;                         const int col = colb + bj * 128 + 4 * n;
;                         f32x4 xv = *(const f32x4*)(zsrc + (size_t)row * DM + col);
;                         if (stin) { const f32x4 gv = *(const f32x4*)(gin + col), bv = *(const f32x4*)(bin + col); xv = (xv - mu) * rs * gv + bv; }
;                         f32x4 zz = ALPHA * xv + acc[ai][bj][m][n];
;                         if (bias) zz += *(const f32x4*)(bias + col);
;                         *(f32x4*)(zdst + (size_t)row * DM + col) = zz;
.LBB0_2636:
	v_lshl_add_u32 v154, s36, 8, v168
	v_ashrrev_i32_e32 v155, 31, v154
	v_lshlrev_b64 v[162:163], 3, v[154:155]
	v_lshl_add_u64 v[146:147], s[6:7], 0, v[162:163]
	s_waitcnt vmcnt(0)
	flat_load_dwordx2 v[166:167], v[146:147]
	v_lshl_or_b32 v144, s38, 8, v170
	v_ashrrev_i32_e32 v145, 31, v144
	v_lshlrev_b64 v[146:147], 12, v[154:155]
	v_lshl_add_u64 v[146:147], s[46:47], 0, v[146:147]
	v_lshlrev_b64 v[148:149], 2, v[144:145]
	v_lshl_add_u64 v[164:165], v[146:147], 0, v[148:149]
	global_load_dwordx4 v[158:161], v[164:165], off
	v_lshl_add_u64 v[150:151], s[12:13], 0, v[148:149]
	v_lshl_add_u64 v[152:153], s[14:15], 0, v[148:149]
	global_load_dwordx4 v[176:179], v[150:151], off
	global_load_dwordx4 v[180:183], v[152:153], off
	v_lshl_add_u64 v[156:157], s[16:17], 0, v[148:149]
	global_load_dwordx4 v[184:187], v[156:157], off
	global_load_dwordx4 v[188:191], v[164:165], off offset:16
	v_or_b32_e32 v146, 4, v144
	v_ashrrev_i32_e32 v147, 31, v146
	v_lshlrev_b64 v[192:193], 2, v[146:147]
	v_lshl_add_u64 v[146:147], s[12:13], 0, v[192:193]
	v_lshl_add_u64 v[148:149], s[14:15], 0, v[192:193]
	s_waitcnt vmcnt(0) lgkmcnt(0)
	v_pk_mul_f32 v[166:167], v[166:167], s[22:23] op_sel:[1,0] op_sel_hi:[0,0]
	v_fma_f32 v166, -v167, v167, v166
	v_max_f32_e32 v166, 0, v166
	v_add_f32_e32 v166, 0x3727c5ac, v166
	v_mul_f32_e32 v175, 0x4b800000, v166
	v_cmp_gt_f32_e32 vcc, s64, v166
	v_sub_f32_e32 v161, v161, v167
	s_nop 0
	v_cndmask_b32_e32 v166, v166, v175, vcc
	v_rsq_f32_e32 v166, v166
	v_sub_f32_e32 v160, v160, v167
	v_sub_f32_e32 v159, v159, v167
	v_sub_f32_e32 v158, v158, v167
	v_mul_f32_e32 v175, 0x45800000, v166
	v_cndmask_b32_e32 v166, v166, v175, vcc
	v_pk_mul_f32 v[158:159], v[158:159], v[166:167] op_sel_hi:[1,0]
	v_pk_mul_f32 v[160:161], v[160:161], v[166:167] op_sel_hi:[1,0]
	v_pk_fma_f32 v[158:159], v[176:177], v[158:159], v[180:181]
	v_pk_fma_f32 v[160:161], v[178:179], v[160:161], v[182:183]
	v_pk_fma_f32 v[124:125], v[158:159], s[24:25], v[124:125] op_sel_hi:[1,0,1]
	v_pk_fma_f32 v[126:127], v[160:161], s[24:25], v[126:127] op_sel_hi:[1,0,1]
	v_pk_add_f32 v[176:177], v[184:185], v[124:125]
	v_pk_add_f32 v[178:179], v[186:187], v[126:127]
	global_store_dwordx4 v[164:165], v[176:179], off
	global_load_dwordx4 v[158:161], v[146:147], off
	global_load_dwordx4 v[180:183], v[148:149], off
	v_lshl_add_u64 v[124:125], s[16:17], 0, v[192:193]
	global_load_dwordx4 v[184:187], v[124:125], off
	v_lshlrev_b64 v[192:193], 11, v[154:155]
	v_lshl_add_u64 v[192:193], s[10:11], 0, v[192:193]
	v_sub_f32_e32 v191, v191, v167
	v_sub_f32_e32 v190, v190, v167
	v_sub_f32_e32 v189, v189, v167
	v_sub_f32_e32 v188, v188, v167
	v_lshl_add_u64 v[204:205], v[144:145], 1, v[192:193]
	v_pk_mul_f32 v[192:193], v[188:189], v[166:167] op_sel_hi:[1,0]
	v_pk_mul_f32 v[190:191], v[190:191], v[166:167] op_sel_hi:[1,0]
	v_or_b32_e32 v126, 0x80, v144
	v_cvt_pk_bf16_f32 v188, v176, v177
	v_cvt_pk_bf16_f32 v189, v178, v179
	v_ashrrev_i32_e32 v127, 31, v126
	v_xor_b32_e32 v155, 32, v174
	v_mul_f32_e32 v175, v177, v177
	v_fmac_f32_e32 v175, v176, v176
	v_fmac_f32_e32 v175, v178, v178
	v_fmac_f32_e32 v175, v179, v179
	s_waitcnt vmcnt(1)
	v_pk_fma_f32 v[160:161], v[160:161], v[190:191], v[182:183]
	v_pk_fma_f32 v[158:159], v[158:159], v[192:193], v[180:181]
	v_pk_fma_f32 v[122:123], v[160:161], s[24:25], v[122:123] op_sel_hi:[1,0,1]
	v_pk_fma_f32 v[120:121], v[158:159], s[24:25], v[120:121] op_sel_hi:[1,0,1]
	s_waitcnt vmcnt(0)
	v_pk_add_f32 v[182:183], v[186:187], v[122:123]
	v_pk_add_f32 v[180:181], v[184:185], v[120:121]
	global_store_dwordx4 v[164:165], v[180:183], off offset:16
	v_cvt_pk_bf16_f32 v190, v180, v181
	v_cvt_pk_bf16_f32 v191, v182, v183
	flat_store_dwordx4 v[204:205], v[188:191]
	global_load_dwordx4 v[184:187], v[164:165], off offset:512
	v_lshlrev_b64 v[120:121], 2, v[126:127]
	v_lshl_add_u64 v[126:127], s[12:13], 0, v[120:121]
	v_lshl_add_u64 v[158:159], s[14:15], 0, v[120:121]
	global_load_dwordx4 v[188:191], v[126:127], off
	global_load_dwordx4 v[192:195], v[158:159], off
	v_lshl_add_u64 v[160:161], s[16:17], 0, v[120:121]
	global_load_dwordx4 v[196:199], v[160:161], off
	global_load_dwordx4 v[200:203], v[164:165], off offset:528
	v_or_b32_e32 v120, 0x84, v144
	v_ashrrev_i32_e32 v121, 31, v120
	v_lshlrev_b64 v[206:207], 2, v[120:121]
	v_lshl_add_u64 v[120:121], s[12:13], 0, v[206:207]
	v_lshl_add_u64 v[122:123], s[14:15], 0, v[206:207]
	s_waitcnt vmcnt(0)
	v_sub_f32_e32 v187, v187, v167
	v_sub_f32_e32 v186, v186, v167
	v_sub_f32_e32 v185, v185, v167
	v_sub_f32_e32 v184, v184, v167
	v_pk_mul_f32 v[184:185], v[166:167], v[184:185] op_sel_hi:[0,1]
	v_pk_mul_f32 v[186:187], v[166:167], v[186:187] op_sel_hi:[0,1]
	v_pk_fma_f32 v[186:187], v[190:191], v[186:187], v[194:195]
	v_pk_fma_f32 v[184:185], v[188:189], v[184:185], v[192:193]
	v_pk_fma_f32 v[118:119], v[186:187], s[24:25], v[118:119] op_sel_hi:[1,0,1]
	v_pk_fma_f32 v[116:117], v[184:185], s[24:25], v[116:117] op_sel_hi:[1,0,1]
	v_pk_add_f32 v[186:187], v[198:199], v[118:119]
	v_pk_add_f32 v[184:185], v[196:197], v[116:117]
	global_store_dwordx4 v[164:165], v[184:187], off offset:512
	global_load_dwordx4 v[188:191], v[120:121], off
	global_load_dwordx4 v[192:195], v[122:123], off
	v_lshl_add_u64 v[116:117], s[16:17], 0, v[206:207]
	global_load_dwordx4 v[196:199], v[116:117], off
	v_and_b32_e32 v119, 64, v174
	v_xor_b32_e32 v118, 16, v174
	v_add_u32_e32 v119, 64, v119
	v_cmp_lt_i32_e32 vcc, v118, v119
	s_nop 1
	v_cndmask_b32_e32 v118, v174, v118, vcc
	v_cmp_lt_i32_e32 vcc, v155, v119
	v_lshlrev_b32_e32 v118, 2, v118
	s_nop 0
	v_cndmask_b32_e32 v119, v174, v155, vcc
	v_add_f32_e32 v155, v176, v177
	v_mul_f32_e32 v177, v181, v181
	v_add_f32_e32 v155, v178, v155
	v_add_f32_e32 v176, v180, v181
	v_fmac_f32_e32 v177, v180, v180
	v_add_f32_e32 v155, v179, v155
	v_add_f32_e32 v176, v182, v176
	v_fmac_f32_e32 v177, v182, v182
	v_add_f32_e32 v155, 0, v155
	v_add_f32_e32 v176, v183, v176
	v_fmac_f32_e32 v177, v183, v183
	v_add_f32_e32 v155, v176, v155
	v_add_f32_e32 v175, v175, v177
	v_sub_f32_e32 v177, v203, v167
	v_sub_f32_e32 v176, v202, v167
	v_sub_f32_e32 v179, v201, v167
	v_sub_f32_e32 v178, v200, v167
	v_pk_mul_f32 v[178:179], v[166:167], v[178:179] op_sel_hi:[0,1]
	v_pk_mul_f32 v[166:167], v[166:167], v[176:177] op_sel_hi:[0,1]
	v_mul_f32_e32 v177, v185, v185
	v_add_f32_e32 v176, v184, v185
	v_fmac_f32_e32 v177, v184, v184
	v_add_f32_e32 v176, v186, v176
	v_fmac_f32_e32 v177, v186, v186
	v_add_f32_e32 v176, v187, v176
	v_fmac_f32_e32 v177, v187, v187
	v_add_f32_e32 v155, v155, v176
	v_add_f32_e32 v175, v175, v177
	v_lshlrev_b32_e32 v119, 2, v119
	v_cvt_pk_bf16_f32 v180, v184, v185
	v_cvt_pk_bf16_f32 v181, v186, v187
	s_waitcnt vmcnt(0)
; DEVI unsigned pk2(float lo, float hi) { unsigned r; asm("v_cvt_pk_bf16_f32 %0, %1, %2" : "=v"(r) : "v"(lo), "v"(hi)); return r; }
;     DEVI void operator()(const f32x4 (&acc)[2][2][4][2], const pg8::Unit& u, int wr, int wc, int fr, int fq) const {
;     ...
;                 const int row = row0 + ai * 128 + m * 16; float mu, rs; row_stats(stin, row, mu, rs);
;                 float sum = 0.f, sq = 0.f;
; #pragma unroll
;                 for (int bj = 0; bj < 2; ++bj) {
;                     f32x4 z[2];
; #pragma unroll
;                     for (int n = 0; n < 2; ++n) {
;                         const int col = colb + bj * 128 + 4 * n;
;                         f32x4 xv = *(const f32x4*)(zsrc + (size_t)row * DM + col);
;                         if (stin) { const f32x4 gv = *(const f32x4*)(gin + col), bv = *(const f32x4*)(bin + col); xv = (xv - mu) * rs * gv + bv; }
;                         f32x4 zz = ALPHA * xv + acc[ai][bj][m][n];
;                         if (bias) zz += *(const f32x4*)(bias + col);
;                         *(f32x4*)(zdst + (size_t)row * DM + col) = zz;
;                         sum += zz[0] + zz[1] + zz[2] + zz[3]; sq += zz[0] * zz[0] + zz[1] * zz[1] + zz[2] * zz[2] + zz[3] * zz[3];
;                         z[n] = zz;
;                     }
;                     u32x4 o; o.x = pk2(z[0][0], z[0][1]); o.y = pk2(z[0][2], z[0][3]); o.z = pk2(z[1][0], z[1][1]); o.w = pk2(z[1][2], z[1][3]);
;                     if (zb) *(u32x4*)(zb + (size_t)row * DM + colb + bj * 128) = o;
;                 }
;                 sum += __shfl_xor(sum, 16); sq += __shfl_xor(sq, 16);
;                 sum += __shfl_xor(sum, 32); sq += __shfl_xor(sq, 32);
;                 if (fq == 0) { atomicAdd(stout + 2 * (size_t)row, sum); atomicAdd(stout + 2 * (size_t)row + 1, sq); }
	v_pk_fma_f32 v[176:177], v[188:189], v[178:179], v[192:193]
	s_nop 0
	v_pk_fma_f32 v[112:113], v[176:177], s[24:25], v[112:113] op_sel_hi:[1,0,1]
	v_pk_fma_f32 v[166:167], v[190:191], v[166:167], v[194:195]
	v_pk_add_f32 v[176:177], v[196:197], v[112:113]
	v_pk_fma_f32 v[114:115], v[166:167], s[24:25], v[114:115] op_sel_hi:[1,0,1]
	v_mul_f32_e32 v113, v177, v177
	v_pk_add_f32 v[178:179], v[198:199], v[114:115]
	v_add_f32_e32 v112, v176, v177
	v_fmac_f32_e32 v113, v176, v176
	v_add_f32_e32 v112, v178, v112
	v_fmac_f32_e32 v113, v178, v178
	v_add_f32_e32 v112, v179, v112
	v_fmac_f32_e32 v113, v179, v179
	v_add_f32_e32 v112, v155, v112
	v_add_f32_e32 v113, v175, v113
	ds_bpermute_b32 v114, v118, v112
	ds_bpermute_b32 v115, v118, v113
	global_store_dwordx4 v[164:165], v[176:179], off offset:528
	v_cvt_pk_bf16_f32 v182, v176, v177
	v_cvt_pk_bf16_f32 v183, v178, v179
	s_waitcnt lgkmcnt(0)
	v_add_f32_e32 v112, v112, v114
	v_add_f32_e32 v113, v113, v115
	ds_bpermute_b32 v114, v119, v112
	ds_bpermute_b32 v115, v119, v113
	flat_store_dwordx4 v[204:205], v[180:183] offset:256
	s_mov_b32 s100, -1
	s_mov_b32 s101, 0
	s_mov_b32 s98, 0xffff0000
	s_mov_b32 s99, 0
	s_and_saveexec_b64 s[36:37], s[100:101]
	s_cbranch_execz .LBB0_2638
	v_lshl_add_u64 v[162:163], s[8:9], 0, v[162:163]
	s_waitcnt lgkmcnt(0)
	v_add_f32_e32 v112, v112, v114
	v_add_f32_e32 v113, v113, v115
	v_cndmask_b32_e64 v112, v112, v113, s[98:99]
	v_cndmask_b32_e64 v113, 0, 4, s[98:99]
	v_or_b32_e32 v162, v162, v113
	v_mov_b32_e32 v250, v162
	v_mov_b32_e32 v251, v163
	v_mov_b32_e32 v252, v112
.LBB0_2638:
	s_or_b64 exec, exec, s[36:37]
	v_or_b32_e32 v166, 16, v154
	v_ashrrev_i32_e32 v167, 31, v166
	v_lshlrev_b64 v[112:113], 3, v[166:167]
	s_waitcnt lgkmcnt(0)
	v_lshl_add_u64 v[114:115], s[6:7], 0, v[112:113]
	flat_load_dwordx2 v[192:193], v[114:115]
	v_lshlrev_b64 v[114:115], 12, v[166:167]
	v_lshl_add_u64 v[114:115], s[46:47], 0, v[114:115]
	v_lshl_add_u64 v[114:115], v[144:145], 2, v[114:115]
	global_load_dwordx4 v[162:165], v[114:115], off
	global_load_dwordx4 v[176:179], v[150:151], off
	global_load_dwordx4 v[180:183], v[152:153], off
	global_load_dwordx4 v[184:187], v[156:157], off
	global_load_dwordx4 v[188:191], v[114:115], off offset:16
	v_lshlrev_b64 v[166:167], 11, v[166:167]
	v_lshl_add_u64 v[166:167], s[10:11], 0, v[166:167]
	v_lshl_add_u64 v[166:167], v[144:145], 1, v[166:167]
	s_waitcnt vmcnt(0) lgkmcnt(0)
	v_pk_mul_f32 v[192:193], v[192:193], s[22:23] op_sel:[1,0] op_sel_hi:[0,0]
	v_fma_f32 v155, -v193, v193, v192
	v_max_f32_e32 v155, 0, v155
	v_add_f32_e32 v155, 0x3727c5ac, v155
	v_mul_f32_e32 v175, 0x4b800000, v155
	v_cmp_gt_f32_e32 vcc, s64, v155
	v_sub_f32_e32 v165, v165, v193
	v_sub_f32_e32 v164, v164, v193
	v_cndmask_b32_e32 v155, v155, v175, vcc
	v_rsq_f32_e32 v155, v155
	v_sub_f32_e32 v163, v163, v193
	v_sub_f32_e32 v162, v162, v193
	v_mul_f32_e32 v175, 0x45800000, v155
	v_cndmask_b32_e32 v192, v155, v175, vcc
	v_pk_mul_f32 v[162:163], v[162:163], v[192:193] op_sel_hi:[1,0]
	v_pk_mul_f32 v[164:165], v[164:165], v[192:193] op_sel_hi:[1,0]
	v_pk_fma_f32 v[162:163], v[176:177], v[162:163], v[180:181]
	v_pk_fma_f32 v[164:165], v[178:179], v[164:165], v[182:183]
	v_pk_fma_f32 v[108:109], v[162:163], s[24:25], v[108:109] op_sel_hi:[1,0,1]
	v_pk_fma_f32 v[110:111], v[164:165], s[24:25], v[110:111] op_sel_hi:[1,0,1]
	v_pk_add_f32 v[108:109], v[184:185], v[108:109]
	v_pk_add_f32 v[110:111], v[186:187], v[110:111]
	global_store_dwordx4 v[114:115], v[108:111], off
	global_load_dwordx4 v[162:165], v[146:147], off
	global_load_dwordx4 v[176:179], v[148:149], off
	global_load_dwordx4 v[180:183], v[124:125], off
	v_sub_f32_e32 v185, v191, v193
	v_sub_f32_e32 v184, v190, v193
	v_sub_f32_e32 v187, v189, v193
	v_sub_f32_e32 v186, v188, v193
	v_pk_mul_f32 v[186:187], v[186:187], v[192:193] op_sel_hi:[1,0]
	v_pk_mul_f32 v[188:189], v[184:185], v[192:193] op_sel_hi:[1,0]
	v_cvt_pk_bf16_f32 v184, v108, v109
	v_cvt_pk_bf16_f32 v185, v110, v111
	v_add_f32_e32 v155, v108, v109
	v_mul_f32_e32 v109, v109, v109
	v_fmac_f32_e32 v109, v108, v108
	v_add_f32_e32 v155, v110, v155
	v_fmac_f32_e32 v109, v110, v110
	v_add_f32_e32 v108, v111, v155
	v_add_f32_e32 v108, 0, v108
	v_fmac_f32_e32 v109, v111, v111
	s_waitcnt vmcnt(1)
	v_pk_fma_f32 v[164:165], v[164:165], v[188:189], v[178:179]
	v_pk_fma_f32 v[162:163], v[162:163], v[186:187], v[176:177]
	v_pk_fma_f32 v[106:107], v[164:165], s[24:25], v[106:107] op_sel_hi:[1,0,1]
	v_pk_fma_f32 v[104:105], v[162:163], s[24:25], v[104:105] op_sel_hi:[1,0,1]
	s_waitcnt vmcnt(0)
	v_pk_add_f32 v[106:107], v[182:183], v[106:107]
	v_pk_add_f32 v[104:105], v[180:181], v[104:105]
	global_store_dwordx4 v[114:115], v[104:107], off offset:16
	v_cvt_pk_bf16_f32 v186, v104, v105
	v_cvt_pk_bf16_f32 v187, v106, v107
	flat_store_dwordx4 v[166:167], v[184:187]
	global_load_dwordx4 v[162:165], v[114:115], off offset:512
	global_load_dwordx4 v[176:179], v[126:127], off
	global_load_dwordx4 v[180:183], v[158:159], off
	s_nop 0
	global_load_dwordx4 v[184:187], v[160:161], off
	global_load_dwordx4 v[188:191], v[114:115], off offset:528
	v_add_f32_e32 v110, v104, v105
	v_mul_f32_e32 v105, v105, v105
	v_fmac_f32_e32 v105, v104, v104
	v_add_f32_e32 v110, v106, v110
	v_fmac_f32_e32 v105, v106, v106
	v_add_f32_e32 v104, v107, v110
	v_fmac_f32_e32 v105, v107, v107
	v_add_f32_e32 v108, v104, v108
	v_add_f32_e32 v109, v109, v105
	s_waitcnt vmcnt(0)
; DEVI unsigned pk2(float lo, float hi) { unsigned r; asm("v_cvt_pk_bf16_f32 %0, %1, %2" : "=v"(r) : "v"(lo), "v"(hi)); return r; }
;     DEVI void operator()(const f32x4 (&acc)[2][2][4][2], const pg8::Unit& u, int wr, int wc, int fr, int fq) const {
;     ...
;                 const int row = row0 + ai * 128 + m * 16; float mu, rs; row_stats(stin, row, mu, rs);
;                 float sum = 0.f, sq = 0.f;
; #pragma unroll
;                 for (int bj = 0; bj < 2; ++bj) {
;                     f32x4 z[2];
; #pragma unroll
;                     for (int n = 0; n < 2; ++n) {
;                         const int col = colb + bj * 128 + 4 * n;
;                         f32x4 xv = *(const f32x4*)(zsrc + (size_t)row * DM + col);
;                         if (stin) { const f32x4 gv = *(const f32x4*)(gin + col), bv = *(const f32x4*)(bin + col); xv = (xv - mu) * rs * gv + bv; }
;                         f32x4 zz = ALPHA * xv + acc[ai][bj][m][n];
;                         if (bias) zz += *(const f32x4*)(bias + col);
;                         *(f32x4*)(zdst + (size_t)row * DM + col) = zz;
;                         sum += zz[0] + zz[1] + zz[2] + zz[3]; sq += zz[0] * zz[0] + zz[1] * zz[1] + zz[2] * zz[2] + zz[3] * zz[3];
;                         z[n] = zz;
;                     }
;                     u32x4 o; o.x = pk2(z[0][0], z[0][1]); o.y = pk2(z[0][2], z[0][3]); o.z = pk2(z[1][0], z[1][1]); o.w = pk2(z[1][2], z[1][3]);
;                     if (zb) *(u32x4*)(zb + (size_t)row * DM + colb + bj * 128) = o;
;                 }
;                 sum += __shfl_xor(sum, 16); sq += __shfl_xor(sq, 16);
;                 sum += __shfl_xor(sum, 32); sq += __shfl_xor(sq, 32);
;                 if (fq == 0) { atomicAdd(stout + 2 * (size_t)row, sum); atomicAdd(stout + 2 * (size_t)row + 1, sq); }
	v_sub_f32_e32 v165, v165, v193
	v_sub_f32_e32 v164, v164, v193
	v_sub_f32_e32 v163, v163, v193
	v_sub_f32_e32 v162, v162, v193
	v_pk_mul_f32 v[162:163], v[192:193], v[162:163] op_sel_hi:[0,1]
	v_pk_mul_f32 v[164:165], v[192:193], v[164:165] op_sel_hi:[0,1]
	v_pk_fma_f32 v[164:165], v[178:179], v[164:165], v[182:183]
	v_pk_fma_f32 v[162:163], v[176:177], v[162:163], v[180:181]
	v_pk_fma_f32 v[102:103], v[164:165], s[24:25], v[102:103] op_sel_hi:[1,0,1]
	v_pk_fma_f32 v[100:101], v[162:163], s[24:25], v[100:101] op_sel_hi:[1,0,1]
	v_pk_add_f32 v[102:103], v[186:187], v[102:103]
	v_pk_add_f32 v[100:101], v[184:185], v[100:101]
	global_store_dwordx4 v[114:115], v[100:103], off offset:512
	global_load_dwordx4 v[162:165], v[120:121], off
	global_load_dwordx4 v[176:179], v[122:123], off
	global_load_dwordx4 v[180:183], v[116:117], off
	v_sub_f32_e32 v107, v189, v193
	v_sub_f32_e32 v106, v188, v193
	v_sub_f32_e32 v105, v191, v193
	v_sub_f32_e32 v104, v190, v193
	v_pk_mul_f32 v[106:107], v[192:193], v[106:107] op_sel_hi:[0,1]
	v_pk_mul_f32 v[104:105], v[192:193], v[104:105] op_sel_hi:[0,1]
	v_mul_f32_e32 v111, v101, v101
	v_add_f32_e32 v110, v100, v101
	v_fmac_f32_e32 v111, v100, v100
	v_add_f32_e32 v110, v102, v110
	v_fmac_f32_e32 v111, v102, v102
	v_add_f32_e32 v110, v103, v110
	v_fmac_f32_e32 v111, v103, v103
	v_add_f32_e32 v108, v108, v110
	v_add_f32_e32 v109, v109, v111
	v_cvt_pk_bf16_f32 v100, v100, v101
	v_cvt_pk_bf16_f32 v101, v102, v103
	s_waitcnt vmcnt(0)
	v_pk_fma_f32 v[106:107], v[162:163], v[106:107], v[176:177]
	v_pk_fma_f32 v[104:105], v[164:165], v[104:105], v[178:179]
	v_pk_fma_f32 v[96:97], v[106:107], s[24:25], v[96:97] op_sel_hi:[1,0,1]
	v_pk_fma_f32 v[98:99], v[104:105], s[24:25], v[98:99] op_sel_hi:[1,0,1]
	v_pk_add_f32 v[104:105], v[180:181], v[96:97]
	v_pk_add_f32 v[106:107], v[182:183], v[98:99]
	v_mul_f32_e32 v97, v105, v105
	v_add_f32_e32 v96, v104, v105
	v_fmac_f32_e32 v97, v104, v104
	v_add_f32_e32 v96, v106, v96
	v_fmac_f32_e32 v97, v106, v106
	v_add_f32_e32 v96, v107, v96
	v_fmac_f32_e32 v97, v107, v107
	v_add_f32_e32 v96, v108, v96
	v_add_f32_e32 v97, v109, v97
	ds_bpermute_b32 v98, v118, v96
	ds_bpermute_b32 v99, v118, v97
	global_store_dwordx4 v[114:115], v[104:107], off offset:528
	v_cvt_pk_bf16_f32 v102, v104, v105
	v_cvt_pk_bf16_f32 v103, v106, v107
	s_waitcnt lgkmcnt(0)
	v_add_f32_e32 v96, v96, v98
	v_add_f32_e32 v97, v97, v99
	ds_bpermute_b32 v98, v119, v96
	ds_bpermute_b32 v99, v119, v97
	flat_store_dwordx4 v[166:167], v[100:103] offset:256
	s_mov_b32 s100, -1
	s_mov_b32 s101, 0
	s_mov_b32 s98, 0xffff0000
	s_mov_b32 s99, 0
	s_and_saveexec_b64 s[36:37], s[100:101]
	s_cbranch_execz .LBB0_2640
	v_lshl_add_u64 v[100:101], s[8:9], 0, v[112:113]
	s_waitcnt lgkmcnt(0)
	v_add_f32_e32 v96, v96, v98
	v_add_f32_e32 v97, v97, v99
	v_cndmask_b32_e64 v96, v96, v97, s[98:99]
	v_cndmask_b32_e64 v97, 0, 4, s[98:99]
	v_or_b32_e32 v100, v100, v97
	v_mov_b32_e32 v253, v96
.LBB0_2640:
	s_or_b64 exec, exec, s[36:37]
	v_or_b32_e32 v166, 32, v154
	v_ashrrev_i32_e32 v167, 31, v166
	v_lshlrev_b64 v[96:97], 3, v[166:167]
	s_waitcnt lgkmcnt(0)
	v_lshl_add_u64 v[98:99], s[6:7], 0, v[96:97]
	flat_load_dwordx2 v[176:177], v[98:99]
	v_lshlrev_b64 v[98:99], 12, v[166:167]
	v_lshl_add_u64 v[98:99], s[46:47], 0, v[98:99]
	v_lshl_add_u64 v[98:99], v[144:145], 2, v[98:99]
	global_load_dwordx4 v[100:103], v[98:99], off
	global_load_dwordx4 v[104:107], v[150:151], off
	global_load_dwordx4 v[108:111], v[152:153], off
	global_load_dwordx4 v[112:115], v[156:157], off
	global_load_dwordx4 v[162:165], v[98:99], off offset:16
	s_waitcnt vmcnt(0) lgkmcnt(0)
	v_pk_mul_f32 v[176:177], v[176:177], s[22:23] op_sel:[1,0] op_sel_hi:[0,0]
	v_fma_f32 v155, -v177, v177, v176
	v_max_f32_e32 v155, 0, v155
	v_add_f32_e32 v155, 0x3727c5ac, v155
	v_mul_f32_e32 v175, 0x4b800000, v155
	v_cmp_gt_f32_e32 vcc, s64, v155
	v_sub_f32_e32 v103, v103, v177
	v_sub_f32_e32 v102, v102, v177
	v_cndmask_b32_e32 v155, v155, v175, vcc
	v_rsq_f32_e32 v155, v155
	v_sub_f32_e32 v101, v101, v177
	v_sub_f32_e32 v100, v100, v177
	v_mul_f32_e32 v175, 0x45800000, v155
	v_cndmask_b32_e32 v176, v155, v175, vcc
	v_pk_mul_f32 v[100:101], v[100:101], v[176:177] op_sel_hi:[1,0]
	v_pk_mul_f32 v[102:103], v[102:103], v[176:177] op_sel_hi:[1,0]
	v_pk_fma_f32 v[100:101], v[104:105], v[100:101], v[108:109]
	v_pk_fma_f32 v[102:103], v[106:107], v[102:103], v[110:111]
	v_pk_fma_f32 v[92:93], v[100:101], s[24:25], v[92:93] op_sel_hi:[1,0,1]
	v_pk_fma_f32 v[94:95], v[102:103], s[24:25], v[94:95] op_sel_hi:[1,0,1]
	v_pk_add_f32 v[92:93], v[112:113], v[92:93]
	v_pk_add_f32 v[94:95], v[114:115], v[94:95]
	global_store_dwordx4 v[98:99], v[92:95], off
	global_load_dwordx4 v[100:103], v[146:147], off
	global_load_dwordx4 v[104:107], v[148:149], off
	global_load_dwordx4 v[108:111], v[124:125], off
	v_lshlrev_b64 v[112:113], 11, v[166:167]
	v_lshl_add_u64 v[112:113], s[10:11], 0, v[112:113]
	v_lshl_add_u64 v[166:167], v[144:145], 1, v[112:113]
	v_sub_f32_e32 v113, v165, v177
	v_sub_f32_e32 v112, v164, v177
	v_sub_f32_e32 v115, v163, v177
	v_sub_f32_e32 v114, v162, v177
	v_pk_mul_f32 v[114:115], v[114:115], v[176:177] op_sel_hi:[1,0]
	v_pk_mul_f32 v[162:163], v[112:113], v[176:177] op_sel_hi:[1,0]
	v_cvt_pk_bf16_f32 v112, v92, v93
	v_cvt_pk_bf16_f32 v113, v94, v95
	s_waitcnt vmcnt(1)
	v_pk_fma_f32 v[100:101], v[100:101], v[114:115], v[104:105]
	v_pk_fma_f32 v[102:103], v[102:103], v[162:163], v[106:107]
	v_pk_fma_f32 v[88:89], v[100:101], s[24:25], v[88:89] op_sel_hi:[1,0,1]
	v_pk_fma_f32 v[90:91], v[102:103], s[24:25], v[90:91] op_sel_hi:[1,0,1]
	s_waitcnt vmcnt(0)
; DEVI unsigned pk2(float lo, float hi) { unsigned r; asm("v_cvt_pk_bf16_f32 %0, %1, %2" : "=v"(r) : "v"(lo), "v"(hi)); return r; }
;     DEVI void operator()(const f32x4 (&acc)[2][2][4][2], const pg8::Unit& u, int wr, int wc, int fr, int fq) const {
;     ...
;                 const int row = row0 + ai * 128 + m * 16; float mu, rs; row_stats(stin, row, mu, rs);
;                 float sum = 0.f, sq = 0.f;
; #pragma unroll
;                 for (int bj = 0; bj < 2; ++bj) {
;                     f32x4 z[2];
; #pragma unroll
;                     for (int n = 0; n < 2; ++n) {
;                         const int col = colb + bj * 128 + 4 * n;
;                         f32x4 xv = *(const f32x4*)(zsrc + (size_t)row * DM + col);
;                         if (stin) { const f32x4 gv = *(const f32x4*)(gin + col), bv = *(const f32x4*)(bin + col); xv = (xv - mu) * rs * gv + bv; }
;                         f32x4 zz = ALPHA * xv + acc[ai][bj][m][n];
;                         if (bias) zz += *(const f32x4*)(bias + col);
;                         *(f32x4*)(zdst + (size_t)row * DM + col) = zz;
;                         sum += zz[0] + zz[1] + zz[2] + zz[3]; sq += zz[0] * zz[0] + zz[1] * zz[1] + zz[2] * zz[2] + zz[3] * zz[3];
;                         z[n] = zz;
;                     }
;                     u32x4 o; o.x = pk2(z[0][0], z[0][1]); o.y = pk2(z[0][2], z[0][3]); o.z = pk2(z[1][0], z[1][1]); o.w = pk2(z[1][2], z[1][3]);
;                     if (zb) *(u32x4*)(zb + (size_t)row * DM + colb + bj * 128) = o;
;                 }
;                 sum += __shfl_xor(sum, 16); sq += __shfl_xor(sq, 16);
;                 sum += __shfl_xor(sum, 32); sq += __shfl_xor(sq, 32);
;                 if (fq == 0) { atomicAdd(stout + 2 * (size_t)row, sum); atomicAdd(stout + 2 * (size_t)row + 1, sq); }
	v_pk_add_f32 v[88:89], v[108:109], v[88:89]
	v_pk_add_f32 v[90:91], v[110:111], v[90:91]
	global_store_dwordx4 v[98:99], v[88:91], off offset:16
	v_cvt_pk_bf16_f32 v114, v88, v89
	v_cvt_pk_bf16_f32 v115, v90, v91
	flat_store_dwordx4 v[166:167], v[112:115]
	global_load_dwordx4 v[100:103], v[98:99], off offset:512
	global_load_dwordx4 v[104:107], v[126:127], off
	global_load_dwordx4 v[108:111], v[158:159], off
	s_nop 0
	global_load_dwordx4 v[112:115], v[160:161], off
	global_load_dwordx4 v[162:165], v[98:99], off offset:528
	s_waitcnt vmcnt(0)
	v_sub_f32_e32 v103, v103, v177
	v_sub_f32_e32 v102, v102, v177
	v_sub_f32_e32 v101, v101, v177
	v_sub_f32_e32 v100, v100, v177
	v_pk_mul_f32 v[100:101], v[176:177], v[100:101] op_sel_hi:[0,1]
	v_pk_mul_f32 v[102:103], v[176:177], v[102:103] op_sel_hi:[0,1]
	v_pk_fma_f32 v[102:103], v[106:107], v[102:103], v[110:111]
	v_pk_fma_f32 v[100:101], v[104:105], v[100:101], v[108:109]
	v_pk_fma_f32 v[86:87], v[102:103], s[24:25], v[86:87] op_sel_hi:[1,0,1]
	v_pk_fma_f32 v[84:85], v[100:101], s[24:25], v[84:85] op_sel_hi:[1,0,1]
	v_pk_add_f32 v[86:87], v[114:115], v[86:87]
	v_pk_add_f32 v[84:85], v[112:113], v[84:85]
	global_store_dwordx4 v[98:99], v[84:87], off offset:512
	global_load_dwordx4 v[100:103], v[120:121], off
	global_load_dwordx4 v[104:107], v[122:123], off
	global_load_dwordx4 v[108:111], v[116:117], off
	v_add_f32_e32 v112, v92, v93
	v_mul_f32_e32 v93, v93, v93
	v_fmac_f32_e32 v93, v92, v92
	v_add_f32_e32 v112, v94, v112
	v_fmac_f32_e32 v93, v94, v94
	v_add_f32_e32 v94, v88, v89
	v_mul_f32_e32 v89, v89, v89
	v_fmac_f32_e32 v89, v88, v88
	v_add_f32_e32 v92, v95, v112
	v_add_f32_e32 v94, v90, v94
	v_fmac_f32_e32 v89, v90, v90
	v_add_f32_e32 v92, 0, v92
	v_fmac_f32_e32 v93, v95, v95
	v_add_f32_e32 v88, v91, v94
	v_fmac_f32_e32 v89, v91, v91
	v_sub_f32_e32 v91, v163, v177
	v_sub_f32_e32 v90, v162, v177
	v_add_f32_e32 v92, v88, v92
	v_add_f32_e32 v93, v93, v89
	v_sub_f32_e32 v89, v165, v177
	v_sub_f32_e32 v88, v164, v177
	v_pk_mul_f32 v[90:91], v[176:177], v[90:91] op_sel_hi:[0,1]
	v_pk_mul_f32 v[88:89], v[176:177], v[88:89] op_sel_hi:[0,1]
	v_mul_f32_e32 v95, v85, v85
	v_add_f32_e32 v94, v84, v85
	v_fmac_f32_e32 v95, v84, v84
	v_add_f32_e32 v94, v86, v94
	v_fmac_f32_e32 v95, v86, v86
	v_add_f32_e32 v94, v87, v94
	v_fmac_f32_e32 v95, v87, v87
	v_add_f32_e32 v92, v92, v94
	v_add_f32_e32 v93, v93, v95
	v_cvt_pk_bf16_f32 v84, v84, v85
	v_cvt_pk_bf16_f32 v85, v86, v87
	s_waitcnt vmcnt(0)
	v_pk_fma_f32 v[90:91], v[100:101], v[90:91], v[104:105]
	v_pk_fma_f32 v[88:89], v[102:103], v[88:89], v[106:107]
	v_pk_fma_f32 v[80:81], v[90:91], s[24:25], v[80:81] op_sel_hi:[1,0,1]
	v_pk_fma_f32 v[82:83], v[88:89], s[24:25], v[82:83] op_sel_hi:[1,0,1]
	v_pk_add_f32 v[88:89], v[108:109], v[80:81]
	v_pk_add_f32 v[90:91], v[110:111], v[82:83]
	v_mul_f32_e32 v81, v89, v89
	v_add_f32_e32 v80, v88, v89
	v_fmac_f32_e32 v81, v88, v88
	v_add_f32_e32 v80, v90, v80
	v_fmac_f32_e32 v81, v90, v90
	v_add_f32_e32 v80, v91, v80
	v_fmac_f32_e32 v81, v91, v91
	v_add_f32_e32 v80, v92, v80
	v_add_f32_e32 v81, v93, v81
	ds_bpermute_b32 v82, v118, v80
	ds_bpermute_b32 v83, v118, v81
	global_store_dwordx4 v[98:99], v[88:91], off offset:528
	v_cvt_pk_bf16_f32 v86, v88, v89
	v_cvt_pk_bf16_f32 v87, v90, v91
	s_waitcnt lgkmcnt(0)
	v_add_f32_e32 v80, v80, v82
	v_add_f32_e32 v81, v81, v83
	ds_bpermute_b32 v82, v119, v80
	ds_bpermute_b32 v83, v119, v81
	flat_store_dwordx4 v[166:167], v[84:87] offset:256
	s_mov_b32 s100, -1
	s_mov_b32 s101, 0
	s_mov_b32 s98, 0xffff0000
	s_mov_b32 s99, 0
	s_and_saveexec_b64 s[36:37], s[100:101]
	s_cbranch_execz .LBB0_2642
	v_lshl_add_u64 v[84:85], s[8:9], 0, v[96:97]
	s_waitcnt lgkmcnt(0)
	v_add_f32_e32 v80, v80, v82
	v_add_f32_e32 v81, v81, v83
	v_cndmask_b32_e64 v80, v80, v81, s[98:99]
	v_cndmask_b32_e64 v81, 0, 4, s[98:99]
	v_or_b32_e32 v84, v84, v81
	v_mov_b32_e32 v254, v80
.LBB0_2642:
	s_or_b64 exec, exec, s[36:37]
	v_or_b32_e32 v104, 48, v154
	v_ashrrev_i32_e32 v105, 31, v104
	v_lshlrev_b64 v[80:81], 3, v[104:105]
	s_waitcnt lgkmcnt(0)
	v_lshl_add_u64 v[82:83], s[6:7], 0, v[80:81]
	flat_load_dwordx2 v[106:107], v[82:83]
	v_lshlrev_b64 v[82:83], 12, v[104:105]
	v_lshl_add_u64 v[82:83], s[46:47], 0, v[82:83]
	v_lshl_add_u64 v[82:83], v[144:145], 2, v[82:83]
	global_load_dwordx4 v[84:87], v[82:83], off
	global_load_dwordx4 v[88:91], v[150:151], off
	global_load_dwordx4 v[92:95], v[152:153], off
	global_load_dwordx4 v[96:99], v[156:157], off
	global_load_dwordx4 v[100:103], v[82:83], off offset:16
	s_waitcnt vmcnt(0) lgkmcnt(0)
	v_pk_mul_f32 v[106:107], v[106:107], s[22:23] op_sel:[1,0] op_sel_hi:[0,0]
	v_fma_f32 v106, -v107, v107, v106
	v_max_f32_e32 v106, 0, v106
	v_add_f32_e32 v106, 0x3727c5ac, v106
	v_mul_f32_e32 v108, 0x4b800000, v106
	v_cmp_gt_f32_e32 vcc, s64, v106
	v_sub_f32_e32 v87, v87, v107
	v_sub_f32_e32 v86, v86, v107
	v_cndmask_b32_e32 v106, v106, v108, vcc
	v_rsq_f32_e32 v106, v106
	v_sub_f32_e32 v85, v85, v107
	v_sub_f32_e32 v84, v84, v107
	v_mul_f32_e32 v108, 0x45800000, v106
	v_cndmask_b32_e32 v106, v106, v108, vcc
	v_pk_mul_f32 v[84:85], v[84:85], v[106:107] op_sel_hi:[1,0]
	v_pk_mul_f32 v[86:87], v[86:87], v[106:107] op_sel_hi:[1,0]
	v_pk_fma_f32 v[84:85], v[88:89], v[84:85], v[92:93]
	v_pk_fma_f32 v[86:87], v[90:91], v[86:87], v[94:95]
	v_pk_fma_f32 v[76:77], v[84:85], s[24:25], v[76:77] op_sel_hi:[1,0,1]
	v_pk_fma_f32 v[78:79], v[86:87], s[24:25], v[78:79] op_sel_hi:[1,0,1]
	v_pk_add_f32 v[76:77], v[96:97], v[76:77]
	v_pk_add_f32 v[78:79], v[98:99], v[78:79]
	global_store_dwordx4 v[82:83], v[76:79], off
	global_load_dwordx4 v[84:87], v[146:147], off
	global_load_dwordx4 v[88:91], v[148:149], off
	global_load_dwordx4 v[92:95], v[124:125], off
	v_lshlrev_b64 v[96:97], 11, v[104:105]
	v_lshl_add_u64 v[96:97], s[10:11], 0, v[96:97]
	v_lshl_add_u64 v[104:105], v[144:145], 1, v[96:97]
	v_sub_f32_e32 v97, v103, v107
	v_sub_f32_e32 v96, v102, v107
	v_sub_f32_e32 v99, v101, v107
	v_sub_f32_e32 v98, v100, v107
	v_pk_mul_f32 v[98:99], v[98:99], v[106:107] op_sel_hi:[1,0]
	v_pk_mul_f32 v[100:101], v[96:97], v[106:107] op_sel_hi:[1,0]
	v_cvt_pk_bf16_f32 v96, v76, v77
	v_cvt_pk_bf16_f32 v97, v78, v79
	s_waitcnt vmcnt(1)
; DEVI unsigned pk2(float lo, float hi) { unsigned r; asm("v_cvt_pk_bf16_f32 %0, %1, %2" : "=v"(r) : "v"(lo), "v"(hi)); return r; }
;     DEVI void operator()(const f32x4 (&acc)[2][2][4][2], const pg8::Unit& u, int wr, int wc, int fr, int fq) const {
;     ...
;                 const int row = row0 + ai * 128 + m * 16; float mu, rs; row_stats(stin, row, mu, rs);
;                 float sum = 0.f, sq = 0.f;
; #pragma unroll
;                 for (int bj = 0; bj < 2; ++bj) {
;                     f32x4 z[2];
; #pragma unroll
;                     for (int n = 0; n < 2; ++n) {
;                         const int col = colb + bj * 128 + 4 * n;
;                         f32x4 xv = *(const f32x4*)(zsrc + (size_t)row * DM + col);
;                         if (stin) { const f32x4 gv = *(const f32x4*)(gin + col), bv = *(const f32x4*)(bin + col); xv = (xv - mu) * rs * gv + bv; }
;                         f32x4 zz = ALPHA * xv + acc[ai][bj][m][n];
;                         if (bias) zz += *(const f32x4*)(bias + col);
;                         *(f32x4*)(zdst + (size_t)row * DM + col) = zz;
;                         sum += zz[0] + zz[1] + zz[2] + zz[3]; sq += zz[0] * zz[0] + zz[1] * zz[1] + zz[2] * zz[2] + zz[3] * zz[3];
;                         z[n] = zz;
;                     }
;                     u32x4 o; o.x = pk2(z[0][0], z[0][1]); o.y = pk2(z[0][2], z[0][3]); o.z = pk2(z[1][0], z[1][1]); o.w = pk2(z[1][2], z[1][3]);
;                     if (zb) *(u32x4*)(zb + (size_t)row * DM + colb + bj * 128) = o;
;                 }
;                 sum += __shfl_xor(sum, 16); sq += __shfl_xor(sq, 16);
;                 sum += __shfl_xor(sum, 32); sq += __shfl_xor(sq, 32);
;                 if (fq == 0) { atomicAdd(stout + 2 * (size_t)row, sum); atomicAdd(stout + 2 * (size_t)row + 1, sq); }
	v_pk_fma_f32 v[84:85], v[84:85], v[98:99], v[88:89]
	v_pk_fma_f32 v[86:87], v[86:87], v[100:101], v[90:91]
	v_pk_fma_f32 v[72:73], v[84:85], s[24:25], v[72:73] op_sel_hi:[1,0,1]
	v_pk_fma_f32 v[74:75], v[86:87], s[24:25], v[74:75] op_sel_hi:[1,0,1]
	s_waitcnt vmcnt(0)
	v_pk_add_f32 v[72:73], v[92:93], v[72:73]
	v_pk_add_f32 v[74:75], v[94:95], v[74:75]
	global_store_dwordx4 v[82:83], v[72:75], off offset:16
	v_cvt_pk_bf16_f32 v98, v72, v73
	v_cvt_pk_bf16_f32 v99, v74, v75
	flat_store_dwordx4 v[104:105], v[96:99]
	global_load_dwordx4 v[84:87], v[82:83], off offset:512
	global_load_dwordx4 v[88:91], v[126:127], off
	global_load_dwordx4 v[92:95], v[158:159], off
	s_nop 0
	global_load_dwordx4 v[96:99], v[160:161], off
	global_load_dwordx4 v[100:103], v[82:83], off offset:528
	s_waitcnt vmcnt(0)
	v_sub_f32_e32 v87, v87, v107
	v_sub_f32_e32 v86, v86, v107
	v_sub_f32_e32 v85, v85, v107
	v_sub_f32_e32 v84, v84, v107
	v_pk_mul_f32 v[84:85], v[106:107], v[84:85] op_sel_hi:[0,1]
	v_pk_mul_f32 v[86:87], v[106:107], v[86:87] op_sel_hi:[0,1]
	v_pk_fma_f32 v[86:87], v[90:91], v[86:87], v[94:95]
	v_pk_fma_f32 v[84:85], v[88:89], v[84:85], v[92:93]
	v_pk_fma_f32 v[70:71], v[86:87], s[24:25], v[70:71] op_sel_hi:[1,0,1]
	v_pk_fma_f32 v[68:69], v[84:85], s[24:25], v[68:69] op_sel_hi:[1,0,1]
	v_pk_add_f32 v[70:71], v[98:99], v[70:71]
	v_pk_add_f32 v[68:69], v[96:97], v[68:69]
	global_store_dwordx4 v[82:83], v[68:71], off offset:512
	global_load_dwordx4 v[84:87], v[120:121], off
	global_load_dwordx4 v[88:91], v[122:123], off
	global_load_dwordx4 v[92:95], v[116:117], off
	v_add_f32_e32 v96, v76, v77
	v_mul_f32_e32 v77, v77, v77
	v_fmac_f32_e32 v77, v76, v76
	v_add_f32_e32 v96, v78, v96
	v_fmac_f32_e32 v77, v78, v78
	v_add_f32_e32 v78, v72, v73
	v_mul_f32_e32 v73, v73, v73
	v_fmac_f32_e32 v73, v72, v72
	v_add_f32_e32 v76, v79, v96
	v_add_f32_e32 v78, v74, v78
	v_fmac_f32_e32 v73, v74, v74
	v_add_f32_e32 v76, 0, v76
	v_fmac_f32_e32 v77, v79, v79
	v_add_f32_e32 v72, v75, v78
	v_fmac_f32_e32 v73, v75, v75
	v_sub_f32_e32 v75, v101, v107
	v_sub_f32_e32 v74, v100, v107
	v_add_f32_e32 v76, v72, v76
	v_add_f32_e32 v77, v77, v73
	v_sub_f32_e32 v73, v103, v107
	v_sub_f32_e32 v72, v102, v107
	v_pk_mul_f32 v[74:75], v[106:107], v[74:75] op_sel_hi:[0,1]
	v_pk_mul_f32 v[72:73], v[106:107], v[72:73] op_sel_hi:[0,1]
	v_mul_f32_e32 v79, v69, v69
	v_add_f32_e32 v78, v68, v69
	v_fmac_f32_e32 v79, v68, v68
	v_add_f32_e32 v78, v70, v78
	v_fmac_f32_e32 v79, v70, v70
	v_add_f32_e32 v78, v71, v78
	v_fmac_f32_e32 v79, v71, v71
	v_add_f32_e32 v76, v76, v78
	v_add_f32_e32 v77, v77, v79
	v_cvt_pk_bf16_f32 v68, v68, v69
	v_cvt_pk_bf16_f32 v69, v70, v71
	s_waitcnt vmcnt(0)
	v_pk_fma_f32 v[74:75], v[84:85], v[74:75], v[88:89]
	v_pk_fma_f32 v[72:73], v[86:87], v[72:73], v[90:91]
	v_pk_fma_f32 v[64:65], v[74:75], s[24:25], v[64:65] op_sel_hi:[1,0,1]
	v_pk_fma_f32 v[66:67], v[72:73], s[24:25], v[66:67] op_sel_hi:[1,0,1]
	v_pk_add_f32 v[72:73], v[92:93], v[64:65]
	v_pk_add_f32 v[74:75], v[94:95], v[66:67]
	v_mul_f32_e32 v65, v73, v73
	v_add_f32_e32 v64, v72, v73
	v_fmac_f32_e32 v65, v72, v72
	v_add_f32_e32 v64, v74, v64
	v_fmac_f32_e32 v65, v74, v74
	v_add_f32_e32 v64, v75, v64
	v_fmac_f32_e32 v65, v75, v75
	v_add_f32_e32 v64, v76, v64
	v_add_f32_e32 v65, v77, v65
	ds_bpermute_b32 v66, v118, v64
	ds_bpermute_b32 v67, v118, v65
	global_store_dwordx4 v[82:83], v[72:75], off offset:528
	v_cvt_pk_bf16_f32 v70, v72, v73
	v_cvt_pk_bf16_f32 v71, v74, v75
	s_waitcnt lgkmcnt(0)
	v_add_f32_e32 v64, v64, v66
	v_add_f32_e32 v65, v65, v67
	ds_bpermute_b32 v66, v119, v64
	ds_bpermute_b32 v67, v119, v65
	flat_store_dwordx4 v[104:105], v[68:71] offset:256
	s_mov_b32 s100, -1
	s_mov_b32 s101, 0
	s_mov_b32 s98, 0xffff0000
	s_mov_b32 s99, 0
	s_and_saveexec_b64 s[36:37], s[100:101]
	s_cbranch_execz .LBB0_2644
	v_lshl_add_u64 v[68:69], s[8:9], 0, v[80:81]
	s_waitcnt lgkmcnt(0)
	v_add_f32_e32 v64, v64, v66
	v_add_f32_e32 v65, v65, v67
	v_cndmask_b32_e64 v64, v64, v65, s[98:99]
	v_cndmask_b32_e64 v65, 0, 4, s[98:99]
	v_or_b32_e32 v68, v68, v65
	v_mov_b32_e32 v255, v64
	flat_atomic_add_f32 v[250:251], v252
	flat_atomic_add_f32 v[250:251], v253 offset:128
	flat_atomic_add_f32 v[250:251], v254 offset:256
	flat_atomic_add_f32 v[250:251], v255 offset:384
; DEVI unsigned pk2(float lo, float hi) { unsigned r; asm("v_cvt_pk_bf16_f32 %0, %1, %2" : "=v"(r) : "v"(lo), "v"(hi)); return r; }
;     DEVI void operator()(const f32x4 (&acc)[2][2][4][2], const pg8::Unit& u, int wr, int wc, int fr, int fq) const {
;     ...
;                 const int row = row0 + ai * 128 + m * 16; float mu, rs; row_stats(stin, row, mu, rs);
;                 float sum = 0.f, sq = 0.f;
; #pragma unroll
;                 for (int bj = 0; bj < 2; ++bj) {
;                     f32x4 z[2];
; #pragma unroll
;                     for (int n = 0; n < 2; ++n) {
;                         const int col = colb + bj * 128 + 4 * n;
;                         f32x4 xv = *(const f32x4*)(zsrc + (size_t)row * DM + col);
;                         if (stin) { const f32x4 gv = *(const f32x4*)(gin + col), bv = *(const f32x4*)(bin + col); xv = (xv - mu) * rs * gv + bv; }
;                         f32x4 zz = ALPHA * xv + acc[ai][bj][m][n];
;                         if (bias) zz += *(const f32x4*)(bias + col);
;                         *(f32x4*)(zdst + (size_t)row * DM + col) = zz;
;                         sum += zz[0] + zz[1] + zz[2] + zz[3]; sq += zz[0] * zz[0] + zz[1] * zz[1] + zz[2] * zz[2] + zz[3] * zz[3];
;                         z[n] = zz;
;                     }
;                     u32x4 o; o.x = pk2(z[0][0], z[0][1]); o.y = pk2(z[0][2], z[0][3]); o.z = pk2(z[1][0], z[1][1]); o.w = pk2(z[1][2], z[1][3]);
;                     if (zb) *(u32x4*)(zb + (size_t)row * DM + colb + bj * 128) = o;
;                 }
;                 sum += __shfl_xor(sum, 16); sq += __shfl_xor(sq, 16);
;                 sum += __shfl_xor(sum, 32); sq += __shfl_xor(sq, 32);
;                 if (fq == 0) { atomicAdd(stout + 2 * (size_t)row, sum); atomicAdd(stout + 2 * (size_t)row + 1, sq); }
.LBB0_2644:
	s_or_b64 exec, exec, s[36:37]
	v_add_u32_e32 v88, 0x80, v154
	v_ashrrev_i32_e32 v89, 31, v88
	v_lshlrev_b64 v[64:65], 3, v[88:89]
	s_waitcnt lgkmcnt(0)
	v_lshl_add_u64 v[66:67], s[6:7], 0, v[64:65]
	flat_load_dwordx2 v[90:91], v[66:67]
	v_lshlrev_b64 v[66:67], 12, v[88:89]
	v_lshl_add_u64 v[66:67], s[46:47], 0, v[66:67]
	v_lshl_add_u64 v[66:67], v[144:145], 2, v[66:67]
	global_load_dwordx4 v[68:71], v[66:67], off
	global_load_dwordx4 v[72:75], v[150:151], off
	global_load_dwordx4 v[76:79], v[152:153], off
	global_load_dwordx4 v[80:83], v[156:157], off
	global_load_dwordx4 v[84:87], v[66:67], off offset:16
	s_waitcnt vmcnt(0) lgkmcnt(0)
	v_pk_mul_f32 v[90:91], v[90:91], s[22:23] op_sel:[1,0] op_sel_hi:[0,0]
	v_fma_f32 v90, -v91, v91, v90
	v_max_f32_e32 v90, 0, v90
	v_add_f32_e32 v90, 0x3727c5ac, v90
	v_mul_f32_e32 v92, 0x4b800000, v90
	v_cmp_gt_f32_e32 vcc, s64, v90
	v_sub_f32_e32 v71, v71, v91
	v_sub_f32_e32 v70, v70, v91
	v_cndmask_b32_e32 v90, v90, v92, vcc
	v_rsq_f32_e32 v90, v90
	v_sub_f32_e32 v69, v69, v91
	v_sub_f32_e32 v68, v68, v91
	v_mul_f32_e32 v92, 0x45800000, v90
	v_cndmask_b32_e32 v90, v90, v92, vcc
	v_pk_mul_f32 v[68:69], v[68:69], v[90:91] op_sel_hi:[1,0]
	v_pk_mul_f32 v[70:71], v[70:71], v[90:91] op_sel_hi:[1,0]
	v_pk_fma_f32 v[68:69], v[72:73], v[68:69], v[76:77]
	v_pk_fma_f32 v[70:71], v[74:75], v[70:71], v[78:79]
	v_pk_fma_f32 v[60:61], v[68:69], s[24:25], v[60:61] op_sel_hi:[1,0,1]
	v_pk_fma_f32 v[62:63], v[70:71], s[24:25], v[62:63] op_sel_hi:[1,0,1]
	v_pk_add_f32 v[60:61], v[80:81], v[60:61]
	v_pk_add_f32 v[62:63], v[82:83], v[62:63]
	global_store_dwordx4 v[66:67], v[60:63], off
	global_load_dwordx4 v[68:71], v[146:147], off
	global_load_dwordx4 v[72:75], v[148:149], off
	global_load_dwordx4 v[76:79], v[124:125], off
	v_lshlrev_b64 v[80:81], 11, v[88:89]
	v_lshl_add_u64 v[80:81], s[10:11], 0, v[80:81]
	v_lshl_add_u64 v[88:89], v[144:145], 1, v[80:81]
	v_sub_f32_e32 v81, v87, v91
	v_sub_f32_e32 v80, v86, v91
	v_sub_f32_e32 v83, v85, v91
	v_sub_f32_e32 v82, v84, v91
	v_pk_mul_f32 v[82:83], v[82:83], v[90:91] op_sel_hi:[1,0]
	v_pk_mul_f32 v[84:85], v[80:81], v[90:91] op_sel_hi:[1,0]
	v_cvt_pk_bf16_f32 v80, v60, v61
	v_cvt_pk_bf16_f32 v81, v62, v63
	s_waitcnt vmcnt(1)
	v_pk_fma_f32 v[68:69], v[68:69], v[82:83], v[72:73]
	v_pk_fma_f32 v[70:71], v[70:71], v[84:85], v[74:75]
	v_pk_fma_f32 v[56:57], v[68:69], s[24:25], v[56:57] op_sel_hi:[1,0,1]
	v_pk_fma_f32 v[58:59], v[70:71], s[24:25], v[58:59] op_sel_hi:[1,0,1]
	s_waitcnt vmcnt(0)
	v_pk_add_f32 v[56:57], v[76:77], v[56:57]
	v_pk_add_f32 v[58:59], v[78:79], v[58:59]
	global_store_dwordx4 v[66:67], v[56:59], off offset:16
	v_cvt_pk_bf16_f32 v82, v56, v57
	v_cvt_pk_bf16_f32 v83, v58, v59
	flat_store_dwordx4 v[88:89], v[80:83]
	global_load_dwordx4 v[68:71], v[66:67], off offset:512
	global_load_dwordx4 v[72:75], v[126:127], off
	global_load_dwordx4 v[76:79], v[158:159], off
	s_nop 0
	global_load_dwordx4 v[80:83], v[160:161], off
	global_load_dwordx4 v[84:87], v[66:67], off offset:528
	s_waitcnt vmcnt(0)
	v_sub_f32_e32 v71, v71, v91
	v_sub_f32_e32 v70, v70, v91
	v_sub_f32_e32 v69, v69, v91
	v_sub_f32_e32 v68, v68, v91
	v_pk_mul_f32 v[68:69], v[90:91], v[68:69] op_sel_hi:[0,1]
	v_pk_mul_f32 v[70:71], v[90:91], v[70:71] op_sel_hi:[0,1]
	v_pk_fma_f32 v[70:71], v[74:75], v[70:71], v[78:79]
	v_pk_fma_f32 v[68:69], v[72:73], v[68:69], v[76:77]
	v_pk_fma_f32 v[54:55], v[70:71], s[24:25], v[54:55] op_sel_hi:[1,0,1]
	v_pk_fma_f32 v[52:53], v[68:69], s[24:25], v[52:53] op_sel_hi:[1,0,1]
	v_pk_add_f32 v[54:55], v[82:83], v[54:55]
	v_pk_add_f32 v[52:53], v[80:81], v[52:53]
	global_store_dwordx4 v[66:67], v[52:55], off offset:512
	global_load_dwordx4 v[68:71], v[120:121], off
	global_load_dwordx4 v[72:75], v[122:123], off
	global_load_dwordx4 v[76:79], v[116:117], off
	v_add_f32_e32 v80, v60, v61
	v_mul_f32_e32 v61, v61, v61
	v_fmac_f32_e32 v61, v60, v60
	v_add_f32_e32 v80, v62, v80
	v_fmac_f32_e32 v61, v62, v62
	v_add_f32_e32 v62, v56, v57
	v_mul_f32_e32 v57, v57, v57
	v_fmac_f32_e32 v57, v56, v56
	v_add_f32_e32 v60, v63, v80
	v_add_f32_e32 v62, v58, v62
	v_fmac_f32_e32 v57, v58, v58
	v_add_f32_e32 v60, 0, v60
	v_fmac_f32_e32 v61, v63, v63
	v_add_f32_e32 v56, v59, v62
	v_fmac_f32_e32 v57, v59, v59
	v_sub_f32_e32 v59, v85, v91
	v_sub_f32_e32 v58, v84, v91
	v_add_f32_e32 v60, v56, v60
	v_add_f32_e32 v61, v61, v57
	v_sub_f32_e32 v57, v87, v91
	v_sub_f32_e32 v56, v86, v91
	v_pk_mul_f32 v[58:59], v[90:91], v[58:59] op_sel_hi:[0,1]
	v_pk_mul_f32 v[56:57], v[90:91], v[56:57] op_sel_hi:[0,1]
	v_mul_f32_e32 v63, v53, v53
	v_add_f32_e32 v62, v52, v53
	v_fmac_f32_e32 v63, v52, v52
	v_add_f32_e32 v62, v54, v62
	v_fmac_f32_e32 v63, v54, v54
	v_add_f32_e32 v62, v55, v62
	v_fmac_f32_e32 v63, v55, v55
	v_add_f32_e32 v60, v60, v62
	v_add_f32_e32 v61, v61, v63
	v_cvt_pk_bf16_f32 v52, v52, v53
	v_cvt_pk_bf16_f32 v53, v54, v55
	s_waitcnt vmcnt(0)
	v_pk_fma_f32 v[58:59], v[68:69], v[58:59], v[72:73]
	v_pk_fma_f32 v[56:57], v[70:71], v[56:57], v[74:75]
	v_pk_fma_f32 v[48:49], v[58:59], s[24:25], v[48:49] op_sel_hi:[1,0,1]
	v_pk_fma_f32 v[50:51], v[56:57], s[24:25], v[50:51] op_sel_hi:[1,0,1]
	v_pk_add_f32 v[56:57], v[76:77], v[48:49]
	v_pk_add_f32 v[58:59], v[78:79], v[50:51]
	v_mul_f32_e32 v49, v57, v57
	v_add_f32_e32 v48, v56, v57
	v_fmac_f32_e32 v49, v56, v56
	v_add_f32_e32 v48, v58, v48
	v_fmac_f32_e32 v49, v58, v58
	v_add_f32_e32 v48, v59, v48
	v_fmac_f32_e32 v49, v59, v59
	v_add_f32_e32 v48, v60, v48
	v_add_f32_e32 v49, v61, v49
	ds_bpermute_b32 v50, v118, v48
	ds_bpermute_b32 v51, v118, v49
	global_store_dwordx4 v[66:67], v[56:59], off offset:528
	v_cvt_pk_bf16_f32 v54, v56, v57
	v_cvt_pk_bf16_f32 v55, v58, v59
	s_waitcnt lgkmcnt(0)
	v_add_f32_e32 v48, v48, v50
	v_add_f32_e32 v49, v49, v51
	ds_bpermute_b32 v50, v119, v48
	ds_bpermute_b32 v51, v119, v49
	flat_store_dwordx4 v[88:89], v[52:55] offset:256
	s_mov_b32 s100, -1
	s_mov_b32 s101, 0
	s_mov_b32 s98, 0xffff0000
	s_mov_b32 s99, 0
	s_and_saveexec_b64 s[36:37], s[100:101]
	s_cbranch_execz .LBB0_2646
	v_lshl_add_u64 v[52:53], s[8:9], 0, v[64:65]
	s_waitcnt lgkmcnt(0)
	v_add_f32_e32 v48, v48, v50
	v_add_f32_e32 v49, v49, v51
	v_cndmask_b32_e64 v48, v48, v49, s[98:99]
	v_cndmask_b32_e64 v49, 0, 4, s[98:99]
	v_or_b32_e32 v52, v52, v49
	v_mov_b32_e32 v250, v52
	v_mov_b32_e32 v251, v53
	v_mov_b32_e32 v252, v48
; DEVI unsigned pk2(float lo, float hi) { unsigned r; asm("v_cvt_pk_bf16_f32 %0, %1, %2" : "=v"(r) : "v"(lo), "v"(hi)); return r; }
;     DEVI void operator()(const f32x4 (&acc)[2][2][4][2], const pg8::Unit& u, int wr, int wc, int fr, int fq) const {
;     ...
;                 const int row = row0 + ai * 128 + m * 16; float mu, rs; row_stats(stin, row, mu, rs);
;                 float sum = 0.f, sq = 0.f;
; #pragma unroll
;                 for (int bj = 0; bj < 2; ++bj) {
;                     f32x4 z[2];
; #pragma unroll
;                     for (int n = 0; n < 2; ++n) {
;                         const int col = colb + bj * 128 + 4 * n;
;                         f32x4 xv = *(const f32x4*)(zsrc + (size_t)row * DM + col);
;                         if (stin) { const f32x4 gv = *(const f32x4*)(gin + col), bv = *(const f32x4*)(bin + col); xv = (xv - mu) * rs * gv + bv; }
;                         f32x4 zz = ALPHA * xv + acc[ai][bj][m][n];
;                         if (bias) zz += *(const f32x4*)(bias + col);
;                         *(f32x4*)(zdst + (size_t)row * DM + col) = zz;
;                         sum += zz[0] + zz[1] + zz[2] + zz[3]; sq += zz[0] * zz[0] + zz[1] * zz[1] + zz[2] * zz[2] + zz[3] * zz[3];
;                         z[n] = zz;
;                     }
;                     u32x4 o; o.x = pk2(z[0][0], z[0][1]); o.y = pk2(z[0][2], z[0][3]); o.z = pk2(z[1][0], z[1][1]); o.w = pk2(z[1][2], z[1][3]);
;                     if (zb) *(u32x4*)(zb + (size_t)row * DM + colb + bj * 128) = o;
;                 }
;                 sum += __shfl_xor(sum, 16); sq += __shfl_xor(sq, 16);
;                 sum += __shfl_xor(sum, 32); sq += __shfl_xor(sq, 32);
;                 if (fq == 0) { atomicAdd(stout + 2 * (size_t)row, sum); atomicAdd(stout + 2 * (size_t)row + 1, sq); }
.LBB0_2646:
	s_or_b64 exec, exec, s[36:37]
	v_add_u32_e32 v72, 0x90, v154
	v_ashrrev_i32_e32 v73, 31, v72
	v_lshlrev_b64 v[48:49], 3, v[72:73]
	s_waitcnt lgkmcnt(0)
	v_lshl_add_u64 v[50:51], s[6:7], 0, v[48:49]
	flat_load_dwordx2 v[74:75], v[50:51]
	v_lshlrev_b64 v[50:51], 12, v[72:73]
	v_lshl_add_u64 v[50:51], s[46:47], 0, v[50:51]
	v_lshl_add_u64 v[50:51], v[144:145], 2, v[50:51]
	global_load_dwordx4 v[52:55], v[50:51], off
	global_load_dwordx4 v[56:59], v[150:151], off
	global_load_dwordx4 v[60:63], v[152:153], off
	global_load_dwordx4 v[64:67], v[156:157], off
	global_load_dwordx4 v[68:71], v[50:51], off offset:16
	s_waitcnt vmcnt(0) lgkmcnt(0)
	v_pk_mul_f32 v[74:75], v[74:75], s[22:23] op_sel:[1,0] op_sel_hi:[0,0]
	v_fma_f32 v74, -v75, v75, v74
	v_max_f32_e32 v74, 0, v74
	v_add_f32_e32 v74, 0x3727c5ac, v74
	v_mul_f32_e32 v76, 0x4b800000, v74
	v_cmp_gt_f32_e32 vcc, s64, v74
	v_sub_f32_e32 v55, v55, v75
	v_sub_f32_e32 v54, v54, v75
	v_cndmask_b32_e32 v74, v74, v76, vcc
	v_rsq_f32_e32 v74, v74
	v_sub_f32_e32 v53, v53, v75
	v_sub_f32_e32 v52, v52, v75
	v_mul_f32_e32 v76, 0x45800000, v74
	v_cndmask_b32_e32 v74, v74, v76, vcc
	v_pk_mul_f32 v[52:53], v[52:53], v[74:75] op_sel_hi:[1,0]
	v_pk_mul_f32 v[54:55], v[54:55], v[74:75] op_sel_hi:[1,0]
	v_pk_fma_f32 v[52:53], v[56:57], v[52:53], v[60:61]
	v_pk_fma_f32 v[54:55], v[58:59], v[54:55], v[62:63]
	v_pk_fma_f32 v[44:45], v[52:53], s[24:25], v[44:45] op_sel_hi:[1,0,1]
	v_pk_fma_f32 v[46:47], v[54:55], s[24:25], v[46:47] op_sel_hi:[1,0,1]
	v_pk_add_f32 v[44:45], v[64:65], v[44:45]
	v_pk_add_f32 v[46:47], v[66:67], v[46:47]
	global_store_dwordx4 v[50:51], v[44:47], off
	global_load_dwordx4 v[52:55], v[146:147], off
	global_load_dwordx4 v[56:59], v[148:149], off
	global_load_dwordx4 v[60:63], v[124:125], off
	v_lshlrev_b64 v[64:65], 11, v[72:73]
	v_lshl_add_u64 v[64:65], s[10:11], 0, v[64:65]
	v_lshl_add_u64 v[72:73], v[144:145], 1, v[64:65]
	v_sub_f32_e32 v65, v71, v75
	v_sub_f32_e32 v64, v70, v75
	v_sub_f32_e32 v67, v69, v75
	v_sub_f32_e32 v66, v68, v75
	v_pk_mul_f32 v[66:67], v[66:67], v[74:75] op_sel_hi:[1,0]
	v_pk_mul_f32 v[68:69], v[64:65], v[74:75] op_sel_hi:[1,0]
	v_cvt_pk_bf16_f32 v64, v44, v45
	v_cvt_pk_bf16_f32 v65, v46, v47
	s_waitcnt vmcnt(1)
	v_pk_fma_f32 v[52:53], v[52:53], v[66:67], v[56:57]
	v_pk_fma_f32 v[54:55], v[54:55], v[68:69], v[58:59]
	v_pk_fma_f32 v[40:41], v[52:53], s[24:25], v[40:41] op_sel_hi:[1,0,1]
	v_pk_fma_f32 v[42:43], v[54:55], s[24:25], v[42:43] op_sel_hi:[1,0,1]
	s_waitcnt vmcnt(0)
	v_pk_add_f32 v[40:41], v[60:61], v[40:41]
	v_pk_add_f32 v[42:43], v[62:63], v[42:43]
	global_store_dwordx4 v[50:51], v[40:43], off offset:16
	v_cvt_pk_bf16_f32 v66, v40, v41
	v_cvt_pk_bf16_f32 v67, v42, v43
	flat_store_dwordx4 v[72:73], v[64:67]
	global_load_dwordx4 v[52:55], v[50:51], off offset:512
	global_load_dwordx4 v[56:59], v[126:127], off
	global_load_dwordx4 v[60:63], v[158:159], off
	s_nop 0
	global_load_dwordx4 v[64:67], v[160:161], off
	global_load_dwordx4 v[68:71], v[50:51], off offset:528
	s_waitcnt vmcnt(0)
	v_sub_f32_e32 v55, v55, v75
	v_sub_f32_e32 v54, v54, v75
	v_sub_f32_e32 v53, v53, v75
	v_sub_f32_e32 v52, v52, v75
	v_pk_mul_f32 v[52:53], v[74:75], v[52:53] op_sel_hi:[0,1]
	v_pk_mul_f32 v[54:55], v[74:75], v[54:55] op_sel_hi:[0,1]
	v_pk_fma_f32 v[54:55], v[58:59], v[54:55], v[62:63]
	v_pk_fma_f32 v[52:53], v[56:57], v[52:53], v[60:61]
	v_pk_fma_f32 v[38:39], v[54:55], s[24:25], v[38:39] op_sel_hi:[1,0,1]
	v_pk_fma_f32 v[36:37], v[52:53], s[24:25], v[36:37] op_sel_hi:[1,0,1]
	v_pk_add_f32 v[38:39], v[66:67], v[38:39]
	v_pk_add_f32 v[36:37], v[64:65], v[36:37]
	global_store_dwordx4 v[50:51], v[36:39], off offset:512
	global_load_dwordx4 v[52:55], v[120:121], off
	global_load_dwordx4 v[56:59], v[122:123], off
	global_load_dwordx4 v[60:63], v[116:117], off
	v_add_f32_e32 v64, v44, v45
	v_mul_f32_e32 v45, v45, v45
	v_fmac_f32_e32 v45, v44, v44
	v_add_f32_e32 v64, v46, v64
	v_fmac_f32_e32 v45, v46, v46
	v_add_f32_e32 v46, v40, v41
	v_mul_f32_e32 v41, v41, v41
	v_fmac_f32_e32 v41, v40, v40
	v_add_f32_e32 v44, v47, v64
	v_add_f32_e32 v46, v42, v46
	v_fmac_f32_e32 v41, v42, v42
	v_add_f32_e32 v44, 0, v44
	v_fmac_f32_e32 v45, v47, v47
	v_add_f32_e32 v40, v43, v46
	v_fmac_f32_e32 v41, v43, v43
	v_sub_f32_e32 v43, v69, v75
	v_sub_f32_e32 v42, v68, v75
	v_add_f32_e32 v44, v40, v44
	v_add_f32_e32 v45, v45, v41
	v_sub_f32_e32 v41, v71, v75
	v_sub_f32_e32 v40, v70, v75
	v_pk_mul_f32 v[42:43], v[74:75], v[42:43] op_sel_hi:[0,1]
	v_pk_mul_f32 v[40:41], v[74:75], v[40:41] op_sel_hi:[0,1]
	v_mul_f32_e32 v47, v37, v37
	v_add_f32_e32 v46, v36, v37
	v_fmac_f32_e32 v47, v36, v36
	v_add_f32_e32 v46, v38, v46
	v_fmac_f32_e32 v47, v38, v38
	v_add_f32_e32 v46, v39, v46
	v_fmac_f32_e32 v47, v39, v39
	v_add_f32_e32 v44, v44, v46
	v_add_f32_e32 v45, v45, v47
	v_cvt_pk_bf16_f32 v36, v36, v37
	v_cvt_pk_bf16_f32 v37, v38, v39
	s_waitcnt vmcnt(0)
	v_pk_fma_f32 v[42:43], v[52:53], v[42:43], v[56:57]
	v_pk_fma_f32 v[40:41], v[54:55], v[40:41], v[58:59]
	v_pk_fma_f32 v[32:33], v[42:43], s[24:25], v[32:33] op_sel_hi:[1,0,1]
	v_pk_fma_f32 v[34:35], v[40:41], s[24:25], v[34:35] op_sel_hi:[1,0,1]
	v_pk_add_f32 v[40:41], v[60:61], v[32:33]
	v_pk_add_f32 v[42:43], v[62:63], v[34:35]
	v_mul_f32_e32 v33, v41, v41
	v_add_f32_e32 v32, v40, v41
	v_fmac_f32_e32 v33, v40, v40
	v_add_f32_e32 v32, v42, v32
	v_fmac_f32_e32 v33, v42, v42
	v_add_f32_e32 v32, v43, v32
	v_fmac_f32_e32 v33, v43, v43
	v_add_f32_e32 v32, v44, v32
	v_add_f32_e32 v33, v45, v33
	ds_bpermute_b32 v34, v118, v32
	ds_bpermute_b32 v35, v118, v33
	global_store_dwordx4 v[50:51], v[40:43], off offset:528
	v_cvt_pk_bf16_f32 v38, v40, v41
	v_cvt_pk_bf16_f32 v39, v42, v43
	s_waitcnt lgkmcnt(0)
	v_add_f32_e32 v32, v32, v34
	v_add_f32_e32 v33, v33, v35
	ds_bpermute_b32 v34, v119, v32
	ds_bpermute_b32 v35, v119, v33
	flat_store_dwordx4 v[72:73], v[36:39] offset:256
	s_mov_b32 s100, -1
	s_mov_b32 s101, 0
	s_mov_b32 s98, 0xffff0000
	s_mov_b32 s99, 0
	s_and_saveexec_b64 s[36:37], s[100:101]
	s_cbranch_execz .LBB0_2648
	v_lshl_add_u64 v[36:37], s[8:9], 0, v[48:49]
	s_waitcnt lgkmcnt(0)
	v_add_f32_e32 v32, v32, v34
	v_add_f32_e32 v33, v33, v35
	v_cndmask_b32_e64 v32, v32, v33, s[98:99]
	v_cndmask_b32_e64 v33, 0, 4, s[98:99]
	v_or_b32_e32 v36, v36, v33
	v_mov_b32_e32 v253, v32
; DEVI unsigned pk2(float lo, float hi) { unsigned r; asm("v_cvt_pk_bf16_f32 %0, %1, %2" : "=v"(r) : "v"(lo), "v"(hi)); return r; }
;     DEVI void operator()(const f32x4 (&acc)[2][2][4][2], const pg8::Unit& u, int wr, int wc, int fr, int fq) const {
;     ...
;                 const int row = row0 + ai * 128 + m * 16; float mu, rs; row_stats(stin, row, mu, rs);
;                 float sum = 0.f, sq = 0.f;
; #pragma unroll
;                 for (int bj = 0; bj < 2; ++bj) {
;                     f32x4 z[2];
; #pragma unroll
;                     for (int n = 0; n < 2; ++n) {
;                         const int col = colb + bj * 128 + 4 * n;
;                         f32x4 xv = *(const f32x4*)(zsrc + (size_t)row * DM + col);
;                         if (stin) { const f32x4 gv = *(const f32x4*)(gin + col), bv = *(const f32x4*)(bin + col); xv = (xv - mu) * rs * gv + bv; }
;                         f32x4 zz = ALPHA * xv + acc[ai][bj][m][n];
;                         if (bias) zz += *(const f32x4*)(bias + col);
;                         *(f32x4*)(zdst + (size_t)row * DM + col) = zz;
;                         sum += zz[0] + zz[1] + zz[2] + zz[3]; sq += zz[0] * zz[0] + zz[1] * zz[1] + zz[2] * zz[2] + zz[3] * zz[3];
;                         z[n] = zz;
;                     }
;                     u32x4 o; o.x = pk2(z[0][0], z[0][1]); o.y = pk2(z[0][2], z[0][3]); o.z = pk2(z[1][0], z[1][1]); o.w = pk2(z[1][2], z[1][3]);
;                     if (zb) *(u32x4*)(zb + (size_t)row * DM + colb + bj * 128) = o;
;                 }
;                 sum += __shfl_xor(sum, 16); sq += __shfl_xor(sq, 16);
;                 sum += __shfl_xor(sum, 32); sq += __shfl_xor(sq, 32);
;                 if (fq == 0) { atomicAdd(stout + 2 * (size_t)row, sum); atomicAdd(stout + 2 * (size_t)row + 1, sq); }
.LBB0_2648:
	s_or_b64 exec, exec, s[36:37]
	v_add_u32_e32 v56, 0xa0, v154
	v_ashrrev_i32_e32 v57, 31, v56
	v_lshlrev_b64 v[32:33], 3, v[56:57]
	s_waitcnt lgkmcnt(0)
	v_lshl_add_u64 v[34:35], s[6:7], 0, v[32:33]
	flat_load_dwordx2 v[58:59], v[34:35]
	v_lshlrev_b64 v[34:35], 12, v[56:57]
	v_lshl_add_u64 v[34:35], s[46:47], 0, v[34:35]
	v_lshl_add_u64 v[34:35], v[144:145], 2, v[34:35]
	global_load_dwordx4 v[36:39], v[34:35], off
	global_load_dwordx4 v[40:43], v[150:151], off
	global_load_dwordx4 v[44:47], v[152:153], off
	global_load_dwordx4 v[48:51], v[156:157], off
	global_load_dwordx4 v[52:55], v[34:35], off offset:16
	s_waitcnt vmcnt(0) lgkmcnt(0)
	v_pk_mul_f32 v[58:59], v[58:59], s[22:23] op_sel:[1,0] op_sel_hi:[0,0]
	v_fma_f32 v58, -v59, v59, v58
	v_max_f32_e32 v58, 0, v58
	v_add_f32_e32 v58, 0x3727c5ac, v58
	v_mul_f32_e32 v60, 0x4b800000, v58
	v_cmp_gt_f32_e32 vcc, s64, v58
	v_sub_f32_e32 v39, v39, v59
	v_sub_f32_e32 v38, v38, v59
	v_cndmask_b32_e32 v58, v58, v60, vcc
	v_rsq_f32_e32 v58, v58
	v_sub_f32_e32 v37, v37, v59
	v_sub_f32_e32 v36, v36, v59
	v_mul_f32_e32 v60, 0x45800000, v58
	v_cndmask_b32_e32 v58, v58, v60, vcc
	v_pk_mul_f32 v[36:37], v[36:37], v[58:59] op_sel_hi:[1,0]
	v_pk_mul_f32 v[38:39], v[38:39], v[58:59] op_sel_hi:[1,0]
	v_pk_fma_f32 v[36:37], v[40:41], v[36:37], v[44:45]
	v_pk_fma_f32 v[38:39], v[42:43], v[38:39], v[46:47]
	v_pk_fma_f32 v[28:29], v[36:37], s[24:25], v[28:29] op_sel_hi:[1,0,1]
	v_pk_fma_f32 v[30:31], v[38:39], s[24:25], v[30:31] op_sel_hi:[1,0,1]
	v_pk_add_f32 v[28:29], v[48:49], v[28:29]
	v_pk_add_f32 v[30:31], v[50:51], v[30:31]
	global_store_dwordx4 v[34:35], v[28:31], off
	global_load_dwordx4 v[36:39], v[146:147], off
	global_load_dwordx4 v[40:43], v[148:149], off
	global_load_dwordx4 v[44:47], v[124:125], off
	v_lshlrev_b64 v[48:49], 11, v[56:57]
	v_lshl_add_u64 v[48:49], s[10:11], 0, v[48:49]
	v_lshl_add_u64 v[56:57], v[144:145], 1, v[48:49]
	v_sub_f32_e32 v49, v55, v59
	v_sub_f32_e32 v48, v54, v59
	v_sub_f32_e32 v51, v53, v59
	v_sub_f32_e32 v50, v52, v59
	v_pk_mul_f32 v[50:51], v[50:51], v[58:59] op_sel_hi:[1,0]
	v_pk_mul_f32 v[52:53], v[48:49], v[58:59] op_sel_hi:[1,0]
	v_cvt_pk_bf16_f32 v48, v28, v29
	v_cvt_pk_bf16_f32 v49, v30, v31
	s_waitcnt vmcnt(1)
	v_pk_fma_f32 v[36:37], v[36:37], v[50:51], v[40:41]
	v_pk_fma_f32 v[38:39], v[38:39], v[52:53], v[42:43]
	v_pk_fma_f32 v[24:25], v[36:37], s[24:25], v[24:25] op_sel_hi:[1,0,1]
	v_pk_fma_f32 v[26:27], v[38:39], s[24:25], v[26:27] op_sel_hi:[1,0,1]
	s_waitcnt vmcnt(0)
	v_pk_add_f32 v[24:25], v[44:45], v[24:25]
	v_pk_add_f32 v[26:27], v[46:47], v[26:27]
	global_store_dwordx4 v[34:35], v[24:27], off offset:16
	v_cvt_pk_bf16_f32 v50, v24, v25
	v_cvt_pk_bf16_f32 v51, v26, v27
	flat_store_dwordx4 v[56:57], v[48:51]
	global_load_dwordx4 v[36:39], v[34:35], off offset:512
	global_load_dwordx4 v[40:43], v[126:127], off
	global_load_dwordx4 v[44:47], v[158:159], off
	s_nop 0
	global_load_dwordx4 v[48:51], v[160:161], off
	global_load_dwordx4 v[52:55], v[34:35], off offset:528
	s_waitcnt vmcnt(0)
	v_sub_f32_e32 v39, v39, v59
	v_sub_f32_e32 v38, v38, v59
	v_sub_f32_e32 v37, v37, v59
	v_sub_f32_e32 v36, v36, v59
	v_pk_mul_f32 v[36:37], v[58:59], v[36:37] op_sel_hi:[0,1]
	v_pk_mul_f32 v[38:39], v[58:59], v[38:39] op_sel_hi:[0,1]
	v_pk_fma_f32 v[38:39], v[42:43], v[38:39], v[46:47]
	v_pk_fma_f32 v[36:37], v[40:41], v[36:37], v[44:45]
	v_pk_fma_f32 v[22:23], v[38:39], s[24:25], v[22:23] op_sel_hi:[1,0,1]
	v_pk_fma_f32 v[20:21], v[36:37], s[24:25], v[20:21] op_sel_hi:[1,0,1]
	v_pk_add_f32 v[22:23], v[50:51], v[22:23]
	v_pk_add_f32 v[20:21], v[48:49], v[20:21]
	global_store_dwordx4 v[34:35], v[20:23], off offset:512
	global_load_dwordx4 v[36:39], v[120:121], off
	global_load_dwordx4 v[40:43], v[122:123], off
	global_load_dwordx4 v[44:47], v[116:117], off
	v_add_f32_e32 v48, v28, v29
	v_mul_f32_e32 v29, v29, v29
	v_fmac_f32_e32 v29, v28, v28
	v_add_f32_e32 v48, v30, v48
	v_fmac_f32_e32 v29, v30, v30
	v_add_f32_e32 v30, v24, v25
	v_mul_f32_e32 v25, v25, v25
	v_fmac_f32_e32 v25, v24, v24
	v_add_f32_e32 v28, v31, v48
	v_add_f32_e32 v30, v26, v30
	v_fmac_f32_e32 v25, v26, v26
	v_add_f32_e32 v28, 0, v28
	v_fmac_f32_e32 v29, v31, v31
	v_add_f32_e32 v24, v27, v30
	v_fmac_f32_e32 v25, v27, v27
	v_sub_f32_e32 v27, v53, v59
	v_sub_f32_e32 v26, v52, v59
	v_add_f32_e32 v28, v24, v28
	v_add_f32_e32 v29, v29, v25
	v_sub_f32_e32 v25, v55, v59
	v_sub_f32_e32 v24, v54, v59
	v_pk_mul_f32 v[26:27], v[58:59], v[26:27] op_sel_hi:[0,1]
	v_pk_mul_f32 v[24:25], v[58:59], v[24:25] op_sel_hi:[0,1]
	v_mul_f32_e32 v31, v21, v21
	v_add_f32_e32 v30, v20, v21
	v_fmac_f32_e32 v31, v20, v20
	v_add_f32_e32 v30, v22, v30
	v_fmac_f32_e32 v31, v22, v22
	v_add_f32_e32 v30, v23, v30
	v_fmac_f32_e32 v31, v23, v23
	v_add_f32_e32 v28, v28, v30
	v_add_f32_e32 v29, v29, v31
	v_cvt_pk_bf16_f32 v20, v20, v21
	v_cvt_pk_bf16_f32 v21, v22, v23
	s_waitcnt vmcnt(0)
	v_pk_fma_f32 v[26:27], v[36:37], v[26:27], v[40:41]
	v_pk_fma_f32 v[24:25], v[38:39], v[24:25], v[42:43]
	v_pk_fma_f32 v[16:17], v[26:27], s[24:25], v[16:17] op_sel_hi:[1,0,1]
	v_pk_fma_f32 v[18:19], v[24:25], s[24:25], v[18:19] op_sel_hi:[1,0,1]
	v_pk_add_f32 v[24:25], v[44:45], v[16:17]
	v_pk_add_f32 v[26:27], v[46:47], v[18:19]
	v_mul_f32_e32 v17, v25, v25
	v_add_f32_e32 v16, v24, v25
	v_fmac_f32_e32 v17, v24, v24
	v_add_f32_e32 v16, v26, v16
	v_fmac_f32_e32 v17, v26, v26
	v_add_f32_e32 v16, v27, v16
	v_fmac_f32_e32 v17, v27, v27
	v_add_f32_e32 v16, v28, v16
	v_add_f32_e32 v17, v29, v17
	ds_bpermute_b32 v18, v118, v16
	ds_bpermute_b32 v19, v118, v17
	global_store_dwordx4 v[34:35], v[24:27], off offset:528
	v_cvt_pk_bf16_f32 v22, v24, v25
	v_cvt_pk_bf16_f32 v23, v26, v27
	s_waitcnt lgkmcnt(0)
	v_add_f32_e32 v16, v16, v18
	v_add_f32_e32 v17, v17, v19
	ds_bpermute_b32 v18, v119, v16
	ds_bpermute_b32 v19, v119, v17
	flat_store_dwordx4 v[56:57], v[20:23] offset:256
	s_mov_b32 s100, -1
	s_mov_b32 s101, 0
	s_mov_b32 s98, 0xffff0000
	s_mov_b32 s99, 0
	s_and_saveexec_b64 s[36:37], s[100:101]
	s_cbranch_execz .LBB0_2650
	v_lshl_add_u64 v[20:21], s[8:9], 0, v[32:33]
	s_waitcnt lgkmcnt(0)
	v_add_f32_e32 v16, v16, v18
	v_add_f32_e32 v17, v17, v19
	v_cndmask_b32_e64 v16, v16, v17, s[98:99]
	v_cndmask_b32_e64 v17, 0, 4, s[98:99]
	v_or_b32_e32 v20, v20, v17
	v_mov_b32_e32 v254, v16
; DEVI unsigned pk2(float lo, float hi) { unsigned r; asm("v_cvt_pk_bf16_f32 %0, %1, %2" : "=v"(r) : "v"(lo), "v"(hi)); return r; }
;     DEVI void operator()(const f32x4 (&acc)[2][2][4][2], const pg8::Unit& u, int wr, int wc, int fr, int fq) const {
;     ...
;                 const int row = row0 + ai * 128 + m * 16; float mu, rs; row_stats(stin, row, mu, rs);
;                 float sum = 0.f, sq = 0.f;
; #pragma unroll
;                 for (int bj = 0; bj < 2; ++bj) {
;                     f32x4 z[2];
; #pragma unroll
;                     for (int n = 0; n < 2; ++n) {
;                         const int col = colb + bj * 128 + 4 * n;
;                         f32x4 xv = *(const f32x4*)(zsrc + (size_t)row * DM + col);
;                         if (stin) { const f32x4 gv = *(const f32x4*)(gin + col), bv = *(const f32x4*)(bin + col); xv = (xv - mu) * rs * gv + bv; }
;                         f32x4 zz = ALPHA * xv + acc[ai][bj][m][n];
;                         if (bias) zz += *(const f32x4*)(bias + col);
;                         *(f32x4*)(zdst + (size_t)row * DM + col) = zz;
;                         sum += zz[0] + zz[1] + zz[2] + zz[3]; sq += zz[0] * zz[0] + zz[1] * zz[1] + zz[2] * zz[2] + zz[3] * zz[3];
;                         z[n] = zz;
;                     }
;                     u32x4 o; o.x = pk2(z[0][0], z[0][1]); o.y = pk2(z[0][2], z[0][3]); o.z = pk2(z[1][0], z[1][1]); o.w = pk2(z[1][2], z[1][3]);
;                     if (zb) *(u32x4*)(zb + (size_t)row * DM + colb + bj * 128) = o;
;                 }
;                 sum += __shfl_xor(sum, 16); sq += __shfl_xor(sq, 16);
;                 sum += __shfl_xor(sum, 32); sq += __shfl_xor(sq, 32);
;                 if (fq == 0) { atomicAdd(stout + 2 * (size_t)row, sum); atomicAdd(stout + 2 * (size_t)row + 1, sq); }
.LBB0_2650:
	s_or_b64 exec, exec, s[36:37]
	v_add_u32_e32 v40, 0xb0, v154
	v_ashrrev_i32_e32 v41, 31, v40
	v_lshlrev_b64 v[16:17], 3, v[40:41]
	s_waitcnt lgkmcnt(0)
	v_lshl_add_u64 v[18:19], s[6:7], 0, v[16:17]
	flat_load_dwordx2 v[42:43], v[18:19]
	v_lshlrev_b64 v[18:19], 12, v[40:41]
	v_lshl_add_u64 v[18:19], s[46:47], 0, v[18:19]
	v_lshl_add_u64 v[18:19], v[144:145], 2, v[18:19]
	global_load_dwordx4 v[20:23], v[18:19], off
	global_load_dwordx4 v[24:27], v[150:151], off
	global_load_dwordx4 v[28:31], v[152:153], off
	global_load_dwordx4 v[32:35], v[156:157], off
	global_load_dwordx4 v[36:39], v[18:19], off offset:16
	s_waitcnt vmcnt(0) lgkmcnt(0)
	v_pk_mul_f32 v[42:43], v[42:43], s[22:23] op_sel:[1,0] op_sel_hi:[0,0]
	v_fma_f32 v42, -v43, v43, v42
	v_max_f32_e32 v42, 0, v42
	v_add_f32_e32 v42, 0x3727c5ac, v42
	v_mul_f32_e32 v44, 0x4b800000, v42
	v_cmp_gt_f32_e32 vcc, s64, v42
	v_sub_f32_e32 v23, v23, v43
	v_sub_f32_e32 v22, v22, v43
	v_cndmask_b32_e32 v42, v42, v44, vcc
	v_rsq_f32_e32 v42, v42
	v_sub_f32_e32 v21, v21, v43
	v_sub_f32_e32 v20, v20, v43
	v_mul_f32_e32 v44, 0x45800000, v42
	v_cndmask_b32_e32 v42, v42, v44, vcc
	v_pk_mul_f32 v[20:21], v[20:21], v[42:43] op_sel_hi:[1,0]
	v_pk_mul_f32 v[22:23], v[22:23], v[42:43] op_sel_hi:[1,0]
	v_pk_fma_f32 v[20:21], v[24:25], v[20:21], v[28:29]
	v_pk_fma_f32 v[22:23], v[26:27], v[22:23], v[30:31]
	v_pk_fma_f32 v[12:13], v[20:21], s[24:25], v[12:13] op_sel_hi:[1,0,1]
	v_pk_fma_f32 v[14:15], v[22:23], s[24:25], v[14:15] op_sel_hi:[1,0,1]
	v_pk_add_f32 v[12:13], v[32:33], v[12:13]
	v_pk_add_f32 v[14:15], v[34:35], v[14:15]
	global_store_dwordx4 v[18:19], v[12:15], off
	global_load_dwordx4 v[20:23], v[146:147], off
	global_load_dwordx4 v[24:27], v[148:149], off
	global_load_dwordx4 v[28:31], v[124:125], off
	v_lshlrev_b64 v[32:33], 11, v[40:41]
	v_lshl_add_u64 v[32:33], s[10:11], 0, v[32:33]
	v_lshl_add_u64 v[40:41], v[144:145], 1, v[32:33]
	v_sub_f32_e32 v33, v39, v43
	v_sub_f32_e32 v32, v38, v43
	v_sub_f32_e32 v35, v37, v43
	v_sub_f32_e32 v34, v36, v43
	v_pk_mul_f32 v[34:35], v[34:35], v[42:43] op_sel_hi:[1,0]
	v_pk_mul_f32 v[36:37], v[32:33], v[42:43] op_sel_hi:[1,0]
	v_cvt_pk_bf16_f32 v32, v12, v13
	v_cvt_pk_bf16_f32 v33, v14, v15
	s_waitcnt vmcnt(1)
	v_pk_fma_f32 v[20:21], v[20:21], v[34:35], v[24:25]
	v_pk_fma_f32 v[22:23], v[22:23], v[36:37], v[26:27]
	v_pk_fma_f32 v[8:9], v[20:21], s[24:25], v[8:9] op_sel_hi:[1,0,1]
	v_pk_fma_f32 v[10:11], v[22:23], s[24:25], v[10:11] op_sel_hi:[1,0,1]
	s_waitcnt vmcnt(0)
	v_pk_add_f32 v[8:9], v[28:29], v[8:9]
	v_pk_add_f32 v[10:11], v[30:31], v[10:11]
	global_store_dwordx4 v[18:19], v[8:11], off offset:16
	v_cvt_pk_bf16_f32 v34, v8, v9
	v_cvt_pk_bf16_f32 v35, v10, v11
	flat_store_dwordx4 v[40:41], v[32:35]
	global_load_dwordx4 v[20:23], v[18:19], off offset:512
	global_load_dwordx4 v[24:27], v[126:127], off
	global_load_dwordx4 v[28:31], v[158:159], off
	s_nop 0
	global_load_dwordx4 v[32:35], v[160:161], off
	global_load_dwordx4 v[36:39], v[18:19], off offset:528
	s_waitcnt vmcnt(0)
	v_sub_f32_e32 v23, v23, v43
	v_sub_f32_e32 v22, v22, v43
	v_sub_f32_e32 v21, v21, v43
	v_sub_f32_e32 v20, v20, v43
	v_pk_mul_f32 v[20:21], v[42:43], v[20:21] op_sel_hi:[0,1]
	v_pk_mul_f32 v[22:23], v[42:43], v[22:23] op_sel_hi:[0,1]
	v_pk_fma_f32 v[22:23], v[26:27], v[22:23], v[30:31]
	v_pk_fma_f32 v[20:21], v[24:25], v[20:21], v[28:29]
	v_pk_fma_f32 v[6:7], v[22:23], s[24:25], v[6:7] op_sel_hi:[1,0,1]
	v_pk_fma_f32 v[4:5], v[20:21], s[24:25], v[4:5] op_sel_hi:[1,0,1]
	v_pk_add_f32 v[6:7], v[34:35], v[6:7]
	v_pk_add_f32 v[4:5], v[32:33], v[4:5]
	global_store_dwordx4 v[18:19], v[4:7], off offset:512
	global_load_dwordx4 v[20:23], v[120:121], off
	global_load_dwordx4 v[24:27], v[122:123], off
	global_load_dwordx4 v[28:31], v[116:117], off
	v_add_f32_e32 v32, v12, v13
	v_mul_f32_e32 v13, v13, v13
	v_fmac_f32_e32 v13, v12, v12
	v_add_f32_e32 v32, v14, v32
	v_fmac_f32_e32 v13, v14, v14
	v_add_f32_e32 v14, v8, v9
	v_mul_f32_e32 v9, v9, v9
	v_fmac_f32_e32 v9, v8, v8
	v_add_f32_e32 v12, v15, v32
	v_add_f32_e32 v14, v10, v14
	v_fmac_f32_e32 v9, v10, v10
	v_add_f32_e32 v12, 0, v12
	v_fmac_f32_e32 v13, v15, v15
	v_add_f32_e32 v8, v11, v14
	v_fmac_f32_e32 v9, v11, v11
	v_sub_f32_e32 v11, v37, v43
	v_sub_f32_e32 v10, v36, v43
	v_add_f32_e32 v12, v8, v12
	v_add_f32_e32 v13, v13, v9
	v_sub_f32_e32 v9, v39, v43
	v_sub_f32_e32 v8, v38, v43
	v_pk_mul_f32 v[10:11], v[42:43], v[10:11] op_sel_hi:[0,1]
	v_pk_mul_f32 v[8:9], v[42:43], v[8:9] op_sel_hi:[0,1]
	v_mul_f32_e32 v15, v5, v5
	v_add_f32_e32 v14, v4, v5
	v_fmac_f32_e32 v15, v4, v4
	v_add_f32_e32 v14, v6, v14
	v_fmac_f32_e32 v15, v6, v6
	v_add_f32_e32 v14, v7, v14
	v_fmac_f32_e32 v15, v7, v7
	v_add_f32_e32 v12, v12, v14
	v_add_f32_e32 v13, v13, v15
	v_cvt_pk_bf16_f32 v4, v4, v5
	v_cvt_pk_bf16_f32 v5, v6, v7
	s_waitcnt vmcnt(0)
	v_pk_fma_f32 v[10:11], v[20:21], v[10:11], v[24:25]
	v_pk_fma_f32 v[8:9], v[22:23], v[8:9], v[26:27]
	v_pk_fma_f32 v[0:1], v[10:11], s[24:25], v[0:1] op_sel_hi:[1,0,1]
	v_pk_fma_f32 v[2:3], v[8:9], s[24:25], v[2:3] op_sel_hi:[1,0,1]
	v_pk_add_f32 v[8:9], v[28:29], v[0:1]
	v_pk_add_f32 v[10:11], v[30:31], v[2:3]
	v_mul_f32_e32 v1, v9, v9
	v_add_f32_e32 v0, v8, v9
	v_fmac_f32_e32 v1, v8, v8
	v_add_f32_e32 v0, v10, v0
	v_fmac_f32_e32 v1, v10, v10
	v_add_f32_e32 v0, v11, v0
	v_fmac_f32_e32 v1, v11, v11
	v_add_f32_e32 v0, v12, v0
	v_add_f32_e32 v1, v13, v1
	ds_bpermute_b32 v2, v118, v0
	ds_bpermute_b32 v3, v118, v1
	global_store_dwordx4 v[18:19], v[8:11], off offset:528
	v_cvt_pk_bf16_f32 v6, v8, v9
	v_cvt_pk_bf16_f32 v7, v10, v11
	s_waitcnt lgkmcnt(0)
	v_add_f32_e32 v0, v0, v2
	v_add_f32_e32 v1, v1, v3
	ds_bpermute_b32 v2, v119, v0
	ds_bpermute_b32 v3, v119, v1
	flat_store_dwordx4 v[40:41], v[4:7] offset:256
	s_mov_b32 s100, -1
	s_mov_b32 s101, 0
	s_mov_b32 s98, 0xffff0000
	s_mov_b32 s99, 0
	s_and_saveexec_b64 s[36:37], s[100:101]
	s_cbranch_execz .LBB0_2652
	v_lshl_add_u64 v[4:5], s[8:9], 0, v[16:17]
	s_waitcnt lgkmcnt(0)
	v_add_f32_e32 v0, v0, v2
	v_add_f32_e32 v1, v1, v3
	v_cndmask_b32_e64 v0, v0, v1, s[98:99]
	v_cndmask_b32_e64 v1, 0, 4, s[98:99]
	v_or_b32_e32 v4, v4, v1
	v_mov_b32_e32 v255, v0
	flat_atomic_add_f32 v[250:251], v252
	flat_atomic_add_f32 v[250:251], v253 offset:128
	flat_atomic_add_f32 v[250:251], v254 offset:256
	flat_atomic_add_f32 v[250:251], v255 offset:384

; DEVI unsigned pk2(float lo, float hi) { unsigned r; asm("v_cvt_pk_bf16_f32 %0, %1, %2" : "=v"(r) : "v"(lo), "v"(hi)); return r; }
;     DEVI void operator()(const f32x4 (&acc)[2][2][4][2], const pg8::Unit& u, int wr, int wc, int fr, int fq) const {
;     ...
;                 const int row = row0 + ai * 128 + m * 16; float mu, rs; row_stats(stin, row, mu, rs);
;                 float sum = 0.f, sq = 0.f;
; #pragma unroll
;                 for (int bj = 0; bj < 2; ++bj) {
;                     f32x4 z[2];
; #pragma unroll
;                     for (int n = 0; n < 2; ++n) {
;                         const int col = colb + bj * 128 + 4 * n;
;                         f32x4 xv = *(const f32x4*)(zsrc + (size_t)row * DM + col);
;                         if (stin) { const f32x4 gv = *(const f32x4*)(gin + col), bv = *(const f32x4*)(bin + col); xv = (xv - mu) * rs * gv + bv; }
;                         f32x4 zz = ALPHA * xv + acc[ai][bj][m][n];
;                         if (bias) zz += *(const f32x4*)(bias + col);
;                         *(f32x4*)(zdst + (size_t)row * DM + col) = zz;
;                         sum += zz[0] + zz[1] + zz[2] + zz[3]; sq += zz[0] * zz[0] + zz[1] * zz[1] + zz[2] * zz[2] + zz[3] * zz[3];
;                         z[n] = zz;
;                     }
;                     u32x4 o; o.x = pk2(z[0][0], z[0][1]); o.y = pk2(z[0][2], z[0][3]); o.z = pk2(z[1][0], z[1][1]); o.w = pk2(z[1][2], z[1][3]);
;                     if (zb) *(u32x4*)(zb + (size_t)row * DM + colb + bj * 128) = o;
;                 }
;                 sum += __shfl_xor(sum, 16); sq += __shfl_xor(sq, 16);
;                 sum += __shfl_xor(sum, 32); sq += __shfl_xor(sq, 32);
;                 if (fq == 0) { atomicAdd(stout + 2 * (size_t)row, sum); atomicAdd(stout + 2 * (size_t)row + 1, sq); }
.LBB0_2845:
	v_lshl_add_u32 v154, s58, 8, v160
	v_ashrrev_i32_e32 v155, 31, v154
	v_lshlrev_b64 v[156:157], 3, v[154:155]
	v_lshl_add_u64 v[146:147], s[12:13], 0, v[156:157]
	s_waitcnt vmcnt(0)
	flat_load_dwordx2 v[184:185], v[146:147]
	v_lshl_or_b32 v144, s59, 8, v162
	v_ashrrev_i32_e32 v145, 31, v144
	v_lshlrev_b64 v[146:147], 12, v[154:155]
	v_lshl_add_u64 v[146:147], s[46:47], 0, v[146:147]
	v_lshlrev_b64 v[148:149], 2, v[144:145]
	v_lshl_add_u64 v[158:159], v[146:147], 0, v[148:149]
	global_load_dwordx4 v[168:171], v[158:159], off
	v_lshl_add_u64 v[150:151], s[14:15], 0, v[148:149]
	v_lshl_add_u64 v[152:153], s[16:17], 0, v[148:149]
	global_load_dwordx4 v[172:175], v[150:151], off
	global_load_dwordx4 v[176:179], v[152:153], off
	global_load_dwordx4 v[180:183], v[158:159], off offset:16
	v_or_b32_e32 v146, 4, v144
	v_ashrrev_i32_e32 v147, 31, v146
	v_lshlrev_b64 v[148:149], 2, v[146:147]
	v_lshl_add_u64 v[146:147], s[14:15], 0, v[148:149]
	v_lshl_add_u64 v[148:149], s[16:17], 0, v[148:149]
	s_waitcnt vmcnt(0) lgkmcnt(0)
	v_pk_mul_f32 v[192:193], v[184:185], s[22:23] op_sel:[1,0] op_sel_hi:[0,0]
	v_fma_f32 v155, -v193, v193, v192
	v_max_f32_e32 v155, 0, v155
	v_add_f32_e32 v155, 0x3727c5ac, v155
	v_mul_f32_e32 v167, 0x4b800000, v155
	v_cmp_gt_f32_e32 vcc, s55, v155
	v_sub_f32_e32 v169, v169, v193
	s_nop 0
	v_cndmask_b32_e32 v155, v155, v167, vcc
	v_rsq_f32_e32 v155, v155
	v_sub_f32_e32 v168, v168, v193
	v_sub_f32_e32 v171, v171, v193
	v_sub_f32_e32 v170, v170, v193
	v_mul_f32_e32 v167, 0x45800000, v155
	v_cndmask_b32_e32 v192, v155, v167, vcc
	v_pk_mul_f32 v[170:171], v[170:171], v[192:193] op_sel_hi:[1,0]
	v_pk_mul_f32 v[168:169], v[168:169], v[192:193] op_sel_hi:[1,0]
	v_pk_fma_f32 v[170:171], v[174:175], v[170:171], v[178:179]
	v_pk_fma_f32 v[168:169], v[172:173], v[168:169], v[176:177]
	v_pk_fma_f32 v[170:171], v[170:171], s[24:25], v[126:127] op_sel_hi:[1,0,1]
	v_pk_fma_f32 v[168:169], v[168:169], s[24:25], v[124:125] op_sel_hi:[1,0,1]
	global_store_dwordx4 v[158:159], v[168:171], off
	global_load_dwordx4 v[172:175], v[146:147], off
	global_load_dwordx4 v[176:179], v[148:149], off
	v_sub_f32_e32 v181, v181, v193
	v_sub_f32_e32 v180, v180, v193
	v_sub_f32_e32 v183, v183, v193
	v_sub_f32_e32 v182, v182, v193
	v_or_b32_e32 v124, 0x80, v144
	v_pk_mul_f32 v[182:183], v[182:183], v[192:193] op_sel_hi:[1,0]
	v_pk_mul_f32 v[180:181], v[180:181], v[192:193] op_sel_hi:[1,0]
	v_ashrrev_i32_e32 v125, 31, v124
	global_load_dwordx4 v[184:187], v[158:159], off offset:512
	v_lshlrev_b64 v[126:127], 2, v[124:125]
	v_lshl_add_u64 v[124:125], s[14:15], 0, v[126:127]
	v_lshl_add_u64 v[126:127], s[16:17], 0, v[126:127]
	v_add_f32_e32 v167, v168, v169
	v_mul_f32_e32 v169, v169, v169
	v_fmac_f32_e32 v169, v168, v168
	v_add_f32_e32 v167, v170, v167
	v_fmac_f32_e32 v169, v170, v170
	v_add_f32_e32 v167, v171, v167
	v_add_f32_e32 v167, 0, v167
	v_fmac_f32_e32 v169, v171, v171
	v_xor_b32_e32 v155, 32, v166
	s_waitcnt vmcnt(1)
	v_pk_fma_f32 v[172:173], v[172:173], v[180:181], v[176:177]
	v_pk_fma_f32 v[174:175], v[174:175], v[182:183], v[178:179]
	v_pk_fma_f32 v[172:173], v[172:173], s[24:25], v[120:121] op_sel_hi:[1,0,1]
	v_pk_fma_f32 v[174:175], v[174:175], s[24:25], v[122:123] op_sel_hi:[1,0,1]
	global_store_dwordx4 v[158:159], v[172:175], off offset:16
	global_load_dwordx4 v[176:179], v[124:125], off
	global_load_dwordx4 v[180:183], v[126:127], off
	global_load_dwordx4 v[188:191], v[158:159], off offset:528
	v_or_b32_e32 v120, 0x84, v144
	v_ashrrev_i32_e32 v121, 31, v120
	v_lshlrev_b64 v[122:123], 2, v[120:121]
	s_waitcnt vmcnt(4)
	v_sub_f32_e32 v185, v185, v193
	v_sub_f32_e32 v184, v184, v193
	v_sub_f32_e32 v187, v187, v193
	v_sub_f32_e32 v186, v186, v193
	v_pk_mul_f32 v[186:187], v[192:193], v[186:187] op_sel_hi:[0,1]
	v_pk_mul_f32 v[184:185], v[192:193], v[184:185] op_sel_hi:[0,1]
	v_lshl_add_u64 v[120:121], s[14:15], 0, v[122:123]
	v_lshl_add_u64 v[122:123], s[16:17], 0, v[122:123]
	v_mul_f32_e32 v170, v173, v173
	v_add_f32_e32 v168, v172, v173
	v_fmac_f32_e32 v170, v172, v172
	v_add_f32_e32 v168, v174, v168
	v_fmac_f32_e32 v170, v174, v174
	v_add_f32_e32 v168, v175, v168
	v_fmac_f32_e32 v170, v175, v175
	v_add_f32_e32 v167, v168, v167
	v_add_f32_e32 v168, v169, v170
	s_waitcnt vmcnt(1)
	v_pk_fma_f32 v[176:177], v[176:177], v[184:185], v[180:181]
	v_pk_fma_f32 v[178:179], v[178:179], v[186:187], v[182:183]
	v_pk_fma_f32 v[176:177], v[176:177], s[24:25], v[116:117] op_sel_hi:[1,0,1]
	v_pk_fma_f32 v[178:179], v[178:179], s[24:25], v[118:119] op_sel_hi:[1,0,1]
	global_store_dwordx4 v[158:159], v[176:179], off offset:512
	global_load_dwordx4 v[180:183], v[120:121], off
	global_load_dwordx4 v[184:187], v[122:123], off
	v_mul_f32_e32 v170, v177, v177
	v_add_f32_e32 v169, v176, v177
	v_fmac_f32_e32 v170, v176, v176
	s_waitcnt vmcnt(3)
	v_sub_f32_e32 v119, v189, v193
	v_sub_f32_e32 v118, v188, v193
	v_sub_f32_e32 v189, v191, v193
	v_sub_f32_e32 v188, v190, v193
	v_add_f32_e32 v169, v178, v169
	v_fmac_f32_e32 v170, v178, v178
	v_pk_mul_f32 v[188:189], v[192:193], v[188:189] op_sel_hi:[0,1]
	v_pk_mul_f32 v[118:119], v[192:193], v[118:119] op_sel_hi:[0,1]
	v_add_f32_e32 v169, v179, v169
	v_fmac_f32_e32 v170, v179, v179
	v_add_f32_e32 v167, v167, v169
	v_add_f32_e32 v172, v168, v170
	v_and_b32_e32 v117, 64, v166
	v_xor_b32_e32 v116, 16, v166
	v_add_u32_e32 v117, 64, v117
	v_cmp_lt_i32_e32 vcc, v116, v117
	s_waitcnt vmcnt(0)
	v_pk_fma_f32 v[118:119], v[180:181], v[118:119], v[184:185]
	v_pk_fma_f32 v[168:169], v[182:183], v[188:189], v[186:187]
	v_cndmask_b32_e32 v116, v166, v116, vcc
	v_pk_fma_f32 v[170:171], v[168:169], s[24:25], v[114:115] op_sel_hi:[1,0,1]
	v_pk_fma_f32 v[168:169], v[118:119], s[24:25], v[112:113] op_sel_hi:[1,0,1]
	v_lshlrev_b32_e32 v116, 2, v116
	v_mul_f32_e32 v113, v169, v169
	v_add_f32_e32 v112, v168, v169
	v_fmac_f32_e32 v113, v168, v168
	v_add_f32_e32 v112, v170, v112
	v_fmac_f32_e32 v113, v170, v170
	v_add_f32_e32 v112, v171, v112
	v_fmac_f32_e32 v113, v171, v171
	v_add_f32_e32 v112, v167, v112
	v_add_f32_e32 v113, v172, v113
	ds_bpermute_b32 v115, v116, v112
	ds_bpermute_b32 v118, v116, v113
	v_cmp_lt_i32_e32 vcc, v155, v117
	global_store_dwordx4 v[158:159], v[168:171], off offset:528
	s_waitcnt lgkmcnt(1)
	v_add_f32_e32 v112, v112, v115
	v_cndmask_b32_e32 v114, v166, v155, vcc
	v_lshlrev_b32_e32 v114, 2, v114
	s_waitcnt lgkmcnt(0)
	v_add_f32_e32 v113, v113, v118
	ds_bpermute_b32 v115, v114, v112
	ds_bpermute_b32 v117, v114, v113
	s_mov_b32 s100, -1
	s_mov_b32 s101, 0
	s_mov_b32 s98, 0xffff0000
	s_mov_b32 s99, 0
	s_and_saveexec_b64 s[28:29], s[100:101]
	s_cbranch_execz .LBB0_2847
	v_lshl_add_u64 v[118:119], s[10:11], 0, v[156:157]
	s_waitcnt lgkmcnt(1)
	v_add_f32_e32 v112, v112, v115
	s_waitcnt lgkmcnt(0)
	v_add_f32_e32 v113, v113, v117
	v_cndmask_b32_e64 v112, v112, v113, s[98:99]
	v_cndmask_b32_e64 v113, 0, 4, s[98:99]
	v_or_b32_e32 v118, v118, v113
	v_mov_b32_e32 v250, v118
	v_mov_b32_e32 v251, v119
	v_mov_b32_e32 v252, v112
; DEVI unsigned pk2(float lo, float hi) { unsigned r; asm("v_cvt_pk_bf16_f32 %0, %1, %2" : "=v"(r) : "v"(lo), "v"(hi)); return r; }
;     DEVI void operator()(const f32x4 (&acc)[2][2][4][2], const pg8::Unit& u, int wr, int wc, int fr, int fq) const {
;     ...
;                 const int row = row0 + ai * 128 + m * 16; float mu, rs; row_stats(stin, row, mu, rs);
;                 float sum = 0.f, sq = 0.f;
; #pragma unroll
;                 for (int bj = 0; bj < 2; ++bj) {
;                     f32x4 z[2];
; #pragma unroll
;                     for (int n = 0; n < 2; ++n) {
;                         const int col = colb + bj * 128 + 4 * n;
;                         f32x4 xv = *(const f32x4*)(zsrc + (size_t)row * DM + col);
;                         if (stin) { const f32x4 gv = *(const f32x4*)(gin + col), bv = *(const f32x4*)(bin + col); xv = (xv - mu) * rs * gv + bv; }
;                         f32x4 zz = ALPHA * xv + acc[ai][bj][m][n];
;                         if (bias) zz += *(const f32x4*)(bias + col);
;                         *(f32x4*)(zdst + (size_t)row * DM + col) = zz;
;                         sum += zz[0] + zz[1] + zz[2] + zz[3]; sq += zz[0] * zz[0] + zz[1] * zz[1] + zz[2] * zz[2] + zz[3] * zz[3];
;                         z[n] = zz;
;                     }
;                     u32x4 o; o.x = pk2(z[0][0], z[0][1]); o.y = pk2(z[0][2], z[0][3]); o.z = pk2(z[1][0], z[1][1]); o.w = pk2(z[1][2], z[1][3]);
;                     if (zb) *(u32x4*)(zb + (size_t)row * DM + colb + bj * 128) = o;
;                 }
;                 sum += __shfl_xor(sum, 16); sq += __shfl_xor(sq, 16);
;                 sum += __shfl_xor(sum, 32); sq += __shfl_xor(sq, 32);
;                 if (fq == 0) { atomicAdd(stout + 2 * (size_t)row, sum); atomicAdd(stout + 2 * (size_t)row + 1, sq); }
.LBB0_2847:
	s_or_b64 exec, exec, s[28:29]
	v_or_b32_e32 v118, 16, v154
	v_ashrrev_i32_e32 v119, 31, v118
	v_lshlrev_b64 v[112:113], 3, v[118:119]
	v_lshl_add_u64 v[156:157], s[12:13], 0, v[112:113]
	flat_load_dwordx2 v[180:181], v[156:157]
	v_lshlrev_b64 v[118:119], 12, v[118:119]
	v_lshl_add_u64 v[118:119], s[46:47], 0, v[118:119]
	v_lshl_add_u64 v[118:119], v[144:145], 2, v[118:119]
	global_load_dwordx4 v[156:159], v[118:119], off
	global_load_dwordx4 v[168:171], v[150:151], off
	global_load_dwordx4 v[172:175], v[152:153], off
	global_load_dwordx4 v[176:179], v[118:119], off offset:16
	s_waitcnt vmcnt(0) lgkmcnt(0)
	v_pk_mul_f32 v[180:181], v[180:181], s[22:23] op_sel:[1,0] op_sel_hi:[0,0]
	v_fma_f32 v115, -v181, v181, v180
	v_max_f32_e32 v115, 0, v115
	v_add_f32_e32 v115, 0x3727c5ac, v115
	v_mul_f32_e32 v117, 0x4b800000, v115
	v_cmp_gt_f32_e32 vcc, s55, v115
	v_sub_f32_e32 v157, v157, v181
	v_sub_f32_e32 v156, v156, v181
	v_cndmask_b32_e32 v115, v115, v117, vcc
	v_rsq_f32_e32 v115, v115
	v_sub_f32_e32 v159, v159, v181
	v_sub_f32_e32 v158, v158, v181
	v_sub_f32_e32 v177, v177, v181
	v_mul_f32_e32 v117, 0x45800000, v115
	v_cndmask_b32_e32 v180, v115, v117, vcc
	v_pk_mul_f32 v[158:159], v[158:159], v[180:181] op_sel_hi:[1,0]
	v_pk_mul_f32 v[156:157], v[156:157], v[180:181] op_sel_hi:[1,0]
	v_pk_fma_f32 v[158:159], v[170:171], v[158:159], v[174:175]
	v_pk_fma_f32 v[156:157], v[168:169], v[156:157], v[172:173]
	v_pk_fma_f32 v[110:111], v[158:159], s[24:25], v[110:111] op_sel_hi:[1,0,1]
	v_pk_fma_f32 v[108:109], v[156:157], s[24:25], v[108:109] op_sel_hi:[1,0,1]
	global_store_dwordx4 v[118:119], v[108:111], off
	global_load_dwordx4 v[156:159], v[146:147], off
	global_load_dwordx4 v[168:171], v[148:149], off
	global_load_dwordx4 v[172:175], v[118:119], off offset:512
	v_sub_f32_e32 v176, v176, v181
	v_sub_f32_e32 v179, v179, v181
	v_sub_f32_e32 v178, v178, v181
	v_pk_mul_f32 v[178:179], v[178:179], v[180:181] op_sel_hi:[1,0]
	v_pk_mul_f32 v[176:177], v[176:177], v[180:181] op_sel_hi:[1,0]
	v_add_f32_e32 v115, v108, v109
	v_mul_f32_e32 v109, v109, v109
	v_fmac_f32_e32 v109, v108, v108
	v_add_f32_e32 v115, v110, v115
	v_fmac_f32_e32 v109, v110, v110
	v_add_f32_e32 v108, v111, v115
	v_add_f32_e32 v108, 0, v108
	v_fmac_f32_e32 v109, v111, v111
	s_waitcnt vmcnt(1)
	v_pk_fma_f32 v[156:157], v[156:157], v[176:177], v[168:169]
	v_pk_fma_f32 v[158:159], v[158:159], v[178:179], v[170:171]
	v_pk_fma_f32 v[104:105], v[156:157], s[24:25], v[104:105] op_sel_hi:[1,0,1]
	v_pk_fma_f32 v[106:107], v[158:159], s[24:25], v[106:107] op_sel_hi:[1,0,1]
	global_store_dwordx4 v[118:119], v[104:107], off offset:16
	global_load_dwordx4 v[156:159], v[124:125], off
	global_load_dwordx4 v[168:171], v[126:127], off
	global_load_dwordx4 v[176:179], v[118:119], off offset:528
	s_waitcnt vmcnt(4)
	v_sub_f32_e32 v173, v173, v181
	v_sub_f32_e32 v172, v172, v181
	v_sub_f32_e32 v175, v175, v181
	v_sub_f32_e32 v174, v174, v181
	v_pk_mul_f32 v[174:175], v[180:181], v[174:175] op_sel_hi:[0,1]
	v_pk_mul_f32 v[172:173], v[180:181], v[172:173] op_sel_hi:[0,1]
	v_add_f32_e32 v110, v104, v105
	v_mul_f32_e32 v105, v105, v105
	v_fmac_f32_e32 v105, v104, v104
	v_add_f32_e32 v110, v106, v110
	v_fmac_f32_e32 v105, v106, v106
	v_add_f32_e32 v104, v107, v110
	v_fmac_f32_e32 v105, v107, v107
	v_add_f32_e32 v104, v104, v108
	v_add_f32_e32 v105, v109, v105
	s_waitcnt vmcnt(1)
	v_pk_fma_f32 v[156:157], v[156:157], v[172:173], v[168:169]
	v_pk_fma_f32 v[158:159], v[158:159], v[174:175], v[170:171]
	v_pk_fma_f32 v[100:101], v[156:157], s[24:25], v[100:101] op_sel_hi:[1,0,1]
	v_pk_fma_f32 v[102:103], v[158:159], s[24:25], v[102:103] op_sel_hi:[1,0,1]
	global_store_dwordx4 v[118:119], v[100:103], off offset:512
	global_load_dwordx4 v[156:159], v[120:121], off
	global_load_dwordx4 v[168:171], v[122:123], off
	v_add_f32_e32 v106, v100, v101
	v_mul_f32_e32 v101, v101, v101
	v_fmac_f32_e32 v101, v100, v100
	s_waitcnt vmcnt(3)
	v_sub_f32_e32 v173, v177, v181
	v_sub_f32_e32 v172, v176, v181
	v_add_f32_e32 v106, v102, v106
	v_fmac_f32_e32 v101, v102, v102
	v_pk_mul_f32 v[172:173], v[180:181], v[172:173] op_sel_hi:[0,1]
	v_add_f32_e32 v100, v103, v106
	v_fmac_f32_e32 v101, v103, v103
	v_sub_f32_e32 v175, v179, v181
	v_sub_f32_e32 v174, v178, v181
	v_add_f32_e32 v104, v104, v100
	v_add_f32_e32 v105, v105, v101
	v_pk_mul_f32 v[174:175], v[180:181], v[174:175] op_sel_hi:[0,1]
	s_waitcnt vmcnt(0)
	v_pk_fma_f32 v[100:101], v[156:157], v[172:173], v[168:169]
	s_nop 0
	v_pk_fma_f32 v[100:101], v[100:101], s[24:25], v[96:97] op_sel_hi:[1,0,1]
	v_pk_fma_f32 v[102:103], v[158:159], v[174:175], v[170:171]
	v_mul_f32_e32 v97, v101, v101
	v_pk_fma_f32 v[102:103], v[102:103], s[24:25], v[98:99] op_sel_hi:[1,0,1]
	v_add_f32_e32 v96, v100, v101
	v_fmac_f32_e32 v97, v100, v100
	v_add_f32_e32 v96, v102, v96
	v_fmac_f32_e32 v97, v102, v102
	v_add_f32_e32 v96, v103, v96
	v_fmac_f32_e32 v97, v103, v103
	v_add_f32_e32 v96, v104, v96
	v_add_f32_e32 v97, v105, v97
	ds_bpermute_b32 v98, v116, v96
	ds_bpermute_b32 v99, v116, v97
	global_store_dwordx4 v[118:119], v[100:103], off offset:528
	s_waitcnt lgkmcnt(1)
	v_add_f32_e32 v96, v96, v98
	s_waitcnt lgkmcnt(0)
	v_add_f32_e32 v97, v97, v99
	ds_bpermute_b32 v98, v114, v96
	ds_bpermute_b32 v99, v114, v97
	s_mov_b32 s100, -1
	s_mov_b32 s101, 0
	s_mov_b32 s98, 0xffff0000
	s_mov_b32 s99, 0
	s_and_saveexec_b64 s[28:29], s[100:101]
	s_cbranch_execz .LBB0_2849
	v_lshl_add_u64 v[100:101], s[10:11], 0, v[112:113]
	s_waitcnt lgkmcnt(1)
	v_add_f32_e32 v96, v96, v98
	s_waitcnt lgkmcnt(0)
	v_add_f32_e32 v97, v97, v99
	v_cndmask_b32_e64 v96, v96, v97, s[98:99]
	v_cndmask_b32_e64 v97, 0, 4, s[98:99]
	v_or_b32_e32 v100, v100, v97
	v_mov_b32_e32 v253, v96
; DEVI unsigned pk2(float lo, float hi) { unsigned r; asm("v_cvt_pk_bf16_f32 %0, %1, %2" : "=v"(r) : "v"(lo), "v"(hi)); return r; }
;     DEVI void operator()(const f32x4 (&acc)[2][2][4][2], const pg8::Unit& u, int wr, int wc, int fr, int fq) const {
;     ...
;                 const int row = row0 + ai * 128 + m * 16; float mu, rs; row_stats(stin, row, mu, rs);
;                 float sum = 0.f, sq = 0.f;
; #pragma unroll
;                 for (int bj = 0; bj < 2; ++bj) {
;                     f32x4 z[2];
; #pragma unroll
;                     for (int n = 0; n < 2; ++n) {
;                         const int col = colb + bj * 128 + 4 * n;
;                         f32x4 xv = *(const f32x4*)(zsrc + (size_t)row * DM + col);
;                         if (stin) { const f32x4 gv = *(const f32x4*)(gin + col), bv = *(const f32x4*)(bin + col); xv = (xv - mu) * rs * gv + bv; }
;                         f32x4 zz = ALPHA * xv + acc[ai][bj][m][n];
;                         if (bias) zz += *(const f32x4*)(bias + col);
;                         *(f32x4*)(zdst + (size_t)row * DM + col) = zz;
;                         sum += zz[0] + zz[1] + zz[2] + zz[3]; sq += zz[0] * zz[0] + zz[1] * zz[1] + zz[2] * zz[2] + zz[3] * zz[3];
;                         z[n] = zz;
;                     }
;                     u32x4 o; o.x = pk2(z[0][0], z[0][1]); o.y = pk2(z[0][2], z[0][3]); o.z = pk2(z[1][0], z[1][1]); o.w = pk2(z[1][2], z[1][3]);
;                     if (zb) *(u32x4*)(zb + (size_t)row * DM + colb + bj * 128) = o;
;                 }
;                 sum += __shfl_xor(sum, 16); sq += __shfl_xor(sq, 16);
;                 sum += __shfl_xor(sum, 32); sq += __shfl_xor(sq, 32);
;                 if (fq == 0) { atomicAdd(stout + 2 * (size_t)row, sum); atomicAdd(stout + 2 * (size_t)row + 1, sq); }
.LBB0_2849:
	s_or_b64 exec, exec, s[28:29]
	s_waitcnt lgkmcnt(0)
	v_or_b32_e32 v98, 32, v154
	v_ashrrev_i32_e32 v99, 31, v98
	v_lshlrev_b64 v[96:97], 3, v[98:99]
	v_lshl_add_u64 v[100:101], s[12:13], 0, v[96:97]
	flat_load_dwordx2 v[118:119], v[100:101]
	v_lshlrev_b64 v[98:99], 12, v[98:99]
	v_lshl_add_u64 v[98:99], s[46:47], 0, v[98:99]
	v_lshl_add_u64 v[156:157], v[144:145], 2, v[98:99]
	global_load_dwordx4 v[98:101], v[156:157], off
	global_load_dwordx4 v[102:105], v[150:151], off
	global_load_dwordx4 v[106:109], v[152:153], off
	global_load_dwordx4 v[110:113], v[156:157], off offset:16
	s_waitcnt vmcnt(0) lgkmcnt(0)
	v_pk_mul_f32 v[118:119], v[118:119], s[22:23] op_sel:[1,0] op_sel_hi:[0,0]
	v_fma_f32 v115, -v119, v119, v118
	v_max_f32_e32 v115, 0, v115
	v_add_f32_e32 v115, 0x3727c5ac, v115
	v_mul_f32_e32 v117, 0x4b800000, v115
	v_cmp_gt_f32_e32 vcc, s55, v115
	v_sub_f32_e32 v99, v99, v119
	v_sub_f32_e32 v98, v98, v119
	v_cndmask_b32_e32 v115, v115, v117, vcc
	v_rsq_f32_e32 v115, v115
	v_sub_f32_e32 v101, v101, v119
	v_sub_f32_e32 v100, v100, v119
	v_sub_f32_e32 v111, v111, v119
	v_mul_f32_e32 v117, 0x45800000, v115
	v_cndmask_b32_e32 v118, v115, v117, vcc
	v_pk_mul_f32 v[100:101], v[100:101], v[118:119] op_sel_hi:[1,0]
	v_pk_mul_f32 v[98:99], v[98:99], v[118:119] op_sel_hi:[1,0]
	v_pk_fma_f32 v[100:101], v[104:105], v[100:101], v[108:109]
	v_pk_fma_f32 v[98:99], v[102:103], v[98:99], v[106:107]
	v_pk_fma_f32 v[94:95], v[100:101], s[24:25], v[94:95] op_sel_hi:[1,0,1]
	v_pk_fma_f32 v[92:93], v[98:99], s[24:25], v[92:93] op_sel_hi:[1,0,1]
	global_store_dwordx4 v[156:157], v[92:95], off
	global_load_dwordx4 v[98:101], v[146:147], off
	global_load_dwordx4 v[102:105], v[148:149], off
	global_load_dwordx4 v[106:109], v[156:157], off offset:512
	v_sub_f32_e32 v110, v110, v119
	v_sub_f32_e32 v113, v113, v119
	v_sub_f32_e32 v112, v112, v119
	v_pk_mul_f32 v[112:113], v[112:113], v[118:119] op_sel_hi:[1,0]
	v_pk_mul_f32 v[110:111], v[110:111], v[118:119] op_sel_hi:[1,0]
	s_waitcnt vmcnt(1)
	v_pk_fma_f32 v[100:101], v[100:101], v[112:113], v[104:105]
	v_pk_fma_f32 v[98:99], v[98:99], v[110:111], v[102:103]
	v_pk_fma_f32 v[90:91], v[100:101], s[24:25], v[90:91] op_sel_hi:[1,0,1]
	v_pk_fma_f32 v[88:89], v[98:99], s[24:25], v[88:89] op_sel_hi:[1,0,1]
	global_store_dwordx4 v[156:157], v[88:91], off offset:16
	global_load_dwordx4 v[98:101], v[124:125], off
	global_load_dwordx4 v[102:105], v[126:127], off
	global_load_dwordx4 v[110:113], v[156:157], off offset:528
	s_waitcnt vmcnt(4)
	v_sub_f32_e32 v107, v107, v119
	v_sub_f32_e32 v106, v106, v119
	v_sub_f32_e32 v109, v109, v119
	v_sub_f32_e32 v108, v108, v119
	v_pk_mul_f32 v[108:109], v[118:119], v[108:109] op_sel_hi:[0,1]
	v_pk_mul_f32 v[106:107], v[118:119], v[106:107] op_sel_hi:[0,1]
	s_waitcnt vmcnt(1)
	v_pk_fma_f32 v[98:99], v[98:99], v[106:107], v[102:103]
	v_pk_fma_f32 v[100:101], v[100:101], v[108:109], v[104:105]
	v_pk_fma_f32 v[84:85], v[98:99], s[24:25], v[84:85] op_sel_hi:[1,0,1]
	v_pk_fma_f32 v[86:87], v[100:101], s[24:25], v[86:87] op_sel_hi:[1,0,1]
	global_store_dwordx4 v[156:157], v[84:87], off offset:512
	global_load_dwordx4 v[98:101], v[120:121], off
	global_load_dwordx4 v[102:105], v[122:123], off
	s_waitcnt vmcnt(3)
	v_sub_f32_e32 v106, v110, v119
	v_add_f32_e32 v110, v92, v93
	v_mul_f32_e32 v93, v93, v93
	v_fmac_f32_e32 v93, v92, v92
	v_add_f32_e32 v110, v94, v110
	v_fmac_f32_e32 v93, v94, v94
	v_add_f32_e32 v94, v88, v89
	v_mul_f32_e32 v89, v89, v89
	v_fmac_f32_e32 v89, v88, v88
	v_add_f32_e32 v94, v90, v94
	v_fmac_f32_e32 v89, v90, v90
	v_add_f32_e32 v90, v84, v85
	v_mul_f32_e32 v85, v85, v85
	v_add_f32_e32 v92, v95, v110
	v_fmac_f32_e32 v85, v84, v84
	v_sub_f32_e32 v107, v111, v119
	v_add_f32_e32 v92, 0, v92
	v_fmac_f32_e32 v93, v95, v95
	v_add_f32_e32 v88, v91, v94
	v_fmac_f32_e32 v89, v91, v91
	v_add_f32_e32 v90, v86, v90
	v_fmac_f32_e32 v85, v86, v86
	v_pk_mul_f32 v[106:107], v[118:119], v[106:107] op_sel_hi:[0,1]
	v_add_f32_e32 v88, v88, v92
	v_add_f32_e32 v89, v93, v89
	v_add_f32_e32 v84, v87, v90
	v_fmac_f32_e32 v85, v87, v87
	v_sub_f32_e32 v109, v113, v119
	v_sub_f32_e32 v108, v112, v119
	v_add_f32_e32 v88, v88, v84
	v_add_f32_e32 v89, v89, v85
	v_pk_mul_f32 v[108:109], v[118:119], v[108:109] op_sel_hi:[0,1]
	s_waitcnt vmcnt(0)
	v_pk_fma_f32 v[84:85], v[98:99], v[106:107], v[102:103]
	s_nop 0
	v_pk_fma_f32 v[84:85], v[84:85], s[24:25], v[80:81] op_sel_hi:[1,0,1]
	v_pk_fma_f32 v[86:87], v[100:101], v[108:109], v[104:105]
	v_mul_f32_e32 v81, v85, v85
	v_pk_fma_f32 v[86:87], v[86:87], s[24:25], v[82:83] op_sel_hi:[1,0,1]
	v_add_f32_e32 v80, v84, v85
	v_fmac_f32_e32 v81, v84, v84
	v_add_f32_e32 v80, v86, v80
	v_fmac_f32_e32 v81, v86, v86
	v_add_f32_e32 v80, v87, v80
	v_fmac_f32_e32 v81, v87, v87
	v_add_f32_e32 v80, v88, v80
	v_add_f32_e32 v81, v89, v81
	ds_bpermute_b32 v82, v116, v80
	ds_bpermute_b32 v83, v116, v81
	global_store_dwordx4 v[156:157], v[84:87], off offset:528
	s_waitcnt lgkmcnt(1)
	v_add_f32_e32 v80, v80, v82
	s_waitcnt lgkmcnt(0)
	v_add_f32_e32 v81, v81, v83
	ds_bpermute_b32 v82, v114, v80
	ds_bpermute_b32 v83, v114, v81
	s_mov_b32 s100, -1
	s_mov_b32 s101, 0
	s_mov_b32 s98, 0xffff0000
	s_mov_b32 s99, 0
	s_and_saveexec_b64 s[28:29], s[100:101]
	s_cbranch_execz .LBB0_2851
	v_lshl_add_u64 v[84:85], s[10:11], 0, v[96:97]
	s_waitcnt lgkmcnt(1)
	v_add_f32_e32 v80, v80, v82
	s_waitcnt lgkmcnt(0)
	v_add_f32_e32 v81, v81, v83
	v_cndmask_b32_e64 v80, v80, v81, s[98:99]
	v_cndmask_b32_e64 v81, 0, 4, s[98:99]
	v_or_b32_e32 v84, v84, v81
	v_mov_b32_e32 v254, v80
; DEVI unsigned pk2(float lo, float hi) { unsigned r; asm("v_cvt_pk_bf16_f32 %0, %1, %2" : "=v"(r) : "v"(lo), "v"(hi)); return r; }
;     DEVI void operator()(const f32x4 (&acc)[2][2][4][2], const pg8::Unit& u, int wr, int wc, int fr, int fq) const {
;     ...
;                 const int row = row0 + ai * 128 + m * 16; float mu, rs; row_stats(stin, row, mu, rs);
;                 float sum = 0.f, sq = 0.f;
; #pragma unroll
;                 for (int bj = 0; bj < 2; ++bj) {
;                     f32x4 z[2];
; #pragma unroll
;                     for (int n = 0; n < 2; ++n) {
;                         const int col = colb + bj * 128 + 4 * n;
;                         f32x4 xv = *(const f32x4*)(zsrc + (size_t)row * DM + col);
;                         if (stin) { const f32x4 gv = *(const f32x4*)(gin + col), bv = *(const f32x4*)(bin + col); xv = (xv - mu) * rs * gv + bv; }
;                         f32x4 zz = ALPHA * xv + acc[ai][bj][m][n];
;                         if (bias) zz += *(const f32x4*)(bias + col);
;                         *(f32x4*)(zdst + (size_t)row * DM + col) = zz;
;                         sum += zz[0] + zz[1] + zz[2] + zz[3]; sq += zz[0] * zz[0] + zz[1] * zz[1] + zz[2] * zz[2] + zz[3] * zz[3];
;                         z[n] = zz;
;                     }
;                     u32x4 o; o.x = pk2(z[0][0], z[0][1]); o.y = pk2(z[0][2], z[0][3]); o.z = pk2(z[1][0], z[1][1]); o.w = pk2(z[1][2], z[1][3]);
;                     if (zb) *(u32x4*)(zb + (size_t)row * DM + colb + bj * 128) = o;
;                 }
;                 sum += __shfl_xor(sum, 16); sq += __shfl_xor(sq, 16);
;                 sum += __shfl_xor(sum, 32); sq += __shfl_xor(sq, 32);
;                 if (fq == 0) { atomicAdd(stout + 2 * (size_t)row, sum); atomicAdd(stout + 2 * (size_t)row + 1, sq); }
.LBB0_2851:
	s_or_b64 exec, exec, s[28:29]
	s_waitcnt lgkmcnt(0)
	v_or_b32_e32 v82, 48, v154
	v_ashrrev_i32_e32 v83, 31, v82
	v_lshlrev_b64 v[80:81], 3, v[82:83]
	v_lshl_add_u64 v[84:85], s[12:13], 0, v[80:81]
	flat_load_dwordx2 v[98:99], v[84:85]
	v_lshlrev_b64 v[82:83], 12, v[82:83]
	v_lshl_add_u64 v[82:83], s[46:47], 0, v[82:83]
	v_lshl_add_u64 v[100:101], v[144:145], 2, v[82:83]
	global_load_dwordx4 v[82:85], v[100:101], off
	global_load_dwordx4 v[86:89], v[150:151], off
	global_load_dwordx4 v[90:93], v[152:153], off
	global_load_dwordx4 v[94:97], v[100:101], off offset:16
	s_waitcnt vmcnt(0) lgkmcnt(0)
	v_pk_mul_f32 v[98:99], v[98:99], s[22:23] op_sel:[1,0] op_sel_hi:[0,0]
	v_fma_f32 v98, -v99, v99, v98
	v_max_f32_e32 v98, 0, v98
	v_add_f32_e32 v98, 0x3727c5ac, v98
	v_mul_f32_e32 v102, 0x4b800000, v98
	v_cmp_gt_f32_e32 vcc, s55, v98
	v_sub_f32_e32 v83, v83, v99
	v_sub_f32_e32 v82, v82, v99
	v_cndmask_b32_e32 v98, v98, v102, vcc
	v_rsq_f32_e32 v98, v98
	v_sub_f32_e32 v85, v85, v99
	v_sub_f32_e32 v84, v84, v99
	v_sub_f32_e32 v95, v95, v99
	v_mul_f32_e32 v102, 0x45800000, v98
	v_cndmask_b32_e32 v98, v98, v102, vcc
	v_pk_mul_f32 v[84:85], v[84:85], v[98:99] op_sel_hi:[1,0]
	v_pk_mul_f32 v[82:83], v[82:83], v[98:99] op_sel_hi:[1,0]
	v_pk_fma_f32 v[84:85], v[88:89], v[84:85], v[92:93]
	v_pk_fma_f32 v[82:83], v[86:87], v[82:83], v[90:91]
	v_pk_fma_f32 v[78:79], v[84:85], s[24:25], v[78:79] op_sel_hi:[1,0,1]
	v_pk_fma_f32 v[76:77], v[82:83], s[24:25], v[76:77] op_sel_hi:[1,0,1]
	global_store_dwordx4 v[100:101], v[76:79], off
	global_load_dwordx4 v[82:85], v[146:147], off
	global_load_dwordx4 v[86:89], v[148:149], off
	global_load_dwordx4 v[90:93], v[100:101], off offset:512
	v_sub_f32_e32 v94, v94, v99
	v_sub_f32_e32 v97, v97, v99
	v_sub_f32_e32 v96, v96, v99
	v_pk_mul_f32 v[96:97], v[96:97], v[98:99] op_sel_hi:[1,0]
	v_pk_mul_f32 v[94:95], v[94:95], v[98:99] op_sel_hi:[1,0]
	s_waitcnt vmcnt(1)
	v_pk_fma_f32 v[84:85], v[84:85], v[96:97], v[88:89]
	v_pk_fma_f32 v[82:83], v[82:83], v[94:95], v[86:87]
	v_pk_fma_f32 v[74:75], v[84:85], s[24:25], v[74:75] op_sel_hi:[1,0,1]
	v_pk_fma_f32 v[72:73], v[82:83], s[24:25], v[72:73] op_sel_hi:[1,0,1]
	global_store_dwordx4 v[100:101], v[72:75], off offset:16
	global_load_dwordx4 v[82:85], v[124:125], off
	global_load_dwordx4 v[86:89], v[126:127], off
	global_load_dwordx4 v[94:97], v[100:101], off offset:528
	s_waitcnt vmcnt(4)
	v_sub_f32_e32 v91, v91, v99
	v_sub_f32_e32 v90, v90, v99
	v_sub_f32_e32 v93, v93, v99
	v_sub_f32_e32 v92, v92, v99
	v_pk_mul_f32 v[92:93], v[98:99], v[92:93] op_sel_hi:[0,1]
	v_pk_mul_f32 v[90:91], v[98:99], v[90:91] op_sel_hi:[0,1]
	s_waitcnt vmcnt(1)
	v_pk_fma_f32 v[82:83], v[82:83], v[90:91], v[86:87]
	v_pk_fma_f32 v[84:85], v[84:85], v[92:93], v[88:89]
	v_pk_fma_f32 v[68:69], v[82:83], s[24:25], v[68:69] op_sel_hi:[1,0,1]
	v_pk_fma_f32 v[70:71], v[84:85], s[24:25], v[70:71] op_sel_hi:[1,0,1]
	global_store_dwordx4 v[100:101], v[68:71], off offset:512
	global_load_dwordx4 v[82:85], v[120:121], off
	global_load_dwordx4 v[86:89], v[122:123], off
	s_waitcnt vmcnt(3)
	v_sub_f32_e32 v90, v94, v99
	v_add_f32_e32 v94, v76, v77
	v_mul_f32_e32 v77, v77, v77
	v_fmac_f32_e32 v77, v76, v76
	v_add_f32_e32 v94, v78, v94
	v_fmac_f32_e32 v77, v78, v78
	v_add_f32_e32 v78, v72, v73
	v_mul_f32_e32 v73, v73, v73
	v_fmac_f32_e32 v73, v72, v72
	v_add_f32_e32 v78, v74, v78
	v_fmac_f32_e32 v73, v74, v74
	v_add_f32_e32 v74, v68, v69
	v_mul_f32_e32 v69, v69, v69
	v_add_f32_e32 v76, v79, v94
	v_fmac_f32_e32 v69, v68, v68
	v_sub_f32_e32 v91, v95, v99
	v_add_f32_e32 v76, 0, v76
	v_fmac_f32_e32 v77, v79, v79
	v_add_f32_e32 v72, v75, v78
	v_fmac_f32_e32 v73, v75, v75
	v_add_f32_e32 v74, v70, v74
	v_fmac_f32_e32 v69, v70, v70
	v_pk_mul_f32 v[90:91], v[98:99], v[90:91] op_sel_hi:[0,1]
	v_add_f32_e32 v72, v72, v76
	v_add_f32_e32 v73, v77, v73
	v_add_f32_e32 v68, v71, v74
	v_fmac_f32_e32 v69, v71, v71
	v_sub_f32_e32 v93, v97, v99
	v_sub_f32_e32 v92, v96, v99
	v_add_f32_e32 v72, v72, v68
	v_add_f32_e32 v73, v73, v69
	v_pk_mul_f32 v[92:93], v[98:99], v[92:93] op_sel_hi:[0,1]
	s_waitcnt vmcnt(0)
	v_pk_fma_f32 v[68:69], v[82:83], v[90:91], v[86:87]
	s_nop 0
	v_pk_fma_f32 v[68:69], v[68:69], s[24:25], v[64:65] op_sel_hi:[1,0,1]
	v_pk_fma_f32 v[70:71], v[84:85], v[92:93], v[88:89]
	v_mul_f32_e32 v65, v69, v69
	v_pk_fma_f32 v[70:71], v[70:71], s[24:25], v[66:67] op_sel_hi:[1,0,1]
	v_add_f32_e32 v64, v68, v69
	v_fmac_f32_e32 v65, v68, v68
	v_add_f32_e32 v64, v70, v64
	v_fmac_f32_e32 v65, v70, v70
	v_add_f32_e32 v64, v71, v64
	v_fmac_f32_e32 v65, v71, v71
	v_add_f32_e32 v64, v72, v64
	v_add_f32_e32 v65, v73, v65
	ds_bpermute_b32 v66, v116, v64
	ds_bpermute_b32 v67, v116, v65
	global_store_dwordx4 v[100:101], v[68:71], off offset:528
	s_waitcnt lgkmcnt(1)
	v_add_f32_e32 v64, v64, v66
	s_waitcnt lgkmcnt(0)
	v_add_f32_e32 v65, v65, v67
	ds_bpermute_b32 v66, v114, v64
	ds_bpermute_b32 v67, v114, v65
	s_mov_b32 s100, -1
	s_mov_b32 s101, 0
	s_mov_b32 s98, 0xffff0000
	s_mov_b32 s99, 0
	s_and_saveexec_b64 s[28:29], s[100:101]
	s_cbranch_execz .LBB0_2853
	v_lshl_add_u64 v[68:69], s[10:11], 0, v[80:81]
	s_waitcnt lgkmcnt(1)
	v_add_f32_e32 v64, v64, v66
	s_waitcnt lgkmcnt(0)
	v_add_f32_e32 v65, v65, v67
	v_cndmask_b32_e64 v64, v64, v65, s[98:99]
	v_cndmask_b32_e64 v65, 0, 4, s[98:99]
	v_or_b32_e32 v68, v68, v65
	v_mov_b32_e32 v255, v64
	flat_atomic_add_f32 v[250:251], v252
	flat_atomic_add_f32 v[250:251], v253 offset:128
	flat_atomic_add_f32 v[250:251], v254 offset:256
	flat_atomic_add_f32 v[250:251], v255 offset:384
; DEVI unsigned pk2(float lo, float hi) { unsigned r; asm("v_cvt_pk_bf16_f32 %0, %1, %2" : "=v"(r) : "v"(lo), "v"(hi)); return r; }
;     DEVI void operator()(const f32x4 (&acc)[2][2][4][2], const pg8::Unit& u, int wr, int wc, int fr, int fq) const {
;     ...
;                 const int row = row0 + ai * 128 + m * 16; float mu, rs; row_stats(stin, row, mu, rs);
;                 float sum = 0.f, sq = 0.f;
; #pragma unroll
;                 for (int bj = 0; bj < 2; ++bj) {
;                     f32x4 z[2];
; #pragma unroll
;                     for (int n = 0; n < 2; ++n) {
;                         const int col = colb + bj * 128 + 4 * n;
;                         f32x4 xv = *(const f32x4*)(zsrc + (size_t)row * DM + col);
;                         if (stin) { const f32x4 gv = *(const f32x4*)(gin + col), bv = *(const f32x4*)(bin + col); xv = (xv - mu) * rs * gv + bv; }
;                         f32x4 zz = ALPHA * xv + acc[ai][bj][m][n];
;                         if (bias) zz += *(const f32x4*)(bias + col);
;                         *(f32x4*)(zdst + (size_t)row * DM + col) = zz;
;                         sum += zz[0] + zz[1] + zz[2] + zz[3]; sq += zz[0] * zz[0] + zz[1] * zz[1] + zz[2] * zz[2] + zz[3] * zz[3];
;                         z[n] = zz;
;                     }
;                     u32x4 o; o.x = pk2(z[0][0], z[0][1]); o.y = pk2(z[0][2], z[0][3]); o.z = pk2(z[1][0], z[1][1]); o.w = pk2(z[1][2], z[1][3]);
;                     if (zb) *(u32x4*)(zb + (size_t)row * DM + colb + bj * 128) = o;
;                 }
;                 sum += __shfl_xor(sum, 16); sq += __shfl_xor(sq, 16);
;                 sum += __shfl_xor(sum, 32); sq += __shfl_xor(sq, 32);
;                 if (fq == 0) { atomicAdd(stout + 2 * (size_t)row, sum); atomicAdd(stout + 2 * (size_t)row + 1, sq); }
.LBB0_2853:
	s_or_b64 exec, exec, s[28:29]
	s_waitcnt lgkmcnt(0)
	v_add_u32_e32 v66, 0x80, v154
	v_ashrrev_i32_e32 v67, 31, v66
	v_lshlrev_b64 v[64:65], 3, v[66:67]
	v_lshl_add_u64 v[68:69], s[12:13], 0, v[64:65]
	flat_load_dwordx2 v[82:83], v[68:69]
	v_lshlrev_b64 v[66:67], 12, v[66:67]
	v_lshl_add_u64 v[66:67], s[46:47], 0, v[66:67]
	v_lshl_add_u64 v[84:85], v[144:145], 2, v[66:67]
	global_load_dwordx4 v[66:69], v[84:85], off
	global_load_dwordx4 v[70:73], v[150:151], off
	global_load_dwordx4 v[74:77], v[152:153], off
	global_load_dwordx4 v[78:81], v[84:85], off offset:16
	s_waitcnt vmcnt(0) lgkmcnt(0)
	v_pk_mul_f32 v[82:83], v[82:83], s[22:23] op_sel:[1,0] op_sel_hi:[0,0]
	v_fma_f32 v82, -v83, v83, v82
	v_max_f32_e32 v82, 0, v82
	v_add_f32_e32 v82, 0x3727c5ac, v82
	v_mul_f32_e32 v86, 0x4b800000, v82
	v_cmp_gt_f32_e32 vcc, s55, v82
	v_sub_f32_e32 v67, v67, v83
	v_sub_f32_e32 v66, v66, v83
	v_cndmask_b32_e32 v82, v82, v86, vcc
	v_rsq_f32_e32 v82, v82
	v_sub_f32_e32 v69, v69, v83
	v_sub_f32_e32 v68, v68, v83
	v_sub_f32_e32 v79, v79, v83
	v_mul_f32_e32 v86, 0x45800000, v82
	v_cndmask_b32_e32 v82, v82, v86, vcc
	v_pk_mul_f32 v[68:69], v[68:69], v[82:83] op_sel_hi:[1,0]
	v_pk_mul_f32 v[66:67], v[66:67], v[82:83] op_sel_hi:[1,0]
	v_pk_fma_f32 v[68:69], v[72:73], v[68:69], v[76:77]
	v_pk_fma_f32 v[66:67], v[70:71], v[66:67], v[74:75]
	v_pk_fma_f32 v[62:63], v[68:69], s[24:25], v[62:63] op_sel_hi:[1,0,1]
	v_pk_fma_f32 v[60:61], v[66:67], s[24:25], v[60:61] op_sel_hi:[1,0,1]
	global_store_dwordx4 v[84:85], v[60:63], off
	global_load_dwordx4 v[66:69], v[146:147], off
	global_load_dwordx4 v[70:73], v[148:149], off
	global_load_dwordx4 v[74:77], v[84:85], off offset:512
	v_sub_f32_e32 v78, v78, v83
	v_sub_f32_e32 v81, v81, v83
	v_sub_f32_e32 v80, v80, v83
	v_pk_mul_f32 v[80:81], v[80:81], v[82:83] op_sel_hi:[1,0]
	v_pk_mul_f32 v[78:79], v[78:79], v[82:83] op_sel_hi:[1,0]
	s_waitcnt vmcnt(1)
	v_pk_fma_f32 v[68:69], v[68:69], v[80:81], v[72:73]
	v_pk_fma_f32 v[66:67], v[66:67], v[78:79], v[70:71]
	v_pk_fma_f32 v[58:59], v[68:69], s[24:25], v[58:59] op_sel_hi:[1,0,1]
	v_pk_fma_f32 v[56:57], v[66:67], s[24:25], v[56:57] op_sel_hi:[1,0,1]
	global_store_dwordx4 v[84:85], v[56:59], off offset:16
	global_load_dwordx4 v[66:69], v[124:125], off
	global_load_dwordx4 v[70:73], v[126:127], off
	global_load_dwordx4 v[78:81], v[84:85], off offset:528
	s_waitcnt vmcnt(4)
	v_sub_f32_e32 v75, v75, v83
	v_sub_f32_e32 v74, v74, v83
	v_sub_f32_e32 v77, v77, v83
	v_sub_f32_e32 v76, v76, v83
	v_pk_mul_f32 v[76:77], v[82:83], v[76:77] op_sel_hi:[0,1]
	v_pk_mul_f32 v[74:75], v[82:83], v[74:75] op_sel_hi:[0,1]
	s_waitcnt vmcnt(1)
	v_pk_fma_f32 v[66:67], v[66:67], v[74:75], v[70:71]
	v_pk_fma_f32 v[68:69], v[68:69], v[76:77], v[72:73]
	v_pk_fma_f32 v[52:53], v[66:67], s[24:25], v[52:53] op_sel_hi:[1,0,1]
	v_pk_fma_f32 v[54:55], v[68:69], s[24:25], v[54:55] op_sel_hi:[1,0,1]
	global_store_dwordx4 v[84:85], v[52:55], off offset:512
	global_load_dwordx4 v[66:69], v[120:121], off
	global_load_dwordx4 v[70:73], v[122:123], off
	s_waitcnt vmcnt(3)
	v_sub_f32_e32 v74, v78, v83
	v_add_f32_e32 v78, v60, v61
	v_mul_f32_e32 v61, v61, v61
	v_fmac_f32_e32 v61, v60, v60
	v_add_f32_e32 v78, v62, v78
	v_fmac_f32_e32 v61, v62, v62
	v_add_f32_e32 v62, v56, v57
	v_mul_f32_e32 v57, v57, v57
	v_fmac_f32_e32 v57, v56, v56
	v_add_f32_e32 v62, v58, v62
	v_fmac_f32_e32 v57, v58, v58
	v_add_f32_e32 v58, v52, v53
	v_mul_f32_e32 v53, v53, v53
	v_add_f32_e32 v60, v63, v78
	v_fmac_f32_e32 v53, v52, v52
	v_sub_f32_e32 v75, v79, v83
	v_add_f32_e32 v60, 0, v60
	v_fmac_f32_e32 v61, v63, v63
	v_add_f32_e32 v56, v59, v62
	v_fmac_f32_e32 v57, v59, v59
	v_add_f32_e32 v58, v54, v58
	v_fmac_f32_e32 v53, v54, v54
	v_pk_mul_f32 v[74:75], v[82:83], v[74:75] op_sel_hi:[0,1]
	v_add_f32_e32 v56, v56, v60
	v_add_f32_e32 v57, v61, v57
	v_add_f32_e32 v52, v55, v58
	v_fmac_f32_e32 v53, v55, v55
	v_sub_f32_e32 v77, v81, v83
	v_sub_f32_e32 v76, v80, v83
	v_add_f32_e32 v56, v56, v52
	v_add_f32_e32 v57, v57, v53
	v_pk_mul_f32 v[76:77], v[82:83], v[76:77] op_sel_hi:[0,1]
	s_waitcnt vmcnt(0)
	v_pk_fma_f32 v[52:53], v[66:67], v[74:75], v[70:71]
	s_nop 0
	v_pk_fma_f32 v[52:53], v[52:53], s[24:25], v[48:49] op_sel_hi:[1,0,1]
	v_pk_fma_f32 v[54:55], v[68:69], v[76:77], v[72:73]
	v_mul_f32_e32 v49, v53, v53
	v_pk_fma_f32 v[54:55], v[54:55], s[24:25], v[50:51] op_sel_hi:[1,0,1]
	v_add_f32_e32 v48, v52, v53
	v_fmac_f32_e32 v49, v52, v52
	v_add_f32_e32 v48, v54, v48
	v_fmac_f32_e32 v49, v54, v54
	v_add_f32_e32 v48, v55, v48
	v_fmac_f32_e32 v49, v55, v55
	v_add_f32_e32 v48, v56, v48
	v_add_f32_e32 v49, v57, v49
	ds_bpermute_b32 v50, v116, v48
	ds_bpermute_b32 v51, v116, v49
	global_store_dwordx4 v[84:85], v[52:55], off offset:528
	s_waitcnt lgkmcnt(1)
	v_add_f32_e32 v48, v48, v50
	s_waitcnt lgkmcnt(0)
	v_add_f32_e32 v49, v49, v51
	ds_bpermute_b32 v50, v114, v48
	ds_bpermute_b32 v51, v114, v49
	s_mov_b32 s100, -1
	s_mov_b32 s101, 0
	s_mov_b32 s98, 0xffff0000
	s_mov_b32 s99, 0
	s_and_saveexec_b64 s[28:29], s[100:101]
	s_cbranch_execz .LBB0_2855
	v_lshl_add_u64 v[52:53], s[10:11], 0, v[64:65]
	s_waitcnt lgkmcnt(1)
	v_add_f32_e32 v48, v48, v50
	s_waitcnt lgkmcnt(0)
	v_add_f32_e32 v49, v49, v51
	v_cndmask_b32_e64 v48, v48, v49, s[98:99]
	v_cndmask_b32_e64 v49, 0, 4, s[98:99]
	v_or_b32_e32 v52, v52, v49
	v_mov_b32_e32 v250, v52
	v_mov_b32_e32 v251, v53
	v_mov_b32_e32 v252, v48
; DEVI unsigned pk2(float lo, float hi) { unsigned r; asm("v_cvt_pk_bf16_f32 %0, %1, %2" : "=v"(r) : "v"(lo), "v"(hi)); return r; }
;     DEVI void operator()(const f32x4 (&acc)[2][2][4][2], const pg8::Unit& u, int wr, int wc, int fr, int fq) const {
;     ...
;                 const int row = row0 + ai * 128 + m * 16; float mu, rs; row_stats(stin, row, mu, rs);
;                 float sum = 0.f, sq = 0.f;
; #pragma unroll
;                 for (int bj = 0; bj < 2; ++bj) {
;                     f32x4 z[2];
; #pragma unroll
;                     for (int n = 0; n < 2; ++n) {
;                         const int col = colb + bj * 128 + 4 * n;
;                         f32x4 xv = *(const f32x4*)(zsrc + (size_t)row * DM + col);
;                         if (stin) { const f32x4 gv = *(const f32x4*)(gin + col), bv = *(const f32x4*)(bin + col); xv = (xv - mu) * rs * gv + bv; }
;                         f32x4 zz = ALPHA * xv + acc[ai][bj][m][n];
;                         if (bias) zz += *(const f32x4*)(bias + col);
;                         *(f32x4*)(zdst + (size_t)row * DM + col) = zz;
;                         sum += zz[0] + zz[1] + zz[2] + zz[3]; sq += zz[0] * zz[0] + zz[1] * zz[1] + zz[2] * zz[2] + zz[3] * zz[3];
;                         z[n] = zz;
;                     }
;                     u32x4 o; o.x = pk2(z[0][0], z[0][1]); o.y = pk2(z[0][2], z[0][3]); o.z = pk2(z[1][0], z[1][1]); o.w = pk2(z[1][2], z[1][3]);
;                     if (zb) *(u32x4*)(zb + (size_t)row * DM + colb + bj * 128) = o;
;                 }
;                 sum += __shfl_xor(sum, 16); sq += __shfl_xor(sq, 16);
;                 sum += __shfl_xor(sum, 32); sq += __shfl_xor(sq, 32);
;                 if (fq == 0) { atomicAdd(stout + 2 * (size_t)row, sum); atomicAdd(stout + 2 * (size_t)row + 1, sq); }
.LBB0_2855:
	s_or_b64 exec, exec, s[28:29]
	s_waitcnt lgkmcnt(0)
	v_add_u32_e32 v50, 0x90, v154
	v_ashrrev_i32_e32 v51, 31, v50
	v_lshlrev_b64 v[48:49], 3, v[50:51]
	v_lshl_add_u64 v[52:53], s[12:13], 0, v[48:49]
	flat_load_dwordx2 v[66:67], v[52:53]
	v_lshlrev_b64 v[50:51], 12, v[50:51]
	v_lshl_add_u64 v[50:51], s[46:47], 0, v[50:51]
	v_lshl_add_u64 v[68:69], v[144:145], 2, v[50:51]
	global_load_dwordx4 v[50:53], v[68:69], off
	global_load_dwordx4 v[54:57], v[150:151], off
	global_load_dwordx4 v[58:61], v[152:153], off
	global_load_dwordx4 v[62:65], v[68:69], off offset:16
	s_waitcnt vmcnt(0) lgkmcnt(0)
	v_pk_mul_f32 v[66:67], v[66:67], s[22:23] op_sel:[1,0] op_sel_hi:[0,0]
	v_fma_f32 v66, -v67, v67, v66
	v_max_f32_e32 v66, 0, v66
	v_add_f32_e32 v66, 0x3727c5ac, v66
	v_mul_f32_e32 v70, 0x4b800000, v66
	v_cmp_gt_f32_e32 vcc, s55, v66
	v_sub_f32_e32 v51, v51, v67
	v_sub_f32_e32 v50, v50, v67
	v_cndmask_b32_e32 v66, v66, v70, vcc
	v_rsq_f32_e32 v66, v66
	v_sub_f32_e32 v53, v53, v67
	v_sub_f32_e32 v52, v52, v67
	v_sub_f32_e32 v63, v63, v67
	v_mul_f32_e32 v70, 0x45800000, v66
	v_cndmask_b32_e32 v66, v66, v70, vcc
	v_pk_mul_f32 v[52:53], v[52:53], v[66:67] op_sel_hi:[1,0]
	v_pk_mul_f32 v[50:51], v[50:51], v[66:67] op_sel_hi:[1,0]
	v_pk_fma_f32 v[52:53], v[56:57], v[52:53], v[60:61]
	v_pk_fma_f32 v[50:51], v[54:55], v[50:51], v[58:59]
	v_pk_fma_f32 v[46:47], v[52:53], s[24:25], v[46:47] op_sel_hi:[1,0,1]
	v_pk_fma_f32 v[44:45], v[50:51], s[24:25], v[44:45] op_sel_hi:[1,0,1]
	global_store_dwordx4 v[68:69], v[44:47], off
	global_load_dwordx4 v[50:53], v[146:147], off
	global_load_dwordx4 v[54:57], v[148:149], off
	global_load_dwordx4 v[58:61], v[68:69], off offset:512
	v_sub_f32_e32 v62, v62, v67
	v_sub_f32_e32 v65, v65, v67
	v_sub_f32_e32 v64, v64, v67
	v_pk_mul_f32 v[64:65], v[64:65], v[66:67] op_sel_hi:[1,0]
	v_pk_mul_f32 v[62:63], v[62:63], v[66:67] op_sel_hi:[1,0]
	s_waitcnt vmcnt(1)
	v_pk_fma_f32 v[52:53], v[52:53], v[64:65], v[56:57]
	v_pk_fma_f32 v[50:51], v[50:51], v[62:63], v[54:55]
	v_pk_fma_f32 v[42:43], v[52:53], s[24:25], v[42:43] op_sel_hi:[1,0,1]
	v_pk_fma_f32 v[40:41], v[50:51], s[24:25], v[40:41] op_sel_hi:[1,0,1]
	global_store_dwordx4 v[68:69], v[40:43], off offset:16
	global_load_dwordx4 v[50:53], v[124:125], off
	global_load_dwordx4 v[54:57], v[126:127], off
	global_load_dwordx4 v[62:65], v[68:69], off offset:528
	s_waitcnt vmcnt(4)
	v_sub_f32_e32 v59, v59, v67
	v_sub_f32_e32 v58, v58, v67
	v_sub_f32_e32 v61, v61, v67
	v_sub_f32_e32 v60, v60, v67
	v_pk_mul_f32 v[60:61], v[66:67], v[60:61] op_sel_hi:[0,1]
	v_pk_mul_f32 v[58:59], v[66:67], v[58:59] op_sel_hi:[0,1]
	s_waitcnt vmcnt(1)
	v_pk_fma_f32 v[50:51], v[50:51], v[58:59], v[54:55]
	v_pk_fma_f32 v[52:53], v[52:53], v[60:61], v[56:57]
	v_pk_fma_f32 v[36:37], v[50:51], s[24:25], v[36:37] op_sel_hi:[1,0,1]
	v_pk_fma_f32 v[38:39], v[52:53], s[24:25], v[38:39] op_sel_hi:[1,0,1]
	global_store_dwordx4 v[68:69], v[36:39], off offset:512
	global_load_dwordx4 v[50:53], v[120:121], off
	global_load_dwordx4 v[54:57], v[122:123], off
	s_waitcnt vmcnt(3)
	v_sub_f32_e32 v58, v62, v67
	v_add_f32_e32 v62, v44, v45
	v_mul_f32_e32 v45, v45, v45
	v_fmac_f32_e32 v45, v44, v44
	v_add_f32_e32 v62, v46, v62
	v_fmac_f32_e32 v45, v46, v46
	v_add_f32_e32 v46, v40, v41
	v_mul_f32_e32 v41, v41, v41
	v_fmac_f32_e32 v41, v40, v40
	v_add_f32_e32 v46, v42, v46
	v_fmac_f32_e32 v41, v42, v42
	v_add_f32_e32 v42, v36, v37
	v_mul_f32_e32 v37, v37, v37
	v_add_f32_e32 v44, v47, v62
	v_fmac_f32_e32 v37, v36, v36
	v_sub_f32_e32 v59, v63, v67
	v_add_f32_e32 v44, 0, v44
	v_fmac_f32_e32 v45, v47, v47
	v_add_f32_e32 v40, v43, v46
	v_fmac_f32_e32 v41, v43, v43
	v_add_f32_e32 v42, v38, v42
	v_fmac_f32_e32 v37, v38, v38
	v_pk_mul_f32 v[58:59], v[66:67], v[58:59] op_sel_hi:[0,1]
	v_add_f32_e32 v40, v40, v44
	v_add_f32_e32 v41, v45, v41
	v_add_f32_e32 v36, v39, v42
	v_fmac_f32_e32 v37, v39, v39
	v_sub_f32_e32 v61, v65, v67
	v_sub_f32_e32 v60, v64, v67
	v_add_f32_e32 v40, v40, v36
	v_add_f32_e32 v41, v41, v37
	v_pk_mul_f32 v[60:61], v[66:67], v[60:61] op_sel_hi:[0,1]
	s_waitcnt vmcnt(0)
	v_pk_fma_f32 v[36:37], v[50:51], v[58:59], v[54:55]
	s_nop 0
	v_pk_fma_f32 v[36:37], v[36:37], s[24:25], v[32:33] op_sel_hi:[1,0,1]
	v_pk_fma_f32 v[38:39], v[52:53], v[60:61], v[56:57]
	v_mul_f32_e32 v33, v37, v37
	v_pk_fma_f32 v[38:39], v[38:39], s[24:25], v[34:35] op_sel_hi:[1,0,1]
	v_add_f32_e32 v32, v36, v37
	v_fmac_f32_e32 v33, v36, v36
	v_add_f32_e32 v32, v38, v32
	v_fmac_f32_e32 v33, v38, v38
	v_add_f32_e32 v32, v39, v32
	v_fmac_f32_e32 v33, v39, v39
	v_add_f32_e32 v32, v40, v32
	v_add_f32_e32 v33, v41, v33
	ds_bpermute_b32 v34, v116, v32
	ds_bpermute_b32 v35, v116, v33
	global_store_dwordx4 v[68:69], v[36:39], off offset:528
	s_waitcnt lgkmcnt(1)
	v_add_f32_e32 v32, v32, v34
	s_waitcnt lgkmcnt(0)
	v_add_f32_e32 v33, v33, v35
	ds_bpermute_b32 v34, v114, v32
	ds_bpermute_b32 v35, v114, v33
	s_mov_b32 s100, -1
	s_mov_b32 s101, 0
	s_mov_b32 s98, 0xffff0000
	s_mov_b32 s99, 0
	s_and_saveexec_b64 s[28:29], s[100:101]
	s_cbranch_execz .LBB0_2857
	v_lshl_add_u64 v[36:37], s[10:11], 0, v[48:49]
	s_waitcnt lgkmcnt(1)
	v_add_f32_e32 v32, v32, v34
	s_waitcnt lgkmcnt(0)
	v_add_f32_e32 v33, v33, v35
	v_cndmask_b32_e64 v32, v32, v33, s[98:99]
	v_cndmask_b32_e64 v33, 0, 4, s[98:99]
	v_or_b32_e32 v36, v36, v33
	v_mov_b32_e32 v253, v32
; DEVI unsigned pk2(float lo, float hi) { unsigned r; asm("v_cvt_pk_bf16_f32 %0, %1, %2" : "=v"(r) : "v"(lo), "v"(hi)); return r; }
;     DEVI void operator()(const f32x4 (&acc)[2][2][4][2], const pg8::Unit& u, int wr, int wc, int fr, int fq) const {
;     ...
;                 const int row = row0 + ai * 128 + m * 16; float mu, rs; row_stats(stin, row, mu, rs);
;                 float sum = 0.f, sq = 0.f;
; #pragma unroll
;                 for (int bj = 0; bj < 2; ++bj) {
;                     f32x4 z[2];
; #pragma unroll
;                     for (int n = 0; n < 2; ++n) {
;                         const int col = colb + bj * 128 + 4 * n;
;                         f32x4 xv = *(const f32x4*)(zsrc + (size_t)row * DM + col);
;                         if (stin) { const f32x4 gv = *(const f32x4*)(gin + col), bv = *(const f32x4*)(bin + col); xv = (xv - mu) * rs * gv + bv; }
;                         f32x4 zz = ALPHA * xv + acc[ai][bj][m][n];
;                         if (bias) zz += *(const f32x4*)(bias + col);
;                         *(f32x4*)(zdst + (size_t)row * DM + col) = zz;
;                         sum += zz[0] + zz[1] + zz[2] + zz[3]; sq += zz[0] * zz[0] + zz[1] * zz[1] + zz[2] * zz[2] + zz[3] * zz[3];
;                         z[n] = zz;
;                     }
;                     u32x4 o; o.x = pk2(z[0][0], z[0][1]); o.y = pk2(z[0][2], z[0][3]); o.z = pk2(z[1][0], z[1][1]); o.w = pk2(z[1][2], z[1][3]);
;                     if (zb) *(u32x4*)(zb + (size_t)row * DM + colb + bj * 128) = o;
;                 }
;                 sum += __shfl_xor(sum, 16); sq += __shfl_xor(sq, 16);
;                 sum += __shfl_xor(sum, 32); sq += __shfl_xor(sq, 32);
;                 if (fq == 0) { atomicAdd(stout + 2 * (size_t)row, sum); atomicAdd(stout + 2 * (size_t)row + 1, sq); }
.LBB0_2857:
	s_or_b64 exec, exec, s[28:29]
	s_waitcnt lgkmcnt(0)
	v_add_u32_e32 v34, 0xa0, v154
	v_ashrrev_i32_e32 v35, 31, v34
	v_lshlrev_b64 v[32:33], 3, v[34:35]
	v_lshl_add_u64 v[36:37], s[12:13], 0, v[32:33]
	flat_load_dwordx2 v[50:51], v[36:37]
	v_lshlrev_b64 v[34:35], 12, v[34:35]
	v_lshl_add_u64 v[34:35], s[46:47], 0, v[34:35]
	v_lshl_add_u64 v[52:53], v[144:145], 2, v[34:35]
	global_load_dwordx4 v[34:37], v[52:53], off
	global_load_dwordx4 v[38:41], v[150:151], off
	global_load_dwordx4 v[42:45], v[152:153], off
	global_load_dwordx4 v[46:49], v[52:53], off offset:16
	s_waitcnt vmcnt(0) lgkmcnt(0)
	v_pk_mul_f32 v[50:51], v[50:51], s[22:23] op_sel:[1,0] op_sel_hi:[0,0]
	v_fma_f32 v50, -v51, v51, v50
	v_max_f32_e32 v50, 0, v50
	v_add_f32_e32 v50, 0x3727c5ac, v50
	v_mul_f32_e32 v54, 0x4b800000, v50
	v_cmp_gt_f32_e32 vcc, s55, v50
	v_sub_f32_e32 v35, v35, v51
	v_sub_f32_e32 v34, v34, v51
	v_cndmask_b32_e32 v50, v50, v54, vcc
	v_rsq_f32_e32 v50, v50
	v_sub_f32_e32 v37, v37, v51
	v_sub_f32_e32 v36, v36, v51
	v_sub_f32_e32 v47, v47, v51
	v_mul_f32_e32 v54, 0x45800000, v50
	v_cndmask_b32_e32 v50, v50, v54, vcc
	v_pk_mul_f32 v[36:37], v[36:37], v[50:51] op_sel_hi:[1,0]
	v_pk_mul_f32 v[34:35], v[34:35], v[50:51] op_sel_hi:[1,0]
	v_pk_fma_f32 v[36:37], v[40:41], v[36:37], v[44:45]
	v_pk_fma_f32 v[34:35], v[38:39], v[34:35], v[42:43]
	v_pk_fma_f32 v[30:31], v[36:37], s[24:25], v[30:31] op_sel_hi:[1,0,1]
	v_pk_fma_f32 v[28:29], v[34:35], s[24:25], v[28:29] op_sel_hi:[1,0,1]
	global_store_dwordx4 v[52:53], v[28:31], off
	global_load_dwordx4 v[34:37], v[146:147], off
	global_load_dwordx4 v[38:41], v[148:149], off
	global_load_dwordx4 v[42:45], v[52:53], off offset:512
	v_sub_f32_e32 v46, v46, v51
	v_sub_f32_e32 v49, v49, v51
	v_sub_f32_e32 v48, v48, v51
	v_pk_mul_f32 v[48:49], v[48:49], v[50:51] op_sel_hi:[1,0]
	v_pk_mul_f32 v[46:47], v[46:47], v[50:51] op_sel_hi:[1,0]
	s_waitcnt vmcnt(1)
	v_pk_fma_f32 v[36:37], v[36:37], v[48:49], v[40:41]
	v_pk_fma_f32 v[34:35], v[34:35], v[46:47], v[38:39]
	v_pk_fma_f32 v[26:27], v[36:37], s[24:25], v[26:27] op_sel_hi:[1,0,1]
	v_pk_fma_f32 v[24:25], v[34:35], s[24:25], v[24:25] op_sel_hi:[1,0,1]
	global_store_dwordx4 v[52:53], v[24:27], off offset:16
	global_load_dwordx4 v[34:37], v[124:125], off
	global_load_dwordx4 v[38:41], v[126:127], off
	global_load_dwordx4 v[46:49], v[52:53], off offset:528
	s_waitcnt vmcnt(4)
	v_sub_f32_e32 v43, v43, v51
	v_sub_f32_e32 v42, v42, v51
	v_sub_f32_e32 v45, v45, v51
	v_sub_f32_e32 v44, v44, v51
	v_pk_mul_f32 v[44:45], v[50:51], v[44:45] op_sel_hi:[0,1]
	v_pk_mul_f32 v[42:43], v[50:51], v[42:43] op_sel_hi:[0,1]
	s_waitcnt vmcnt(1)
	v_pk_fma_f32 v[34:35], v[34:35], v[42:43], v[38:39]
	v_pk_fma_f32 v[36:37], v[36:37], v[44:45], v[40:41]
	v_pk_fma_f32 v[20:21], v[34:35], s[24:25], v[20:21] op_sel_hi:[1,0,1]
	v_pk_fma_f32 v[22:23], v[36:37], s[24:25], v[22:23] op_sel_hi:[1,0,1]
	global_store_dwordx4 v[52:53], v[20:23], off offset:512
	global_load_dwordx4 v[34:37], v[120:121], off
	global_load_dwordx4 v[38:41], v[122:123], off
	s_waitcnt vmcnt(3)
	v_sub_f32_e32 v42, v46, v51
	v_add_f32_e32 v46, v28, v29
	v_mul_f32_e32 v29, v29, v29
	v_fmac_f32_e32 v29, v28, v28
	v_add_f32_e32 v46, v30, v46
	v_fmac_f32_e32 v29, v30, v30
	v_add_f32_e32 v30, v24, v25
	v_mul_f32_e32 v25, v25, v25
	v_fmac_f32_e32 v25, v24, v24
	v_add_f32_e32 v30, v26, v30
	v_fmac_f32_e32 v25, v26, v26
	v_add_f32_e32 v26, v20, v21
	v_mul_f32_e32 v21, v21, v21
	v_add_f32_e32 v28, v31, v46
	v_fmac_f32_e32 v21, v20, v20
	v_sub_f32_e32 v43, v47, v51
	v_add_f32_e32 v28, 0, v28
	v_fmac_f32_e32 v29, v31, v31
	v_add_f32_e32 v24, v27, v30
	v_fmac_f32_e32 v25, v27, v27
	v_add_f32_e32 v26, v22, v26
	v_fmac_f32_e32 v21, v22, v22
	v_pk_mul_f32 v[42:43], v[50:51], v[42:43] op_sel_hi:[0,1]
	v_add_f32_e32 v24, v24, v28
	v_add_f32_e32 v25, v29, v25
	v_add_f32_e32 v20, v23, v26
	v_fmac_f32_e32 v21, v23, v23
	v_sub_f32_e32 v45, v49, v51
	v_sub_f32_e32 v44, v48, v51
	v_add_f32_e32 v24, v24, v20
	v_add_f32_e32 v25, v25, v21
	v_pk_mul_f32 v[44:45], v[50:51], v[44:45] op_sel_hi:[0,1]
	s_waitcnt vmcnt(0)
	v_pk_fma_f32 v[20:21], v[34:35], v[42:43], v[38:39]
	s_nop 0
	v_pk_fma_f32 v[20:21], v[20:21], s[24:25], v[16:17] op_sel_hi:[1,0,1]
	v_pk_fma_f32 v[22:23], v[36:37], v[44:45], v[40:41]
	v_mul_f32_e32 v17, v21, v21
	v_pk_fma_f32 v[22:23], v[22:23], s[24:25], v[18:19] op_sel_hi:[1,0,1]
	v_add_f32_e32 v16, v20, v21
	v_fmac_f32_e32 v17, v20, v20
	v_add_f32_e32 v16, v22, v16
	v_fmac_f32_e32 v17, v22, v22
	v_add_f32_e32 v16, v23, v16
	v_fmac_f32_e32 v17, v23, v23
	v_add_f32_e32 v16, v24, v16
	v_add_f32_e32 v17, v25, v17
	ds_bpermute_b32 v18, v116, v16
	ds_bpermute_b32 v19, v116, v17
	global_store_dwordx4 v[52:53], v[20:23], off offset:528
	s_waitcnt lgkmcnt(1)
	v_add_f32_e32 v16, v16, v18
	s_waitcnt lgkmcnt(0)
	v_add_f32_e32 v17, v17, v19
	ds_bpermute_b32 v18, v114, v16
	ds_bpermute_b32 v19, v114, v17
	s_mov_b32 s100, -1
	s_mov_b32 s101, 0
	s_mov_b32 s98, 0xffff0000
	s_mov_b32 s99, 0
	s_and_saveexec_b64 s[28:29], s[100:101]
	s_cbranch_execz .LBB0_2859
	v_lshl_add_u64 v[20:21], s[10:11], 0, v[32:33]
	s_waitcnt lgkmcnt(1)
	v_add_f32_e32 v16, v16, v18
	s_waitcnt lgkmcnt(0)
	v_add_f32_e32 v17, v17, v19
	v_cndmask_b32_e64 v16, v16, v17, s[98:99]
	v_cndmask_b32_e64 v17, 0, 4, s[98:99]
	v_or_b32_e32 v20, v20, v17
	v_mov_b32_e32 v254, v16
; DEVI unsigned pk2(float lo, float hi) { unsigned r; asm("v_cvt_pk_bf16_f32 %0, %1, %2" : "=v"(r) : "v"(lo), "v"(hi)); return r; }
;     DEVI void operator()(const f32x4 (&acc)[2][2][4][2], const pg8::Unit& u, int wr, int wc, int fr, int fq) const {
;     ...
;                 const int row = row0 + ai * 128 + m * 16; float mu, rs; row_stats(stin, row, mu, rs);
;                 float sum = 0.f, sq = 0.f;
; #pragma unroll
;                 for (int bj = 0; bj < 2; ++bj) {
;                     f32x4 z[2];
; #pragma unroll
;                     for (int n = 0; n < 2; ++n) {
;                         const int col = colb + bj * 128 + 4 * n;
;                         f32x4 xv = *(const f32x4*)(zsrc + (size_t)row * DM + col);
;                         if (stin) { const f32x4 gv = *(const f32x4*)(gin + col), bv = *(const f32x4*)(bin + col); xv = (xv - mu) * rs * gv + bv; }
;                         f32x4 zz = ALPHA * xv + acc[ai][bj][m][n];
;                         if (bias) zz += *(const f32x4*)(bias + col);
;                         *(f32x4*)(zdst + (size_t)row * DM + col) = zz;
;                         sum += zz[0] + zz[1] + zz[2] + zz[3]; sq += zz[0] * zz[0] + zz[1] * zz[1] + zz[2] * zz[2] + zz[3] * zz[3];
;                         z[n] = zz;
;                     }
;                     u32x4 o; o.x = pk2(z[0][0], z[0][1]); o.y = pk2(z[0][2], z[0][3]); o.z = pk2(z[1][0], z[1][1]); o.w = pk2(z[1][2], z[1][3]);
;                     if (zb) *(u32x4*)(zb + (size_t)row * DM + colb + bj * 128) = o;
;                 }
;                 sum += __shfl_xor(sum, 16); sq += __shfl_xor(sq, 16);
;                 sum += __shfl_xor(sum, 32); sq += __shfl_xor(sq, 32);
;                 if (fq == 0) { atomicAdd(stout + 2 * (size_t)row, sum); atomicAdd(stout + 2 * (size_t)row + 1, sq); }
.LBB0_2859:
	s_or_b64 exec, exec, s[28:29]
	s_waitcnt lgkmcnt(0)
	v_add_u32_e32 v18, 0xb0, v154
	v_ashrrev_i32_e32 v19, 31, v18
	v_lshlrev_b64 v[16:17], 3, v[18:19]
	v_lshl_add_u64 v[20:21], s[12:13], 0, v[16:17]
	flat_load_dwordx2 v[34:35], v[20:21]
	v_lshlrev_b64 v[18:19], 12, v[18:19]
	v_lshl_add_u64 v[18:19], s[46:47], 0, v[18:19]
	v_lshl_add_u64 v[36:37], v[144:145], 2, v[18:19]
	global_load_dwordx4 v[18:21], v[36:37], off
	global_load_dwordx4 v[22:25], v[150:151], off
	global_load_dwordx4 v[26:29], v[152:153], off
	global_load_dwordx4 v[30:33], v[36:37], off offset:16
	s_waitcnt vmcnt(0) lgkmcnt(0)
	v_pk_mul_f32 v[34:35], v[34:35], s[22:23] op_sel:[1,0] op_sel_hi:[0,0]
	v_fma_f32 v34, -v35, v35, v34
	v_max_f32_e32 v34, 0, v34
	v_add_f32_e32 v34, 0x3727c5ac, v34
	v_mul_f32_e32 v38, 0x4b800000, v34
	v_cmp_gt_f32_e32 vcc, s55, v34
	v_sub_f32_e32 v19, v19, v35
	v_sub_f32_e32 v18, v18, v35
	v_cndmask_b32_e32 v34, v34, v38, vcc
	v_rsq_f32_e32 v34, v34
	v_sub_f32_e32 v21, v21, v35
	v_sub_f32_e32 v20, v20, v35
	v_sub_f32_e32 v31, v31, v35
	v_mul_f32_e32 v38, 0x45800000, v34
	v_cndmask_b32_e32 v34, v34, v38, vcc
	v_pk_mul_f32 v[20:21], v[20:21], v[34:35] op_sel_hi:[1,0]
	v_pk_mul_f32 v[18:19], v[18:19], v[34:35] op_sel_hi:[1,0]
	v_pk_fma_f32 v[20:21], v[24:25], v[20:21], v[28:29]
	v_pk_fma_f32 v[18:19], v[22:23], v[18:19], v[26:27]
	v_pk_fma_f32 v[14:15], v[20:21], s[24:25], v[14:15] op_sel_hi:[1,0,1]
	v_pk_fma_f32 v[12:13], v[18:19], s[24:25], v[12:13] op_sel_hi:[1,0,1]
	global_store_dwordx4 v[36:37], v[12:15], off
	global_load_dwordx4 v[18:21], v[146:147], off
	global_load_dwordx4 v[22:25], v[148:149], off
	global_load_dwordx4 v[26:29], v[36:37], off offset:512
	v_sub_f32_e32 v30, v30, v35
	v_sub_f32_e32 v33, v33, v35
	v_sub_f32_e32 v32, v32, v35
	v_pk_mul_f32 v[32:33], v[32:33], v[34:35] op_sel_hi:[1,0]
	v_pk_mul_f32 v[30:31], v[30:31], v[34:35] op_sel_hi:[1,0]
	s_waitcnt vmcnt(1)
	v_pk_fma_f32 v[20:21], v[20:21], v[32:33], v[24:25]
	v_pk_fma_f32 v[18:19], v[18:19], v[30:31], v[22:23]
	v_pk_fma_f32 v[10:11], v[20:21], s[24:25], v[10:11] op_sel_hi:[1,0,1]
	v_pk_fma_f32 v[8:9], v[18:19], s[24:25], v[8:9] op_sel_hi:[1,0,1]
	global_store_dwordx4 v[36:37], v[8:11], off offset:16
	global_load_dwordx4 v[18:21], v[124:125], off
	global_load_dwordx4 v[22:25], v[126:127], off
	global_load_dwordx4 v[30:33], v[36:37], off offset:528
	s_waitcnt vmcnt(4)
	v_sub_f32_e32 v27, v27, v35
	v_sub_f32_e32 v26, v26, v35
	v_sub_f32_e32 v29, v29, v35
	v_sub_f32_e32 v28, v28, v35
	v_pk_mul_f32 v[28:29], v[34:35], v[28:29] op_sel_hi:[0,1]
	v_pk_mul_f32 v[26:27], v[34:35], v[26:27] op_sel_hi:[0,1]
	s_waitcnt vmcnt(1)
	v_pk_fma_f32 v[18:19], v[18:19], v[26:27], v[22:23]
	v_pk_fma_f32 v[20:21], v[20:21], v[28:29], v[24:25]
	v_pk_fma_f32 v[4:5], v[18:19], s[24:25], v[4:5] op_sel_hi:[1,0,1]
	v_pk_fma_f32 v[6:7], v[20:21], s[24:25], v[6:7] op_sel_hi:[1,0,1]
	global_store_dwordx4 v[36:37], v[4:7], off offset:512
	global_load_dwordx4 v[18:21], v[120:121], off
	global_load_dwordx4 v[22:25], v[122:123], off
	s_waitcnt vmcnt(3)
	v_sub_f32_e32 v26, v30, v35
	v_add_f32_e32 v30, v12, v13
	v_mul_f32_e32 v13, v13, v13
	v_fmac_f32_e32 v13, v12, v12
	v_add_f32_e32 v30, v14, v30
	v_fmac_f32_e32 v13, v14, v14
	v_add_f32_e32 v14, v8, v9
	v_mul_f32_e32 v9, v9, v9
	v_fmac_f32_e32 v9, v8, v8
	v_add_f32_e32 v14, v10, v14
	v_fmac_f32_e32 v9, v10, v10
	v_add_f32_e32 v10, v4, v5
	v_mul_f32_e32 v5, v5, v5
	v_add_f32_e32 v12, v15, v30
	v_fmac_f32_e32 v5, v4, v4
	v_sub_f32_e32 v27, v31, v35
	v_add_f32_e32 v12, 0, v12
	v_fmac_f32_e32 v13, v15, v15
	v_add_f32_e32 v8, v11, v14
	v_fmac_f32_e32 v9, v11, v11
	v_add_f32_e32 v10, v6, v10
	v_fmac_f32_e32 v5, v6, v6
	v_pk_mul_f32 v[26:27], v[34:35], v[26:27] op_sel_hi:[0,1]
	v_add_f32_e32 v8, v8, v12
	v_add_f32_e32 v9, v13, v9
	v_add_f32_e32 v4, v7, v10
	v_fmac_f32_e32 v5, v7, v7
	v_sub_f32_e32 v29, v33, v35
	v_sub_f32_e32 v28, v32, v35
	v_add_f32_e32 v8, v8, v4
	v_add_f32_e32 v9, v9, v5
	v_pk_mul_f32 v[28:29], v[34:35], v[28:29] op_sel_hi:[0,1]
	s_waitcnt vmcnt(0)
	v_pk_fma_f32 v[4:5], v[18:19], v[26:27], v[22:23]
	s_nop 0
	v_pk_fma_f32 v[4:5], v[4:5], s[24:25], v[0:1] op_sel_hi:[1,0,1]
	v_pk_fma_f32 v[6:7], v[20:21], v[28:29], v[24:25]
	v_mul_f32_e32 v1, v5, v5
	v_pk_fma_f32 v[6:7], v[6:7], s[24:25], v[2:3] op_sel_hi:[1,0,1]
	v_add_f32_e32 v0, v4, v5
	v_fmac_f32_e32 v1, v4, v4
	v_add_f32_e32 v0, v6, v0
	v_fmac_f32_e32 v1, v6, v6
	v_add_f32_e32 v0, v7, v0
	v_fmac_f32_e32 v1, v7, v7
	v_add_f32_e32 v0, v8, v0
	v_add_f32_e32 v1, v9, v1
	ds_bpermute_b32 v2, v116, v0
	ds_bpermute_b32 v3, v116, v1
	global_store_dwordx4 v[36:37], v[4:7], off offset:528
	s_waitcnt lgkmcnt(1)
	v_add_f32_e32 v0, v0, v2
	s_waitcnt lgkmcnt(0)
	v_add_f32_e32 v1, v1, v3
	ds_bpermute_b32 v2, v114, v0
	ds_bpermute_b32 v3, v114, v1
	s_mov_b32 s100, -1
	s_mov_b32 s101, 0
	s_mov_b32 s98, 0xffff0000
	s_mov_b32 s99, 0
	s_and_saveexec_b64 s[28:29], s[100:101]
	s_cbranch_execz .LBB0_2861
	v_lshl_add_u64 v[4:5], s[10:11], 0, v[16:17]
	s_waitcnt lgkmcnt(1)
	v_add_f32_e32 v0, v0, v2
	s_waitcnt lgkmcnt(0)
	v_add_f32_e32 v1, v1, v3
	v_cndmask_b32_e64 v0, v0, v1, s[98:99]
	v_cndmask_b32_e64 v1, 0, 4, s[98:99]
	v_or_b32_e32 v4, v4, v1
	v_mov_b32_e32 v255, v0
	flat_atomic_add_f32 v[250:251], v252
	flat_atomic_add_f32 v[250:251], v253 offset:128
	flat_atomic_add_f32 v[250:251], v254 offset:256
	flat_atomic_add_f32 v[250:251], v255 offset:384
